# P5 u-pass: single round-major traversal for all 8 tokens of a wave (two tokens share one MFMA B operand: columns 0-7 / 8-15), halves compulsory L2 fills of the fp4 U table
# speedup vs baseline: 1.0991x; 1.0029x over previous
; __device__ __forceinline__ void peer_token(const Params& P, int t, int lane, int* sidx, float* sval, const int* sid, const float* sgate, const unsigned* szero) {
;     ...
;     {
;         typedef int v8i __attribute__((ext_vector_type(8)));
;         const unsigned char* Ub = P.ws + WS_U;
;         const unsigned lofs = 64u * (unsigned)(lr >> 3) + 16u * (unsigned)g;
;         const unsigned char* bsrc = (lr < 4) ? (((lr & 2) ? slo : shi) + 128 * (lr & 1) + 16 * g) : (const unsigned char*)szero;
;         const int bstep = (lr < 4) ? 256 : 0, bhalf = (lr < 4) ? 64 : 16;
;         v8i Bv[4];
; #pragma unroll
;         for (int st = 0; st < 4; ++st) {
;             const uint4 b0 = *(const uint4*)(bsrc + bstep * st), b1 = *(const uint4*)(bsrc + bstep * st + bhalf);
;             Bv[st] = (v8i){(int)b0.x, (int)b0.y, (int)b0.z, (int)b0.w, (int)b1.x, (int)b1.y, (int)b1.z, (int)b1.w};
;         }
;         __builtin_amdgcn_s_waitcnt(0xc07f);
;         __builtin_amdgcn_wave_barrier();
;         float* sact = (float*)sidx + 128 * (lr & 3) + 4 * (g & 1);
;         const bool owner = (lr < 4) && ((g >> 1) == (lr & 1));
;         uint4 abuf[2][2][4];
;         unsigned off2[2];
; #pragma unroll
;         for (int hh = 0; hh < 2; ++hh) off2[hh] = (unsigned)sid[8 * hh + (lr & 7)] * 512u + lofs;
; __global__ void __launch_bounds__(256, 2) mega(Params P) {
;     ...
;     {
;         unsigned* szero = (unsigned*)(smem + 40960);
;         if (tid < 16) szero[tid] = 0u;
;         __syncthreads();
;         unsigned char* res = smem + wave * 10240; unsigned char* work = res + 8192;
;         int* sidx = (int*)work; float* sval = (float*)(work + 1024);
;         int lane5 = lane;
;         asm volatile("" : "+v"(lane5));
;         const int tstride = G * 4;
;         for (int tb = bid * 4 + wave; tb < T2; tb += tstride * 8) {
.LBB0_1375:
	s_or_b64 exec, exec, s[18:19]
	v_cmp_gt_u32_e32 vcc, 16, v0
	s_barrier
	s_and_saveexec_b64 s[0:1], vcc
	v_lshl_add_u32 v0, v0, 2, 0
	v_mov_b32_e32 v2, 0
	ds_write_b32 v0, v2 offset:40960
	s_or_b64 exec, exec, s[0:1]
	s_movk_i32 s20, 0x4000
	v_cmp_gt_i32_e32 vcc, s20, v130
	s_waitcnt lgkmcnt(0)
	s_barrier
	s_and_saveexec_b64 s[0:1], vcc
	s_cbranch_execz .LBB0_1426
	s_movk_i32 s0, 0x2800
	v_and_b32_e32 v115, 7, v131
	v_mad_u32_u24 v114, v1, s0, 0
	v_lshlrev_b32_e32 v0, 7, v115
	v_mov_b32_e32 v1, 0
	v_ashrrev_i32_e32 v2, 3, v131
	v_lshl_add_u64 v[0:1], s[28:29], 0, v[0:1]
	s_mov_b64 s[0:1], 0xc075800
	v_lshl_add_u64 v[100:101], v[0:1], 0, s[0:1]
	v_lshlrev_b32_e32 v0, 10, v2
	v_lshlrev_b32_e32 v1, 6, v115
	s_add_u32 s4, s28, 0x93b3000
	v_add3_u32 v118, v114, v0, v1
	s_addc_u32 s5, s29, 0
	v_lshlrev_b32_e32 v1, 3, v131
	v_and_b32_e32 v3, 2, v131
	v_mul_lo_u32 v116, v2, s22
	s_add_u32 s6, s28, 0xf5a5800
	v_and_b32_e32 v1, 64, v1
	v_and_b32_e32 v2, -16, v131
	v_mov_b32_e32 v4, 0x2000
	v_mov_b32_e32 v5, 0x2400
	v_cmp_eq_u32_e32 vcc, 0, v3
	s_addc_u32 s7, s29, 0
	v_add_u32_e32 v120, v1, v2
	v_lshlrev_b32_e32 v1, 7, v131
	v_cndmask_b32_e32 v3, v4, v5, vcc
	s_add_u32 s8, s28, 0xf595800
	v_add_u32_e32 v3, v114, v3
	v_and_b32_e32 v1, 0x80, v1
	s_addc_u32 s9, s29, 0
	v_and_b32_e32 v0, 15, v131
	v_add3_u32 v2, v3, v1, v2
	v_ashrrev_i32_e32 v3, 5, v131
	v_and_b32_e32 v1, 1, v131
	s_add_u32 s10, s28, 0xe595800
	v_cmp_eq_u32_e32 vcc, v3, v1
	v_cmp_gt_u32_e64 s[2:3], 4, v0
	v_and_b32_e32 v0, 31, v131
	v_lshlrev_b32_e32 v1, 4, v3
	s_addc_u32 s11, s29, 0
	s_and_b64 s[12:13], s[2:3], vcc
	v_lshl_add_u32 v104, v0, 5, v1
	s_add_u32 s14, s28, 0xed95800
	v_ashrrev_i32_e32 v105, 31, v104
	s_addc_u32 s15, s29, 0
	v_lshlrev_b32_e32 v122, 4, v0
	v_lshlrev_b64 v[0:1], 2, v[104:105]
	s_add_i32 s16, 0, 0xa000
	v_lshl_add_u64 v[106:107], s[26:27], 0, v[0:1]
	v_lshl_add_u64 v[108:109], s[44:45], 0, v[0:1]
	v_mov_b32_e32 v0, 0x100
	v_mov_b32_e32 v1, s16
	v_cndmask_b32_e64 v0, 0, v0, s[2:3]
	v_cndmask_b32_e64 v123, v1, v2, s[2:3]
	v_lshlrev_b32_e32 v102, 4, v131
	v_add_u32_e32 v124, v123, v0
	v_lshl_add_u32 v125, v0, 1, v123
	v_mad_u32_u24 v126, v0, 3, v123
	v_lshlrev_b32_e32 v0, 9, v131
	v_add_u32_e32 v119, v114, v102
	v_and_b32_e32 v4, 16, v131
	v_mul_lo_u32 v5, v131, -12
	v_and_b32_e32 v0, 0x600, v0
	v_lshl_add_u32 v117, v131, 5, v114
	v_ashrrev_i32_e32 v103, 31, v102
	v_cndmask_b32_e64 v121, 16, 64, s[2:3]
	v_cmp_gt_u32_e64 s[0:1], 32, v131
	s_lshl_b32 s21, s33, 5
	v_add3_u32 v127, v114, v4, v0
	v_lshlrev_b32_e32 v128, 2, v3
	s_mov_b64 s[2:3], 0
	v_bfrev_b32_e32 v129, 1
	s_movk_i32 s23, 0xff80
	s_movk_i32 s24, 0x7f
	s_movk_i32 s25, 0xff00
	v_mov_b32_e32 v132, 0xffffff00
	s_movk_i32 s26, 0xff
	s_movk_i32 s27, 0xfe
	s_movk_i32 s28, 0xfd
	s_movk_i32 s29, 0xfc
	s_movk_i32 s30, 0xfb
	s_movk_i32 s31, 0xfa
	s_movk_i32 s33, 0xf9
	s_movk_i32 s34, 0xf8
	s_movk_i32 s35, 0xf7
	s_movk_i32 s38, 0xf6
	s_movk_i32 s39, 0xf5
	s_movk_i32 s40, 0xf4
	s_movk_i32 s41, 0xf3
	s_movk_i32 s42, 0xf2
	s_movk_i32 s43, 0xf1
	s_movk_i32 s44, 0xf0
	s_movk_i32 s45, 0xef
	s_movk_i32 s46, 0xee
	s_movk_i32 s47, 0xed
	s_movk_i32 s48, 0xec
	s_movk_i32 s49, 0xeb
	s_movk_i32 s50, 0xea
	s_movk_i32 s51, 0xe9
	s_movk_i32 s52, 0xe8
	s_movk_i32 s53, 0xdf
	s_movk_i32 s54, 0xde
	s_movk_i32 s55, 0xdd
	s_movk_i32 s56, 0xdc
	s_movk_i32 s57, 0xdb
	s_movk_i32 s58, 0xcf
	s_movk_i32 s59, 0xce
	s_movk_i32 s60, 0xcd
	s_movk_i32 s61, 0xcc
	s_movk_i32 s62, 0xbf
	s_movk_i32 s63, 0xbe
	s_movk_i32 s64, 0xbd
	s_movk_i32 s65, 0xaf
	s_movk_i32 s66, 0xae
	s_movk_i32 s67, 0x9f
	s_movk_i32 s68, 0x9e
	s_movk_i32 s69, 0x8f
	s_movk_i32 s70, 0x8e
	s_movk_i32 s71, 0x6f
	s_movk_i32 s72, 0x5f
	s_movk_i32 s73, 0x4f
	v_mov_b32_e32 v133, 0x7f7f7f7f
	s_mov_b32 s74, 0x378e98ab
	s_mov_b32 s75, 0x3b7cd369
	s_mov_b32 s76, 0xbcc618b2
	s_mov_b32 s77, 0x3dda74e4
	s_mov_b32 s78, 0x3f228afd
	s_mov_b32 s79, 0x3e03c728
	s_mov_b32 s80, 0xbfb8aa3b
	s_mov_b32 s81, 0x42ce8ed0
	s_mov_b32 s82, 0xc2b17218
	v_mov_b32_e32 v134, 0x3ba10414
	s_brev_b32 s83, -2
	s_movk_i32 s84, 0x3fff
	v_add_u32_e32 v135, v119, v5
	v_mov_b32_e32 v136, 0xb9c68948
	v_mov_b32_e32 v137, 0x7f800000
	v_lshrrev_b32_e32 v142, 4, v131
	v_and_b32_e32 v143, 3, v131
	v_lshlrev_b32_e32 v144, 6, v142
	v_lshl_add_u32 v144, v143, 4, v144
	v_and_b32_e32 v145, 12, v131
	v_and_b32_e32 v157, 15, v131
	v_lshrrev_b32_e32 v154, 1, v142
	v_lshlrev_b32_e32 v154, 7, v154
	v_and_b32_e32 v146, 1, v142
	v_lshl_add_u32 v154, v146, 4, v154
	v_lshl_add_u32 v154, v143, 5, v154
	v_and_b32_e32 v146, 4, v157
	v_cmp_eq_u32_e32 vcc, 0, v146
	v_mov_b32_e32 v147, 0x400
	s_nop 1
	v_cndmask_b32_e32 v146, 0, v147, vcc
	v_add3_u32 v146, v154, v146, v114
	v_add_u32_e32 v146, 0x2000, v146
	v_add_u32_e32 v147, 0x100, v146
	v_add_u32_e32 v148, 0x200, v146
	v_add_u32_e32 v149, 0x300, v146
	v_cmp_gt_u32_e32 vcc, 8, v157
	v_mov_b32_e32 v154, 0xa000
	v_add_u32_e32 v156, 16, v154
	s_nop 0
	v_cndmask_b32_e32 v150, v154, v146, vcc
	v_cndmask_b32_e32 v151, v156, v147, vcc
	v_cndmask_b32_e32 v152, v154, v148, vcc
	v_cndmask_b32_e32 v153, v156, v149, vcc
	v_lshrrev_b32_e32 v156, 11, v114
	v_mul_u32_u24_e32 v156, 52, v156
	v_lshrrev_b32_e32 v156, 8, v156
	v_lshlrev_b32_e32 v156, 12, v156
	v_add_u32_e32 v156, 0xa800, v156
	v_lshl_add_u32 v155, v142, 2, v156
	v_lshl_add_u32 v156, v131, 2, v156
	v_cmp_eq_u32_e32 vcc, 0, v157
	s_nop 1
	v_cndmask_b32_e64 v158, 0, 1.0, vcc
	v_cmp_eq_u32_e32 vcc, 4, v157
	s_nop 1
	v_cndmask_b32_e64 v154, 0, 1.0, vcc
	v_cmp_eq_u32_e32 vcc, 8, v157
	v_add_f32_e32 v158, v158, v154
	s_nop 1
	v_cndmask_b32_e64 v226, 0, 1.0, vcc
	v_cmp_eq_u32_e32 vcc, 12, v157
	s_nop 1
	v_cndmask_b32_e64 v154, 0, 1.0, vcc
	v_add_f32_e32 v226, v226, v154
	v_cmp_eq_u32_e32 vcc, 1, v157
	s_nop 1
	v_cndmask_b32_e64 v159, 0, 1.0, vcc
	v_cmp_eq_u32_e32 vcc, 5, v157
	s_nop 1
	v_cndmask_b32_e64 v154, 0, 1.0, vcc
	v_cmp_eq_u32_e32 vcc, 9, v157
	v_add_f32_e32 v159, v159, v154
	s_nop 1
	v_cndmask_b32_e64 v227, 0, 1.0, vcc
	v_cmp_eq_u32_e32 vcc, 13, v157
	s_nop 1
	v_cndmask_b32_e64 v154, 0, 1.0, vcc
	v_add_f32_e32 v227, v227, v154
	v_cmp_eq_u32_e32 vcc, 2, v157
	s_nop 1
	v_cndmask_b32_e64 v160, 0, 1.0, vcc
	v_cmp_eq_u32_e32 vcc, 6, v157
	s_nop 1
	v_cndmask_b32_e64 v154, 0, 1.0, vcc
	v_cmp_eq_u32_e32 vcc, 10, v157
	v_add_f32_e32 v160, v160, v154
	s_nop 1
	v_cndmask_b32_e64 v228, 0, 1.0, vcc
	v_cmp_eq_u32_e32 vcc, 14, v157
	s_nop 1
	v_cndmask_b32_e64 v154, 0, 1.0, vcc
	v_add_f32_e32 v228, v228, v154
	v_cmp_eq_u32_e32 vcc, 3, v157
	s_nop 1
	v_cndmask_b32_e64 v161, 0, 1.0, vcc
	v_cmp_eq_u32_e32 vcc, 7, v157
	s_nop 1
	v_cndmask_b32_e64 v154, 0, 1.0, vcc
	v_cmp_eq_u32_e32 vcc, 11, v157
	v_add_f32_e32 v161, v161, v154
	s_nop 1
	v_cndmask_b32_e64 v229, 0, 1.0, vcc
	v_cmp_eq_u32_e32 vcc, 15, v157
	s_nop 1
	v_cndmask_b32_e64 v154, 0, 1.0, vcc
	v_add_f32_e32 v229, v229, v154
	s_branch .LBB0_1380

; __device__ __forceinline__ void peer_stage2_batch(const Params& P, int tbase, int tstride, int lane, unsigned char* res, unsigned char* scr) {
;     ...
;     int* sid = (int*)(res + tau * 1024) + hd * 16; float* sgate = (float*)(res + tau * 1024 + 512) + hd * 16;
; #pragma unroll
;     for (int q = 0; q < 4; ++q) {
;         *(int4*)(sid + 4 * q) = make_int4(ids[4 * q], ids[4 * q + 1], ids[4 * q + 2], ids[4 * q + 3]);
;         *(float4*)(sgate + 4 * q) = make_float4(e[4 * q] * inv, e[4 * q + 1] * inv, e[4 * q + 2] * inv, e[4 * q + 3] * inv);
;     }
; __device__ __forceinline__ void peer_token(const Params& P, int t, int lane, int* sidx, float* sval, const int* sid, const float* sgate, const unsigned* szero) {
;     const bf16_t* xn = (const bf16_t*)(P.ws + WS_XN) + (size_t)t * DM;
;     const uint4 xa_pre = *(const uint4*)(xn + lane * 16), xb_pre = *(const uint4*)(xn + lane * 16 + 8);
.Lbk_loop:
	v_lshl_add_u32 v10, s88, 10, v114
	v_lshl_add_u32 v11, v131, 2, v10
	ds_read2st64_b32 v[0:1], v11 offset1:1
	ds_read2st64_b32 v[2:3], v11 offset0:2 offset1:3
	s_waitcnt lgkmcnt(0)
	v_lshrrev_b32_e32 v4, 12, v0
	v_lshrrev_b32_e32 v5, 12, v1
	s_mov_b32 s89, 0
	v_cmp_eq_u32_e32 vcc, 0, v4
	s_nop 1
	v_mbcnt_lo_u32_b32 v6, vcc_lo, 0
	v_mbcnt_hi_u32_b32 v6, vcc_hi, v6
	s_bcnt1_i32_b64 s90, vcc
	v_add_u32_e32 v6, s89, v6
	v_cndmask_b32_e32 v8, v8, v6, vcc
	s_add_i32 s89, s89, s90
	v_cmp_eq_u32_e32 vcc, 0, v5
	s_nop 1
	v_mbcnt_lo_u32_b32 v7, vcc_lo, 0
	v_mbcnt_hi_u32_b32 v7, vcc_hi, v7
	s_bcnt1_i32_b64 s90, vcc
	v_add_u32_e32 v7, s89, v7
	v_cndmask_b32_e32 v9, v9, v7, vcc
	s_add_i32 s89, s89, s90
	v_cmp_eq_u32_e32 vcc, 1, v4
	s_nop 1
	v_mbcnt_lo_u32_b32 v6, vcc_lo, 0
	v_mbcnt_hi_u32_b32 v6, vcc_hi, v6
	s_bcnt1_i32_b64 s90, vcc
	v_add_u32_e32 v6, s89, v6
	v_cndmask_b32_e32 v8, v8, v6, vcc
	s_add_i32 s89, s89, s90
	v_cmp_eq_u32_e32 vcc, 1, v5
	s_nop 1
	v_mbcnt_lo_u32_b32 v7, vcc_lo, 0
	v_mbcnt_hi_u32_b32 v7, vcc_hi, v7
	s_bcnt1_i32_b64 s90, vcc
	v_add_u32_e32 v7, s89, v7
	v_cndmask_b32_e32 v9, v9, v7, vcc
	s_add_i32 s89, s89, s90
	v_cmp_eq_u32_e32 vcc, 2, v4
	s_nop 1
	v_mbcnt_lo_u32_b32 v6, vcc_lo, 0
	v_mbcnt_hi_u32_b32 v6, vcc_hi, v6
	s_bcnt1_i32_b64 s90, vcc
	v_add_u32_e32 v6, s89, v6
	v_cndmask_b32_e32 v8, v8, v6, vcc
	s_add_i32 s89, s89, s90
	v_cmp_eq_u32_e32 vcc, 2, v5
	s_nop 1
	v_mbcnt_lo_u32_b32 v7, vcc_lo, 0
	v_mbcnt_hi_u32_b32 v7, vcc_hi, v7
	s_bcnt1_i32_b64 s90, vcc
	v_add_u32_e32 v7, s89, v7
	v_cndmask_b32_e32 v9, v9, v7, vcc
	s_add_i32 s89, s89, s90
	v_cmp_eq_u32_e32 vcc, 3, v4
	s_nop 1
	v_mbcnt_lo_u32_b32 v6, vcc_lo, 0
	v_mbcnt_hi_u32_b32 v6, vcc_hi, v6
	s_bcnt1_i32_b64 s90, vcc
	v_add_u32_e32 v6, s89, v6
	v_cndmask_b32_e32 v8, v8, v6, vcc
	s_add_i32 s89, s89, s90
	v_cmp_eq_u32_e32 vcc, 3, v5
	s_nop 1
	v_mbcnt_lo_u32_b32 v7, vcc_lo, 0
	v_mbcnt_hi_u32_b32 v7, vcc_hi, v7
	s_bcnt1_i32_b64 s90, vcc
	v_add_u32_e32 v7, s89, v7
	v_cndmask_b32_e32 v9, v9, v7, vcc
	s_add_i32 s89, s89, s90
	v_lshl_add_u32 v8, v8, 2, v10
	v_lshl_add_u32 v9, v9, 2, v10
	ds_write_b32 v8, v0
	ds_write_b32 v8, v2 offset:512
	ds_write_b32 v9, v1
	ds_write_b32 v9, v3 offset:512
	s_waitcnt lgkmcnt(0)
	s_add_i32 s88, s88, 1
	s_cmp_lt_u32 s88, 8
	s_cbranch_scc1 .Lbk_loop
	s_mul_i32 s16, s85, s22
	v_add_u32_e32 v254, s16, v130
	v_ashrrev_i32_e32 v255, 31, v254
	v_lshlrev_b64 v[254:255], 11, v[254:255]
	v_lshl_add_u64 v[254:255], s[36:37], 0, v[254:255]
	v_lshl_add_u64 v[254:255], v[102:103], 1, v[254:255]
	global_load_dwordx4 v[246:249], v[254:255], off
	global_load_dwordx4 v[250:253], v[254:255], off offset:16
	s_branch .LBB0_1382

; __device__ __forceinline__ float bflo(unsigned w) { return __uint_as_float(w << 16); }
; __device__ __forceinline__ float bfhi(unsigned w) { return __uint_as_float(w & 0xffff0000u); }
; __device__ __forceinline__ void peer_token(const Params& P, int t, int lane, int* sidx, float* sval, const int* sid, const float* sgate, const unsigned* szero) {
;     ...
;     {
;         const uint4 xa = xa_pre, xb = xb_pre;
;         const unsigned xw[8] = {xa.x, xa.y, xa.z, xa.w, xb.x, xb.y, xb.z, xb.w};
;         unsigned hi[4], lo[4];
; #pragma unroll
;         for (int i = 0; i < 4; ++i) {
;             const float x0 = bflo(xw[2 * i]), x1 = bfhi(xw[2 * i]), x2 = bflo(xw[2 * i + 1]), x3 = bfhi(xw[2 * i + 1]);
;             int wd = 0;
;             wd = __builtin_amdgcn_cvt_pk_fp8_f32(x0, x1, wd, false);
;             wd = __builtin_amdgcn_cvt_pk_fp8_f32(x2, x3, wd, true);
;             const f32x2 h01 = __builtin_amdgcn_cvt_pk_f32_fp8(wd, false), h23 = __builtin_amdgcn_cvt_pk_f32_fp8(wd, true);
;             int wl = 0;
;             wl = __builtin_amdgcn_cvt_pk_fp8_f32(x0 - h01.x, x1 - h01.y, wl, false);
;             wl = __builtin_amdgcn_cvt_pk_fp8_f32(x2 - h23.x, x3 - h23.y, wl, true);
;             hi[i] = (unsigned)wd; lo[i] = (unsigned)wl;
;         }
;         *(uint4*)(shi + lane * 16) = make_uint4(hi[0], hi[1], hi[2], hi[3]);
;         *(uint4*)(slo + lane * 16) = make_uint4(lo[0], lo[1], lo[2], lo[3]);
;     }
;     __builtin_amdgcn_s_waitcnt(0xc07f);
;     __builtin_amdgcn_wave_barrier();
;     {
;         typedef int v8i __attribute__((ext_vector_type(8)));
;         const unsigned char* Ub = P.ws + WS_U;
;         const unsigned lofs = 64u * (unsigned)(lr >> 3) + 16u * (unsigned)g;
;         const unsigned char* bsrc = (lr < 4) ? (((lr & 2) ? slo : shi) + 128 * (lr & 1) + 16 * g) : (const unsigned char*)szero;
;         const int bstep = (lr < 4) ? 256 : 0, bhalf = (lr < 4) ? 64 : 16;
;         v8i Bv[4];
; #pragma unroll
;         for (int st = 0; st < 4; ++st) {
;             const uint4 b0 = *(const uint4*)(bsrc + bstep * st), b1 = *(const uint4*)(bsrc + bstep * st + bhalf);
;             Bv[st] = (v8i){(int)b0.x, (int)b0.y, (int)b0.z, (int)b0.w, (int)b1.x, (int)b1.y, (int)b1.z, (int)b1.w};
;         }
.LBB0_1382:
	s_mul_i32 s16, s85, s22
	v_add_u32_e32 v112, s16, v130
	v_cmp_gt_i32_e32 vcc, s20, v112
	s_and_saveexec_b64 s[16:17], vcc
	s_cbranch_execz .LBB0_1381
	v_ashrrev_i32_e32 v113, 31, v112
	v_lshlrev_b64 v[0:1], 11, v[112:113]
	v_lshl_add_u64 v[110:111], s[36:37], 0, v[0:1]
	v_lshl_add_u64 v[4:5], v[102:103], 1, v[110:111]
	s_waitcnt vmcnt(0)
	v_mov_b64_e32 v[0:1], v[246:247]
	v_mov_b64_e32 v[2:3], v[248:249]
	v_mov_b64_e32 v[4:5], v[250:251]
	v_mov_b64_e32 v[6:7], v[252:253]
	s_cmp_eq_u32 s85, 7
	s_cbranch_scc1 .Lax_nopf
	s_add_i32 s91, s85, 1
	s_mul_i32 s16, s91, s22
	v_add_u32_e32 v254, s16, v130
	v_ashrrev_i32_e32 v255, 31, v254
	v_lshlrev_b64 v[254:255], 11, v[254:255]
	v_lshl_add_u64 v[254:255], s[36:37], 0, v[254:255]
	v_lshl_add_u64 v[254:255], v[102:103], 1, v[254:255]
	global_load_dwordx4 v[246:249], v[254:255], off
	global_load_dwordx4 v[250:253], v[254:255], off offset:16
.Lax_nopf:
	v_mov_b32_e32 v8, 0
	v_mov_b32_e32 v9, 0
	v_mov_b32_e32 v10, 0
	v_mov_b32_e32 v11, 0
	v_mov_b32_e32 v12, 0
	v_mov_b32_e32 v13, 0
	v_mov_b32_e32 v14, 0
	v_mov_b32_e32 v15, 0
	v_lshl_add_u32 v139, s85, 10, v114
	v_add_u32_e32 v26, v123, v121
	v_add_u32_e32 v27, v124, v121
	v_add_u32_e32 v28, v125, v121
	v_add_u32_e32 v32, v126, v121
	v_lshl_add_u64 v[16:17], v[112:113], 2, s[4:5]
	v_lshl_add_u32 v141, v115, 2, v139
	v_lshlrev_b32_e32 v29, 16, v0
	v_and_b32_e32 v30, 0xffff0000, v0
	v_lshlrev_b32_e32 v34, 16, v2
	v_and_b32_e32 v35, 0xffff0000, v2
	v_lshlrev_b32_e32 v38, 16, v4
	v_and_b32_e32 v39, 0xffff0000, v4
	v_lshlrev_b32_e32 v42, 16, v6
	v_and_b32_e32 v43, 0xffff0000, v6
	v_cvt_pk_fp8_f32 v8, v29, v30
	v_cvt_pk_fp8_f32 v9, v34, v35
	v_cvt_pk_fp8_f32 v10, v38, v39
	v_cvt_pk_fp8_f32 v11, v42, v43
	v_lshlrev_b32_e32 v31, 16, v1
	v_and_b32_e32 v33, 0xffff0000, v1
	v_lshlrev_b32_e32 v36, 16, v3
	v_and_b32_e32 v37, 0xffff0000, v3
	v_lshlrev_b32_e32 v40, 16, v5
	v_and_b32_e32 v41, 0xffff0000, v5
	v_lshlrev_b32_e32 v44, 16, v7
	v_and_b32_e32 v45, 0xffff0000, v7
	v_cvt_pk_fp8_f32 v8, v31, v33 op_sel:[0,0,1]
	v_cvt_pk_fp8_f32 v9, v36, v37 op_sel:[0,0,1]
	v_cvt_pk_fp8_f32 v10, v40, v41 op_sel:[0,0,1]
	v_cvt_pk_fp8_f32 v11, v44, v45 op_sel:[0,0,1]
	v_cvt_pk_f32_fp8_e32 v[0:1], v8
	v_cvt_pk_f32_fp8_e32 v[4:5], v9
	v_cvt_pk_f32_fp8_e32 v[18:19], v10
	v_cvt_pk_f32_fp8_e32 v[22:23], v11
	v_cvt_pk_f32_fp8_sdwa v[2:3], v8 src0_sel:WORD_1
	v_cvt_pk_f32_fp8_sdwa v[6:7], v9 src0_sel:WORD_1
	v_cvt_pk_f32_fp8_sdwa v[20:21], v10 src0_sel:WORD_1
	v_cvt_pk_f32_fp8_sdwa v[24:25], v11 src0_sel:WORD_1
	v_sub_f32_e32 v0, v29, v0
	v_sub_f32_e32 v1, v30, v1
	v_sub_f32_e32 v4, v34, v4
	v_sub_f32_e32 v5, v35, v5
	v_sub_f32_e32 v18, v38, v18
	v_sub_f32_e32 v19, v39, v19
	v_sub_f32_e32 v22, v42, v22
	v_sub_f32_e32 v23, v43, v23
	v_cvt_pk_fp8_f32 v12, v0, v1
	v_cvt_pk_fp8_f32 v13, v4, v5
	v_cvt_pk_fp8_f32 v14, v18, v19
	v_cvt_pk_fp8_f32 v15, v22, v23
	v_sub_f32_e32 v2, v31, v2
	v_sub_f32_e32 v3, v33, v3
	v_sub_f32_e32 v6, v36, v6
	v_sub_f32_e32 v7, v37, v7
	v_sub_f32_e32 v20, v40, v20
	v_sub_f32_e32 v21, v41, v21
	v_sub_f32_e32 v24, v44, v24
	v_sub_f32_e32 v25, v45, v25
	v_cvt_pk_fp8_f32 v12, v2, v3 op_sel:[0,0,1]
	v_cvt_pk_fp8_f32 v13, v6, v7 op_sel:[0,0,1]
	v_cvt_pk_fp8_f32 v14, v20, v21 op_sel:[0,0,1]
	v_cvt_pk_fp8_f32 v15, v24, v25 op_sel:[0,0,1]
	ds_write_b128 v119, v[8:11] offset:9216
	ds_write_b128 v119, v[12:15] offset:8192
	s_waitcnt lgkmcnt(0)
	s_and_b32 s90, s85, 3
	s_cmp_gt_u32 s85, 3
	s_cbranch_scc1 .LbsY
	s_cmp_eq_u32 s90, 1
	s_cbranch_scc1 .Lbs1
	s_cmp_eq_u32 s90, 2
	s_cbranch_scc1 .Lbs2
	s_cmp_eq_u32 s90, 3
	s_cbranch_scc1 .Lbs3
	ds_read_b128 v[162:165], v150
	ds_read_b128 v[166:169], v151
	ds_read_b128 v[170:173], v152
	ds_read_b128 v[174:177], v153
	s_branch .Lbs_join

; __device__ __forceinline__ void peer_token(const Params& P, int t, int lane, int* sidx, float* sval, const int* sid, const float* sgate, const unsigned* szero) {
;     ...
;         for (int st = 0; st < 4; ++st) {
;             const uint4 b0 = *(const uint4*)(bsrc + bstep * st), b1 = *(const uint4*)(bsrc + bstep * st + bhalf);
;             Bv[st] = (v8i){(int)b0.x, (int)b0.y, (int)b0.z, (int)b0.w, (int)b1.x, (int)b1.y, (int)b1.z, (int)b1.w};
;         }
;     ...
; #pragma unroll
;         for (int hh = 0; hh < 2; ++hh)
; #pragma unroll
;             for (int st = 0; st < 4; ++st) abuf[0][hh][st] = *(const uint4*)(Ub + (off2[hh] + 128 * st));
; #pragma unroll
;         for (int T = 0; T < 8; ++T) {
;             if (T + 1 < 8) {
; #pragma unroll
;                 for (int hh = 0; hh < 2; ++hh) off2[hh] = (unsigned)sid[16 * (T + 1) + 8 * hh + (lr & 7)] * 512u + lofs;
; #pragma unroll
;                 for (int hh = 0; hh < 2; ++hh)
; #pragma unroll
;                     for (int st = 0; st < 4; ++st) abuf[(T + 1) & 1][hh][st] = *(const uint4*)(Ub + (off2[hh] + 128 * st));
;             }
; #pragma unroll
;             for (int hh = 0; hh < 2; ++hh) {
;                 f32x4 au = (f32x4){0.f, 0.f, 0.f, 0.f};
; #pragma unroll
;                 for (int st = 0; st < 4; ++st) {
;                     const uint4 a4 = abuf[T & 1][hh][st];
;                     const v8i Av = {(int)a4.x, (int)a4.y, (int)a4.z, (int)a4.w, 0, 0, 0, 0};
;                     au = __builtin_amdgcn_mfma_scale_f32_16x16x128_f8f6f4(Av, Bv[st], au, 4, 0, 0, 0x7f7f7f7f, 0, 0x7f7f7f7f);
;                 }
;                 if (owner) *(f32x4*)(sact + 16 * T + 8 * hh) = au;
;             }
.Lbs3:
	ds_read_b128 v[210:213], v150
	ds_read_b128 v[214:217], v151
	ds_read_b128 v[218:221], v152
	ds_read_b128 v[222:225], v153
	s_branch .Lbs_join
.LbsY:
	s_mov_b32 exec_lo, 0xff00ff00
	s_mov_b32 exec_hi, 0xff00ff00
	s_cmp_eq_u32 s90, 1
	s_cbranch_scc1 .Lby1
	s_cmp_eq_u32 s90, 2
	s_cbranch_scc1 .Lby2
	s_cmp_eq_u32 s90, 3
	s_cbranch_scc1 .Lby3
	ds_read_b128 v[162:165], v146
	ds_read_b128 v[166:169], v147
	ds_read_b128 v[170:173], v148
	ds_read_b128 v[174:177], v149
	s_branch .Lbs_join
.Lby1:
	ds_read_b128 v[178:181], v146
	ds_read_b128 v[182:185], v147
	ds_read_b128 v[186:189], v148
	ds_read_b128 v[190:193], v149
	s_branch .Lbs_join
.Lby2:
	ds_read_b128 v[194:197], v146
	ds_read_b128 v[198:201], v147
	ds_read_b128 v[202:205], v148
	ds_read_b128 v[206:209], v149
	s_branch .Lbs_join
.Lby3:
	ds_read_b128 v[210:213], v146
	ds_read_b128 v[214:217], v147
	ds_read_b128 v[218:221], v148
	ds_read_b128 v[222:225], v149
.Lbs_join:
	s_waitcnt lgkmcnt(0)
	s_mov_b64 exec, -1
	s_add_i32 s85, s85, 1
	s_cmp_lt_u32 s85, 8
	s_cbranch_scc1 .LBB0_1382
	v_add_u32_e32 v238, v114, v145
	v_add_u32_e32 v239, 1024, v238
	v_add_u32_e32 v240, 2048, v238
	v_add_u32_e32 v241, 3072, v238
	v_add_u32_e32 v242, 4096, v238
	v_add_u32_e32 v243, 5120, v238
	v_add_u32_e32 v244, 6144, v238
	v_add_u32_e32 v245, 7168, v238
	ds_read2_b32 v[96:97], v238 offset1:4
	ds_read2_b32 v[98:99], v238 offset0:8 offset1:12
	s_waitcnt lgkmcnt(0)
	v_lshl_add_u32 v96, v96, 9, v144
	v_lshl_add_u32 v97, v97, 9, v144
	v_lshl_add_u32 v98, v98, 9, v144
	v_lshl_add_u32 v99, v99, 9, v144
	global_load_dwordx4 v[0:3], v96, s[10:11]
	global_load_dwordx4 v[4:7], v96, s[10:11] offset:256
	global_load_dwordx4 v[8:11], v97, s[10:11]
	global_load_dwordx4 v[12:15], v97, s[10:11] offset:256
	global_load_dwordx4 v[16:19], v98, s[10:11]
	global_load_dwordx4 v[20:23], v98, s[10:11] offset:256
	global_load_dwordx4 v[24:27], v99, s[10:11]
	global_load_dwordx4 v[28:31], v99, s[10:11] offset:256
	ds_read2_b32 v[230:231], v239 offset1:4
	ds_read2_b32 v[232:233], v239 offset0:8 offset1:12
	s_waitcnt lgkmcnt(0)
	v_lshl_add_u32 v230, v230, 9, v144
	v_lshl_add_u32 v231, v231, 9, v144
	v_lshl_add_u32 v232, v232, 9, v144
	v_lshl_add_u32 v233, v233, 9, v144
	global_load_dwordx4 v[32:35], v230, s[10:11]
	global_load_dwordx4 v[36:39], v230, s[10:11] offset:256
	global_load_dwordx4 v[40:43], v231, s[10:11]
	global_load_dwordx4 v[44:47], v231, s[10:11] offset:256
	global_load_dwordx4 v[48:51], v232, s[10:11]
	global_load_dwordx4 v[52:55], v232, s[10:11] offset:256
	global_load_dwordx4 v[56:59], v233, s[10:11]
	global_load_dwordx4 v[60:63], v233, s[10:11] offset:256
	s_waitcnt vmcnt(8)
	v_mfma_scale_f32_16x16x128_f8f6f4 v[64:67], v[0:3], v[162:169], 0, v133, v133 op_sel_hi:[0,0,0] cbsz:4
	v_mfma_scale_f32_16x16x128_f8f6f4 v[64:67], v[4:7], v[170:177], v[64:67], v133, v133 op_sel_hi:[0,0,0] cbsz:4
	v_mfma_scale_f32_16x16x128_f8f6f4 v[68:71], v[8:11], v[162:169], 0, v133, v133 op_sel_hi:[0,0,0] cbsz:4
	v_mfma_scale_f32_16x16x128_f8f6f4 v[68:71], v[12:15], v[170:177], v[68:71], v133, v133 op_sel_hi:[0,0,0] cbsz:4
	v_mfma_scale_f32_16x16x128_f8f6f4 v[72:75], v[16:19], v[162:169], 0, v133, v133 op_sel_hi:[0,0,0] cbsz:4
	v_mfma_scale_f32_16x16x128_f8f6f4 v[72:75], v[20:23], v[170:177], v[72:75], v133, v133 op_sel_hi:[0,0,0] cbsz:4
	v_mfma_scale_f32_16x16x128_f8f6f4 v[76:79], v[24:27], v[162:169], 0, v133, v133 op_sel_hi:[0,0,0] cbsz:4
	v_mfma_scale_f32_16x16x128_f8f6f4 v[76:79], v[28:31], v[170:177], v[76:79], v133, v133 op_sel_hi:[0,0,0] cbsz:4
	ds_read2_b32 v[96:97], v240 offset1:4
	ds_read2_b32 v[98:99], v240 offset0:8 offset1:12
	s_waitcnt lgkmcnt(0)
	v_lshl_add_u32 v96, v96, 9, v144
	v_lshl_add_u32 v97, v97, 9, v144
	v_lshl_add_u32 v98, v98, 9, v144
	v_lshl_add_u32 v99, v99, 9, v144
	global_load_dwordx4 v[0:3], v96, s[10:11]
	global_load_dwordx4 v[4:7], v96, s[10:11] offset:256
	global_load_dwordx4 v[8:11], v97, s[10:11]
	global_load_dwordx4 v[12:15], v97, s[10:11] offset:256
	global_load_dwordx4 v[16:19], v98, s[10:11]
	global_load_dwordx4 v[20:23], v98, s[10:11] offset:256
	global_load_dwordx4 v[24:27], v99, s[10:11]
	global_load_dwordx4 v[28:31], v99, s[10:11] offset:256
	s_waitcnt vmcnt(8)
	v_mfma_scale_f32_16x16x128_f8f6f4 v[80:83], v[32:35], v[178:185], 0, v133, v133 op_sel_hi:[0,0,0] cbsz:4
	v_mfma_scale_f32_16x16x128_f8f6f4 v[80:83], v[36:39], v[186:193], v[80:83], v133, v133 op_sel_hi:[0,0,0] cbsz:4
	v_mfma_scale_f32_16x16x128_f8f6f4 v[84:87], v[40:43], v[178:185], 0, v133, v133 op_sel_hi:[0,0,0] cbsz:4
	v_mfma_scale_f32_16x16x128_f8f6f4 v[84:87], v[44:47], v[186:193], v[84:87], v133, v133 op_sel_hi:[0,0,0] cbsz:4
	v_mfma_scale_f32_16x16x128_f8f6f4 v[88:91], v[48:51], v[178:185], 0, v133, v133 op_sel_hi:[0,0,0] cbsz:4
	v_mfma_scale_f32_16x16x128_f8f6f4 v[88:91], v[52:55], v[186:193], v[88:91], v133, v133 op_sel_hi:[0,0,0] cbsz:4
	v_mfma_scale_f32_16x16x128_f8f6f4 v[92:95], v[56:59], v[178:185], 0, v133, v133 op_sel_hi:[0,0,0] cbsz:4
	v_mfma_scale_f32_16x16x128_f8f6f4 v[92:95], v[60:63], v[186:193], v[92:95], v133, v133 op_sel_hi:[0,0,0] cbsz:4
	s_nop 3
	v_mul_f32_e32 v234, v158, v64
	v_mul_f32_e32 v235, v158, v68
	v_mul_f32_e32 v236, v158, v72
	v_mul_f32_e32 v237, v158, v76
	v_fmac_f32_e32 v234, v159, v65
	v_fmac_f32_e32 v235, v159, v69
	v_fmac_f32_e32 v236, v159, v73
	v_fmac_f32_e32 v237, v159, v77
	v_fmac_f32_e32 v234, v160, v66
	v_fmac_f32_e32 v235, v160, v70
	v_fmac_f32_e32 v236, v160, v74
	v_fmac_f32_e32 v237, v160, v78
	v_fmac_f32_e32 v234, v161, v67
	v_fmac_f32_e32 v235, v161, v71
	v_fmac_f32_e32 v236, v161, v75
	v_fmac_f32_e32 v237, v161, v79
	v_add_f32_dpp v234, v234, v234 quad_perm:[1,0,3,2] row_mask:0xf bank_mask:0xf
	v_add_f32_dpp v235, v235, v235 quad_perm:[1,0,3,2] row_mask:0xf bank_mask:0xf
	v_add_f32_dpp v236, v236, v236 quad_perm:[1,0,3,2] row_mask:0xf bank_mask:0xf
	v_add_f32_dpp v237, v237, v237 quad_perm:[1,0,3,2] row_mask:0xf bank_mask:0xf
	v_add_f32_dpp v234, v234, v234 quad_perm:[2,3,0,1] row_mask:0xf bank_mask:0xf
	v_add_f32_dpp v235, v235, v235 quad_perm:[2,3,0,1] row_mask:0xf bank_mask:0xf
	v_add_f32_dpp v236, v236, v236 quad_perm:[2,3,0,1] row_mask:0xf bank_mask:0xf
	v_add_f32_dpp v237, v237, v237 quad_perm:[2,3,0,1] row_mask:0xf bank_mask:0xf
	v_add_f32_dpp v234, v234, v234 row_half_mirror row_mask:0xf bank_mask:0xf
	v_add_f32_dpp v235, v235, v235 row_half_mirror row_mask:0xf bank_mask:0xf
	v_add_f32_dpp v236, v236, v236 row_half_mirror row_mask:0xf bank_mask:0xf
	v_add_f32_dpp v237, v237, v237 row_half_mirror row_mask:0xf bank_mask:0xf
	s_mov_b32 exec_lo, 0x10001
	s_mov_b32 exec_hi, 0x10001
	ds_write_b32 v155, v234
	ds_write_b32 v155, v235 offset:16
	ds_write_b32 v155, v236 offset:32
	ds_write_b32 v155, v237 offset:48
	s_mov_b64 exec, -1
	ds_read2_b32 v[230:231], v241 offset1:4
	ds_read2_b32 v[232:233], v241 offset0:8 offset1:12
	s_waitcnt lgkmcnt(0)
; __device__ __forceinline__ void peer_token(const Params& P, int t, int lane, int* sidx, float* sval, const int* sid, const float* sgate, const unsigned* szero) {
;     ...
; #pragma unroll
;         for (int hh = 0; hh < 2; ++hh)
; #pragma unroll
;             for (int st = 0; st < 4; ++st) abuf[0][hh][st] = *(const uint4*)(Ub + (off2[hh] + 128 * st));
; #pragma unroll
;         for (int T = 0; T < 8; ++T) {
;             if (T + 1 < 8) {
; #pragma unroll
;                 for (int hh = 0; hh < 2; ++hh) off2[hh] = (unsigned)sid[16 * (T + 1) + 8 * hh + (lr & 7)] * 512u + lofs;
; #pragma unroll
;                 for (int hh = 0; hh < 2; ++hh)
; #pragma unroll
;                     for (int st = 0; st < 4; ++st) abuf[(T + 1) & 1][hh][st] = *(const uint4*)(Ub + (off2[hh] + 128 * st));
;             }
; #pragma unroll
;             for (int hh = 0; hh < 2; ++hh) {
;                 f32x4 au = (f32x4){0.f, 0.f, 0.f, 0.f};
; #pragma unroll
;                 for (int st = 0; st < 4; ++st) {
;                     const uint4 a4 = abuf[T & 1][hh][st];
;                     const v8i Av = {(int)a4.x, (int)a4.y, (int)a4.z, (int)a4.w, 0, 0, 0, 0};
;                     au = __builtin_amdgcn_mfma_scale_f32_16x16x128_f8f6f4(Av, Bv[st], au, 4, 0, 0, 0x7f7f7f7f, 0, 0x7f7f7f7f);
;                 }
;                 if (owner) *(f32x4*)(sact + 16 * T + 8 * hh) = au;
;             }
	v_lshl_add_u32 v230, v230, 9, v144
	v_lshl_add_u32 v231, v231, 9, v144
	v_lshl_add_u32 v232, v232, 9, v144
	v_lshl_add_u32 v233, v233, 9, v144
	global_load_dwordx4 v[32:35], v230, s[10:11]
	global_load_dwordx4 v[36:39], v230, s[10:11] offset:256
	global_load_dwordx4 v[40:43], v231, s[10:11]
	global_load_dwordx4 v[44:47], v231, s[10:11] offset:256
	global_load_dwordx4 v[48:51], v232, s[10:11]
	global_load_dwordx4 v[52:55], v232, s[10:11] offset:256
	global_load_dwordx4 v[56:59], v233, s[10:11]
	global_load_dwordx4 v[60:63], v233, s[10:11] offset:256
	s_waitcnt vmcnt(8)
	v_mfma_scale_f32_16x16x128_f8f6f4 v[64:67], v[0:3], v[194:201], 0, v133, v133 op_sel_hi:[0,0,0] cbsz:4
	v_mfma_scale_f32_16x16x128_f8f6f4 v[64:67], v[4:7], v[202:209], v[64:67], v133, v133 op_sel_hi:[0,0,0] cbsz:4
	v_mfma_scale_f32_16x16x128_f8f6f4 v[68:71], v[8:11], v[194:201], 0, v133, v133 op_sel_hi:[0,0,0] cbsz:4
	v_mfma_scale_f32_16x16x128_f8f6f4 v[68:71], v[12:15], v[202:209], v[68:71], v133, v133 op_sel_hi:[0,0,0] cbsz:4
	v_mfma_scale_f32_16x16x128_f8f6f4 v[72:75], v[16:19], v[194:201], 0, v133, v133 op_sel_hi:[0,0,0] cbsz:4
	v_mfma_scale_f32_16x16x128_f8f6f4 v[72:75], v[20:23], v[202:209], v[72:75], v133, v133 op_sel_hi:[0,0,0] cbsz:4
	v_mfma_scale_f32_16x16x128_f8f6f4 v[76:79], v[24:27], v[194:201], 0, v133, v133 op_sel_hi:[0,0,0] cbsz:4
	v_mfma_scale_f32_16x16x128_f8f6f4 v[76:79], v[28:31], v[202:209], v[76:79], v133, v133 op_sel_hi:[0,0,0] cbsz:4
	s_nop 3
	v_mul_f32_e32 v234, v158, v80
	v_mul_f32_e32 v235, v158, v84
	v_mul_f32_e32 v236, v158, v88
	v_mul_f32_e32 v237, v158, v92
	v_fmac_f32_e32 v234, v159, v81
	v_fmac_f32_e32 v235, v159, v85
	v_fmac_f32_e32 v236, v159, v89
	v_fmac_f32_e32 v237, v159, v93
	v_fmac_f32_e32 v234, v160, v82
	v_fmac_f32_e32 v235, v160, v86
	v_fmac_f32_e32 v236, v160, v90
	v_fmac_f32_e32 v237, v160, v94
	v_fmac_f32_e32 v234, v161, v83
	v_fmac_f32_e32 v235, v161, v87
	v_fmac_f32_e32 v236, v161, v91
	v_fmac_f32_e32 v237, v161, v95
	v_add_f32_dpp v234, v234, v234 quad_perm:[1,0,3,2] row_mask:0xf bank_mask:0xf
	v_add_f32_dpp v235, v235, v235 quad_perm:[1,0,3,2] row_mask:0xf bank_mask:0xf
	v_add_f32_dpp v236, v236, v236 quad_perm:[1,0,3,2] row_mask:0xf bank_mask:0xf
	v_add_f32_dpp v237, v237, v237 quad_perm:[1,0,3,2] row_mask:0xf bank_mask:0xf
	v_add_f32_dpp v234, v234, v234 quad_perm:[2,3,0,1] row_mask:0xf bank_mask:0xf
	v_add_f32_dpp v235, v235, v235 quad_perm:[2,3,0,1] row_mask:0xf bank_mask:0xf
	v_add_f32_dpp v236, v236, v236 quad_perm:[2,3,0,1] row_mask:0xf bank_mask:0xf
	v_add_f32_dpp v237, v237, v237 quad_perm:[2,3,0,1] row_mask:0xf bank_mask:0xf
	v_add_f32_dpp v234, v234, v234 row_half_mirror row_mask:0xf bank_mask:0xf
	v_add_f32_dpp v235, v235, v235 row_half_mirror row_mask:0xf bank_mask:0xf
	v_add_f32_dpp v236, v236, v236 row_half_mirror row_mask:0xf bank_mask:0xf
	v_add_f32_dpp v237, v237, v237 row_half_mirror row_mask:0xf bank_mask:0xf
	s_mov_b32 exec_lo, 0x10001
	s_mov_b32 exec_hi, 0x10001
	ds_write_b32 v155, v234 offset:512
	ds_write_b32 v155, v235 offset:528
	ds_write_b32 v155, v236 offset:544
	ds_write_b32 v155, v237 offset:560
	s_mov_b64 exec, -1
	ds_read2_b32 v[96:97], v242 offset1:4
	ds_read2_b32 v[98:99], v242 offset0:8 offset1:12
	s_waitcnt lgkmcnt(0)
	v_lshl_add_u32 v96, v96, 9, v144
	v_lshl_add_u32 v97, v97, 9, v144
	v_lshl_add_u32 v98, v98, 9, v144
	v_lshl_add_u32 v99, v99, 9, v144
	global_load_dwordx4 v[0:3], v96, s[10:11]
	global_load_dwordx4 v[4:7], v96, s[10:11] offset:256
	global_load_dwordx4 v[8:11], v97, s[10:11]
	global_load_dwordx4 v[12:15], v97, s[10:11] offset:256
	global_load_dwordx4 v[16:19], v98, s[10:11]
	global_load_dwordx4 v[20:23], v98, s[10:11] offset:256
	global_load_dwordx4 v[24:27], v99, s[10:11]
	global_load_dwordx4 v[28:31], v99, s[10:11] offset:256
	s_waitcnt vmcnt(8)
	v_mfma_scale_f32_16x16x128_f8f6f4 v[80:83], v[32:35], v[210:217], 0, v133, v133 op_sel_hi:[0,0,0] cbsz:4
	v_mfma_scale_f32_16x16x128_f8f6f4 v[80:83], v[36:39], v[218:225], v[80:83], v133, v133 op_sel_hi:[0,0,0] cbsz:4
	v_mfma_scale_f32_16x16x128_f8f6f4 v[84:87], v[40:43], v[210:217], 0, v133, v133 op_sel_hi:[0,0,0] cbsz:4
	v_mfma_scale_f32_16x16x128_f8f6f4 v[84:87], v[44:47], v[218:225], v[84:87], v133, v133 op_sel_hi:[0,0,0] cbsz:4
	v_mfma_scale_f32_16x16x128_f8f6f4 v[88:91], v[48:51], v[210:217], 0, v133, v133 op_sel_hi:[0,0,0] cbsz:4
	v_mfma_scale_f32_16x16x128_f8f6f4 v[88:91], v[52:55], v[218:225], v[88:91], v133, v133 op_sel_hi:[0,0,0] cbsz:4
	v_mfma_scale_f32_16x16x128_f8f6f4 v[92:95], v[56:59], v[210:217], 0, v133, v133 op_sel_hi:[0,0,0] cbsz:4
	v_mfma_scale_f32_16x16x128_f8f6f4 v[92:95], v[60:63], v[218:225], v[92:95], v133, v133 op_sel_hi:[0,0,0] cbsz:4
	s_nop 3
	v_mul_f32_e32 v234, v158, v64
	v_mul_f32_e32 v235, v158, v68
	v_mul_f32_e32 v236, v158, v72
	v_mul_f32_e32 v237, v158, v76
	v_fmac_f32_e32 v234, v159, v65
	v_fmac_f32_e32 v235, v159, v69
	v_fmac_f32_e32 v236, v159, v73
	v_fmac_f32_e32 v237, v159, v77
	v_fmac_f32_e32 v234, v160, v66
	v_fmac_f32_e32 v235, v160, v70
	v_fmac_f32_e32 v236, v160, v74
	v_fmac_f32_e32 v237, v160, v78
	v_fmac_f32_e32 v234, v161, v67
	v_fmac_f32_e32 v235, v161, v71
	v_fmac_f32_e32 v236, v161, v75
	v_fmac_f32_e32 v237, v161, v79
	v_add_f32_dpp v234, v234, v234 quad_perm:[1,0,3,2] row_mask:0xf bank_mask:0xf
	v_add_f32_dpp v235, v235, v235 quad_perm:[1,0,3,2] row_mask:0xf bank_mask:0xf
	v_add_f32_dpp v236, v236, v236 quad_perm:[1,0,3,2] row_mask:0xf bank_mask:0xf
	v_add_f32_dpp v237, v237, v237 quad_perm:[1,0,3,2] row_mask:0xf bank_mask:0xf
	v_add_f32_dpp v234, v234, v234 quad_perm:[2,3,0,1] row_mask:0xf bank_mask:0xf
	v_add_f32_dpp v235, v235, v235 quad_perm:[2,3,0,1] row_mask:0xf bank_mask:0xf
	v_add_f32_dpp v236, v236, v236 quad_perm:[2,3,0,1] row_mask:0xf bank_mask:0xf
	v_add_f32_dpp v237, v237, v237 quad_perm:[2,3,0,1] row_mask:0xf bank_mask:0xf
	v_add_f32_dpp v234, v234, v234 row_half_mirror row_mask:0xf bank_mask:0xf
	v_add_f32_dpp v235, v235, v235 row_half_mirror row_mask:0xf bank_mask:0xf
	v_add_f32_dpp v236, v236, v236 row_half_mirror row_mask:0xf bank_mask:0xf
	v_add_f32_dpp v237, v237, v237 row_half_mirror row_mask:0xf bank_mask:0xf
	s_mov_b32 exec_lo, 0x10001
	s_mov_b32 exec_hi, 0x10001
	ds_write_b32 v155, v234 offset:1024
	ds_write_b32 v155, v235 offset:1040
	ds_write_b32 v155, v236 offset:1056
	ds_write_b32 v155, v237 offset:1072
	s_mov_b64 exec, -1
	ds_read2_b32 v[230:231], v243 offset1:4
	ds_read2_b32 v[232:233], v243 offset0:8 offset1:12
	s_waitcnt lgkmcnt(0)
; __device__ __forceinline__ void peer_token(const Params& P, int t, int lane, int* sidx, float* sval, const int* sid, const float* sgate, const unsigned* szero) {
;     ...
; #pragma unroll
;         for (int hh = 0; hh < 2; ++hh)
; #pragma unroll
;             for (int st = 0; st < 4; ++st) abuf[0][hh][st] = *(const uint4*)(Ub + (off2[hh] + 128 * st));
; #pragma unroll
;         for (int T = 0; T < 8; ++T) {
;             if (T + 1 < 8) {
; #pragma unroll
;                 for (int hh = 0; hh < 2; ++hh) off2[hh] = (unsigned)sid[16 * (T + 1) + 8 * hh + (lr & 7)] * 512u + lofs;
; #pragma unroll
;                 for (int hh = 0; hh < 2; ++hh)
; #pragma unroll
;                     for (int st = 0; st < 4; ++st) abuf[(T + 1) & 1][hh][st] = *(const uint4*)(Ub + (off2[hh] + 128 * st));
;             }
; #pragma unroll
;             for (int hh = 0; hh < 2; ++hh) {
;                 f32x4 au = (f32x4){0.f, 0.f, 0.f, 0.f};
; #pragma unroll
;                 for (int st = 0; st < 4; ++st) {
;                     const uint4 a4 = abuf[T & 1][hh][st];
;                     const v8i Av = {(int)a4.x, (int)a4.y, (int)a4.z, (int)a4.w, 0, 0, 0, 0};
;                     au = __builtin_amdgcn_mfma_scale_f32_16x16x128_f8f6f4(Av, Bv[st], au, 4, 0, 0, 0x7f7f7f7f, 0, 0x7f7f7f7f);
;                 }
;                 if (owner) *(f32x4*)(sact + 16 * T + 8 * hh) = au;
;             }
	v_lshl_add_u32 v230, v230, 9, v144
	v_lshl_add_u32 v231, v231, 9, v144
	v_lshl_add_u32 v232, v232, 9, v144
	v_lshl_add_u32 v233, v233, 9, v144
	global_load_dwordx4 v[32:35], v230, s[10:11]
	global_load_dwordx4 v[36:39], v230, s[10:11] offset:256
	global_load_dwordx4 v[40:43], v231, s[10:11]
	global_load_dwordx4 v[44:47], v231, s[10:11] offset:256
	global_load_dwordx4 v[48:51], v232, s[10:11]
	global_load_dwordx4 v[52:55], v232, s[10:11] offset:256
	global_load_dwordx4 v[56:59], v233, s[10:11]
	global_load_dwordx4 v[60:63], v233, s[10:11] offset:256
	s_waitcnt vmcnt(8)
	v_mfma_scale_f32_16x16x128_f8f6f4 v[64:67], v[0:3], v[162:169], 0, v133, v133 op_sel_hi:[0,0,0] cbsz:4
	v_mfma_scale_f32_16x16x128_f8f6f4 v[64:67], v[4:7], v[170:177], v[64:67], v133, v133 op_sel_hi:[0,0,0] cbsz:4
	v_mfma_scale_f32_16x16x128_f8f6f4 v[68:71], v[8:11], v[162:169], 0, v133, v133 op_sel_hi:[0,0,0] cbsz:4
	v_mfma_scale_f32_16x16x128_f8f6f4 v[68:71], v[12:15], v[170:177], v[68:71], v133, v133 op_sel_hi:[0,0,0] cbsz:4
	v_mfma_scale_f32_16x16x128_f8f6f4 v[72:75], v[16:19], v[162:169], 0, v133, v133 op_sel_hi:[0,0,0] cbsz:4
	v_mfma_scale_f32_16x16x128_f8f6f4 v[72:75], v[20:23], v[170:177], v[72:75], v133, v133 op_sel_hi:[0,0,0] cbsz:4
	v_mfma_scale_f32_16x16x128_f8f6f4 v[76:79], v[24:27], v[162:169], 0, v133, v133 op_sel_hi:[0,0,0] cbsz:4
	v_mfma_scale_f32_16x16x128_f8f6f4 v[76:79], v[28:31], v[170:177], v[76:79], v133, v133 op_sel_hi:[0,0,0] cbsz:4
	s_nop 3
	v_mul_f32_e32 v234, v158, v80
	v_mul_f32_e32 v235, v158, v84
	v_mul_f32_e32 v236, v158, v88
	v_mul_f32_e32 v237, v158, v92
	v_fmac_f32_e32 v234, v159, v81
	v_fmac_f32_e32 v235, v159, v85
	v_fmac_f32_e32 v236, v159, v89
	v_fmac_f32_e32 v237, v159, v93
	v_fmac_f32_e32 v234, v160, v82
	v_fmac_f32_e32 v235, v160, v86
	v_fmac_f32_e32 v236, v160, v90
	v_fmac_f32_e32 v237, v160, v94
	v_fmac_f32_e32 v234, v161, v83
	v_fmac_f32_e32 v235, v161, v87
	v_fmac_f32_e32 v236, v161, v91
	v_fmac_f32_e32 v237, v161, v95
	v_add_f32_dpp v234, v234, v234 quad_perm:[1,0,3,2] row_mask:0xf bank_mask:0xf
	v_add_f32_dpp v235, v235, v235 quad_perm:[1,0,3,2] row_mask:0xf bank_mask:0xf
	v_add_f32_dpp v236, v236, v236 quad_perm:[1,0,3,2] row_mask:0xf bank_mask:0xf
	v_add_f32_dpp v237, v237, v237 quad_perm:[1,0,3,2] row_mask:0xf bank_mask:0xf
	v_add_f32_dpp v234, v234, v234 quad_perm:[2,3,0,1] row_mask:0xf bank_mask:0xf
	v_add_f32_dpp v235, v235, v235 quad_perm:[2,3,0,1] row_mask:0xf bank_mask:0xf
	v_add_f32_dpp v236, v236, v236 quad_perm:[2,3,0,1] row_mask:0xf bank_mask:0xf
	v_add_f32_dpp v237, v237, v237 quad_perm:[2,3,0,1] row_mask:0xf bank_mask:0xf
	v_add_f32_dpp v234, v234, v234 row_half_mirror row_mask:0xf bank_mask:0xf
	v_add_f32_dpp v235, v235, v235 row_half_mirror row_mask:0xf bank_mask:0xf
	v_add_f32_dpp v236, v236, v236 row_half_mirror row_mask:0xf bank_mask:0xf
	v_add_f32_dpp v237, v237, v237 row_half_mirror row_mask:0xf bank_mask:0xf
	s_mov_b32 exec_lo, 0x10001
	s_mov_b32 exec_hi, 0x10001
	ds_write_b32 v155, v234 offset:1536
	ds_write_b32 v155, v235 offset:1552
	ds_write_b32 v155, v236 offset:1568
	ds_write_b32 v155, v237 offset:1584
	s_mov_b64 exec, -1
	ds_read2_b32 v[96:97], v244 offset1:4
	ds_read2_b32 v[98:99], v244 offset0:8 offset1:12
	s_waitcnt lgkmcnt(0)
	v_lshl_add_u32 v96, v96, 9, v144
	v_lshl_add_u32 v97, v97, 9, v144
	v_lshl_add_u32 v98, v98, 9, v144
	v_lshl_add_u32 v99, v99, 9, v144
	global_load_dwordx4 v[0:3], v96, s[10:11]
	global_load_dwordx4 v[4:7], v96, s[10:11] offset:256
	global_load_dwordx4 v[8:11], v97, s[10:11]
	global_load_dwordx4 v[12:15], v97, s[10:11] offset:256
	global_load_dwordx4 v[16:19], v98, s[10:11]
	global_load_dwordx4 v[20:23], v98, s[10:11] offset:256
	global_load_dwordx4 v[24:27], v99, s[10:11]
	global_load_dwordx4 v[28:31], v99, s[10:11] offset:256
	s_waitcnt vmcnt(8)
	v_mfma_scale_f32_16x16x128_f8f6f4 v[80:83], v[32:35], v[178:185], 0, v133, v133 op_sel_hi:[0,0,0] cbsz:4
	v_mfma_scale_f32_16x16x128_f8f6f4 v[80:83], v[36:39], v[186:193], v[80:83], v133, v133 op_sel_hi:[0,0,0] cbsz:4
	v_mfma_scale_f32_16x16x128_f8f6f4 v[84:87], v[40:43], v[178:185], 0, v133, v133 op_sel_hi:[0,0,0] cbsz:4
	v_mfma_scale_f32_16x16x128_f8f6f4 v[84:87], v[44:47], v[186:193], v[84:87], v133, v133 op_sel_hi:[0,0,0] cbsz:4
	v_mfma_scale_f32_16x16x128_f8f6f4 v[88:91], v[48:51], v[178:185], 0, v133, v133 op_sel_hi:[0,0,0] cbsz:4
	v_mfma_scale_f32_16x16x128_f8f6f4 v[88:91], v[52:55], v[186:193], v[88:91], v133, v133 op_sel_hi:[0,0,0] cbsz:4
	v_mfma_scale_f32_16x16x128_f8f6f4 v[92:95], v[56:59], v[178:185], 0, v133, v133 op_sel_hi:[0,0,0] cbsz:4
	v_mfma_scale_f32_16x16x128_f8f6f4 v[92:95], v[60:63], v[186:193], v[92:95], v133, v133 op_sel_hi:[0,0,0] cbsz:4
	s_nop 3
	v_mul_f32_e32 v234, v226, v64
	v_mul_f32_e32 v235, v226, v68
	v_mul_f32_e32 v236, v226, v72
	v_mul_f32_e32 v237, v226, v76
	v_fmac_f32_e32 v234, v227, v65
	v_fmac_f32_e32 v235, v227, v69
	v_fmac_f32_e32 v236, v227, v73
	v_fmac_f32_e32 v237, v227, v77
	v_fmac_f32_e32 v234, v228, v66
	v_fmac_f32_e32 v235, v228, v70
	v_fmac_f32_e32 v236, v228, v74
	v_fmac_f32_e32 v237, v228, v78
	v_fmac_f32_e32 v234, v229, v67
	v_fmac_f32_e32 v235, v229, v71
	v_fmac_f32_e32 v236, v229, v75
	v_fmac_f32_e32 v237, v229, v79
	v_add_f32_dpp v234, v234, v234 quad_perm:[1,0,3,2] row_mask:0xf bank_mask:0xf
	v_add_f32_dpp v235, v235, v235 quad_perm:[1,0,3,2] row_mask:0xf bank_mask:0xf
	v_add_f32_dpp v236, v236, v236 quad_perm:[1,0,3,2] row_mask:0xf bank_mask:0xf
	v_add_f32_dpp v237, v237, v237 quad_perm:[1,0,3,2] row_mask:0xf bank_mask:0xf
	v_add_f32_dpp v234, v234, v234 quad_perm:[2,3,0,1] row_mask:0xf bank_mask:0xf
	v_add_f32_dpp v235, v235, v235 quad_perm:[2,3,0,1] row_mask:0xf bank_mask:0xf
	v_add_f32_dpp v236, v236, v236 quad_perm:[2,3,0,1] row_mask:0xf bank_mask:0xf
	v_add_f32_dpp v237, v237, v237 quad_perm:[2,3,0,1] row_mask:0xf bank_mask:0xf
	v_add_f32_dpp v234, v234, v234 row_half_mirror row_mask:0xf bank_mask:0xf
	v_add_f32_dpp v235, v235, v235 row_half_mirror row_mask:0xf bank_mask:0xf
	v_add_f32_dpp v236, v236, v236 row_half_mirror row_mask:0xf bank_mask:0xf
	v_add_f32_dpp v237, v237, v237 row_half_mirror row_mask:0xf bank_mask:0xf
	s_mov_b32 exec_lo, 0x1000100
	s_mov_b32 exec_hi, 0x1000100
	ds_write_b32 v155, v234 offset:2048
	ds_write_b32 v155, v235 offset:2064
	ds_write_b32 v155, v236 offset:2080
	ds_write_b32 v155, v237 offset:2096
	s_mov_b64 exec, -1
	ds_read2_b32 v[230:231], v245 offset1:4
	ds_read2_b32 v[232:233], v245 offset0:8 offset1:12
	s_waitcnt lgkmcnt(0)
; __device__ __forceinline__ void peer_token(const Params& P, int t, int lane, int* sidx, float* sval, const int* sid, const float* sgate, const unsigned* szero) {
;     ...
; #pragma unroll
;         for (int hh = 0; hh < 2; ++hh)
; #pragma unroll
;             for (int st = 0; st < 4; ++st) abuf[0][hh][st] = *(const uint4*)(Ub + (off2[hh] + 128 * st));
; #pragma unroll
;         for (int T = 0; T < 8; ++T) {
;             if (T + 1 < 8) {
; #pragma unroll
;                 for (int hh = 0; hh < 2; ++hh) off2[hh] = (unsigned)sid[16 * (T + 1) + 8 * hh + (lr & 7)] * 512u + lofs;
; #pragma unroll
;                 for (int hh = 0; hh < 2; ++hh)
; #pragma unroll
;                     for (int st = 0; st < 4; ++st) abuf[(T + 1) & 1][hh][st] = *(const uint4*)(Ub + (off2[hh] + 128 * st));
;             }
; #pragma unroll
;             for (int hh = 0; hh < 2; ++hh) {
;                 f32x4 au = (f32x4){0.f, 0.f, 0.f, 0.f};
; #pragma unroll
;                 for (int st = 0; st < 4; ++st) {
;                     const uint4 a4 = abuf[T & 1][hh][st];
;                     const v8i Av = {(int)a4.x, (int)a4.y, (int)a4.z, (int)a4.w, 0, 0, 0, 0};
;                     au = __builtin_amdgcn_mfma_scale_f32_16x16x128_f8f6f4(Av, Bv[st], au, 4, 0, 0, 0x7f7f7f7f, 0, 0x7f7f7f7f);
;                 }
;                 if (owner) *(f32x4*)(sact + 16 * T + 8 * hh) = au;
;             }
	v_lshl_add_u32 v230, v230, 9, v144
	v_lshl_add_u32 v231, v231, 9, v144
	v_lshl_add_u32 v232, v232, 9, v144
	v_lshl_add_u32 v233, v233, 9, v144
	global_load_dwordx4 v[32:35], v230, s[10:11]
	global_load_dwordx4 v[36:39], v230, s[10:11] offset:256
	global_load_dwordx4 v[40:43], v231, s[10:11]
	global_load_dwordx4 v[44:47], v231, s[10:11] offset:256
	global_load_dwordx4 v[48:51], v232, s[10:11]
	global_load_dwordx4 v[52:55], v232, s[10:11] offset:256
	global_load_dwordx4 v[56:59], v233, s[10:11]
	global_load_dwordx4 v[60:63], v233, s[10:11] offset:256
	s_waitcnt vmcnt(8)
	v_mfma_scale_f32_16x16x128_f8f6f4 v[64:67], v[0:3], v[194:201], 0, v133, v133 op_sel_hi:[0,0,0] cbsz:4
	v_mfma_scale_f32_16x16x128_f8f6f4 v[64:67], v[4:7], v[202:209], v[64:67], v133, v133 op_sel_hi:[0,0,0] cbsz:4
	v_mfma_scale_f32_16x16x128_f8f6f4 v[68:71], v[8:11], v[194:201], 0, v133, v133 op_sel_hi:[0,0,0] cbsz:4
	v_mfma_scale_f32_16x16x128_f8f6f4 v[68:71], v[12:15], v[202:209], v[68:71], v133, v133 op_sel_hi:[0,0,0] cbsz:4
	v_mfma_scale_f32_16x16x128_f8f6f4 v[72:75], v[16:19], v[194:201], 0, v133, v133 op_sel_hi:[0,0,0] cbsz:4
	v_mfma_scale_f32_16x16x128_f8f6f4 v[72:75], v[20:23], v[202:209], v[72:75], v133, v133 op_sel_hi:[0,0,0] cbsz:4
	v_mfma_scale_f32_16x16x128_f8f6f4 v[76:79], v[24:27], v[194:201], 0, v133, v133 op_sel_hi:[0,0,0] cbsz:4
	v_mfma_scale_f32_16x16x128_f8f6f4 v[76:79], v[28:31], v[202:209], v[76:79], v133, v133 op_sel_hi:[0,0,0] cbsz:4
	s_nop 3
	v_mul_f32_e32 v234, v226, v80
	v_mul_f32_e32 v235, v226, v84
	v_mul_f32_e32 v236, v226, v88
	v_mul_f32_e32 v237, v226, v92
	v_fmac_f32_e32 v234, v227, v81
	v_fmac_f32_e32 v235, v227, v85
	v_fmac_f32_e32 v236, v227, v89
	v_fmac_f32_e32 v237, v227, v93
	v_fmac_f32_e32 v234, v228, v82
	v_fmac_f32_e32 v235, v228, v86
	v_fmac_f32_e32 v236, v228, v90
	v_fmac_f32_e32 v237, v228, v94
	v_fmac_f32_e32 v234, v229, v83
	v_fmac_f32_e32 v235, v229, v87
	v_fmac_f32_e32 v236, v229, v91
	v_fmac_f32_e32 v237, v229, v95
	v_add_f32_dpp v234, v234, v234 quad_perm:[1,0,3,2] row_mask:0xf bank_mask:0xf
	v_add_f32_dpp v235, v235, v235 quad_perm:[1,0,3,2] row_mask:0xf bank_mask:0xf
	v_add_f32_dpp v236, v236, v236 quad_perm:[1,0,3,2] row_mask:0xf bank_mask:0xf
	v_add_f32_dpp v237, v237, v237 quad_perm:[1,0,3,2] row_mask:0xf bank_mask:0xf
	v_add_f32_dpp v234, v234, v234 quad_perm:[2,3,0,1] row_mask:0xf bank_mask:0xf
	v_add_f32_dpp v235, v235, v235 quad_perm:[2,3,0,1] row_mask:0xf bank_mask:0xf
	v_add_f32_dpp v236, v236, v236 quad_perm:[2,3,0,1] row_mask:0xf bank_mask:0xf
	v_add_f32_dpp v237, v237, v237 quad_perm:[2,3,0,1] row_mask:0xf bank_mask:0xf
	v_add_f32_dpp v234, v234, v234 row_half_mirror row_mask:0xf bank_mask:0xf
	v_add_f32_dpp v235, v235, v235 row_half_mirror row_mask:0xf bank_mask:0xf
	v_add_f32_dpp v236, v236, v236 row_half_mirror row_mask:0xf bank_mask:0xf
	v_add_f32_dpp v237, v237, v237 row_half_mirror row_mask:0xf bank_mask:0xf
	s_mov_b32 exec_lo, 0x1000100
	s_mov_b32 exec_hi, 0x1000100
	ds_write_b32 v155, v234 offset:2560
	ds_write_b32 v155, v235 offset:2576
	ds_write_b32 v155, v236 offset:2592
	ds_write_b32 v155, v237 offset:2608
	s_mov_b64 exec, -1
	ds_read2_b32 v[96:97], v238 offset0:16 offset1:20
	ds_read2_b32 v[98:99], v238 offset0:24 offset1:28
	s_waitcnt lgkmcnt(0)
	v_lshl_add_u32 v96, v96, 9, v144
	v_lshl_add_u32 v97, v97, 9, v144
	v_lshl_add_u32 v98, v98, 9, v144
	v_lshl_add_u32 v99, v99, 9, v144
	global_load_dwordx4 v[0:3], v96, s[10:11]
	global_load_dwordx4 v[4:7], v96, s[10:11] offset:256
	global_load_dwordx4 v[8:11], v97, s[10:11]
	global_load_dwordx4 v[12:15], v97, s[10:11] offset:256
	global_load_dwordx4 v[16:19], v98, s[10:11]
	global_load_dwordx4 v[20:23], v98, s[10:11] offset:256
	global_load_dwordx4 v[24:27], v99, s[10:11]
	global_load_dwordx4 v[28:31], v99, s[10:11] offset:256
	s_waitcnt vmcnt(8)
	v_mfma_scale_f32_16x16x128_f8f6f4 v[80:83], v[32:35], v[210:217], 0, v133, v133 op_sel_hi:[0,0,0] cbsz:4
	v_mfma_scale_f32_16x16x128_f8f6f4 v[80:83], v[36:39], v[218:225], v[80:83], v133, v133 op_sel_hi:[0,0,0] cbsz:4
	v_mfma_scale_f32_16x16x128_f8f6f4 v[84:87], v[40:43], v[210:217], 0, v133, v133 op_sel_hi:[0,0,0] cbsz:4
	v_mfma_scale_f32_16x16x128_f8f6f4 v[84:87], v[44:47], v[218:225], v[84:87], v133, v133 op_sel_hi:[0,0,0] cbsz:4
	v_mfma_scale_f32_16x16x128_f8f6f4 v[88:91], v[48:51], v[210:217], 0, v133, v133 op_sel_hi:[0,0,0] cbsz:4
	v_mfma_scale_f32_16x16x128_f8f6f4 v[88:91], v[52:55], v[218:225], v[88:91], v133, v133 op_sel_hi:[0,0,0] cbsz:4
	v_mfma_scale_f32_16x16x128_f8f6f4 v[92:95], v[56:59], v[210:217], 0, v133, v133 op_sel_hi:[0,0,0] cbsz:4
	v_mfma_scale_f32_16x16x128_f8f6f4 v[92:95], v[60:63], v[218:225], v[92:95], v133, v133 op_sel_hi:[0,0,0] cbsz:4
	s_nop 3
	v_mul_f32_e32 v234, v226, v64
	v_mul_f32_e32 v235, v226, v68
	v_mul_f32_e32 v236, v226, v72
	v_mul_f32_e32 v237, v226, v76
	v_fmac_f32_e32 v234, v227, v65
	v_fmac_f32_e32 v235, v227, v69
	v_fmac_f32_e32 v236, v227, v73
	v_fmac_f32_e32 v237, v227, v77
	v_fmac_f32_e32 v234, v228, v66
	v_fmac_f32_e32 v235, v228, v70
	v_fmac_f32_e32 v236, v228, v74
	v_fmac_f32_e32 v237, v228, v78
	v_fmac_f32_e32 v234, v229, v67
	v_fmac_f32_e32 v235, v229, v71
	v_fmac_f32_e32 v236, v229, v75
	v_fmac_f32_e32 v237, v229, v79
	v_add_f32_dpp v234, v234, v234 quad_perm:[1,0,3,2] row_mask:0xf bank_mask:0xf
	v_add_f32_dpp v235, v235, v235 quad_perm:[1,0,3,2] row_mask:0xf bank_mask:0xf
	v_add_f32_dpp v236, v236, v236 quad_perm:[1,0,3,2] row_mask:0xf bank_mask:0xf
	v_add_f32_dpp v237, v237, v237 quad_perm:[1,0,3,2] row_mask:0xf bank_mask:0xf
	v_add_f32_dpp v234, v234, v234 quad_perm:[2,3,0,1] row_mask:0xf bank_mask:0xf
	v_add_f32_dpp v235, v235, v235 quad_perm:[2,3,0,1] row_mask:0xf bank_mask:0xf
	v_add_f32_dpp v236, v236, v236 quad_perm:[2,3,0,1] row_mask:0xf bank_mask:0xf
	v_add_f32_dpp v237, v237, v237 quad_perm:[2,3,0,1] row_mask:0xf bank_mask:0xf
	v_add_f32_dpp v234, v234, v234 row_half_mirror row_mask:0xf bank_mask:0xf
	v_add_f32_dpp v235, v235, v235 row_half_mirror row_mask:0xf bank_mask:0xf
	v_add_f32_dpp v236, v236, v236 row_half_mirror row_mask:0xf bank_mask:0xf
	v_add_f32_dpp v237, v237, v237 row_half_mirror row_mask:0xf bank_mask:0xf
	s_mov_b32 exec_lo, 0x1000100
	s_mov_b32 exec_hi, 0x1000100
	ds_write_b32 v155, v234 offset:3072
	ds_write_b32 v155, v235 offset:3088
	ds_write_b32 v155, v236 offset:3104
	ds_write_b32 v155, v237 offset:3120
	s_mov_b64 exec, -1
	ds_read2_b32 v[230:231], v239 offset0:16 offset1:20
	ds_read2_b32 v[232:233], v239 offset0:24 offset1:28
	s_waitcnt lgkmcnt(0)
; __device__ __forceinline__ void peer_token(const Params& P, int t, int lane, int* sidx, float* sval, const int* sid, const float* sgate, const unsigned* szero) {
;     ...
; #pragma unroll
;         for (int hh = 0; hh < 2; ++hh)
; #pragma unroll
;             for (int st = 0; st < 4; ++st) abuf[0][hh][st] = *(const uint4*)(Ub + (off2[hh] + 128 * st));
; #pragma unroll
;         for (int T = 0; T < 8; ++T) {
;             if (T + 1 < 8) {
; #pragma unroll
;                 for (int hh = 0; hh < 2; ++hh) off2[hh] = (unsigned)sid[16 * (T + 1) + 8 * hh + (lr & 7)] * 512u + lofs;
; #pragma unroll
;                 for (int hh = 0; hh < 2; ++hh)
; #pragma unroll
;                     for (int st = 0; st < 4; ++st) abuf[(T + 1) & 1][hh][st] = *(const uint4*)(Ub + (off2[hh] + 128 * st));
;             }
; #pragma unroll
;             for (int hh = 0; hh < 2; ++hh) {
;                 f32x4 au = (f32x4){0.f, 0.f, 0.f, 0.f};
; #pragma unroll
;                 for (int st = 0; st < 4; ++st) {
;                     const uint4 a4 = abuf[T & 1][hh][st];
;                     const v8i Av = {(int)a4.x, (int)a4.y, (int)a4.z, (int)a4.w, 0, 0, 0, 0};
;                     au = __builtin_amdgcn_mfma_scale_f32_16x16x128_f8f6f4(Av, Bv[st], au, 4, 0, 0, 0x7f7f7f7f, 0, 0x7f7f7f7f);
;                 }
;                 if (owner) *(f32x4*)(sact + 16 * T + 8 * hh) = au;
;             }
	v_lshl_add_u32 v230, v230, 9, v144
	v_lshl_add_u32 v231, v231, 9, v144
	v_lshl_add_u32 v232, v232, 9, v144
	v_lshl_add_u32 v233, v233, 9, v144
	global_load_dwordx4 v[32:35], v230, s[10:11]
	global_load_dwordx4 v[36:39], v230, s[10:11] offset:256
	global_load_dwordx4 v[40:43], v231, s[10:11]
	global_load_dwordx4 v[44:47], v231, s[10:11] offset:256
	global_load_dwordx4 v[48:51], v232, s[10:11]
	global_load_dwordx4 v[52:55], v232, s[10:11] offset:256
	global_load_dwordx4 v[56:59], v233, s[10:11]
	global_load_dwordx4 v[60:63], v233, s[10:11] offset:256
	s_waitcnt vmcnt(8)
	v_mfma_scale_f32_16x16x128_f8f6f4 v[64:67], v[0:3], v[162:169], 0, v133, v133 op_sel_hi:[0,0,0] cbsz:4
	v_mfma_scale_f32_16x16x128_f8f6f4 v[64:67], v[4:7], v[170:177], v[64:67], v133, v133 op_sel_hi:[0,0,0] cbsz:4
	v_mfma_scale_f32_16x16x128_f8f6f4 v[68:71], v[8:11], v[162:169], 0, v133, v133 op_sel_hi:[0,0,0] cbsz:4
	v_mfma_scale_f32_16x16x128_f8f6f4 v[68:71], v[12:15], v[170:177], v[68:71], v133, v133 op_sel_hi:[0,0,0] cbsz:4
	v_mfma_scale_f32_16x16x128_f8f6f4 v[72:75], v[16:19], v[162:169], 0, v133, v133 op_sel_hi:[0,0,0] cbsz:4
	v_mfma_scale_f32_16x16x128_f8f6f4 v[72:75], v[20:23], v[170:177], v[72:75], v133, v133 op_sel_hi:[0,0,0] cbsz:4
	v_mfma_scale_f32_16x16x128_f8f6f4 v[76:79], v[24:27], v[162:169], 0, v133, v133 op_sel_hi:[0,0,0] cbsz:4
	v_mfma_scale_f32_16x16x128_f8f6f4 v[76:79], v[28:31], v[170:177], v[76:79], v133, v133 op_sel_hi:[0,0,0] cbsz:4
	s_nop 3
	v_mul_f32_e32 v234, v226, v80
	v_mul_f32_e32 v235, v226, v84
	v_mul_f32_e32 v236, v226, v88
	v_mul_f32_e32 v237, v226, v92
	v_fmac_f32_e32 v234, v227, v81
	v_fmac_f32_e32 v235, v227, v85
	v_fmac_f32_e32 v236, v227, v89
	v_fmac_f32_e32 v237, v227, v93
	v_fmac_f32_e32 v234, v228, v82
	v_fmac_f32_e32 v235, v228, v86
	v_fmac_f32_e32 v236, v228, v90
	v_fmac_f32_e32 v237, v228, v94
	v_fmac_f32_e32 v234, v229, v83
	v_fmac_f32_e32 v235, v229, v87
	v_fmac_f32_e32 v236, v229, v91
	v_fmac_f32_e32 v237, v229, v95
	v_add_f32_dpp v234, v234, v234 quad_perm:[1,0,3,2] row_mask:0xf bank_mask:0xf
	v_add_f32_dpp v235, v235, v235 quad_perm:[1,0,3,2] row_mask:0xf bank_mask:0xf
	v_add_f32_dpp v236, v236, v236 quad_perm:[1,0,3,2] row_mask:0xf bank_mask:0xf
	v_add_f32_dpp v237, v237, v237 quad_perm:[1,0,3,2] row_mask:0xf bank_mask:0xf
	v_add_f32_dpp v234, v234, v234 quad_perm:[2,3,0,1] row_mask:0xf bank_mask:0xf
	v_add_f32_dpp v235, v235, v235 quad_perm:[2,3,0,1] row_mask:0xf bank_mask:0xf
	v_add_f32_dpp v236, v236, v236 quad_perm:[2,3,0,1] row_mask:0xf bank_mask:0xf
	v_add_f32_dpp v237, v237, v237 quad_perm:[2,3,0,1] row_mask:0xf bank_mask:0xf
	v_add_f32_dpp v234, v234, v234 row_half_mirror row_mask:0xf bank_mask:0xf
	v_add_f32_dpp v235, v235, v235 row_half_mirror row_mask:0xf bank_mask:0xf
	v_add_f32_dpp v236, v236, v236 row_half_mirror row_mask:0xf bank_mask:0xf
	v_add_f32_dpp v237, v237, v237 row_half_mirror row_mask:0xf bank_mask:0xf
	s_mov_b32 exec_lo, 0x1000100
	s_mov_b32 exec_hi, 0x1000100
	ds_write_b32 v155, v234 offset:3584
	ds_write_b32 v155, v235 offset:3600
	ds_write_b32 v155, v236 offset:3616
	ds_write_b32 v155, v237 offset:3632
	s_mov_b64 exec, -1
	ds_read2_b32 v[96:97], v240 offset0:16 offset1:20
	ds_read2_b32 v[98:99], v240 offset0:24 offset1:28
	s_waitcnt lgkmcnt(0)
	v_lshl_add_u32 v96, v96, 9, v144
	v_lshl_add_u32 v97, v97, 9, v144
	v_lshl_add_u32 v98, v98, 9, v144
	v_lshl_add_u32 v99, v99, 9, v144
	global_load_dwordx4 v[0:3], v96, s[10:11]
	global_load_dwordx4 v[4:7], v96, s[10:11] offset:256
	global_load_dwordx4 v[8:11], v97, s[10:11]
	global_load_dwordx4 v[12:15], v97, s[10:11] offset:256
	global_load_dwordx4 v[16:19], v98, s[10:11]
	global_load_dwordx4 v[20:23], v98, s[10:11] offset:256
	global_load_dwordx4 v[24:27], v99, s[10:11]
	global_load_dwordx4 v[28:31], v99, s[10:11] offset:256
	s_waitcnt vmcnt(8)
	v_mfma_scale_f32_16x16x128_f8f6f4 v[80:83], v[32:35], v[178:185], 0, v133, v133 op_sel_hi:[0,0,0] cbsz:4
	v_mfma_scale_f32_16x16x128_f8f6f4 v[80:83], v[36:39], v[186:193], v[80:83], v133, v133 op_sel_hi:[0,0,0] cbsz:4
	v_mfma_scale_f32_16x16x128_f8f6f4 v[84:87], v[40:43], v[178:185], 0, v133, v133 op_sel_hi:[0,0,0] cbsz:4
	v_mfma_scale_f32_16x16x128_f8f6f4 v[84:87], v[44:47], v[186:193], v[84:87], v133, v133 op_sel_hi:[0,0,0] cbsz:4
	v_mfma_scale_f32_16x16x128_f8f6f4 v[88:91], v[48:51], v[178:185], 0, v133, v133 op_sel_hi:[0,0,0] cbsz:4
	v_mfma_scale_f32_16x16x128_f8f6f4 v[88:91], v[52:55], v[186:193], v[88:91], v133, v133 op_sel_hi:[0,0,0] cbsz:4
	v_mfma_scale_f32_16x16x128_f8f6f4 v[92:95], v[56:59], v[178:185], 0, v133, v133 op_sel_hi:[0,0,0] cbsz:4
	v_mfma_scale_f32_16x16x128_f8f6f4 v[92:95], v[60:63], v[186:193], v[92:95], v133, v133 op_sel_hi:[0,0,0] cbsz:4
	s_nop 3
	v_mul_f32_e32 v234, v158, v64
	v_mul_f32_e32 v235, v158, v68
	v_mul_f32_e32 v236, v158, v72
	v_mul_f32_e32 v237, v158, v76
	v_fmac_f32_e32 v234, v159, v65
	v_fmac_f32_e32 v235, v159, v69
	v_fmac_f32_e32 v236, v159, v73
	v_fmac_f32_e32 v237, v159, v77
	v_fmac_f32_e32 v234, v160, v66
	v_fmac_f32_e32 v235, v160, v70
	v_fmac_f32_e32 v236, v160, v74
	v_fmac_f32_e32 v237, v160, v78
	v_fmac_f32_e32 v234, v161, v67
	v_fmac_f32_e32 v235, v161, v71
	v_fmac_f32_e32 v236, v161, v75
	v_fmac_f32_e32 v237, v161, v79
	v_add_f32_dpp v234, v234, v234 quad_perm:[1,0,3,2] row_mask:0xf bank_mask:0xf
	v_add_f32_dpp v235, v235, v235 quad_perm:[1,0,3,2] row_mask:0xf bank_mask:0xf
	v_add_f32_dpp v236, v236, v236 quad_perm:[1,0,3,2] row_mask:0xf bank_mask:0xf
	v_add_f32_dpp v237, v237, v237 quad_perm:[1,0,3,2] row_mask:0xf bank_mask:0xf
	v_add_f32_dpp v234, v234, v234 quad_perm:[2,3,0,1] row_mask:0xf bank_mask:0xf
	v_add_f32_dpp v235, v235, v235 quad_perm:[2,3,0,1] row_mask:0xf bank_mask:0xf
	v_add_f32_dpp v236, v236, v236 quad_perm:[2,3,0,1] row_mask:0xf bank_mask:0xf
	v_add_f32_dpp v237, v237, v237 quad_perm:[2,3,0,1] row_mask:0xf bank_mask:0xf
	v_add_f32_dpp v234, v234, v234 row_half_mirror row_mask:0xf bank_mask:0xf
	v_add_f32_dpp v235, v235, v235 row_half_mirror row_mask:0xf bank_mask:0xf
	v_add_f32_dpp v236, v236, v236 row_half_mirror row_mask:0xf bank_mask:0xf
	v_add_f32_dpp v237, v237, v237 row_half_mirror row_mask:0xf bank_mask:0xf
	s_mov_b32 exec_lo, 0x10001
	s_mov_b32 exec_hi, 0x10001
	ds_write_b32 v155, v234 offset:64
	ds_write_b32 v155, v235 offset:80
	ds_write_b32 v155, v236 offset:96
	ds_write_b32 v155, v237 offset:112
	s_mov_b64 exec, -1
	ds_read2_b32 v[230:231], v241 offset0:16 offset1:20
	ds_read2_b32 v[232:233], v241 offset0:24 offset1:28
	s_waitcnt lgkmcnt(0)
; __device__ __forceinline__ void peer_token(const Params& P, int t, int lane, int* sidx, float* sval, const int* sid, const float* sgate, const unsigned* szero) {
;     ...
; #pragma unroll
;         for (int hh = 0; hh < 2; ++hh)
; #pragma unroll
;             for (int st = 0; st < 4; ++st) abuf[0][hh][st] = *(const uint4*)(Ub + (off2[hh] + 128 * st));
; #pragma unroll
;         for (int T = 0; T < 8; ++T) {
;             if (T + 1 < 8) {
; #pragma unroll
;                 for (int hh = 0; hh < 2; ++hh) off2[hh] = (unsigned)sid[16 * (T + 1) + 8 * hh + (lr & 7)] * 512u + lofs;
; #pragma unroll
;                 for (int hh = 0; hh < 2; ++hh)
; #pragma unroll
;                     for (int st = 0; st < 4; ++st) abuf[(T + 1) & 1][hh][st] = *(const uint4*)(Ub + (off2[hh] + 128 * st));
;             }
; #pragma unroll
;             for (int hh = 0; hh < 2; ++hh) {
;                 f32x4 au = (f32x4){0.f, 0.f, 0.f, 0.f};
; #pragma unroll
;                 for (int st = 0; st < 4; ++st) {
;                     const uint4 a4 = abuf[T & 1][hh][st];
;                     const v8i Av = {(int)a4.x, (int)a4.y, (int)a4.z, (int)a4.w, 0, 0, 0, 0};
;                     au = __builtin_amdgcn_mfma_scale_f32_16x16x128_f8f6f4(Av, Bv[st], au, 4, 0, 0, 0x7f7f7f7f, 0, 0x7f7f7f7f);
;                 }
;                 if (owner) *(f32x4*)(sact + 16 * T + 8 * hh) = au;
;             }
	v_lshl_add_u32 v230, v230, 9, v144
	v_lshl_add_u32 v231, v231, 9, v144
	v_lshl_add_u32 v232, v232, 9, v144
	v_lshl_add_u32 v233, v233, 9, v144
	global_load_dwordx4 v[32:35], v230, s[10:11]
	global_load_dwordx4 v[36:39], v230, s[10:11] offset:256
	global_load_dwordx4 v[40:43], v231, s[10:11]
	global_load_dwordx4 v[44:47], v231, s[10:11] offset:256
	global_load_dwordx4 v[48:51], v232, s[10:11]
	global_load_dwordx4 v[52:55], v232, s[10:11] offset:256
	global_load_dwordx4 v[56:59], v233, s[10:11]
	global_load_dwordx4 v[60:63], v233, s[10:11] offset:256
	s_waitcnt vmcnt(8)
	v_mfma_scale_f32_16x16x128_f8f6f4 v[64:67], v[0:3], v[194:201], 0, v133, v133 op_sel_hi:[0,0,0] cbsz:4
	v_mfma_scale_f32_16x16x128_f8f6f4 v[64:67], v[4:7], v[202:209], v[64:67], v133, v133 op_sel_hi:[0,0,0] cbsz:4
	v_mfma_scale_f32_16x16x128_f8f6f4 v[68:71], v[8:11], v[194:201], 0, v133, v133 op_sel_hi:[0,0,0] cbsz:4
	v_mfma_scale_f32_16x16x128_f8f6f4 v[68:71], v[12:15], v[202:209], v[68:71], v133, v133 op_sel_hi:[0,0,0] cbsz:4
	v_mfma_scale_f32_16x16x128_f8f6f4 v[72:75], v[16:19], v[194:201], 0, v133, v133 op_sel_hi:[0,0,0] cbsz:4
	v_mfma_scale_f32_16x16x128_f8f6f4 v[72:75], v[20:23], v[202:209], v[72:75], v133, v133 op_sel_hi:[0,0,0] cbsz:4
	v_mfma_scale_f32_16x16x128_f8f6f4 v[76:79], v[24:27], v[194:201], 0, v133, v133 op_sel_hi:[0,0,0] cbsz:4
	v_mfma_scale_f32_16x16x128_f8f6f4 v[76:79], v[28:31], v[202:209], v[76:79], v133, v133 op_sel_hi:[0,0,0] cbsz:4
	s_nop 3
	v_mul_f32_e32 v234, v158, v80
	v_mul_f32_e32 v235, v158, v84
	v_mul_f32_e32 v236, v158, v88
	v_mul_f32_e32 v237, v158, v92
	v_fmac_f32_e32 v234, v159, v81
	v_fmac_f32_e32 v235, v159, v85
	v_fmac_f32_e32 v236, v159, v89
	v_fmac_f32_e32 v237, v159, v93
	v_fmac_f32_e32 v234, v160, v82
	v_fmac_f32_e32 v235, v160, v86
	v_fmac_f32_e32 v236, v160, v90
	v_fmac_f32_e32 v237, v160, v94
	v_fmac_f32_e32 v234, v161, v83
	v_fmac_f32_e32 v235, v161, v87
	v_fmac_f32_e32 v236, v161, v91
	v_fmac_f32_e32 v237, v161, v95
	v_add_f32_dpp v234, v234, v234 quad_perm:[1,0,3,2] row_mask:0xf bank_mask:0xf
	v_add_f32_dpp v235, v235, v235 quad_perm:[1,0,3,2] row_mask:0xf bank_mask:0xf
	v_add_f32_dpp v236, v236, v236 quad_perm:[1,0,3,2] row_mask:0xf bank_mask:0xf
	v_add_f32_dpp v237, v237, v237 quad_perm:[1,0,3,2] row_mask:0xf bank_mask:0xf
	v_add_f32_dpp v234, v234, v234 quad_perm:[2,3,0,1] row_mask:0xf bank_mask:0xf
	v_add_f32_dpp v235, v235, v235 quad_perm:[2,3,0,1] row_mask:0xf bank_mask:0xf
	v_add_f32_dpp v236, v236, v236 quad_perm:[2,3,0,1] row_mask:0xf bank_mask:0xf
	v_add_f32_dpp v237, v237, v237 quad_perm:[2,3,0,1] row_mask:0xf bank_mask:0xf
	v_add_f32_dpp v234, v234, v234 row_half_mirror row_mask:0xf bank_mask:0xf
	v_add_f32_dpp v235, v235, v235 row_half_mirror row_mask:0xf bank_mask:0xf
	v_add_f32_dpp v236, v236, v236 row_half_mirror row_mask:0xf bank_mask:0xf
	v_add_f32_dpp v237, v237, v237 row_half_mirror row_mask:0xf bank_mask:0xf
	s_mov_b32 exec_lo, 0x10001
	s_mov_b32 exec_hi, 0x10001
	ds_write_b32 v155, v234 offset:576
	ds_write_b32 v155, v235 offset:592
	ds_write_b32 v155, v236 offset:608
	ds_write_b32 v155, v237 offset:624
	s_mov_b64 exec, -1
	ds_read2_b32 v[96:97], v242 offset0:16 offset1:20
	ds_read2_b32 v[98:99], v242 offset0:24 offset1:28
	s_waitcnt lgkmcnt(0)
	v_lshl_add_u32 v96, v96, 9, v144
	v_lshl_add_u32 v97, v97, 9, v144
	v_lshl_add_u32 v98, v98, 9, v144
	v_lshl_add_u32 v99, v99, 9, v144
	global_load_dwordx4 v[0:3], v96, s[10:11]
	global_load_dwordx4 v[4:7], v96, s[10:11] offset:256
	global_load_dwordx4 v[8:11], v97, s[10:11]
	global_load_dwordx4 v[12:15], v97, s[10:11] offset:256
	global_load_dwordx4 v[16:19], v98, s[10:11]
	global_load_dwordx4 v[20:23], v98, s[10:11] offset:256
	global_load_dwordx4 v[24:27], v99, s[10:11]
	global_load_dwordx4 v[28:31], v99, s[10:11] offset:256
	s_waitcnt vmcnt(8)
	v_mfma_scale_f32_16x16x128_f8f6f4 v[80:83], v[32:35], v[210:217], 0, v133, v133 op_sel_hi:[0,0,0] cbsz:4
	v_mfma_scale_f32_16x16x128_f8f6f4 v[80:83], v[36:39], v[218:225], v[80:83], v133, v133 op_sel_hi:[0,0,0] cbsz:4
	v_mfma_scale_f32_16x16x128_f8f6f4 v[84:87], v[40:43], v[210:217], 0, v133, v133 op_sel_hi:[0,0,0] cbsz:4
	v_mfma_scale_f32_16x16x128_f8f6f4 v[84:87], v[44:47], v[218:225], v[84:87], v133, v133 op_sel_hi:[0,0,0] cbsz:4
	v_mfma_scale_f32_16x16x128_f8f6f4 v[88:91], v[48:51], v[210:217], 0, v133, v133 op_sel_hi:[0,0,0] cbsz:4
	v_mfma_scale_f32_16x16x128_f8f6f4 v[88:91], v[52:55], v[218:225], v[88:91], v133, v133 op_sel_hi:[0,0,0] cbsz:4
	v_mfma_scale_f32_16x16x128_f8f6f4 v[92:95], v[56:59], v[210:217], 0, v133, v133 op_sel_hi:[0,0,0] cbsz:4
	v_mfma_scale_f32_16x16x128_f8f6f4 v[92:95], v[60:63], v[218:225], v[92:95], v133, v133 op_sel_hi:[0,0,0] cbsz:4
	s_nop 3
	v_mul_f32_e32 v234, v158, v64
	v_mul_f32_e32 v235, v158, v68
	v_mul_f32_e32 v236, v158, v72
	v_mul_f32_e32 v237, v158, v76
	v_fmac_f32_e32 v234, v159, v65
	v_fmac_f32_e32 v235, v159, v69
	v_fmac_f32_e32 v236, v159, v73
	v_fmac_f32_e32 v237, v159, v77
	v_fmac_f32_e32 v234, v160, v66
	v_fmac_f32_e32 v235, v160, v70
	v_fmac_f32_e32 v236, v160, v74
	v_fmac_f32_e32 v237, v160, v78
	v_fmac_f32_e32 v234, v161, v67
	v_fmac_f32_e32 v235, v161, v71
	v_fmac_f32_e32 v236, v161, v75
	v_fmac_f32_e32 v237, v161, v79
	v_add_f32_dpp v234, v234, v234 quad_perm:[1,0,3,2] row_mask:0xf bank_mask:0xf
	v_add_f32_dpp v235, v235, v235 quad_perm:[1,0,3,2] row_mask:0xf bank_mask:0xf
	v_add_f32_dpp v236, v236, v236 quad_perm:[1,0,3,2] row_mask:0xf bank_mask:0xf
	v_add_f32_dpp v237, v237, v237 quad_perm:[1,0,3,2] row_mask:0xf bank_mask:0xf
	v_add_f32_dpp v234, v234, v234 quad_perm:[2,3,0,1] row_mask:0xf bank_mask:0xf
	v_add_f32_dpp v235, v235, v235 quad_perm:[2,3,0,1] row_mask:0xf bank_mask:0xf
	v_add_f32_dpp v236, v236, v236 quad_perm:[2,3,0,1] row_mask:0xf bank_mask:0xf
	v_add_f32_dpp v237, v237, v237 quad_perm:[2,3,0,1] row_mask:0xf bank_mask:0xf
	v_add_f32_dpp v234, v234, v234 row_half_mirror row_mask:0xf bank_mask:0xf
	v_add_f32_dpp v235, v235, v235 row_half_mirror row_mask:0xf bank_mask:0xf
	v_add_f32_dpp v236, v236, v236 row_half_mirror row_mask:0xf bank_mask:0xf
	v_add_f32_dpp v237, v237, v237 row_half_mirror row_mask:0xf bank_mask:0xf
	s_mov_b32 exec_lo, 0x10001
	s_mov_b32 exec_hi, 0x10001
	ds_write_b32 v155, v234 offset:1088
	ds_write_b32 v155, v235 offset:1104
	ds_write_b32 v155, v236 offset:1120
	ds_write_b32 v155, v237 offset:1136
	s_mov_b64 exec, -1
	ds_read2_b32 v[230:231], v243 offset0:16 offset1:20
	ds_read2_b32 v[232:233], v243 offset0:24 offset1:28
	s_waitcnt lgkmcnt(0)
; __device__ __forceinline__ void peer_token(const Params& P, int t, int lane, int* sidx, float* sval, const int* sid, const float* sgate, const unsigned* szero) {
;     ...
; #pragma unroll
;         for (int hh = 0; hh < 2; ++hh)
; #pragma unroll
;             for (int st = 0; st < 4; ++st) abuf[0][hh][st] = *(const uint4*)(Ub + (off2[hh] + 128 * st));
; #pragma unroll
;         for (int T = 0; T < 8; ++T) {
;             if (T + 1 < 8) {
; #pragma unroll
;                 for (int hh = 0; hh < 2; ++hh) off2[hh] = (unsigned)sid[16 * (T + 1) + 8 * hh + (lr & 7)] * 512u + lofs;
; #pragma unroll
;                 for (int hh = 0; hh < 2; ++hh)
; #pragma unroll
;                     for (int st = 0; st < 4; ++st) abuf[(T + 1) & 1][hh][st] = *(const uint4*)(Ub + (off2[hh] + 128 * st));
;             }
; #pragma unroll
;             for (int hh = 0; hh < 2; ++hh) {
;                 f32x4 au = (f32x4){0.f, 0.f, 0.f, 0.f};
; #pragma unroll
;                 for (int st = 0; st < 4; ++st) {
;                     const uint4 a4 = abuf[T & 1][hh][st];
;                     const v8i Av = {(int)a4.x, (int)a4.y, (int)a4.z, (int)a4.w, 0, 0, 0, 0};
;                     au = __builtin_amdgcn_mfma_scale_f32_16x16x128_f8f6f4(Av, Bv[st], au, 4, 0, 0, 0x7f7f7f7f, 0, 0x7f7f7f7f);
;                 }
;                 if (owner) *(f32x4*)(sact + 16 * T + 8 * hh) = au;
;             }
	v_lshl_add_u32 v230, v230, 9, v144
	v_lshl_add_u32 v231, v231, 9, v144
	v_lshl_add_u32 v232, v232, 9, v144
	v_lshl_add_u32 v233, v233, 9, v144
	global_load_dwordx4 v[32:35], v230, s[10:11]
	global_load_dwordx4 v[36:39], v230, s[10:11] offset:256
	global_load_dwordx4 v[40:43], v231, s[10:11]
	global_load_dwordx4 v[44:47], v231, s[10:11] offset:256
	global_load_dwordx4 v[48:51], v232, s[10:11]
	global_load_dwordx4 v[52:55], v232, s[10:11] offset:256
	global_load_dwordx4 v[56:59], v233, s[10:11]
	global_load_dwordx4 v[60:63], v233, s[10:11] offset:256
	s_waitcnt vmcnt(8)
	v_mfma_scale_f32_16x16x128_f8f6f4 v[64:67], v[0:3], v[162:169], 0, v133, v133 op_sel_hi:[0,0,0] cbsz:4
	v_mfma_scale_f32_16x16x128_f8f6f4 v[64:67], v[4:7], v[170:177], v[64:67], v133, v133 op_sel_hi:[0,0,0] cbsz:4
	v_mfma_scale_f32_16x16x128_f8f6f4 v[68:71], v[8:11], v[162:169], 0, v133, v133 op_sel_hi:[0,0,0] cbsz:4
	v_mfma_scale_f32_16x16x128_f8f6f4 v[68:71], v[12:15], v[170:177], v[68:71], v133, v133 op_sel_hi:[0,0,0] cbsz:4
	v_mfma_scale_f32_16x16x128_f8f6f4 v[72:75], v[16:19], v[162:169], 0, v133, v133 op_sel_hi:[0,0,0] cbsz:4
	v_mfma_scale_f32_16x16x128_f8f6f4 v[72:75], v[20:23], v[170:177], v[72:75], v133, v133 op_sel_hi:[0,0,0] cbsz:4
	v_mfma_scale_f32_16x16x128_f8f6f4 v[76:79], v[24:27], v[162:169], 0, v133, v133 op_sel_hi:[0,0,0] cbsz:4
	v_mfma_scale_f32_16x16x128_f8f6f4 v[76:79], v[28:31], v[170:177], v[76:79], v133, v133 op_sel_hi:[0,0,0] cbsz:4
	s_nop 3
	v_mul_f32_e32 v234, v158, v80
	v_mul_f32_e32 v235, v158, v84
	v_mul_f32_e32 v236, v158, v88
	v_mul_f32_e32 v237, v158, v92
	v_fmac_f32_e32 v234, v159, v81
	v_fmac_f32_e32 v235, v159, v85
	v_fmac_f32_e32 v236, v159, v89
	v_fmac_f32_e32 v237, v159, v93
	v_fmac_f32_e32 v234, v160, v82
	v_fmac_f32_e32 v235, v160, v86
	v_fmac_f32_e32 v236, v160, v90
	v_fmac_f32_e32 v237, v160, v94
	v_fmac_f32_e32 v234, v161, v83
	v_fmac_f32_e32 v235, v161, v87
	v_fmac_f32_e32 v236, v161, v91
	v_fmac_f32_e32 v237, v161, v95
	v_add_f32_dpp v234, v234, v234 quad_perm:[1,0,3,2] row_mask:0xf bank_mask:0xf
	v_add_f32_dpp v235, v235, v235 quad_perm:[1,0,3,2] row_mask:0xf bank_mask:0xf
	v_add_f32_dpp v236, v236, v236 quad_perm:[1,0,3,2] row_mask:0xf bank_mask:0xf
	v_add_f32_dpp v237, v237, v237 quad_perm:[1,0,3,2] row_mask:0xf bank_mask:0xf
	v_add_f32_dpp v234, v234, v234 quad_perm:[2,3,0,1] row_mask:0xf bank_mask:0xf
	v_add_f32_dpp v235, v235, v235 quad_perm:[2,3,0,1] row_mask:0xf bank_mask:0xf
	v_add_f32_dpp v236, v236, v236 quad_perm:[2,3,0,1] row_mask:0xf bank_mask:0xf
	v_add_f32_dpp v237, v237, v237 quad_perm:[2,3,0,1] row_mask:0xf bank_mask:0xf
	v_add_f32_dpp v234, v234, v234 row_half_mirror row_mask:0xf bank_mask:0xf
	v_add_f32_dpp v235, v235, v235 row_half_mirror row_mask:0xf bank_mask:0xf
	v_add_f32_dpp v236, v236, v236 row_half_mirror row_mask:0xf bank_mask:0xf
	v_add_f32_dpp v237, v237, v237 row_half_mirror row_mask:0xf bank_mask:0xf
	s_mov_b32 exec_lo, 0x10001
	s_mov_b32 exec_hi, 0x10001
	ds_write_b32 v155, v234 offset:1600
	ds_write_b32 v155, v235 offset:1616
	ds_write_b32 v155, v236 offset:1632
	ds_write_b32 v155, v237 offset:1648
	s_mov_b64 exec, -1
	ds_read2_b32 v[96:97], v244 offset0:16 offset1:20
	ds_read2_b32 v[98:99], v244 offset0:24 offset1:28
	s_waitcnt lgkmcnt(0)
	v_lshl_add_u32 v96, v96, 9, v144
	v_lshl_add_u32 v97, v97, 9, v144
	v_lshl_add_u32 v98, v98, 9, v144
	v_lshl_add_u32 v99, v99, 9, v144
	global_load_dwordx4 v[0:3], v96, s[10:11]
	global_load_dwordx4 v[4:7], v96, s[10:11] offset:256
	global_load_dwordx4 v[8:11], v97, s[10:11]
	global_load_dwordx4 v[12:15], v97, s[10:11] offset:256
	global_load_dwordx4 v[16:19], v98, s[10:11]
	global_load_dwordx4 v[20:23], v98, s[10:11] offset:256
	global_load_dwordx4 v[24:27], v99, s[10:11]
	global_load_dwordx4 v[28:31], v99, s[10:11] offset:256
	s_waitcnt vmcnt(8)
	v_mfma_scale_f32_16x16x128_f8f6f4 v[80:83], v[32:35], v[178:185], 0, v133, v133 op_sel_hi:[0,0,0] cbsz:4
	v_mfma_scale_f32_16x16x128_f8f6f4 v[80:83], v[36:39], v[186:193], v[80:83], v133, v133 op_sel_hi:[0,0,0] cbsz:4
	v_mfma_scale_f32_16x16x128_f8f6f4 v[84:87], v[40:43], v[178:185], 0, v133, v133 op_sel_hi:[0,0,0] cbsz:4
	v_mfma_scale_f32_16x16x128_f8f6f4 v[84:87], v[44:47], v[186:193], v[84:87], v133, v133 op_sel_hi:[0,0,0] cbsz:4
	v_mfma_scale_f32_16x16x128_f8f6f4 v[88:91], v[48:51], v[178:185], 0, v133, v133 op_sel_hi:[0,0,0] cbsz:4
	v_mfma_scale_f32_16x16x128_f8f6f4 v[88:91], v[52:55], v[186:193], v[88:91], v133, v133 op_sel_hi:[0,0,0] cbsz:4
	v_mfma_scale_f32_16x16x128_f8f6f4 v[92:95], v[56:59], v[178:185], 0, v133, v133 op_sel_hi:[0,0,0] cbsz:4
	v_mfma_scale_f32_16x16x128_f8f6f4 v[92:95], v[60:63], v[186:193], v[92:95], v133, v133 op_sel_hi:[0,0,0] cbsz:4
	s_nop 3
	v_mul_f32_e32 v234, v226, v64
	v_mul_f32_e32 v235, v226, v68
	v_mul_f32_e32 v236, v226, v72
	v_mul_f32_e32 v237, v226, v76
	v_fmac_f32_e32 v234, v227, v65
	v_fmac_f32_e32 v235, v227, v69
	v_fmac_f32_e32 v236, v227, v73
	v_fmac_f32_e32 v237, v227, v77
	v_fmac_f32_e32 v234, v228, v66
	v_fmac_f32_e32 v235, v228, v70
	v_fmac_f32_e32 v236, v228, v74
	v_fmac_f32_e32 v237, v228, v78
	v_fmac_f32_e32 v234, v229, v67
	v_fmac_f32_e32 v235, v229, v71
	v_fmac_f32_e32 v236, v229, v75
	v_fmac_f32_e32 v237, v229, v79
	v_add_f32_dpp v234, v234, v234 quad_perm:[1,0,3,2] row_mask:0xf bank_mask:0xf
	v_add_f32_dpp v235, v235, v235 quad_perm:[1,0,3,2] row_mask:0xf bank_mask:0xf
	v_add_f32_dpp v236, v236, v236 quad_perm:[1,0,3,2] row_mask:0xf bank_mask:0xf
	v_add_f32_dpp v237, v237, v237 quad_perm:[1,0,3,2] row_mask:0xf bank_mask:0xf
	v_add_f32_dpp v234, v234, v234 quad_perm:[2,3,0,1] row_mask:0xf bank_mask:0xf
	v_add_f32_dpp v235, v235, v235 quad_perm:[2,3,0,1] row_mask:0xf bank_mask:0xf
	v_add_f32_dpp v236, v236, v236 quad_perm:[2,3,0,1] row_mask:0xf bank_mask:0xf
	v_add_f32_dpp v237, v237, v237 quad_perm:[2,3,0,1] row_mask:0xf bank_mask:0xf
	v_add_f32_dpp v234, v234, v234 row_half_mirror row_mask:0xf bank_mask:0xf
	v_add_f32_dpp v235, v235, v235 row_half_mirror row_mask:0xf bank_mask:0xf
	v_add_f32_dpp v236, v236, v236 row_half_mirror row_mask:0xf bank_mask:0xf
	v_add_f32_dpp v237, v237, v237 row_half_mirror row_mask:0xf bank_mask:0xf
	s_mov_b32 exec_lo, 0x1000100
	s_mov_b32 exec_hi, 0x1000100
	ds_write_b32 v155, v234 offset:2112
	ds_write_b32 v155, v235 offset:2128
	ds_write_b32 v155, v236 offset:2144
	ds_write_b32 v155, v237 offset:2160
	s_mov_b64 exec, -1
	ds_read2_b32 v[230:231], v245 offset0:16 offset1:20
	ds_read2_b32 v[232:233], v245 offset0:24 offset1:28
	s_waitcnt lgkmcnt(0)
; __device__ __forceinline__ void peer_token(const Params& P, int t, int lane, int* sidx, float* sval, const int* sid, const float* sgate, const unsigned* szero) {
;     ...
; #pragma unroll
;         for (int hh = 0; hh < 2; ++hh)
; #pragma unroll
;             for (int st = 0; st < 4; ++st) abuf[0][hh][st] = *(const uint4*)(Ub + (off2[hh] + 128 * st));
; #pragma unroll
;         for (int T = 0; T < 8; ++T) {
;             if (T + 1 < 8) {
; #pragma unroll
;                 for (int hh = 0; hh < 2; ++hh) off2[hh] = (unsigned)sid[16 * (T + 1) + 8 * hh + (lr & 7)] * 512u + lofs;
; #pragma unroll
;                 for (int hh = 0; hh < 2; ++hh)
; #pragma unroll
;                     for (int st = 0; st < 4; ++st) abuf[(T + 1) & 1][hh][st] = *(const uint4*)(Ub + (off2[hh] + 128 * st));
;             }
; #pragma unroll
;             for (int hh = 0; hh < 2; ++hh) {
;                 f32x4 au = (f32x4){0.f, 0.f, 0.f, 0.f};
; #pragma unroll
;                 for (int st = 0; st < 4; ++st) {
;                     const uint4 a4 = abuf[T & 1][hh][st];
;                     const v8i Av = {(int)a4.x, (int)a4.y, (int)a4.z, (int)a4.w, 0, 0, 0, 0};
;                     au = __builtin_amdgcn_mfma_scale_f32_16x16x128_f8f6f4(Av, Bv[st], au, 4, 0, 0, 0x7f7f7f7f, 0, 0x7f7f7f7f);
;                 }
;                 if (owner) *(f32x4*)(sact + 16 * T + 8 * hh) = au;
;             }
	v_lshl_add_u32 v230, v230, 9, v144
	v_lshl_add_u32 v231, v231, 9, v144
	v_lshl_add_u32 v232, v232, 9, v144
	v_lshl_add_u32 v233, v233, 9, v144
	global_load_dwordx4 v[32:35], v230, s[10:11]
	global_load_dwordx4 v[36:39], v230, s[10:11] offset:256
	global_load_dwordx4 v[40:43], v231, s[10:11]
	global_load_dwordx4 v[44:47], v231, s[10:11] offset:256
	global_load_dwordx4 v[48:51], v232, s[10:11]
	global_load_dwordx4 v[52:55], v232, s[10:11] offset:256
	global_load_dwordx4 v[56:59], v233, s[10:11]
	global_load_dwordx4 v[60:63], v233, s[10:11] offset:256
	s_waitcnt vmcnt(8)
	v_mfma_scale_f32_16x16x128_f8f6f4 v[64:67], v[0:3], v[194:201], 0, v133, v133 op_sel_hi:[0,0,0] cbsz:4
	v_mfma_scale_f32_16x16x128_f8f6f4 v[64:67], v[4:7], v[202:209], v[64:67], v133, v133 op_sel_hi:[0,0,0] cbsz:4
	v_mfma_scale_f32_16x16x128_f8f6f4 v[68:71], v[8:11], v[194:201], 0, v133, v133 op_sel_hi:[0,0,0] cbsz:4
	v_mfma_scale_f32_16x16x128_f8f6f4 v[68:71], v[12:15], v[202:209], v[68:71], v133, v133 op_sel_hi:[0,0,0] cbsz:4
	v_mfma_scale_f32_16x16x128_f8f6f4 v[72:75], v[16:19], v[194:201], 0, v133, v133 op_sel_hi:[0,0,0] cbsz:4
	v_mfma_scale_f32_16x16x128_f8f6f4 v[72:75], v[20:23], v[202:209], v[72:75], v133, v133 op_sel_hi:[0,0,0] cbsz:4
	v_mfma_scale_f32_16x16x128_f8f6f4 v[76:79], v[24:27], v[194:201], 0, v133, v133 op_sel_hi:[0,0,0] cbsz:4
	v_mfma_scale_f32_16x16x128_f8f6f4 v[76:79], v[28:31], v[202:209], v[76:79], v133, v133 op_sel_hi:[0,0,0] cbsz:4
	s_nop 3
	v_mul_f32_e32 v234, v226, v80
	v_mul_f32_e32 v235, v226, v84
	v_mul_f32_e32 v236, v226, v88
	v_mul_f32_e32 v237, v226, v92
	v_fmac_f32_e32 v234, v227, v81
	v_fmac_f32_e32 v235, v227, v85
	v_fmac_f32_e32 v236, v227, v89
	v_fmac_f32_e32 v237, v227, v93
	v_fmac_f32_e32 v234, v228, v82
	v_fmac_f32_e32 v235, v228, v86
	v_fmac_f32_e32 v236, v228, v90
	v_fmac_f32_e32 v237, v228, v94
	v_fmac_f32_e32 v234, v229, v83
	v_fmac_f32_e32 v235, v229, v87
	v_fmac_f32_e32 v236, v229, v91
	v_fmac_f32_e32 v237, v229, v95
	v_add_f32_dpp v234, v234, v234 quad_perm:[1,0,3,2] row_mask:0xf bank_mask:0xf
	v_add_f32_dpp v235, v235, v235 quad_perm:[1,0,3,2] row_mask:0xf bank_mask:0xf
	v_add_f32_dpp v236, v236, v236 quad_perm:[1,0,3,2] row_mask:0xf bank_mask:0xf
	v_add_f32_dpp v237, v237, v237 quad_perm:[1,0,3,2] row_mask:0xf bank_mask:0xf
	v_add_f32_dpp v234, v234, v234 quad_perm:[2,3,0,1] row_mask:0xf bank_mask:0xf
	v_add_f32_dpp v235, v235, v235 quad_perm:[2,3,0,1] row_mask:0xf bank_mask:0xf
	v_add_f32_dpp v236, v236, v236 quad_perm:[2,3,0,1] row_mask:0xf bank_mask:0xf
	v_add_f32_dpp v237, v237, v237 quad_perm:[2,3,0,1] row_mask:0xf bank_mask:0xf
	v_add_f32_dpp v234, v234, v234 row_half_mirror row_mask:0xf bank_mask:0xf
	v_add_f32_dpp v235, v235, v235 row_half_mirror row_mask:0xf bank_mask:0xf
	v_add_f32_dpp v236, v236, v236 row_half_mirror row_mask:0xf bank_mask:0xf
	v_add_f32_dpp v237, v237, v237 row_half_mirror row_mask:0xf bank_mask:0xf
	s_mov_b32 exec_lo, 0x1000100
	s_mov_b32 exec_hi, 0x1000100
	ds_write_b32 v155, v234 offset:2624
	ds_write_b32 v155, v235 offset:2640
	ds_write_b32 v155, v236 offset:2656
	ds_write_b32 v155, v237 offset:2672
	s_mov_b64 exec, -1
	ds_read2_b32 v[96:97], v238 offset0:32 offset1:36
	ds_read2_b32 v[98:99], v238 offset0:40 offset1:44
	s_waitcnt lgkmcnt(0)
	v_lshl_add_u32 v96, v96, 9, v144
	v_lshl_add_u32 v97, v97, 9, v144
	v_lshl_add_u32 v98, v98, 9, v144
	v_lshl_add_u32 v99, v99, 9, v144
	global_load_dwordx4 v[0:3], v96, s[10:11]
	global_load_dwordx4 v[4:7], v96, s[10:11] offset:256
	global_load_dwordx4 v[8:11], v97, s[10:11]
	global_load_dwordx4 v[12:15], v97, s[10:11] offset:256
	global_load_dwordx4 v[16:19], v98, s[10:11]
	global_load_dwordx4 v[20:23], v98, s[10:11] offset:256
	global_load_dwordx4 v[24:27], v99, s[10:11]
	global_load_dwordx4 v[28:31], v99, s[10:11] offset:256
	s_waitcnt vmcnt(8)
	v_mfma_scale_f32_16x16x128_f8f6f4 v[80:83], v[32:35], v[210:217], 0, v133, v133 op_sel_hi:[0,0,0] cbsz:4
	v_mfma_scale_f32_16x16x128_f8f6f4 v[80:83], v[36:39], v[218:225], v[80:83], v133, v133 op_sel_hi:[0,0,0] cbsz:4
	v_mfma_scale_f32_16x16x128_f8f6f4 v[84:87], v[40:43], v[210:217], 0, v133, v133 op_sel_hi:[0,0,0] cbsz:4
	v_mfma_scale_f32_16x16x128_f8f6f4 v[84:87], v[44:47], v[218:225], v[84:87], v133, v133 op_sel_hi:[0,0,0] cbsz:4
	v_mfma_scale_f32_16x16x128_f8f6f4 v[88:91], v[48:51], v[210:217], 0, v133, v133 op_sel_hi:[0,0,0] cbsz:4
	v_mfma_scale_f32_16x16x128_f8f6f4 v[88:91], v[52:55], v[218:225], v[88:91], v133, v133 op_sel_hi:[0,0,0] cbsz:4
	v_mfma_scale_f32_16x16x128_f8f6f4 v[92:95], v[56:59], v[210:217], 0, v133, v133 op_sel_hi:[0,0,0] cbsz:4
	v_mfma_scale_f32_16x16x128_f8f6f4 v[92:95], v[60:63], v[218:225], v[92:95], v133, v133 op_sel_hi:[0,0,0] cbsz:4
	s_nop 3
	v_mul_f32_e32 v234, v226, v64
	v_mul_f32_e32 v235, v226, v68
	v_mul_f32_e32 v236, v226, v72
	v_mul_f32_e32 v237, v226, v76
	v_fmac_f32_e32 v234, v227, v65
	v_fmac_f32_e32 v235, v227, v69
	v_fmac_f32_e32 v236, v227, v73
	v_fmac_f32_e32 v237, v227, v77
	v_fmac_f32_e32 v234, v228, v66
	v_fmac_f32_e32 v235, v228, v70
	v_fmac_f32_e32 v236, v228, v74
	v_fmac_f32_e32 v237, v228, v78
	v_fmac_f32_e32 v234, v229, v67
	v_fmac_f32_e32 v235, v229, v71
	v_fmac_f32_e32 v236, v229, v75
	v_fmac_f32_e32 v237, v229, v79
	v_add_f32_dpp v234, v234, v234 quad_perm:[1,0,3,2] row_mask:0xf bank_mask:0xf
	v_add_f32_dpp v235, v235, v235 quad_perm:[1,0,3,2] row_mask:0xf bank_mask:0xf
	v_add_f32_dpp v236, v236, v236 quad_perm:[1,0,3,2] row_mask:0xf bank_mask:0xf
	v_add_f32_dpp v237, v237, v237 quad_perm:[1,0,3,2] row_mask:0xf bank_mask:0xf
	v_add_f32_dpp v234, v234, v234 quad_perm:[2,3,0,1] row_mask:0xf bank_mask:0xf
	v_add_f32_dpp v235, v235, v235 quad_perm:[2,3,0,1] row_mask:0xf bank_mask:0xf
	v_add_f32_dpp v236, v236, v236 quad_perm:[2,3,0,1] row_mask:0xf bank_mask:0xf
	v_add_f32_dpp v237, v237, v237 quad_perm:[2,3,0,1] row_mask:0xf bank_mask:0xf
	v_add_f32_dpp v234, v234, v234 row_half_mirror row_mask:0xf bank_mask:0xf
	v_add_f32_dpp v235, v235, v235 row_half_mirror row_mask:0xf bank_mask:0xf
	v_add_f32_dpp v236, v236, v236 row_half_mirror row_mask:0xf bank_mask:0xf
	v_add_f32_dpp v237, v237, v237 row_half_mirror row_mask:0xf bank_mask:0xf
	s_mov_b32 exec_lo, 0x1000100
	s_mov_b32 exec_hi, 0x1000100
	ds_write_b32 v155, v234 offset:3136
	ds_write_b32 v155, v235 offset:3152
	ds_write_b32 v155, v236 offset:3168
	ds_write_b32 v155, v237 offset:3184
	s_mov_b64 exec, -1
	ds_read2_b32 v[230:231], v239 offset0:32 offset1:36
	ds_read2_b32 v[232:233], v239 offset0:40 offset1:44
	s_waitcnt lgkmcnt(0)
; __device__ __forceinline__ void peer_token(const Params& P, int t, int lane, int* sidx, float* sval, const int* sid, const float* sgate, const unsigned* szero) {
;     ...
;         for (int hh = 0; hh < 2; ++hh) off2[hh] = (unsigned)sid[8 * hh + (lr & 7)] * 512u + lofs;
; #pragma unroll
;         for (int hh = 0; hh < 2; ++hh)
; #pragma unroll
;             for (int st = 0; st < 4; ++st) abuf[0][hh][st] = *(const uint4*)(Ub + (off2[hh] + 128 * st));
; #pragma unroll
;         for (int T = 0; T < 8; ++T) {
;             if (T + 1 < 8) {
; #pragma unroll
;                 for (int hh = 0; hh < 2; ++hh) off2[hh] = (unsigned)sid[16 * (T + 1) + 8 * hh + (lr & 7)] * 512u + lofs;
; #pragma unroll
;                 for (int hh = 0; hh < 2; ++hh)
; #pragma unroll
;                     for (int st = 0; st < 4; ++st) abuf[(T + 1) & 1][hh][st] = *(const uint4*)(Ub + (off2[hh] + 128 * st));
;             }
; #pragma unroll
;             for (int hh = 0; hh < 2; ++hh) {
;                 f32x4 au = (f32x4){0.f, 0.f, 0.f, 0.f};
; #pragma unroll
;                 for (int st = 0; st < 4; ++st) {
;                     const uint4 a4 = abuf[T & 1][hh][st];
;                     const v8i Av = {(int)a4.x, (int)a4.y, (int)a4.z, (int)a4.w, 0, 0, 0, 0};
;                     au = __builtin_amdgcn_mfma_scale_f32_16x16x128_f8f6f4(Av, Bv[st], au, 4, 0, 0, 0x7f7f7f7f, 0, 0x7f7f7f7f);
;                 }
;                 if (owner) *(f32x4*)(sact + 16 * T + 8 * hh) = au;
;             }
	v_lshl_add_u32 v230, v230, 9, v144
	v_lshl_add_u32 v231, v231, 9, v144
	v_lshl_add_u32 v232, v232, 9, v144
	v_lshl_add_u32 v233, v233, 9, v144
	global_load_dwordx4 v[32:35], v230, s[10:11]
	global_load_dwordx4 v[36:39], v230, s[10:11] offset:256
	global_load_dwordx4 v[40:43], v231, s[10:11]
	global_load_dwordx4 v[44:47], v231, s[10:11] offset:256
	global_load_dwordx4 v[48:51], v232, s[10:11]
	global_load_dwordx4 v[52:55], v232, s[10:11] offset:256
	global_load_dwordx4 v[56:59], v233, s[10:11]
	global_load_dwordx4 v[60:63], v233, s[10:11] offset:256
	s_waitcnt vmcnt(8)
	v_mfma_scale_f32_16x16x128_f8f6f4 v[64:67], v[0:3], v[162:169], 0, v133, v133 op_sel_hi:[0,0,0] cbsz:4
	v_mfma_scale_f32_16x16x128_f8f6f4 v[64:67], v[4:7], v[170:177], v[64:67], v133, v133 op_sel_hi:[0,0,0] cbsz:4
	v_mfma_scale_f32_16x16x128_f8f6f4 v[68:71], v[8:11], v[162:169], 0, v133, v133 op_sel_hi:[0,0,0] cbsz:4
	v_mfma_scale_f32_16x16x128_f8f6f4 v[68:71], v[12:15], v[170:177], v[68:71], v133, v133 op_sel_hi:[0,0,0] cbsz:4
	v_mfma_scale_f32_16x16x128_f8f6f4 v[72:75], v[16:19], v[162:169], 0, v133, v133 op_sel_hi:[0,0,0] cbsz:4
	v_mfma_scale_f32_16x16x128_f8f6f4 v[72:75], v[20:23], v[170:177], v[72:75], v133, v133 op_sel_hi:[0,0,0] cbsz:4
	v_mfma_scale_f32_16x16x128_f8f6f4 v[76:79], v[24:27], v[162:169], 0, v133, v133 op_sel_hi:[0,0,0] cbsz:4
	v_mfma_scale_f32_16x16x128_f8f6f4 v[76:79], v[28:31], v[170:177], v[76:79], v133, v133 op_sel_hi:[0,0,0] cbsz:4
	s_nop 3
	v_mul_f32_e32 v234, v226, v80
	v_mul_f32_e32 v235, v226, v84
	v_mul_f32_e32 v236, v226, v88
	v_mul_f32_e32 v237, v226, v92
	v_fmac_f32_e32 v234, v227, v81
	v_fmac_f32_e32 v235, v227, v85
	v_fmac_f32_e32 v236, v227, v89
	v_fmac_f32_e32 v237, v227, v93
	v_fmac_f32_e32 v234, v228, v82
	v_fmac_f32_e32 v235, v228, v86
	v_fmac_f32_e32 v236, v228, v90
	v_fmac_f32_e32 v237, v228, v94
	v_fmac_f32_e32 v234, v229, v83
	v_fmac_f32_e32 v235, v229, v87
	v_fmac_f32_e32 v236, v229, v91
	v_fmac_f32_e32 v237, v229, v95
	v_add_f32_dpp v234, v234, v234 quad_perm:[1,0,3,2] row_mask:0xf bank_mask:0xf
	v_add_f32_dpp v235, v235, v235 quad_perm:[1,0,3,2] row_mask:0xf bank_mask:0xf
	v_add_f32_dpp v236, v236, v236 quad_perm:[1,0,3,2] row_mask:0xf bank_mask:0xf
	v_add_f32_dpp v237, v237, v237 quad_perm:[1,0,3,2] row_mask:0xf bank_mask:0xf
	v_add_f32_dpp v234, v234, v234 quad_perm:[2,3,0,1] row_mask:0xf bank_mask:0xf
	v_add_f32_dpp v235, v235, v235 quad_perm:[2,3,0,1] row_mask:0xf bank_mask:0xf
	v_add_f32_dpp v236, v236, v236 quad_perm:[2,3,0,1] row_mask:0xf bank_mask:0xf
	v_add_f32_dpp v237, v237, v237 quad_perm:[2,3,0,1] row_mask:0xf bank_mask:0xf
	v_add_f32_dpp v234, v234, v234 row_half_mirror row_mask:0xf bank_mask:0xf
	v_add_f32_dpp v235, v235, v235 row_half_mirror row_mask:0xf bank_mask:0xf
	v_add_f32_dpp v236, v236, v236 row_half_mirror row_mask:0xf bank_mask:0xf
	v_add_f32_dpp v237, v237, v237 row_half_mirror row_mask:0xf bank_mask:0xf
	s_mov_b32 exec_lo, 0x1000100
	s_mov_b32 exec_hi, 0x1000100
	ds_write_b32 v155, v234 offset:3648
	ds_write_b32 v155, v235 offset:3664
	ds_write_b32 v155, v236 offset:3680
	ds_write_b32 v155, v237 offset:3696
	s_mov_b64 exec, -1
	ds_read2_b32 v[96:97], v240 offset0:32 offset1:36
	ds_read2_b32 v[98:99], v240 offset0:40 offset1:44
	s_waitcnt lgkmcnt(0)
	v_lshl_add_u32 v96, v96, 9, v144
	v_lshl_add_u32 v97, v97, 9, v144
	v_lshl_add_u32 v98, v98, 9, v144
	v_lshl_add_u32 v99, v99, 9, v144
	global_load_dwordx4 v[0:3], v96, s[10:11]
	global_load_dwordx4 v[4:7], v96, s[10:11] offset:256
	global_load_dwordx4 v[8:11], v97, s[10:11]
	global_load_dwordx4 v[12:15], v97, s[10:11] offset:256
	global_load_dwordx4 v[16:19], v98, s[10:11]
	global_load_dwordx4 v[20:23], v98, s[10:11] offset:256
	global_load_dwordx4 v[24:27], v99, s[10:11]
	global_load_dwordx4 v[28:31], v99, s[10:11] offset:256
	s_waitcnt vmcnt(8)
	v_mfma_scale_f32_16x16x128_f8f6f4 v[80:83], v[32:35], v[178:185], 0, v133, v133 op_sel_hi:[0,0,0] cbsz:4
	v_mfma_scale_f32_16x16x128_f8f6f4 v[80:83], v[36:39], v[186:193], v[80:83], v133, v133 op_sel_hi:[0,0,0] cbsz:4
	v_mfma_scale_f32_16x16x128_f8f6f4 v[84:87], v[40:43], v[178:185], 0, v133, v133 op_sel_hi:[0,0,0] cbsz:4
	v_mfma_scale_f32_16x16x128_f8f6f4 v[84:87], v[44:47], v[186:193], v[84:87], v133, v133 op_sel_hi:[0,0,0] cbsz:4
	v_mfma_scale_f32_16x16x128_f8f6f4 v[88:91], v[48:51], v[178:185], 0, v133, v133 op_sel_hi:[0,0,0] cbsz:4
	v_mfma_scale_f32_16x16x128_f8f6f4 v[88:91], v[52:55], v[186:193], v[88:91], v133, v133 op_sel_hi:[0,0,0] cbsz:4
	v_mfma_scale_f32_16x16x128_f8f6f4 v[92:95], v[56:59], v[178:185], 0, v133, v133 op_sel_hi:[0,0,0] cbsz:4
	v_mfma_scale_f32_16x16x128_f8f6f4 v[92:95], v[60:63], v[186:193], v[92:95], v133, v133 op_sel_hi:[0,0,0] cbsz:4
	s_nop 3
	v_mul_f32_e32 v234, v158, v64
	v_mul_f32_e32 v235, v158, v68
	v_mul_f32_e32 v236, v158, v72
	v_mul_f32_e32 v237, v158, v76
	v_fmac_f32_e32 v234, v159, v65
	v_fmac_f32_e32 v235, v159, v69
	v_fmac_f32_e32 v236, v159, v73
	v_fmac_f32_e32 v237, v159, v77
	v_fmac_f32_e32 v234, v160, v66
	v_fmac_f32_e32 v235, v160, v70
	v_fmac_f32_e32 v236, v160, v74
	v_fmac_f32_e32 v237, v160, v78
	v_fmac_f32_e32 v234, v161, v67
	v_fmac_f32_e32 v235, v161, v71
	v_fmac_f32_e32 v236, v161, v75
	v_fmac_f32_e32 v237, v161, v79
	v_add_f32_dpp v234, v234, v234 quad_perm:[1,0,3,2] row_mask:0xf bank_mask:0xf
	v_add_f32_dpp v235, v235, v235 quad_perm:[1,0,3,2] row_mask:0xf bank_mask:0xf
	v_add_f32_dpp v236, v236, v236 quad_perm:[1,0,3,2] row_mask:0xf bank_mask:0xf
	v_add_f32_dpp v237, v237, v237 quad_perm:[1,0,3,2] row_mask:0xf bank_mask:0xf
	v_add_f32_dpp v234, v234, v234 quad_perm:[2,3,0,1] row_mask:0xf bank_mask:0xf
	v_add_f32_dpp v235, v235, v235 quad_perm:[2,3,0,1] row_mask:0xf bank_mask:0xf
	v_add_f32_dpp v236, v236, v236 quad_perm:[2,3,0,1] row_mask:0xf bank_mask:0xf
	v_add_f32_dpp v237, v237, v237 quad_perm:[2,3,0,1] row_mask:0xf bank_mask:0xf
	v_add_f32_dpp v234, v234, v234 row_half_mirror row_mask:0xf bank_mask:0xf
	v_add_f32_dpp v235, v235, v235 row_half_mirror row_mask:0xf bank_mask:0xf
	v_add_f32_dpp v236, v236, v236 row_half_mirror row_mask:0xf bank_mask:0xf
	v_add_f32_dpp v237, v237, v237 row_half_mirror row_mask:0xf bank_mask:0xf
	s_mov_b32 exec_lo, 0x10001
	s_mov_b32 exec_hi, 0x10001
	ds_write_b32 v155, v234 offset:128
	ds_write_b32 v155, v235 offset:144
	ds_write_b32 v155, v236 offset:160
	ds_write_b32 v155, v237 offset:176
	s_mov_b64 exec, -1
	ds_read2_b32 v[230:231], v241 offset0:32 offset1:36
	ds_read2_b32 v[232:233], v241 offset0:40 offset1:44
	s_waitcnt lgkmcnt(0)
; __device__ __forceinline__ void peer_token(const Params& P, int t, int lane, int* sidx, float* sval, const int* sid, const float* sgate, const unsigned* szero) {
;     ...
;         for (int hh = 0; hh < 2; ++hh) off2[hh] = (unsigned)sid[8 * hh + (lr & 7)] * 512u + lofs;
; #pragma unroll
;         for (int hh = 0; hh < 2; ++hh)
; #pragma unroll
;             for (int st = 0; st < 4; ++st) abuf[0][hh][st] = *(const uint4*)(Ub + (off2[hh] + 128 * st));
; #pragma unroll
;         for (int T = 0; T < 8; ++T) {
;             if (T + 1 < 8) {
; #pragma unroll
;                 for (int hh = 0; hh < 2; ++hh) off2[hh] = (unsigned)sid[16 * (T + 1) + 8 * hh + (lr & 7)] * 512u + lofs;
; #pragma unroll
;                 for (int hh = 0; hh < 2; ++hh)
; #pragma unroll
;                     for (int st = 0; st < 4; ++st) abuf[(T + 1) & 1][hh][st] = *(const uint4*)(Ub + (off2[hh] + 128 * st));
;             }
; #pragma unroll
;             for (int hh = 0; hh < 2; ++hh) {
;                 f32x4 au = (f32x4){0.f, 0.f, 0.f, 0.f};
; #pragma unroll
;                 for (int st = 0; st < 4; ++st) {
;                     const uint4 a4 = abuf[T & 1][hh][st];
;                     const v8i Av = {(int)a4.x, (int)a4.y, (int)a4.z, (int)a4.w, 0, 0, 0, 0};
;                     au = __builtin_amdgcn_mfma_scale_f32_16x16x128_f8f6f4(Av, Bv[st], au, 4, 0, 0, 0x7f7f7f7f, 0, 0x7f7f7f7f);
;                 }
;                 if (owner) *(f32x4*)(sact + 16 * T + 8 * hh) = au;
;             }
	v_lshl_add_u32 v230, v230, 9, v144
	v_lshl_add_u32 v231, v231, 9, v144
	v_lshl_add_u32 v232, v232, 9, v144
	v_lshl_add_u32 v233, v233, 9, v144
	global_load_dwordx4 v[32:35], v230, s[10:11]
	global_load_dwordx4 v[36:39], v230, s[10:11] offset:256
	global_load_dwordx4 v[40:43], v231, s[10:11]
	global_load_dwordx4 v[44:47], v231, s[10:11] offset:256
	global_load_dwordx4 v[48:51], v232, s[10:11]
	global_load_dwordx4 v[52:55], v232, s[10:11] offset:256
	global_load_dwordx4 v[56:59], v233, s[10:11]
	global_load_dwordx4 v[60:63], v233, s[10:11] offset:256
	s_waitcnt vmcnt(8)
	v_mfma_scale_f32_16x16x128_f8f6f4 v[64:67], v[0:3], v[194:201], 0, v133, v133 op_sel_hi:[0,0,0] cbsz:4
	v_mfma_scale_f32_16x16x128_f8f6f4 v[64:67], v[4:7], v[202:209], v[64:67], v133, v133 op_sel_hi:[0,0,0] cbsz:4
	v_mfma_scale_f32_16x16x128_f8f6f4 v[68:71], v[8:11], v[194:201], 0, v133, v133 op_sel_hi:[0,0,0] cbsz:4
	v_mfma_scale_f32_16x16x128_f8f6f4 v[68:71], v[12:15], v[202:209], v[68:71], v133, v133 op_sel_hi:[0,0,0] cbsz:4
	v_mfma_scale_f32_16x16x128_f8f6f4 v[72:75], v[16:19], v[194:201], 0, v133, v133 op_sel_hi:[0,0,0] cbsz:4
	v_mfma_scale_f32_16x16x128_f8f6f4 v[72:75], v[20:23], v[202:209], v[72:75], v133, v133 op_sel_hi:[0,0,0] cbsz:4
	v_mfma_scale_f32_16x16x128_f8f6f4 v[76:79], v[24:27], v[194:201], 0, v133, v133 op_sel_hi:[0,0,0] cbsz:4
	v_mfma_scale_f32_16x16x128_f8f6f4 v[76:79], v[28:31], v[202:209], v[76:79], v133, v133 op_sel_hi:[0,0,0] cbsz:4
	s_nop 3
	v_mul_f32_e32 v234, v158, v80
	v_mul_f32_e32 v235, v158, v84
	v_mul_f32_e32 v236, v158, v88
	v_mul_f32_e32 v237, v158, v92
	v_fmac_f32_e32 v234, v159, v81
	v_fmac_f32_e32 v235, v159, v85
	v_fmac_f32_e32 v236, v159, v89
	v_fmac_f32_e32 v237, v159, v93
	v_fmac_f32_e32 v234, v160, v82
	v_fmac_f32_e32 v235, v160, v86
	v_fmac_f32_e32 v236, v160, v90
	v_fmac_f32_e32 v237, v160, v94
	v_fmac_f32_e32 v234, v161, v83
	v_fmac_f32_e32 v235, v161, v87
	v_fmac_f32_e32 v236, v161, v91
	v_fmac_f32_e32 v237, v161, v95
	v_add_f32_dpp v234, v234, v234 quad_perm:[1,0,3,2] row_mask:0xf bank_mask:0xf
	v_add_f32_dpp v235, v235, v235 quad_perm:[1,0,3,2] row_mask:0xf bank_mask:0xf
	v_add_f32_dpp v236, v236, v236 quad_perm:[1,0,3,2] row_mask:0xf bank_mask:0xf
	v_add_f32_dpp v237, v237, v237 quad_perm:[1,0,3,2] row_mask:0xf bank_mask:0xf
	v_add_f32_dpp v234, v234, v234 quad_perm:[2,3,0,1] row_mask:0xf bank_mask:0xf
	v_add_f32_dpp v235, v235, v235 quad_perm:[2,3,0,1] row_mask:0xf bank_mask:0xf
	v_add_f32_dpp v236, v236, v236 quad_perm:[2,3,0,1] row_mask:0xf bank_mask:0xf
	v_add_f32_dpp v237, v237, v237 quad_perm:[2,3,0,1] row_mask:0xf bank_mask:0xf
	v_add_f32_dpp v234, v234, v234 row_half_mirror row_mask:0xf bank_mask:0xf
	v_add_f32_dpp v235, v235, v235 row_half_mirror row_mask:0xf bank_mask:0xf
	v_add_f32_dpp v236, v236, v236 row_half_mirror row_mask:0xf bank_mask:0xf
	v_add_f32_dpp v237, v237, v237 row_half_mirror row_mask:0xf bank_mask:0xf
	s_mov_b32 exec_lo, 0x10001
	s_mov_b32 exec_hi, 0x10001
	ds_write_b32 v155, v234 offset:640
	ds_write_b32 v155, v235 offset:656
	ds_write_b32 v155, v236 offset:672
	ds_write_b32 v155, v237 offset:688
	s_mov_b64 exec, -1
	ds_read2_b32 v[96:97], v242 offset0:32 offset1:36
	ds_read2_b32 v[98:99], v242 offset0:40 offset1:44
	s_waitcnt lgkmcnt(0)
	v_lshl_add_u32 v96, v96, 9, v144
	v_lshl_add_u32 v97, v97, 9, v144
	v_lshl_add_u32 v98, v98, 9, v144
	v_lshl_add_u32 v99, v99, 9, v144
	global_load_dwordx4 v[0:3], v96, s[10:11]
	global_load_dwordx4 v[4:7], v96, s[10:11] offset:256
	global_load_dwordx4 v[8:11], v97, s[10:11]
	global_load_dwordx4 v[12:15], v97, s[10:11] offset:256
	global_load_dwordx4 v[16:19], v98, s[10:11]
	global_load_dwordx4 v[20:23], v98, s[10:11] offset:256
	global_load_dwordx4 v[24:27], v99, s[10:11]
	global_load_dwordx4 v[28:31], v99, s[10:11] offset:256
	s_waitcnt vmcnt(8)
	v_mfma_scale_f32_16x16x128_f8f6f4 v[80:83], v[32:35], v[210:217], 0, v133, v133 op_sel_hi:[0,0,0] cbsz:4
	v_mfma_scale_f32_16x16x128_f8f6f4 v[80:83], v[36:39], v[218:225], v[80:83], v133, v133 op_sel_hi:[0,0,0] cbsz:4
	v_mfma_scale_f32_16x16x128_f8f6f4 v[84:87], v[40:43], v[210:217], 0, v133, v133 op_sel_hi:[0,0,0] cbsz:4
	v_mfma_scale_f32_16x16x128_f8f6f4 v[84:87], v[44:47], v[218:225], v[84:87], v133, v133 op_sel_hi:[0,0,0] cbsz:4
	v_mfma_scale_f32_16x16x128_f8f6f4 v[88:91], v[48:51], v[210:217], 0, v133, v133 op_sel_hi:[0,0,0] cbsz:4
	v_mfma_scale_f32_16x16x128_f8f6f4 v[88:91], v[52:55], v[218:225], v[88:91], v133, v133 op_sel_hi:[0,0,0] cbsz:4
	v_mfma_scale_f32_16x16x128_f8f6f4 v[92:95], v[56:59], v[210:217], 0, v133, v133 op_sel_hi:[0,0,0] cbsz:4
	v_mfma_scale_f32_16x16x128_f8f6f4 v[92:95], v[60:63], v[218:225], v[92:95], v133, v133 op_sel_hi:[0,0,0] cbsz:4
	s_nop 3
	v_mul_f32_e32 v234, v158, v64
	v_mul_f32_e32 v235, v158, v68
	v_mul_f32_e32 v236, v158, v72
	v_mul_f32_e32 v237, v158, v76
	v_fmac_f32_e32 v234, v159, v65
	v_fmac_f32_e32 v235, v159, v69
	v_fmac_f32_e32 v236, v159, v73
	v_fmac_f32_e32 v237, v159, v77
	v_fmac_f32_e32 v234, v160, v66
	v_fmac_f32_e32 v235, v160, v70
	v_fmac_f32_e32 v236, v160, v74
	v_fmac_f32_e32 v237, v160, v78
	v_fmac_f32_e32 v234, v161, v67
	v_fmac_f32_e32 v235, v161, v71
	v_fmac_f32_e32 v236, v161, v75
	v_fmac_f32_e32 v237, v161, v79
	v_add_f32_dpp v234, v234, v234 quad_perm:[1,0,3,2] row_mask:0xf bank_mask:0xf
	v_add_f32_dpp v235, v235, v235 quad_perm:[1,0,3,2] row_mask:0xf bank_mask:0xf
	v_add_f32_dpp v236, v236, v236 quad_perm:[1,0,3,2] row_mask:0xf bank_mask:0xf
	v_add_f32_dpp v237, v237, v237 quad_perm:[1,0,3,2] row_mask:0xf bank_mask:0xf
	v_add_f32_dpp v234, v234, v234 quad_perm:[2,3,0,1] row_mask:0xf bank_mask:0xf
	v_add_f32_dpp v235, v235, v235 quad_perm:[2,3,0,1] row_mask:0xf bank_mask:0xf
	v_add_f32_dpp v236, v236, v236 quad_perm:[2,3,0,1] row_mask:0xf bank_mask:0xf
	v_add_f32_dpp v237, v237, v237 quad_perm:[2,3,0,1] row_mask:0xf bank_mask:0xf
	v_add_f32_dpp v234, v234, v234 row_half_mirror row_mask:0xf bank_mask:0xf
	v_add_f32_dpp v235, v235, v235 row_half_mirror row_mask:0xf bank_mask:0xf
	v_add_f32_dpp v236, v236, v236 row_half_mirror row_mask:0xf bank_mask:0xf
	v_add_f32_dpp v237, v237, v237 row_half_mirror row_mask:0xf bank_mask:0xf
	s_mov_b32 exec_lo, 0x10001
	s_mov_b32 exec_hi, 0x10001
	ds_write_b32 v155, v234 offset:1152
	ds_write_b32 v155, v235 offset:1168
	ds_write_b32 v155, v236 offset:1184
	ds_write_b32 v155, v237 offset:1200
	s_mov_b64 exec, -1
	ds_read2_b32 v[230:231], v243 offset0:32 offset1:36
	ds_read2_b32 v[232:233], v243 offset0:40 offset1:44
	s_waitcnt lgkmcnt(0)
; __device__ __forceinline__ void peer_token(const Params& P, int t, int lane, int* sidx, float* sval, const int* sid, const float* sgate, const unsigned* szero) {
;     ...
;         for (int hh = 0; hh < 2; ++hh) off2[hh] = (unsigned)sid[8 * hh + (lr & 7)] * 512u + lofs;
; #pragma unroll
;         for (int hh = 0; hh < 2; ++hh)
; #pragma unroll
;             for (int st = 0; st < 4; ++st) abuf[0][hh][st] = *(const uint4*)(Ub + (off2[hh] + 128 * st));
; #pragma unroll
;         for (int T = 0; T < 8; ++T) {
;             if (T + 1 < 8) {
; #pragma unroll
;                 for (int hh = 0; hh < 2; ++hh) off2[hh] = (unsigned)sid[16 * (T + 1) + 8 * hh + (lr & 7)] * 512u + lofs;
; #pragma unroll
;                 for (int hh = 0; hh < 2; ++hh)
; #pragma unroll
;                     for (int st = 0; st < 4; ++st) abuf[(T + 1) & 1][hh][st] = *(const uint4*)(Ub + (off2[hh] + 128 * st));
;             }
; #pragma unroll
;             for (int hh = 0; hh < 2; ++hh) {
;                 f32x4 au = (f32x4){0.f, 0.f, 0.f, 0.f};
; #pragma unroll
;                 for (int st = 0; st < 4; ++st) {
;                     const uint4 a4 = abuf[T & 1][hh][st];
;                     const v8i Av = {(int)a4.x, (int)a4.y, (int)a4.z, (int)a4.w, 0, 0, 0, 0};
;                     au = __builtin_amdgcn_mfma_scale_f32_16x16x128_f8f6f4(Av, Bv[st], au, 4, 0, 0, 0x7f7f7f7f, 0, 0x7f7f7f7f);
;                 }
;                 if (owner) *(f32x4*)(sact + 16 * T + 8 * hh) = au;
;             }
	v_lshl_add_u32 v230, v230, 9, v144
	v_lshl_add_u32 v231, v231, 9, v144
	v_lshl_add_u32 v232, v232, 9, v144
	v_lshl_add_u32 v233, v233, 9, v144
	global_load_dwordx4 v[32:35], v230, s[10:11]
	global_load_dwordx4 v[36:39], v230, s[10:11] offset:256
	global_load_dwordx4 v[40:43], v231, s[10:11]
	global_load_dwordx4 v[44:47], v231, s[10:11] offset:256
	global_load_dwordx4 v[48:51], v232, s[10:11]
	global_load_dwordx4 v[52:55], v232, s[10:11] offset:256
	global_load_dwordx4 v[56:59], v233, s[10:11]
	global_load_dwordx4 v[60:63], v233, s[10:11] offset:256
	s_waitcnt vmcnt(8)
	v_mfma_scale_f32_16x16x128_f8f6f4 v[64:67], v[0:3], v[162:169], 0, v133, v133 op_sel_hi:[0,0,0] cbsz:4
	v_mfma_scale_f32_16x16x128_f8f6f4 v[64:67], v[4:7], v[170:177], v[64:67], v133, v133 op_sel_hi:[0,0,0] cbsz:4
	v_mfma_scale_f32_16x16x128_f8f6f4 v[68:71], v[8:11], v[162:169], 0, v133, v133 op_sel_hi:[0,0,0] cbsz:4
	v_mfma_scale_f32_16x16x128_f8f6f4 v[68:71], v[12:15], v[170:177], v[68:71], v133, v133 op_sel_hi:[0,0,0] cbsz:4
	v_mfma_scale_f32_16x16x128_f8f6f4 v[72:75], v[16:19], v[162:169], 0, v133, v133 op_sel_hi:[0,0,0] cbsz:4
	v_mfma_scale_f32_16x16x128_f8f6f4 v[72:75], v[20:23], v[170:177], v[72:75], v133, v133 op_sel_hi:[0,0,0] cbsz:4
	v_mfma_scale_f32_16x16x128_f8f6f4 v[76:79], v[24:27], v[162:169], 0, v133, v133 op_sel_hi:[0,0,0] cbsz:4
	v_mfma_scale_f32_16x16x128_f8f6f4 v[76:79], v[28:31], v[170:177], v[76:79], v133, v133 op_sel_hi:[0,0,0] cbsz:4
	s_nop 3
	v_mul_f32_e32 v234, v158, v80
	v_mul_f32_e32 v235, v158, v84
	v_mul_f32_e32 v236, v158, v88
	v_mul_f32_e32 v237, v158, v92
	v_fmac_f32_e32 v234, v159, v81
	v_fmac_f32_e32 v235, v159, v85
	v_fmac_f32_e32 v236, v159, v89
	v_fmac_f32_e32 v237, v159, v93
	v_fmac_f32_e32 v234, v160, v82
	v_fmac_f32_e32 v235, v160, v86
	v_fmac_f32_e32 v236, v160, v90
	v_fmac_f32_e32 v237, v160, v94
	v_fmac_f32_e32 v234, v161, v83
	v_fmac_f32_e32 v235, v161, v87
	v_fmac_f32_e32 v236, v161, v91
	v_fmac_f32_e32 v237, v161, v95
	v_add_f32_dpp v234, v234, v234 quad_perm:[1,0,3,2] row_mask:0xf bank_mask:0xf
	v_add_f32_dpp v235, v235, v235 quad_perm:[1,0,3,2] row_mask:0xf bank_mask:0xf
	v_add_f32_dpp v236, v236, v236 quad_perm:[1,0,3,2] row_mask:0xf bank_mask:0xf
	v_add_f32_dpp v237, v237, v237 quad_perm:[1,0,3,2] row_mask:0xf bank_mask:0xf
	v_add_f32_dpp v234, v234, v234 quad_perm:[2,3,0,1] row_mask:0xf bank_mask:0xf
	v_add_f32_dpp v235, v235, v235 quad_perm:[2,3,0,1] row_mask:0xf bank_mask:0xf
	v_add_f32_dpp v236, v236, v236 quad_perm:[2,3,0,1] row_mask:0xf bank_mask:0xf
	v_add_f32_dpp v237, v237, v237 quad_perm:[2,3,0,1] row_mask:0xf bank_mask:0xf
	v_add_f32_dpp v234, v234, v234 row_half_mirror row_mask:0xf bank_mask:0xf
	v_add_f32_dpp v235, v235, v235 row_half_mirror row_mask:0xf bank_mask:0xf
	v_add_f32_dpp v236, v236, v236 row_half_mirror row_mask:0xf bank_mask:0xf
	v_add_f32_dpp v237, v237, v237 row_half_mirror row_mask:0xf bank_mask:0xf
	s_mov_b32 exec_lo, 0x10001
	s_mov_b32 exec_hi, 0x10001
	ds_write_b32 v155, v234 offset:1664
	ds_write_b32 v155, v235 offset:1680
	ds_write_b32 v155, v236 offset:1696
	ds_write_b32 v155, v237 offset:1712
	s_mov_b64 exec, -1
	ds_read2_b32 v[96:97], v244 offset0:32 offset1:36
	ds_read2_b32 v[98:99], v244 offset0:40 offset1:44
	s_waitcnt lgkmcnt(0)
	v_lshl_add_u32 v96, v96, 9, v144
	v_lshl_add_u32 v97, v97, 9, v144
	v_lshl_add_u32 v98, v98, 9, v144
	v_lshl_add_u32 v99, v99, 9, v144
	global_load_dwordx4 v[0:3], v96, s[10:11]
	global_load_dwordx4 v[4:7], v96, s[10:11] offset:256
	global_load_dwordx4 v[8:11], v97, s[10:11]
	global_load_dwordx4 v[12:15], v97, s[10:11] offset:256
	global_load_dwordx4 v[16:19], v98, s[10:11]
	global_load_dwordx4 v[20:23], v98, s[10:11] offset:256
	global_load_dwordx4 v[24:27], v99, s[10:11]
	global_load_dwordx4 v[28:31], v99, s[10:11] offset:256
	s_waitcnt vmcnt(8)
	v_mfma_scale_f32_16x16x128_f8f6f4 v[80:83], v[32:35], v[178:185], 0, v133, v133 op_sel_hi:[0,0,0] cbsz:4
	v_mfma_scale_f32_16x16x128_f8f6f4 v[80:83], v[36:39], v[186:193], v[80:83], v133, v133 op_sel_hi:[0,0,0] cbsz:4
	v_mfma_scale_f32_16x16x128_f8f6f4 v[84:87], v[40:43], v[178:185], 0, v133, v133 op_sel_hi:[0,0,0] cbsz:4
	v_mfma_scale_f32_16x16x128_f8f6f4 v[84:87], v[44:47], v[186:193], v[84:87], v133, v133 op_sel_hi:[0,0,0] cbsz:4
	v_mfma_scale_f32_16x16x128_f8f6f4 v[88:91], v[48:51], v[178:185], 0, v133, v133 op_sel_hi:[0,0,0] cbsz:4
	v_mfma_scale_f32_16x16x128_f8f6f4 v[88:91], v[52:55], v[186:193], v[88:91], v133, v133 op_sel_hi:[0,0,0] cbsz:4
	v_mfma_scale_f32_16x16x128_f8f6f4 v[92:95], v[56:59], v[178:185], 0, v133, v133 op_sel_hi:[0,0,0] cbsz:4
	v_mfma_scale_f32_16x16x128_f8f6f4 v[92:95], v[60:63], v[186:193], v[92:95], v133, v133 op_sel_hi:[0,0,0] cbsz:4
	s_nop 3
	v_mul_f32_e32 v234, v226, v64
	v_mul_f32_e32 v235, v226, v68
	v_mul_f32_e32 v236, v226, v72
	v_mul_f32_e32 v237, v226, v76
	v_fmac_f32_e32 v234, v227, v65
	v_fmac_f32_e32 v235, v227, v69
	v_fmac_f32_e32 v236, v227, v73
	v_fmac_f32_e32 v237, v227, v77
	v_fmac_f32_e32 v234, v228, v66
	v_fmac_f32_e32 v235, v228, v70
	v_fmac_f32_e32 v236, v228, v74
	v_fmac_f32_e32 v237, v228, v78
	v_fmac_f32_e32 v234, v229, v67
	v_fmac_f32_e32 v235, v229, v71
	v_fmac_f32_e32 v236, v229, v75
	v_fmac_f32_e32 v237, v229, v79
	v_add_f32_dpp v234, v234, v234 quad_perm:[1,0,3,2] row_mask:0xf bank_mask:0xf
	v_add_f32_dpp v235, v235, v235 quad_perm:[1,0,3,2] row_mask:0xf bank_mask:0xf
	v_add_f32_dpp v236, v236, v236 quad_perm:[1,0,3,2] row_mask:0xf bank_mask:0xf
	v_add_f32_dpp v237, v237, v237 quad_perm:[1,0,3,2] row_mask:0xf bank_mask:0xf
	v_add_f32_dpp v234, v234, v234 quad_perm:[2,3,0,1] row_mask:0xf bank_mask:0xf
	v_add_f32_dpp v235, v235, v235 quad_perm:[2,3,0,1] row_mask:0xf bank_mask:0xf
	v_add_f32_dpp v236, v236, v236 quad_perm:[2,3,0,1] row_mask:0xf bank_mask:0xf
	v_add_f32_dpp v237, v237, v237 quad_perm:[2,3,0,1] row_mask:0xf bank_mask:0xf
	v_add_f32_dpp v234, v234, v234 row_half_mirror row_mask:0xf bank_mask:0xf
	v_add_f32_dpp v235, v235, v235 row_half_mirror row_mask:0xf bank_mask:0xf
	v_add_f32_dpp v236, v236, v236 row_half_mirror row_mask:0xf bank_mask:0xf
	v_add_f32_dpp v237, v237, v237 row_half_mirror row_mask:0xf bank_mask:0xf
	s_mov_b32 exec_lo, 0x1000100
	s_mov_b32 exec_hi, 0x1000100
	ds_write_b32 v155, v234 offset:2176
	ds_write_b32 v155, v235 offset:2192
	ds_write_b32 v155, v236 offset:2208
	ds_write_b32 v155, v237 offset:2224
	s_mov_b64 exec, -1
	ds_read2_b32 v[230:231], v245 offset0:32 offset1:36
	ds_read2_b32 v[232:233], v245 offset0:40 offset1:44
	s_waitcnt lgkmcnt(0)
; __device__ __forceinline__ void peer_token(const Params& P, int t, int lane, int* sidx, float* sval, const int* sid, const float* sgate, const unsigned* szero) {
;     ...
;         for (int hh = 0; hh < 2; ++hh) off2[hh] = (unsigned)sid[8 * hh + (lr & 7)] * 512u + lofs;
; #pragma unroll
;         for (int hh = 0; hh < 2; ++hh)
; #pragma unroll
;             for (int st = 0; st < 4; ++st) abuf[0][hh][st] = *(const uint4*)(Ub + (off2[hh] + 128 * st));
; #pragma unroll
;         for (int T = 0; T < 8; ++T) {
;             if (T + 1 < 8) {
; #pragma unroll
;                 for (int hh = 0; hh < 2; ++hh) off2[hh] = (unsigned)sid[16 * (T + 1) + 8 * hh + (lr & 7)] * 512u + lofs;
; #pragma unroll
;                 for (int hh = 0; hh < 2; ++hh)
; #pragma unroll
;                     for (int st = 0; st < 4; ++st) abuf[(T + 1) & 1][hh][st] = *(const uint4*)(Ub + (off2[hh] + 128 * st));
;             }
; #pragma unroll
;             for (int hh = 0; hh < 2; ++hh) {
;                 f32x4 au = (f32x4){0.f, 0.f, 0.f, 0.f};
; #pragma unroll
;                 for (int st = 0; st < 4; ++st) {
;                     const uint4 a4 = abuf[T & 1][hh][st];
;                     const v8i Av = {(int)a4.x, (int)a4.y, (int)a4.z, (int)a4.w, 0, 0, 0, 0};
;                     au = __builtin_amdgcn_mfma_scale_f32_16x16x128_f8f6f4(Av, Bv[st], au, 4, 0, 0, 0x7f7f7f7f, 0, 0x7f7f7f7f);
;                 }
;                 if (owner) *(f32x4*)(sact + 16 * T + 8 * hh) = au;
;             }
	v_lshl_add_u32 v230, v230, 9, v144
	v_lshl_add_u32 v231, v231, 9, v144
	v_lshl_add_u32 v232, v232, 9, v144
	v_lshl_add_u32 v233, v233, 9, v144
	global_load_dwordx4 v[32:35], v230, s[10:11]
	global_load_dwordx4 v[36:39], v230, s[10:11] offset:256
	global_load_dwordx4 v[40:43], v231, s[10:11]
	global_load_dwordx4 v[44:47], v231, s[10:11] offset:256
	global_load_dwordx4 v[48:51], v232, s[10:11]
	global_load_dwordx4 v[52:55], v232, s[10:11] offset:256
	global_load_dwordx4 v[56:59], v233, s[10:11]
	global_load_dwordx4 v[60:63], v233, s[10:11] offset:256
	s_waitcnt vmcnt(8)
	v_mfma_scale_f32_16x16x128_f8f6f4 v[64:67], v[0:3], v[194:201], 0, v133, v133 op_sel_hi:[0,0,0] cbsz:4
	v_mfma_scale_f32_16x16x128_f8f6f4 v[64:67], v[4:7], v[202:209], v[64:67], v133, v133 op_sel_hi:[0,0,0] cbsz:4
	v_mfma_scale_f32_16x16x128_f8f6f4 v[68:71], v[8:11], v[194:201], 0, v133, v133 op_sel_hi:[0,0,0] cbsz:4
	v_mfma_scale_f32_16x16x128_f8f6f4 v[68:71], v[12:15], v[202:209], v[68:71], v133, v133 op_sel_hi:[0,0,0] cbsz:4
	v_mfma_scale_f32_16x16x128_f8f6f4 v[72:75], v[16:19], v[194:201], 0, v133, v133 op_sel_hi:[0,0,0] cbsz:4
	v_mfma_scale_f32_16x16x128_f8f6f4 v[72:75], v[20:23], v[202:209], v[72:75], v133, v133 op_sel_hi:[0,0,0] cbsz:4
	v_mfma_scale_f32_16x16x128_f8f6f4 v[76:79], v[24:27], v[194:201], 0, v133, v133 op_sel_hi:[0,0,0] cbsz:4
	v_mfma_scale_f32_16x16x128_f8f6f4 v[76:79], v[28:31], v[202:209], v[76:79], v133, v133 op_sel_hi:[0,0,0] cbsz:4
	s_nop 3
	v_mul_f32_e32 v234, v226, v80
	v_mul_f32_e32 v235, v226, v84
	v_mul_f32_e32 v236, v226, v88
	v_mul_f32_e32 v237, v226, v92
	v_fmac_f32_e32 v234, v227, v81
	v_fmac_f32_e32 v235, v227, v85
	v_fmac_f32_e32 v236, v227, v89
	v_fmac_f32_e32 v237, v227, v93
	v_fmac_f32_e32 v234, v228, v82
	v_fmac_f32_e32 v235, v228, v86
	v_fmac_f32_e32 v236, v228, v90
	v_fmac_f32_e32 v237, v228, v94
	v_fmac_f32_e32 v234, v229, v83
	v_fmac_f32_e32 v235, v229, v87
	v_fmac_f32_e32 v236, v229, v91
	v_fmac_f32_e32 v237, v229, v95
	v_add_f32_dpp v234, v234, v234 quad_perm:[1,0,3,2] row_mask:0xf bank_mask:0xf
	v_add_f32_dpp v235, v235, v235 quad_perm:[1,0,3,2] row_mask:0xf bank_mask:0xf
	v_add_f32_dpp v236, v236, v236 quad_perm:[1,0,3,2] row_mask:0xf bank_mask:0xf
	v_add_f32_dpp v237, v237, v237 quad_perm:[1,0,3,2] row_mask:0xf bank_mask:0xf
	v_add_f32_dpp v234, v234, v234 quad_perm:[2,3,0,1] row_mask:0xf bank_mask:0xf
	v_add_f32_dpp v235, v235, v235 quad_perm:[2,3,0,1] row_mask:0xf bank_mask:0xf
	v_add_f32_dpp v236, v236, v236 quad_perm:[2,3,0,1] row_mask:0xf bank_mask:0xf
	v_add_f32_dpp v237, v237, v237 quad_perm:[2,3,0,1] row_mask:0xf bank_mask:0xf
	v_add_f32_dpp v234, v234, v234 row_half_mirror row_mask:0xf bank_mask:0xf
	v_add_f32_dpp v235, v235, v235 row_half_mirror row_mask:0xf bank_mask:0xf
	v_add_f32_dpp v236, v236, v236 row_half_mirror row_mask:0xf bank_mask:0xf
	v_add_f32_dpp v237, v237, v237 row_half_mirror row_mask:0xf bank_mask:0xf
	s_mov_b32 exec_lo, 0x1000100
	s_mov_b32 exec_hi, 0x1000100
	ds_write_b32 v155, v234 offset:2688
	ds_write_b32 v155, v235 offset:2704
	ds_write_b32 v155, v236 offset:2720
	ds_write_b32 v155, v237 offset:2736
	s_mov_b64 exec, -1
	ds_read2_b32 v[96:97], v238 offset0:48 offset1:52
	ds_read2_b32 v[98:99], v238 offset0:56 offset1:60
	s_waitcnt lgkmcnt(0)
	v_lshl_add_u32 v96, v96, 9, v144
	v_lshl_add_u32 v97, v97, 9, v144
	v_lshl_add_u32 v98, v98, 9, v144
	v_lshl_add_u32 v99, v99, 9, v144
	global_load_dwordx4 v[0:3], v96, s[10:11]
	global_load_dwordx4 v[4:7], v96, s[10:11] offset:256
	global_load_dwordx4 v[8:11], v97, s[10:11]
	global_load_dwordx4 v[12:15], v97, s[10:11] offset:256
	global_load_dwordx4 v[16:19], v98, s[10:11]
	global_load_dwordx4 v[20:23], v98, s[10:11] offset:256
	global_load_dwordx4 v[24:27], v99, s[10:11]
	global_load_dwordx4 v[28:31], v99, s[10:11] offset:256
	s_waitcnt vmcnt(8)
	v_mfma_scale_f32_16x16x128_f8f6f4 v[80:83], v[32:35], v[210:217], 0, v133, v133 op_sel_hi:[0,0,0] cbsz:4
	v_mfma_scale_f32_16x16x128_f8f6f4 v[80:83], v[36:39], v[218:225], v[80:83], v133, v133 op_sel_hi:[0,0,0] cbsz:4
	v_mfma_scale_f32_16x16x128_f8f6f4 v[84:87], v[40:43], v[210:217], 0, v133, v133 op_sel_hi:[0,0,0] cbsz:4
	v_mfma_scale_f32_16x16x128_f8f6f4 v[84:87], v[44:47], v[218:225], v[84:87], v133, v133 op_sel_hi:[0,0,0] cbsz:4
	v_mfma_scale_f32_16x16x128_f8f6f4 v[88:91], v[48:51], v[210:217], 0, v133, v133 op_sel_hi:[0,0,0] cbsz:4
	v_mfma_scale_f32_16x16x128_f8f6f4 v[88:91], v[52:55], v[218:225], v[88:91], v133, v133 op_sel_hi:[0,0,0] cbsz:4
	v_mfma_scale_f32_16x16x128_f8f6f4 v[92:95], v[56:59], v[210:217], 0, v133, v133 op_sel_hi:[0,0,0] cbsz:4
	v_mfma_scale_f32_16x16x128_f8f6f4 v[92:95], v[60:63], v[218:225], v[92:95], v133, v133 op_sel_hi:[0,0,0] cbsz:4
	s_nop 3
	v_mul_f32_e32 v234, v226, v64
	v_mul_f32_e32 v235, v226, v68
	v_mul_f32_e32 v236, v226, v72
	v_mul_f32_e32 v237, v226, v76
	v_fmac_f32_e32 v234, v227, v65
	v_fmac_f32_e32 v235, v227, v69
	v_fmac_f32_e32 v236, v227, v73
	v_fmac_f32_e32 v237, v227, v77
	v_fmac_f32_e32 v234, v228, v66
	v_fmac_f32_e32 v235, v228, v70
	v_fmac_f32_e32 v236, v228, v74
	v_fmac_f32_e32 v237, v228, v78
	v_fmac_f32_e32 v234, v229, v67
	v_fmac_f32_e32 v235, v229, v71
	v_fmac_f32_e32 v236, v229, v75
	v_fmac_f32_e32 v237, v229, v79
	v_add_f32_dpp v234, v234, v234 quad_perm:[1,0,3,2] row_mask:0xf bank_mask:0xf
	v_add_f32_dpp v235, v235, v235 quad_perm:[1,0,3,2] row_mask:0xf bank_mask:0xf
	v_add_f32_dpp v236, v236, v236 quad_perm:[1,0,3,2] row_mask:0xf bank_mask:0xf
	v_add_f32_dpp v237, v237, v237 quad_perm:[1,0,3,2] row_mask:0xf bank_mask:0xf
	v_add_f32_dpp v234, v234, v234 quad_perm:[2,3,0,1] row_mask:0xf bank_mask:0xf
	v_add_f32_dpp v235, v235, v235 quad_perm:[2,3,0,1] row_mask:0xf bank_mask:0xf
	v_add_f32_dpp v236, v236, v236 quad_perm:[2,3,0,1] row_mask:0xf bank_mask:0xf
	v_add_f32_dpp v237, v237, v237 quad_perm:[2,3,0,1] row_mask:0xf bank_mask:0xf
	v_add_f32_dpp v234, v234, v234 row_half_mirror row_mask:0xf bank_mask:0xf
	v_add_f32_dpp v235, v235, v235 row_half_mirror row_mask:0xf bank_mask:0xf
	v_add_f32_dpp v236, v236, v236 row_half_mirror row_mask:0xf bank_mask:0xf
	v_add_f32_dpp v237, v237, v237 row_half_mirror row_mask:0xf bank_mask:0xf
	s_mov_b32 exec_lo, 0x1000100
	s_mov_b32 exec_hi, 0x1000100
	ds_write_b32 v155, v234 offset:3200
	ds_write_b32 v155, v235 offset:3216
	ds_write_b32 v155, v236 offset:3232
	ds_write_b32 v155, v237 offset:3248
	s_mov_b64 exec, -1
	ds_read2_b32 v[230:231], v239 offset0:48 offset1:52
	ds_read2_b32 v[232:233], v239 offset0:56 offset1:60
	s_waitcnt lgkmcnt(0)
; __device__ __forceinline__ void peer_token(const Params& P, int t, int lane, int* sidx, float* sval, const int* sid, const float* sgate, const unsigned* szero) {
;     ...
;         for (int hh = 0; hh < 2; ++hh) off2[hh] = (unsigned)sid[8 * hh + (lr & 7)] * 512u + lofs;
; #pragma unroll
;         for (int hh = 0; hh < 2; ++hh)
; #pragma unroll
;             for (int st = 0; st < 4; ++st) abuf[0][hh][st] = *(const uint4*)(Ub + (off2[hh] + 128 * st));
; #pragma unroll
;         for (int T = 0; T < 8; ++T) {
;             if (T + 1 < 8) {
; #pragma unroll
;                 for (int hh = 0; hh < 2; ++hh) off2[hh] = (unsigned)sid[16 * (T + 1) + 8 * hh + (lr & 7)] * 512u + lofs;
; #pragma unroll
;                 for (int hh = 0; hh < 2; ++hh)
; #pragma unroll
;                     for (int st = 0; st < 4; ++st) abuf[(T + 1) & 1][hh][st] = *(const uint4*)(Ub + (off2[hh] + 128 * st));
;             }
; #pragma unroll
;             for (int hh = 0; hh < 2; ++hh) {
;                 f32x4 au = (f32x4){0.f, 0.f, 0.f, 0.f};
; #pragma unroll
;                 for (int st = 0; st < 4; ++st) {
;                     const uint4 a4 = abuf[T & 1][hh][st];
;                     const v8i Av = {(int)a4.x, (int)a4.y, (int)a4.z, (int)a4.w, 0, 0, 0, 0};
;                     au = __builtin_amdgcn_mfma_scale_f32_16x16x128_f8f6f4(Av, Bv[st], au, 4, 0, 0, 0x7f7f7f7f, 0, 0x7f7f7f7f);
;                 }
;                 if (owner) *(f32x4*)(sact + 16 * T + 8 * hh) = au;
;             }
	v_lshl_add_u32 v230, v230, 9, v144
	v_lshl_add_u32 v231, v231, 9, v144
	v_lshl_add_u32 v232, v232, 9, v144
	v_lshl_add_u32 v233, v233, 9, v144
	global_load_dwordx4 v[32:35], v230, s[10:11]
	global_load_dwordx4 v[36:39], v230, s[10:11] offset:256
	global_load_dwordx4 v[40:43], v231, s[10:11]
	global_load_dwordx4 v[44:47], v231, s[10:11] offset:256
	global_load_dwordx4 v[48:51], v232, s[10:11]
	global_load_dwordx4 v[52:55], v232, s[10:11] offset:256
	global_load_dwordx4 v[56:59], v233, s[10:11]
	global_load_dwordx4 v[60:63], v233, s[10:11] offset:256
	s_waitcnt vmcnt(8)
	v_mfma_scale_f32_16x16x128_f8f6f4 v[64:67], v[0:3], v[162:169], 0, v133, v133 op_sel_hi:[0,0,0] cbsz:4
	v_mfma_scale_f32_16x16x128_f8f6f4 v[64:67], v[4:7], v[170:177], v[64:67], v133, v133 op_sel_hi:[0,0,0] cbsz:4
	v_mfma_scale_f32_16x16x128_f8f6f4 v[68:71], v[8:11], v[162:169], 0, v133, v133 op_sel_hi:[0,0,0] cbsz:4
	v_mfma_scale_f32_16x16x128_f8f6f4 v[68:71], v[12:15], v[170:177], v[68:71], v133, v133 op_sel_hi:[0,0,0] cbsz:4
	v_mfma_scale_f32_16x16x128_f8f6f4 v[72:75], v[16:19], v[162:169], 0, v133, v133 op_sel_hi:[0,0,0] cbsz:4
	v_mfma_scale_f32_16x16x128_f8f6f4 v[72:75], v[20:23], v[170:177], v[72:75], v133, v133 op_sel_hi:[0,0,0] cbsz:4
	v_mfma_scale_f32_16x16x128_f8f6f4 v[76:79], v[24:27], v[162:169], 0, v133, v133 op_sel_hi:[0,0,0] cbsz:4
	v_mfma_scale_f32_16x16x128_f8f6f4 v[76:79], v[28:31], v[170:177], v[76:79], v133, v133 op_sel_hi:[0,0,0] cbsz:4
	s_nop 3
	v_mul_f32_e32 v234, v226, v80
	v_mul_f32_e32 v235, v226, v84
	v_mul_f32_e32 v236, v226, v88
	v_mul_f32_e32 v237, v226, v92
	v_fmac_f32_e32 v234, v227, v81
	v_fmac_f32_e32 v235, v227, v85
	v_fmac_f32_e32 v236, v227, v89
	v_fmac_f32_e32 v237, v227, v93
	v_fmac_f32_e32 v234, v228, v82
	v_fmac_f32_e32 v235, v228, v86
	v_fmac_f32_e32 v236, v228, v90
	v_fmac_f32_e32 v237, v228, v94
	v_fmac_f32_e32 v234, v229, v83
	v_fmac_f32_e32 v235, v229, v87
	v_fmac_f32_e32 v236, v229, v91
	v_fmac_f32_e32 v237, v229, v95
	v_add_f32_dpp v234, v234, v234 quad_perm:[1,0,3,2] row_mask:0xf bank_mask:0xf
	v_add_f32_dpp v235, v235, v235 quad_perm:[1,0,3,2] row_mask:0xf bank_mask:0xf
	v_add_f32_dpp v236, v236, v236 quad_perm:[1,0,3,2] row_mask:0xf bank_mask:0xf
	v_add_f32_dpp v237, v237, v237 quad_perm:[1,0,3,2] row_mask:0xf bank_mask:0xf
	v_add_f32_dpp v234, v234, v234 quad_perm:[2,3,0,1] row_mask:0xf bank_mask:0xf
	v_add_f32_dpp v235, v235, v235 quad_perm:[2,3,0,1] row_mask:0xf bank_mask:0xf
	v_add_f32_dpp v236, v236, v236 quad_perm:[2,3,0,1] row_mask:0xf bank_mask:0xf
	v_add_f32_dpp v237, v237, v237 quad_perm:[2,3,0,1] row_mask:0xf bank_mask:0xf
	v_add_f32_dpp v234, v234, v234 row_half_mirror row_mask:0xf bank_mask:0xf
	v_add_f32_dpp v235, v235, v235 row_half_mirror row_mask:0xf bank_mask:0xf
	v_add_f32_dpp v236, v236, v236 row_half_mirror row_mask:0xf bank_mask:0xf
	v_add_f32_dpp v237, v237, v237 row_half_mirror row_mask:0xf bank_mask:0xf
	s_mov_b32 exec_lo, 0x1000100
	s_mov_b32 exec_hi, 0x1000100
	ds_write_b32 v155, v234 offset:3712
	ds_write_b32 v155, v235 offset:3728
	ds_write_b32 v155, v236 offset:3744
	ds_write_b32 v155, v237 offset:3760
	s_mov_b64 exec, -1
	ds_read2_b32 v[96:97], v240 offset0:48 offset1:52
	ds_read2_b32 v[98:99], v240 offset0:56 offset1:60
	s_waitcnt lgkmcnt(0)
	v_lshl_add_u32 v96, v96, 9, v144
	v_lshl_add_u32 v97, v97, 9, v144
	v_lshl_add_u32 v98, v98, 9, v144
	v_lshl_add_u32 v99, v99, 9, v144
	global_load_dwordx4 v[0:3], v96, s[10:11]
	global_load_dwordx4 v[4:7], v96, s[10:11] offset:256
	global_load_dwordx4 v[8:11], v97, s[10:11]
	global_load_dwordx4 v[12:15], v97, s[10:11] offset:256
	global_load_dwordx4 v[16:19], v98, s[10:11]
	global_load_dwordx4 v[20:23], v98, s[10:11] offset:256
	global_load_dwordx4 v[24:27], v99, s[10:11]
	global_load_dwordx4 v[28:31], v99, s[10:11] offset:256
	s_waitcnt vmcnt(8)
	v_mfma_scale_f32_16x16x128_f8f6f4 v[80:83], v[32:35], v[178:185], 0, v133, v133 op_sel_hi:[0,0,0] cbsz:4
	v_mfma_scale_f32_16x16x128_f8f6f4 v[80:83], v[36:39], v[186:193], v[80:83], v133, v133 op_sel_hi:[0,0,0] cbsz:4
	v_mfma_scale_f32_16x16x128_f8f6f4 v[84:87], v[40:43], v[178:185], 0, v133, v133 op_sel_hi:[0,0,0] cbsz:4
	v_mfma_scale_f32_16x16x128_f8f6f4 v[84:87], v[44:47], v[186:193], v[84:87], v133, v133 op_sel_hi:[0,0,0] cbsz:4
	v_mfma_scale_f32_16x16x128_f8f6f4 v[88:91], v[48:51], v[178:185], 0, v133, v133 op_sel_hi:[0,0,0] cbsz:4
	v_mfma_scale_f32_16x16x128_f8f6f4 v[88:91], v[52:55], v[186:193], v[88:91], v133, v133 op_sel_hi:[0,0,0] cbsz:4
	v_mfma_scale_f32_16x16x128_f8f6f4 v[92:95], v[56:59], v[178:185], 0, v133, v133 op_sel_hi:[0,0,0] cbsz:4
	v_mfma_scale_f32_16x16x128_f8f6f4 v[92:95], v[60:63], v[186:193], v[92:95], v133, v133 op_sel_hi:[0,0,0] cbsz:4
	s_nop 3
	v_mul_f32_e32 v234, v158, v64
	v_mul_f32_e32 v235, v158, v68
	v_mul_f32_e32 v236, v158, v72
	v_mul_f32_e32 v237, v158, v76
	v_fmac_f32_e32 v234, v159, v65
	v_fmac_f32_e32 v235, v159, v69
	v_fmac_f32_e32 v236, v159, v73
	v_fmac_f32_e32 v237, v159, v77
	v_fmac_f32_e32 v234, v160, v66
	v_fmac_f32_e32 v235, v160, v70
	v_fmac_f32_e32 v236, v160, v74
	v_fmac_f32_e32 v237, v160, v78
	v_fmac_f32_e32 v234, v161, v67
	v_fmac_f32_e32 v235, v161, v71
	v_fmac_f32_e32 v236, v161, v75
	v_fmac_f32_e32 v237, v161, v79
	v_add_f32_dpp v234, v234, v234 quad_perm:[1,0,3,2] row_mask:0xf bank_mask:0xf
	v_add_f32_dpp v235, v235, v235 quad_perm:[1,0,3,2] row_mask:0xf bank_mask:0xf
	v_add_f32_dpp v236, v236, v236 quad_perm:[1,0,3,2] row_mask:0xf bank_mask:0xf
	v_add_f32_dpp v237, v237, v237 quad_perm:[1,0,3,2] row_mask:0xf bank_mask:0xf
	v_add_f32_dpp v234, v234, v234 quad_perm:[2,3,0,1] row_mask:0xf bank_mask:0xf
	v_add_f32_dpp v235, v235, v235 quad_perm:[2,3,0,1] row_mask:0xf bank_mask:0xf
	v_add_f32_dpp v236, v236, v236 quad_perm:[2,3,0,1] row_mask:0xf bank_mask:0xf
	v_add_f32_dpp v237, v237, v237 quad_perm:[2,3,0,1] row_mask:0xf bank_mask:0xf
	v_add_f32_dpp v234, v234, v234 row_half_mirror row_mask:0xf bank_mask:0xf
	v_add_f32_dpp v235, v235, v235 row_half_mirror row_mask:0xf bank_mask:0xf
	v_add_f32_dpp v236, v236, v236 row_half_mirror row_mask:0xf bank_mask:0xf
	v_add_f32_dpp v237, v237, v237 row_half_mirror row_mask:0xf bank_mask:0xf
	s_mov_b32 exec_lo, 0x10001
	s_mov_b32 exec_hi, 0x10001
	ds_write_b32 v155, v234 offset:192
	ds_write_b32 v155, v235 offset:208
	ds_write_b32 v155, v236 offset:224
	ds_write_b32 v155, v237 offset:240
	s_mov_b64 exec, -1
	ds_read2_b32 v[230:231], v241 offset0:48 offset1:52
	ds_read2_b32 v[232:233], v241 offset0:56 offset1:60
	s_waitcnt lgkmcnt(0)
; __device__ __forceinline__ void peer_token(const Params& P, int t, int lane, int* sidx, float* sval, const int* sid, const float* sgate, const unsigned* szero) {
;     ...
;         for (int hh = 0; hh < 2; ++hh) off2[hh] = (unsigned)sid[8 * hh + (lr & 7)] * 512u + lofs;
; #pragma unroll
;         for (int hh = 0; hh < 2; ++hh)
; #pragma unroll
;             for (int st = 0; st < 4; ++st) abuf[0][hh][st] = *(const uint4*)(Ub + (off2[hh] + 128 * st));
; #pragma unroll
;         for (int T = 0; T < 8; ++T) {
;             if (T + 1 < 8) {
; #pragma unroll
;                 for (int hh = 0; hh < 2; ++hh) off2[hh] = (unsigned)sid[16 * (T + 1) + 8 * hh + (lr & 7)] * 512u + lofs;
; #pragma unroll
;                 for (int hh = 0; hh < 2; ++hh)
; #pragma unroll
;                     for (int st = 0; st < 4; ++st) abuf[(T + 1) & 1][hh][st] = *(const uint4*)(Ub + (off2[hh] + 128 * st));
;             }
; #pragma unroll
;             for (int hh = 0; hh < 2; ++hh) {
;                 f32x4 au = (f32x4){0.f, 0.f, 0.f, 0.f};
; #pragma unroll
;                 for (int st = 0; st < 4; ++st) {
;                     const uint4 a4 = abuf[T & 1][hh][st];
;                     const v8i Av = {(int)a4.x, (int)a4.y, (int)a4.z, (int)a4.w, 0, 0, 0, 0};
;                     au = __builtin_amdgcn_mfma_scale_f32_16x16x128_f8f6f4(Av, Bv[st], au, 4, 0, 0, 0x7f7f7f7f, 0, 0x7f7f7f7f);
;                 }
;                 if (owner) *(f32x4*)(sact + 16 * T + 8 * hh) = au;
;             }
	v_lshl_add_u32 v230, v230, 9, v144
	v_lshl_add_u32 v231, v231, 9, v144
	v_lshl_add_u32 v232, v232, 9, v144
	v_lshl_add_u32 v233, v233, 9, v144
	global_load_dwordx4 v[32:35], v230, s[10:11]
	global_load_dwordx4 v[36:39], v230, s[10:11] offset:256
	global_load_dwordx4 v[40:43], v231, s[10:11]
	global_load_dwordx4 v[44:47], v231, s[10:11] offset:256
	global_load_dwordx4 v[48:51], v232, s[10:11]
	global_load_dwordx4 v[52:55], v232, s[10:11] offset:256
	global_load_dwordx4 v[56:59], v233, s[10:11]
	global_load_dwordx4 v[60:63], v233, s[10:11] offset:256
	s_waitcnt vmcnt(8)
	v_mfma_scale_f32_16x16x128_f8f6f4 v[64:67], v[0:3], v[194:201], 0, v133, v133 op_sel_hi:[0,0,0] cbsz:4
	v_mfma_scale_f32_16x16x128_f8f6f4 v[64:67], v[4:7], v[202:209], v[64:67], v133, v133 op_sel_hi:[0,0,0] cbsz:4
	v_mfma_scale_f32_16x16x128_f8f6f4 v[68:71], v[8:11], v[194:201], 0, v133, v133 op_sel_hi:[0,0,0] cbsz:4
	v_mfma_scale_f32_16x16x128_f8f6f4 v[68:71], v[12:15], v[202:209], v[68:71], v133, v133 op_sel_hi:[0,0,0] cbsz:4
	v_mfma_scale_f32_16x16x128_f8f6f4 v[72:75], v[16:19], v[194:201], 0, v133, v133 op_sel_hi:[0,0,0] cbsz:4
	v_mfma_scale_f32_16x16x128_f8f6f4 v[72:75], v[20:23], v[202:209], v[72:75], v133, v133 op_sel_hi:[0,0,0] cbsz:4
	v_mfma_scale_f32_16x16x128_f8f6f4 v[76:79], v[24:27], v[194:201], 0, v133, v133 op_sel_hi:[0,0,0] cbsz:4
	v_mfma_scale_f32_16x16x128_f8f6f4 v[76:79], v[28:31], v[202:209], v[76:79], v133, v133 op_sel_hi:[0,0,0] cbsz:4
	s_nop 3
	v_mul_f32_e32 v234, v158, v80
	v_mul_f32_e32 v235, v158, v84
	v_mul_f32_e32 v236, v158, v88
	v_mul_f32_e32 v237, v158, v92
	v_fmac_f32_e32 v234, v159, v81
	v_fmac_f32_e32 v235, v159, v85
	v_fmac_f32_e32 v236, v159, v89
	v_fmac_f32_e32 v237, v159, v93
	v_fmac_f32_e32 v234, v160, v82
	v_fmac_f32_e32 v235, v160, v86
	v_fmac_f32_e32 v236, v160, v90
	v_fmac_f32_e32 v237, v160, v94
	v_fmac_f32_e32 v234, v161, v83
	v_fmac_f32_e32 v235, v161, v87
	v_fmac_f32_e32 v236, v161, v91
	v_fmac_f32_e32 v237, v161, v95
	v_add_f32_dpp v234, v234, v234 quad_perm:[1,0,3,2] row_mask:0xf bank_mask:0xf
	v_add_f32_dpp v235, v235, v235 quad_perm:[1,0,3,2] row_mask:0xf bank_mask:0xf
	v_add_f32_dpp v236, v236, v236 quad_perm:[1,0,3,2] row_mask:0xf bank_mask:0xf
	v_add_f32_dpp v237, v237, v237 quad_perm:[1,0,3,2] row_mask:0xf bank_mask:0xf
	v_add_f32_dpp v234, v234, v234 quad_perm:[2,3,0,1] row_mask:0xf bank_mask:0xf
	v_add_f32_dpp v235, v235, v235 quad_perm:[2,3,0,1] row_mask:0xf bank_mask:0xf
	v_add_f32_dpp v236, v236, v236 quad_perm:[2,3,0,1] row_mask:0xf bank_mask:0xf
	v_add_f32_dpp v237, v237, v237 quad_perm:[2,3,0,1] row_mask:0xf bank_mask:0xf
	v_add_f32_dpp v234, v234, v234 row_half_mirror row_mask:0xf bank_mask:0xf
	v_add_f32_dpp v235, v235, v235 row_half_mirror row_mask:0xf bank_mask:0xf
	v_add_f32_dpp v236, v236, v236 row_half_mirror row_mask:0xf bank_mask:0xf
	v_add_f32_dpp v237, v237, v237 row_half_mirror row_mask:0xf bank_mask:0xf
	s_mov_b32 exec_lo, 0x10001
	s_mov_b32 exec_hi, 0x10001
	ds_write_b32 v155, v234 offset:704
	ds_write_b32 v155, v235 offset:720
	ds_write_b32 v155, v236 offset:736
	ds_write_b32 v155, v237 offset:752
	s_mov_b64 exec, -1
	ds_read2_b32 v[96:97], v242 offset0:48 offset1:52
	ds_read2_b32 v[98:99], v242 offset0:56 offset1:60
	s_waitcnt lgkmcnt(0)
	v_lshl_add_u32 v96, v96, 9, v144
	v_lshl_add_u32 v97, v97, 9, v144
	v_lshl_add_u32 v98, v98, 9, v144
	v_lshl_add_u32 v99, v99, 9, v144
	global_load_dwordx4 v[0:3], v96, s[10:11]
	global_load_dwordx4 v[4:7], v96, s[10:11] offset:256
	global_load_dwordx4 v[8:11], v97, s[10:11]
	global_load_dwordx4 v[12:15], v97, s[10:11] offset:256
	global_load_dwordx4 v[16:19], v98, s[10:11]
	global_load_dwordx4 v[20:23], v98, s[10:11] offset:256
	global_load_dwordx4 v[24:27], v99, s[10:11]
	global_load_dwordx4 v[28:31], v99, s[10:11] offset:256
	s_waitcnt vmcnt(8)
	v_mfma_scale_f32_16x16x128_f8f6f4 v[80:83], v[32:35], v[210:217], 0, v133, v133 op_sel_hi:[0,0,0] cbsz:4
	v_mfma_scale_f32_16x16x128_f8f6f4 v[80:83], v[36:39], v[218:225], v[80:83], v133, v133 op_sel_hi:[0,0,0] cbsz:4
	v_mfma_scale_f32_16x16x128_f8f6f4 v[84:87], v[40:43], v[210:217], 0, v133, v133 op_sel_hi:[0,0,0] cbsz:4
	v_mfma_scale_f32_16x16x128_f8f6f4 v[84:87], v[44:47], v[218:225], v[84:87], v133, v133 op_sel_hi:[0,0,0] cbsz:4
	v_mfma_scale_f32_16x16x128_f8f6f4 v[88:91], v[48:51], v[210:217], 0, v133, v133 op_sel_hi:[0,0,0] cbsz:4
	v_mfma_scale_f32_16x16x128_f8f6f4 v[88:91], v[52:55], v[218:225], v[88:91], v133, v133 op_sel_hi:[0,0,0] cbsz:4
	v_mfma_scale_f32_16x16x128_f8f6f4 v[92:95], v[56:59], v[210:217], 0, v133, v133 op_sel_hi:[0,0,0] cbsz:4
	v_mfma_scale_f32_16x16x128_f8f6f4 v[92:95], v[60:63], v[218:225], v[92:95], v133, v133 op_sel_hi:[0,0,0] cbsz:4
	s_nop 3
	v_mul_f32_e32 v234, v158, v64
	v_mul_f32_e32 v235, v158, v68
	v_mul_f32_e32 v236, v158, v72
	v_mul_f32_e32 v237, v158, v76
	v_fmac_f32_e32 v234, v159, v65
	v_fmac_f32_e32 v235, v159, v69
	v_fmac_f32_e32 v236, v159, v73
	v_fmac_f32_e32 v237, v159, v77
	v_fmac_f32_e32 v234, v160, v66
	v_fmac_f32_e32 v235, v160, v70
	v_fmac_f32_e32 v236, v160, v74
	v_fmac_f32_e32 v237, v160, v78
	v_fmac_f32_e32 v234, v161, v67
	v_fmac_f32_e32 v235, v161, v71
	v_fmac_f32_e32 v236, v161, v75
	v_fmac_f32_e32 v237, v161, v79
	v_add_f32_dpp v234, v234, v234 quad_perm:[1,0,3,2] row_mask:0xf bank_mask:0xf
	v_add_f32_dpp v235, v235, v235 quad_perm:[1,0,3,2] row_mask:0xf bank_mask:0xf
	v_add_f32_dpp v236, v236, v236 quad_perm:[1,0,3,2] row_mask:0xf bank_mask:0xf
	v_add_f32_dpp v237, v237, v237 quad_perm:[1,0,3,2] row_mask:0xf bank_mask:0xf
	v_add_f32_dpp v234, v234, v234 quad_perm:[2,3,0,1] row_mask:0xf bank_mask:0xf
	v_add_f32_dpp v235, v235, v235 quad_perm:[2,3,0,1] row_mask:0xf bank_mask:0xf
	v_add_f32_dpp v236, v236, v236 quad_perm:[2,3,0,1] row_mask:0xf bank_mask:0xf
	v_add_f32_dpp v237, v237, v237 quad_perm:[2,3,0,1] row_mask:0xf bank_mask:0xf
	v_add_f32_dpp v234, v234, v234 row_half_mirror row_mask:0xf bank_mask:0xf
	v_add_f32_dpp v235, v235, v235 row_half_mirror row_mask:0xf bank_mask:0xf
	v_add_f32_dpp v236, v236, v236 row_half_mirror row_mask:0xf bank_mask:0xf
	v_add_f32_dpp v237, v237, v237 row_half_mirror row_mask:0xf bank_mask:0xf
	s_mov_b32 exec_lo, 0x10001
	s_mov_b32 exec_hi, 0x10001
	ds_write_b32 v155, v234 offset:1216
	ds_write_b32 v155, v235 offset:1232
	ds_write_b32 v155, v236 offset:1248
	ds_write_b32 v155, v237 offset:1264
	s_mov_b64 exec, -1
	ds_read2_b32 v[230:231], v243 offset0:48 offset1:52
	ds_read2_b32 v[232:233], v243 offset0:56 offset1:60
	s_waitcnt lgkmcnt(0)
; __device__ __forceinline__ void peer_token(const Params& P, int t, int lane, int* sidx, float* sval, const int* sid, const float* sgate, const unsigned* szero) {
;     ...
;         for (int hh = 0; hh < 2; ++hh) off2[hh] = (unsigned)sid[8 * hh + (lr & 7)] * 512u + lofs;
; #pragma unroll
;         for (int hh = 0; hh < 2; ++hh)
; #pragma unroll
;             for (int st = 0; st < 4; ++st) abuf[0][hh][st] = *(const uint4*)(Ub + (off2[hh] + 128 * st));
; #pragma unroll
;         for (int T = 0; T < 8; ++T) {
;             if (T + 1 < 8) {
; #pragma unroll
;                 for (int hh = 0; hh < 2; ++hh) off2[hh] = (unsigned)sid[16 * (T + 1) + 8 * hh + (lr & 7)] * 512u + lofs;
; #pragma unroll
;                 for (int hh = 0; hh < 2; ++hh)
; #pragma unroll
;                     for (int st = 0; st < 4; ++st) abuf[(T + 1) & 1][hh][st] = *(const uint4*)(Ub + (off2[hh] + 128 * st));
;             }
; #pragma unroll
;             for (int hh = 0; hh < 2; ++hh) {
;                 f32x4 au = (f32x4){0.f, 0.f, 0.f, 0.f};
; #pragma unroll
;                 for (int st = 0; st < 4; ++st) {
;                     const uint4 a4 = abuf[T & 1][hh][st];
;                     const v8i Av = {(int)a4.x, (int)a4.y, (int)a4.z, (int)a4.w, 0, 0, 0, 0};
;                     au = __builtin_amdgcn_mfma_scale_f32_16x16x128_f8f6f4(Av, Bv[st], au, 4, 0, 0, 0x7f7f7f7f, 0, 0x7f7f7f7f);
;                 }
;                 if (owner) *(f32x4*)(sact + 16 * T + 8 * hh) = au;
;             }
	v_lshl_add_u32 v230, v230, 9, v144
	v_lshl_add_u32 v231, v231, 9, v144
	v_lshl_add_u32 v232, v232, 9, v144
	v_lshl_add_u32 v233, v233, 9, v144
	global_load_dwordx4 v[32:35], v230, s[10:11]
	global_load_dwordx4 v[36:39], v230, s[10:11] offset:256
	global_load_dwordx4 v[40:43], v231, s[10:11]
	global_load_dwordx4 v[44:47], v231, s[10:11] offset:256
	global_load_dwordx4 v[48:51], v232, s[10:11]
	global_load_dwordx4 v[52:55], v232, s[10:11] offset:256
	global_load_dwordx4 v[56:59], v233, s[10:11]
	global_load_dwordx4 v[60:63], v233, s[10:11] offset:256
	s_waitcnt vmcnt(8)
	v_mfma_scale_f32_16x16x128_f8f6f4 v[64:67], v[0:3], v[162:169], 0, v133, v133 op_sel_hi:[0,0,0] cbsz:4
	v_mfma_scale_f32_16x16x128_f8f6f4 v[64:67], v[4:7], v[170:177], v[64:67], v133, v133 op_sel_hi:[0,0,0] cbsz:4
	v_mfma_scale_f32_16x16x128_f8f6f4 v[68:71], v[8:11], v[162:169], 0, v133, v133 op_sel_hi:[0,0,0] cbsz:4
	v_mfma_scale_f32_16x16x128_f8f6f4 v[68:71], v[12:15], v[170:177], v[68:71], v133, v133 op_sel_hi:[0,0,0] cbsz:4
	v_mfma_scale_f32_16x16x128_f8f6f4 v[72:75], v[16:19], v[162:169], 0, v133, v133 op_sel_hi:[0,0,0] cbsz:4
	v_mfma_scale_f32_16x16x128_f8f6f4 v[72:75], v[20:23], v[170:177], v[72:75], v133, v133 op_sel_hi:[0,0,0] cbsz:4
	v_mfma_scale_f32_16x16x128_f8f6f4 v[76:79], v[24:27], v[162:169], 0, v133, v133 op_sel_hi:[0,0,0] cbsz:4
	v_mfma_scale_f32_16x16x128_f8f6f4 v[76:79], v[28:31], v[170:177], v[76:79], v133, v133 op_sel_hi:[0,0,0] cbsz:4
	s_nop 3
	v_mul_f32_e32 v234, v158, v80
	v_mul_f32_e32 v235, v158, v84
	v_mul_f32_e32 v236, v158, v88
	v_mul_f32_e32 v237, v158, v92
	v_fmac_f32_e32 v234, v159, v81
	v_fmac_f32_e32 v235, v159, v85
	v_fmac_f32_e32 v236, v159, v89
	v_fmac_f32_e32 v237, v159, v93
	v_fmac_f32_e32 v234, v160, v82
	v_fmac_f32_e32 v235, v160, v86
	v_fmac_f32_e32 v236, v160, v90
	v_fmac_f32_e32 v237, v160, v94
	v_fmac_f32_e32 v234, v161, v83
	v_fmac_f32_e32 v235, v161, v87
	v_fmac_f32_e32 v236, v161, v91
	v_fmac_f32_e32 v237, v161, v95
	v_add_f32_dpp v234, v234, v234 quad_perm:[1,0,3,2] row_mask:0xf bank_mask:0xf
	v_add_f32_dpp v235, v235, v235 quad_perm:[1,0,3,2] row_mask:0xf bank_mask:0xf
	v_add_f32_dpp v236, v236, v236 quad_perm:[1,0,3,2] row_mask:0xf bank_mask:0xf
	v_add_f32_dpp v237, v237, v237 quad_perm:[1,0,3,2] row_mask:0xf bank_mask:0xf
	v_add_f32_dpp v234, v234, v234 quad_perm:[2,3,0,1] row_mask:0xf bank_mask:0xf
	v_add_f32_dpp v235, v235, v235 quad_perm:[2,3,0,1] row_mask:0xf bank_mask:0xf
	v_add_f32_dpp v236, v236, v236 quad_perm:[2,3,0,1] row_mask:0xf bank_mask:0xf
	v_add_f32_dpp v237, v237, v237 quad_perm:[2,3,0,1] row_mask:0xf bank_mask:0xf
	v_add_f32_dpp v234, v234, v234 row_half_mirror row_mask:0xf bank_mask:0xf
	v_add_f32_dpp v235, v235, v235 row_half_mirror row_mask:0xf bank_mask:0xf
	v_add_f32_dpp v236, v236, v236 row_half_mirror row_mask:0xf bank_mask:0xf
	v_add_f32_dpp v237, v237, v237 row_half_mirror row_mask:0xf bank_mask:0xf
	s_mov_b32 exec_lo, 0x10001
	s_mov_b32 exec_hi, 0x10001
	ds_write_b32 v155, v234 offset:1728
	ds_write_b32 v155, v235 offset:1744
	ds_write_b32 v155, v236 offset:1760
	ds_write_b32 v155, v237 offset:1776
	s_mov_b64 exec, -1
	ds_read2_b32 v[96:97], v244 offset0:48 offset1:52
	ds_read2_b32 v[98:99], v244 offset0:56 offset1:60
	s_waitcnt lgkmcnt(0)
	v_lshl_add_u32 v96, v96, 9, v144
	v_lshl_add_u32 v97, v97, 9, v144
	v_lshl_add_u32 v98, v98, 9, v144
	v_lshl_add_u32 v99, v99, 9, v144
	global_load_dwordx4 v[0:3], v96, s[10:11]
	global_load_dwordx4 v[4:7], v96, s[10:11] offset:256
	global_load_dwordx4 v[8:11], v97, s[10:11]
	global_load_dwordx4 v[12:15], v97, s[10:11] offset:256
	global_load_dwordx4 v[16:19], v98, s[10:11]
	global_load_dwordx4 v[20:23], v98, s[10:11] offset:256
	global_load_dwordx4 v[24:27], v99, s[10:11]
	global_load_dwordx4 v[28:31], v99, s[10:11] offset:256
	s_waitcnt vmcnt(8)
	v_mfma_scale_f32_16x16x128_f8f6f4 v[80:83], v[32:35], v[178:185], 0, v133, v133 op_sel_hi:[0,0,0] cbsz:4
	v_mfma_scale_f32_16x16x128_f8f6f4 v[80:83], v[36:39], v[186:193], v[80:83], v133, v133 op_sel_hi:[0,0,0] cbsz:4
	v_mfma_scale_f32_16x16x128_f8f6f4 v[84:87], v[40:43], v[178:185], 0, v133, v133 op_sel_hi:[0,0,0] cbsz:4
	v_mfma_scale_f32_16x16x128_f8f6f4 v[84:87], v[44:47], v[186:193], v[84:87], v133, v133 op_sel_hi:[0,0,0] cbsz:4
	v_mfma_scale_f32_16x16x128_f8f6f4 v[88:91], v[48:51], v[178:185], 0, v133, v133 op_sel_hi:[0,0,0] cbsz:4
	v_mfma_scale_f32_16x16x128_f8f6f4 v[88:91], v[52:55], v[186:193], v[88:91], v133, v133 op_sel_hi:[0,0,0] cbsz:4
	v_mfma_scale_f32_16x16x128_f8f6f4 v[92:95], v[56:59], v[178:185], 0, v133, v133 op_sel_hi:[0,0,0] cbsz:4
	v_mfma_scale_f32_16x16x128_f8f6f4 v[92:95], v[60:63], v[186:193], v[92:95], v133, v133 op_sel_hi:[0,0,0] cbsz:4
	s_nop 3
	v_mul_f32_e32 v234, v226, v64
	v_mul_f32_e32 v235, v226, v68
	v_mul_f32_e32 v236, v226, v72
	v_mul_f32_e32 v237, v226, v76
	v_fmac_f32_e32 v234, v227, v65
	v_fmac_f32_e32 v235, v227, v69
	v_fmac_f32_e32 v236, v227, v73
	v_fmac_f32_e32 v237, v227, v77
	v_fmac_f32_e32 v234, v228, v66
	v_fmac_f32_e32 v235, v228, v70
	v_fmac_f32_e32 v236, v228, v74
	v_fmac_f32_e32 v237, v228, v78
	v_fmac_f32_e32 v234, v229, v67
	v_fmac_f32_e32 v235, v229, v71
	v_fmac_f32_e32 v236, v229, v75
	v_fmac_f32_e32 v237, v229, v79
	v_add_f32_dpp v234, v234, v234 quad_perm:[1,0,3,2] row_mask:0xf bank_mask:0xf
	v_add_f32_dpp v235, v235, v235 quad_perm:[1,0,3,2] row_mask:0xf bank_mask:0xf
	v_add_f32_dpp v236, v236, v236 quad_perm:[1,0,3,2] row_mask:0xf bank_mask:0xf
	v_add_f32_dpp v237, v237, v237 quad_perm:[1,0,3,2] row_mask:0xf bank_mask:0xf
	v_add_f32_dpp v234, v234, v234 quad_perm:[2,3,0,1] row_mask:0xf bank_mask:0xf
	v_add_f32_dpp v235, v235, v235 quad_perm:[2,3,0,1] row_mask:0xf bank_mask:0xf
	v_add_f32_dpp v236, v236, v236 quad_perm:[2,3,0,1] row_mask:0xf bank_mask:0xf
	v_add_f32_dpp v237, v237, v237 quad_perm:[2,3,0,1] row_mask:0xf bank_mask:0xf
	v_add_f32_dpp v234, v234, v234 row_half_mirror row_mask:0xf bank_mask:0xf
	v_add_f32_dpp v235, v235, v235 row_half_mirror row_mask:0xf bank_mask:0xf
	v_add_f32_dpp v236, v236, v236 row_half_mirror row_mask:0xf bank_mask:0xf
	v_add_f32_dpp v237, v237, v237 row_half_mirror row_mask:0xf bank_mask:0xf
	s_mov_b32 exec_lo, 0x1000100
	s_mov_b32 exec_hi, 0x1000100
	ds_write_b32 v155, v234 offset:2240
	ds_write_b32 v155, v235 offset:2256
	ds_write_b32 v155, v236 offset:2272
	ds_write_b32 v155, v237 offset:2288
	s_mov_b64 exec, -1
	ds_read2_b32 v[230:231], v245 offset0:48 offset1:52
	ds_read2_b32 v[232:233], v245 offset0:56 offset1:60
	s_waitcnt lgkmcnt(0)
; __device__ __forceinline__ void peer_token(const Params& P, int t, int lane, int* sidx, float* sval, const int* sid, const float* sgate, const unsigned* szero) {
;     ...
;         for (int hh = 0; hh < 2; ++hh) off2[hh] = (unsigned)sid[8 * hh + (lr & 7)] * 512u + lofs;
; #pragma unroll
;         for (int hh = 0; hh < 2; ++hh)
; #pragma unroll
;             for (int st = 0; st < 4; ++st) abuf[0][hh][st] = *(const uint4*)(Ub + (off2[hh] + 128 * st));
; #pragma unroll
;         for (int T = 0; T < 8; ++T) {
;             if (T + 1 < 8) {
; #pragma unroll
;                 for (int hh = 0; hh < 2; ++hh) off2[hh] = (unsigned)sid[16 * (T + 1) + 8 * hh + (lr & 7)] * 512u + lofs;
; #pragma unroll
;                 for (int hh = 0; hh < 2; ++hh)
; #pragma unroll
;                     for (int st = 0; st < 4; ++st) abuf[(T + 1) & 1][hh][st] = *(const uint4*)(Ub + (off2[hh] + 128 * st));
;             }
; #pragma unroll
;             for (int hh = 0; hh < 2; ++hh) {
;                 f32x4 au = (f32x4){0.f, 0.f, 0.f, 0.f};
; #pragma unroll
;                 for (int st = 0; st < 4; ++st) {
;                     const uint4 a4 = abuf[T & 1][hh][st];
;                     const v8i Av = {(int)a4.x, (int)a4.y, (int)a4.z, (int)a4.w, 0, 0, 0, 0};
;                     au = __builtin_amdgcn_mfma_scale_f32_16x16x128_f8f6f4(Av, Bv[st], au, 4, 0, 0, 0x7f7f7f7f, 0, 0x7f7f7f7f);
;                 }
;                 if (owner) *(f32x4*)(sact + 16 * T + 8 * hh) = au;
;             }
	v_lshl_add_u32 v230, v230, 9, v144
	v_lshl_add_u32 v231, v231, 9, v144
	v_lshl_add_u32 v232, v232, 9, v144
	v_lshl_add_u32 v233, v233, 9, v144
	global_load_dwordx4 v[32:35], v230, s[10:11]
	global_load_dwordx4 v[36:39], v230, s[10:11] offset:256
	global_load_dwordx4 v[40:43], v231, s[10:11]
	global_load_dwordx4 v[44:47], v231, s[10:11] offset:256
	global_load_dwordx4 v[48:51], v232, s[10:11]
	global_load_dwordx4 v[52:55], v232, s[10:11] offset:256
	global_load_dwordx4 v[56:59], v233, s[10:11]
	global_load_dwordx4 v[60:63], v233, s[10:11] offset:256
	s_waitcnt vmcnt(8)
	v_mfma_scale_f32_16x16x128_f8f6f4 v[64:67], v[0:3], v[194:201], 0, v133, v133 op_sel_hi:[0,0,0] cbsz:4
	v_mfma_scale_f32_16x16x128_f8f6f4 v[64:67], v[4:7], v[202:209], v[64:67], v133, v133 op_sel_hi:[0,0,0] cbsz:4
	v_mfma_scale_f32_16x16x128_f8f6f4 v[68:71], v[8:11], v[194:201], 0, v133, v133 op_sel_hi:[0,0,0] cbsz:4
	v_mfma_scale_f32_16x16x128_f8f6f4 v[68:71], v[12:15], v[202:209], v[68:71], v133, v133 op_sel_hi:[0,0,0] cbsz:4
	v_mfma_scale_f32_16x16x128_f8f6f4 v[72:75], v[16:19], v[194:201], 0, v133, v133 op_sel_hi:[0,0,0] cbsz:4
	v_mfma_scale_f32_16x16x128_f8f6f4 v[72:75], v[20:23], v[202:209], v[72:75], v133, v133 op_sel_hi:[0,0,0] cbsz:4
	v_mfma_scale_f32_16x16x128_f8f6f4 v[76:79], v[24:27], v[194:201], 0, v133, v133 op_sel_hi:[0,0,0] cbsz:4
	v_mfma_scale_f32_16x16x128_f8f6f4 v[76:79], v[28:31], v[202:209], v[76:79], v133, v133 op_sel_hi:[0,0,0] cbsz:4
	s_nop 3
	v_mul_f32_e32 v234, v226, v80
	v_mul_f32_e32 v235, v226, v84
	v_mul_f32_e32 v236, v226, v88
	v_mul_f32_e32 v237, v226, v92
	v_fmac_f32_e32 v234, v227, v81
	v_fmac_f32_e32 v235, v227, v85
	v_fmac_f32_e32 v236, v227, v89
	v_fmac_f32_e32 v237, v227, v93
	v_fmac_f32_e32 v234, v228, v82
	v_fmac_f32_e32 v235, v228, v86
	v_fmac_f32_e32 v236, v228, v90
	v_fmac_f32_e32 v237, v228, v94
	v_fmac_f32_e32 v234, v229, v83
	v_fmac_f32_e32 v235, v229, v87
	v_fmac_f32_e32 v236, v229, v91
	v_fmac_f32_e32 v237, v229, v95
	v_add_f32_dpp v234, v234, v234 quad_perm:[1,0,3,2] row_mask:0xf bank_mask:0xf
	v_add_f32_dpp v235, v235, v235 quad_perm:[1,0,3,2] row_mask:0xf bank_mask:0xf
	v_add_f32_dpp v236, v236, v236 quad_perm:[1,0,3,2] row_mask:0xf bank_mask:0xf
	v_add_f32_dpp v237, v237, v237 quad_perm:[1,0,3,2] row_mask:0xf bank_mask:0xf
	v_add_f32_dpp v234, v234, v234 quad_perm:[2,3,0,1] row_mask:0xf bank_mask:0xf
	v_add_f32_dpp v235, v235, v235 quad_perm:[2,3,0,1] row_mask:0xf bank_mask:0xf
	v_add_f32_dpp v236, v236, v236 quad_perm:[2,3,0,1] row_mask:0xf bank_mask:0xf
	v_add_f32_dpp v237, v237, v237 quad_perm:[2,3,0,1] row_mask:0xf bank_mask:0xf
	v_add_f32_dpp v234, v234, v234 row_half_mirror row_mask:0xf bank_mask:0xf
	v_add_f32_dpp v235, v235, v235 row_half_mirror row_mask:0xf bank_mask:0xf
	v_add_f32_dpp v236, v236, v236 row_half_mirror row_mask:0xf bank_mask:0xf
	v_add_f32_dpp v237, v237, v237 row_half_mirror row_mask:0xf bank_mask:0xf
	s_mov_b32 exec_lo, 0x1000100
	s_mov_b32 exec_hi, 0x1000100
	ds_write_b32 v155, v234 offset:2752
	ds_write_b32 v155, v235 offset:2768
	ds_write_b32 v155, v236 offset:2784
	ds_write_b32 v155, v237 offset:2800
	s_mov_b64 exec, -1
	ds_read2_b32 v[96:97], v238 offset0:64 offset1:68
	ds_read2_b32 v[98:99], v238 offset0:72 offset1:76
	s_waitcnt lgkmcnt(0)
	v_lshl_add_u32 v96, v96, 9, v144
	v_lshl_add_u32 v97, v97, 9, v144
	v_lshl_add_u32 v98, v98, 9, v144
	v_lshl_add_u32 v99, v99, 9, v144
	global_load_dwordx4 v[0:3], v96, s[10:11]
	global_load_dwordx4 v[4:7], v96, s[10:11] offset:256
	global_load_dwordx4 v[8:11], v97, s[10:11]
	global_load_dwordx4 v[12:15], v97, s[10:11] offset:256
	global_load_dwordx4 v[16:19], v98, s[10:11]
	global_load_dwordx4 v[20:23], v98, s[10:11] offset:256
	global_load_dwordx4 v[24:27], v99, s[10:11]
	global_load_dwordx4 v[28:31], v99, s[10:11] offset:256
	s_waitcnt vmcnt(8)
	v_mfma_scale_f32_16x16x128_f8f6f4 v[80:83], v[32:35], v[210:217], 0, v133, v133 op_sel_hi:[0,0,0] cbsz:4
	v_mfma_scale_f32_16x16x128_f8f6f4 v[80:83], v[36:39], v[218:225], v[80:83], v133, v133 op_sel_hi:[0,0,0] cbsz:4
	v_mfma_scale_f32_16x16x128_f8f6f4 v[84:87], v[40:43], v[210:217], 0, v133, v133 op_sel_hi:[0,0,0] cbsz:4
	v_mfma_scale_f32_16x16x128_f8f6f4 v[84:87], v[44:47], v[218:225], v[84:87], v133, v133 op_sel_hi:[0,0,0] cbsz:4
	v_mfma_scale_f32_16x16x128_f8f6f4 v[88:91], v[48:51], v[210:217], 0, v133, v133 op_sel_hi:[0,0,0] cbsz:4
	v_mfma_scale_f32_16x16x128_f8f6f4 v[88:91], v[52:55], v[218:225], v[88:91], v133, v133 op_sel_hi:[0,0,0] cbsz:4
	v_mfma_scale_f32_16x16x128_f8f6f4 v[92:95], v[56:59], v[210:217], 0, v133, v133 op_sel_hi:[0,0,0] cbsz:4
	v_mfma_scale_f32_16x16x128_f8f6f4 v[92:95], v[60:63], v[218:225], v[92:95], v133, v133 op_sel_hi:[0,0,0] cbsz:4
	s_nop 3
	v_mul_f32_e32 v234, v226, v64
	v_mul_f32_e32 v235, v226, v68
	v_mul_f32_e32 v236, v226, v72
	v_mul_f32_e32 v237, v226, v76
	v_fmac_f32_e32 v234, v227, v65
	v_fmac_f32_e32 v235, v227, v69
	v_fmac_f32_e32 v236, v227, v73
	v_fmac_f32_e32 v237, v227, v77
	v_fmac_f32_e32 v234, v228, v66
	v_fmac_f32_e32 v235, v228, v70
	v_fmac_f32_e32 v236, v228, v74
	v_fmac_f32_e32 v237, v228, v78
	v_fmac_f32_e32 v234, v229, v67
	v_fmac_f32_e32 v235, v229, v71
	v_fmac_f32_e32 v236, v229, v75
	v_fmac_f32_e32 v237, v229, v79
	v_add_f32_dpp v234, v234, v234 quad_perm:[1,0,3,2] row_mask:0xf bank_mask:0xf
	v_add_f32_dpp v235, v235, v235 quad_perm:[1,0,3,2] row_mask:0xf bank_mask:0xf
	v_add_f32_dpp v236, v236, v236 quad_perm:[1,0,3,2] row_mask:0xf bank_mask:0xf
	v_add_f32_dpp v237, v237, v237 quad_perm:[1,0,3,2] row_mask:0xf bank_mask:0xf
	v_add_f32_dpp v234, v234, v234 quad_perm:[2,3,0,1] row_mask:0xf bank_mask:0xf
	v_add_f32_dpp v235, v235, v235 quad_perm:[2,3,0,1] row_mask:0xf bank_mask:0xf
	v_add_f32_dpp v236, v236, v236 quad_perm:[2,3,0,1] row_mask:0xf bank_mask:0xf
	v_add_f32_dpp v237, v237, v237 quad_perm:[2,3,0,1] row_mask:0xf bank_mask:0xf
	v_add_f32_dpp v234, v234, v234 row_half_mirror row_mask:0xf bank_mask:0xf
	v_add_f32_dpp v235, v235, v235 row_half_mirror row_mask:0xf bank_mask:0xf
	v_add_f32_dpp v236, v236, v236 row_half_mirror row_mask:0xf bank_mask:0xf
	v_add_f32_dpp v237, v237, v237 row_half_mirror row_mask:0xf bank_mask:0xf
	s_mov_b32 exec_lo, 0x1000100
	s_mov_b32 exec_hi, 0x1000100
	ds_write_b32 v155, v234 offset:3264
	ds_write_b32 v155, v235 offset:3280
	ds_write_b32 v155, v236 offset:3296
	ds_write_b32 v155, v237 offset:3312
	s_mov_b64 exec, -1
	ds_read2_b32 v[230:231], v239 offset0:64 offset1:68
	ds_read2_b32 v[232:233], v239 offset0:72 offset1:76
	s_waitcnt lgkmcnt(0)
; __device__ __forceinline__ void peer_token(const Params& P, int t, int lane, int* sidx, float* sval, const int* sid, const float* sgate, const unsigned* szero) {
;     ...
;         for (int hh = 0; hh < 2; ++hh) off2[hh] = (unsigned)sid[8 * hh + (lr & 7)] * 512u + lofs;
; #pragma unroll
;         for (int hh = 0; hh < 2; ++hh)
; #pragma unroll
;             for (int st = 0; st < 4; ++st) abuf[0][hh][st] = *(const uint4*)(Ub + (off2[hh] + 128 * st));
; #pragma unroll
;         for (int T = 0; T < 8; ++T) {
;             if (T + 1 < 8) {
; #pragma unroll
;                 for (int hh = 0; hh < 2; ++hh) off2[hh] = (unsigned)sid[16 * (T + 1) + 8 * hh + (lr & 7)] * 512u + lofs;
; #pragma unroll
;                 for (int hh = 0; hh < 2; ++hh)
; #pragma unroll
;                     for (int st = 0; st < 4; ++st) abuf[(T + 1) & 1][hh][st] = *(const uint4*)(Ub + (off2[hh] + 128 * st));
;             }
; #pragma unroll
;             for (int hh = 0; hh < 2; ++hh) {
;                 f32x4 au = (f32x4){0.f, 0.f, 0.f, 0.f};
; #pragma unroll
;                 for (int st = 0; st < 4; ++st) {
;                     const uint4 a4 = abuf[T & 1][hh][st];
;                     const v8i Av = {(int)a4.x, (int)a4.y, (int)a4.z, (int)a4.w, 0, 0, 0, 0};
;                     au = __builtin_amdgcn_mfma_scale_f32_16x16x128_f8f6f4(Av, Bv[st], au, 4, 0, 0, 0x7f7f7f7f, 0, 0x7f7f7f7f);
;                 }
;                 if (owner) *(f32x4*)(sact + 16 * T + 8 * hh) = au;
;             }
	v_lshl_add_u32 v230, v230, 9, v144
	v_lshl_add_u32 v231, v231, 9, v144
	v_lshl_add_u32 v232, v232, 9, v144
	v_lshl_add_u32 v233, v233, 9, v144
	global_load_dwordx4 v[32:35], v230, s[10:11]
	global_load_dwordx4 v[36:39], v230, s[10:11] offset:256
	global_load_dwordx4 v[40:43], v231, s[10:11]
	global_load_dwordx4 v[44:47], v231, s[10:11] offset:256
	global_load_dwordx4 v[48:51], v232, s[10:11]
	global_load_dwordx4 v[52:55], v232, s[10:11] offset:256
	global_load_dwordx4 v[56:59], v233, s[10:11]
	global_load_dwordx4 v[60:63], v233, s[10:11] offset:256
	s_waitcnt vmcnt(8)
	v_mfma_scale_f32_16x16x128_f8f6f4 v[64:67], v[0:3], v[162:169], 0, v133, v133 op_sel_hi:[0,0,0] cbsz:4
	v_mfma_scale_f32_16x16x128_f8f6f4 v[64:67], v[4:7], v[170:177], v[64:67], v133, v133 op_sel_hi:[0,0,0] cbsz:4
	v_mfma_scale_f32_16x16x128_f8f6f4 v[68:71], v[8:11], v[162:169], 0, v133, v133 op_sel_hi:[0,0,0] cbsz:4
	v_mfma_scale_f32_16x16x128_f8f6f4 v[68:71], v[12:15], v[170:177], v[68:71], v133, v133 op_sel_hi:[0,0,0] cbsz:4
	v_mfma_scale_f32_16x16x128_f8f6f4 v[72:75], v[16:19], v[162:169], 0, v133, v133 op_sel_hi:[0,0,0] cbsz:4
	v_mfma_scale_f32_16x16x128_f8f6f4 v[72:75], v[20:23], v[170:177], v[72:75], v133, v133 op_sel_hi:[0,0,0] cbsz:4
	v_mfma_scale_f32_16x16x128_f8f6f4 v[76:79], v[24:27], v[162:169], 0, v133, v133 op_sel_hi:[0,0,0] cbsz:4
	v_mfma_scale_f32_16x16x128_f8f6f4 v[76:79], v[28:31], v[170:177], v[76:79], v133, v133 op_sel_hi:[0,0,0] cbsz:4
	s_nop 3
	v_mul_f32_e32 v234, v226, v80
	v_mul_f32_e32 v235, v226, v84
	v_mul_f32_e32 v236, v226, v88
	v_mul_f32_e32 v237, v226, v92
	v_fmac_f32_e32 v234, v227, v81
	v_fmac_f32_e32 v235, v227, v85
	v_fmac_f32_e32 v236, v227, v89
	v_fmac_f32_e32 v237, v227, v93
	v_fmac_f32_e32 v234, v228, v82
	v_fmac_f32_e32 v235, v228, v86
	v_fmac_f32_e32 v236, v228, v90
	v_fmac_f32_e32 v237, v228, v94
	v_fmac_f32_e32 v234, v229, v83
	v_fmac_f32_e32 v235, v229, v87
	v_fmac_f32_e32 v236, v229, v91
	v_fmac_f32_e32 v237, v229, v95
	v_add_f32_dpp v234, v234, v234 quad_perm:[1,0,3,2] row_mask:0xf bank_mask:0xf
	v_add_f32_dpp v235, v235, v235 quad_perm:[1,0,3,2] row_mask:0xf bank_mask:0xf
	v_add_f32_dpp v236, v236, v236 quad_perm:[1,0,3,2] row_mask:0xf bank_mask:0xf
	v_add_f32_dpp v237, v237, v237 quad_perm:[1,0,3,2] row_mask:0xf bank_mask:0xf
	v_add_f32_dpp v234, v234, v234 quad_perm:[2,3,0,1] row_mask:0xf bank_mask:0xf
	v_add_f32_dpp v235, v235, v235 quad_perm:[2,3,0,1] row_mask:0xf bank_mask:0xf
	v_add_f32_dpp v236, v236, v236 quad_perm:[2,3,0,1] row_mask:0xf bank_mask:0xf
	v_add_f32_dpp v237, v237, v237 quad_perm:[2,3,0,1] row_mask:0xf bank_mask:0xf
	v_add_f32_dpp v234, v234, v234 row_half_mirror row_mask:0xf bank_mask:0xf
	v_add_f32_dpp v235, v235, v235 row_half_mirror row_mask:0xf bank_mask:0xf
	v_add_f32_dpp v236, v236, v236 row_half_mirror row_mask:0xf bank_mask:0xf
	v_add_f32_dpp v237, v237, v237 row_half_mirror row_mask:0xf bank_mask:0xf
	s_mov_b32 exec_lo, 0x1000100
	s_mov_b32 exec_hi, 0x1000100
	ds_write_b32 v155, v234 offset:3776
	ds_write_b32 v155, v235 offset:3792
	ds_write_b32 v155, v236 offset:3808
	ds_write_b32 v155, v237 offset:3824
	s_mov_b64 exec, -1
	ds_read2_b32 v[96:97], v240 offset0:64 offset1:68
	ds_read2_b32 v[98:99], v240 offset0:72 offset1:76
	s_waitcnt lgkmcnt(0)
	v_lshl_add_u32 v96, v96, 9, v144
	v_lshl_add_u32 v97, v97, 9, v144
	v_lshl_add_u32 v98, v98, 9, v144
	v_lshl_add_u32 v99, v99, 9, v144
	global_load_dwordx4 v[0:3], v96, s[10:11]
	global_load_dwordx4 v[4:7], v96, s[10:11] offset:256
	global_load_dwordx4 v[8:11], v97, s[10:11]
	global_load_dwordx4 v[12:15], v97, s[10:11] offset:256
	global_load_dwordx4 v[16:19], v98, s[10:11]
	global_load_dwordx4 v[20:23], v98, s[10:11] offset:256
	global_load_dwordx4 v[24:27], v99, s[10:11]
	global_load_dwordx4 v[28:31], v99, s[10:11] offset:256
	s_waitcnt vmcnt(8)
	v_mfma_scale_f32_16x16x128_f8f6f4 v[80:83], v[32:35], v[178:185], 0, v133, v133 op_sel_hi:[0,0,0] cbsz:4
	v_mfma_scale_f32_16x16x128_f8f6f4 v[80:83], v[36:39], v[186:193], v[80:83], v133, v133 op_sel_hi:[0,0,0] cbsz:4
	v_mfma_scale_f32_16x16x128_f8f6f4 v[84:87], v[40:43], v[178:185], 0, v133, v133 op_sel_hi:[0,0,0] cbsz:4
	v_mfma_scale_f32_16x16x128_f8f6f4 v[84:87], v[44:47], v[186:193], v[84:87], v133, v133 op_sel_hi:[0,0,0] cbsz:4
	v_mfma_scale_f32_16x16x128_f8f6f4 v[88:91], v[48:51], v[178:185], 0, v133, v133 op_sel_hi:[0,0,0] cbsz:4
	v_mfma_scale_f32_16x16x128_f8f6f4 v[88:91], v[52:55], v[186:193], v[88:91], v133, v133 op_sel_hi:[0,0,0] cbsz:4
	v_mfma_scale_f32_16x16x128_f8f6f4 v[92:95], v[56:59], v[178:185], 0, v133, v133 op_sel_hi:[0,0,0] cbsz:4
	v_mfma_scale_f32_16x16x128_f8f6f4 v[92:95], v[60:63], v[186:193], v[92:95], v133, v133 op_sel_hi:[0,0,0] cbsz:4
	s_nop 3
	v_mul_f32_e32 v234, v158, v64
	v_mul_f32_e32 v235, v158, v68
	v_mul_f32_e32 v236, v158, v72
	v_mul_f32_e32 v237, v158, v76
	v_fmac_f32_e32 v234, v159, v65
	v_fmac_f32_e32 v235, v159, v69
	v_fmac_f32_e32 v236, v159, v73
	v_fmac_f32_e32 v237, v159, v77
	v_fmac_f32_e32 v234, v160, v66
	v_fmac_f32_e32 v235, v160, v70
	v_fmac_f32_e32 v236, v160, v74
	v_fmac_f32_e32 v237, v160, v78
	v_fmac_f32_e32 v234, v161, v67
	v_fmac_f32_e32 v235, v161, v71
	v_fmac_f32_e32 v236, v161, v75
	v_fmac_f32_e32 v237, v161, v79
	v_add_f32_dpp v234, v234, v234 quad_perm:[1,0,3,2] row_mask:0xf bank_mask:0xf
	v_add_f32_dpp v235, v235, v235 quad_perm:[1,0,3,2] row_mask:0xf bank_mask:0xf
	v_add_f32_dpp v236, v236, v236 quad_perm:[1,0,3,2] row_mask:0xf bank_mask:0xf
	v_add_f32_dpp v237, v237, v237 quad_perm:[1,0,3,2] row_mask:0xf bank_mask:0xf
	v_add_f32_dpp v234, v234, v234 quad_perm:[2,3,0,1] row_mask:0xf bank_mask:0xf
	v_add_f32_dpp v235, v235, v235 quad_perm:[2,3,0,1] row_mask:0xf bank_mask:0xf
	v_add_f32_dpp v236, v236, v236 quad_perm:[2,3,0,1] row_mask:0xf bank_mask:0xf
	v_add_f32_dpp v237, v237, v237 quad_perm:[2,3,0,1] row_mask:0xf bank_mask:0xf
	v_add_f32_dpp v234, v234, v234 row_half_mirror row_mask:0xf bank_mask:0xf
	v_add_f32_dpp v235, v235, v235 row_half_mirror row_mask:0xf bank_mask:0xf
	v_add_f32_dpp v236, v236, v236 row_half_mirror row_mask:0xf bank_mask:0xf
	v_add_f32_dpp v237, v237, v237 row_half_mirror row_mask:0xf bank_mask:0xf
	s_mov_b32 exec_lo, 0x10001
	s_mov_b32 exec_hi, 0x10001
	ds_write_b32 v155, v234 offset:256
	ds_write_b32 v155, v235 offset:272
	ds_write_b32 v155, v236 offset:288
	ds_write_b32 v155, v237 offset:304
	s_mov_b64 exec, -1
	ds_read2_b32 v[230:231], v241 offset0:64 offset1:68
	ds_read2_b32 v[232:233], v241 offset0:72 offset1:76
	s_waitcnt lgkmcnt(0)
; __device__ __forceinline__ void peer_token(const Params& P, int t, int lane, int* sidx, float* sval, const int* sid, const float* sgate, const unsigned* szero) {
;     ...
;         for (int hh = 0; hh < 2; ++hh) off2[hh] = (unsigned)sid[8 * hh + (lr & 7)] * 512u + lofs;
; #pragma unroll
;         for (int hh = 0; hh < 2; ++hh)
; #pragma unroll
;             for (int st = 0; st < 4; ++st) abuf[0][hh][st] = *(const uint4*)(Ub + (off2[hh] + 128 * st));
; #pragma unroll
;         for (int T = 0; T < 8; ++T) {
;             if (T + 1 < 8) {
; #pragma unroll
;                 for (int hh = 0; hh < 2; ++hh) off2[hh] = (unsigned)sid[16 * (T + 1) + 8 * hh + (lr & 7)] * 512u + lofs;
; #pragma unroll
;                 for (int hh = 0; hh < 2; ++hh)
; #pragma unroll
;                     for (int st = 0; st < 4; ++st) abuf[(T + 1) & 1][hh][st] = *(const uint4*)(Ub + (off2[hh] + 128 * st));
;             }
; #pragma unroll
;             for (int hh = 0; hh < 2; ++hh) {
;                 f32x4 au = (f32x4){0.f, 0.f, 0.f, 0.f};
; #pragma unroll
;                 for (int st = 0; st < 4; ++st) {
;                     const uint4 a4 = abuf[T & 1][hh][st];
;                     const v8i Av = {(int)a4.x, (int)a4.y, (int)a4.z, (int)a4.w, 0, 0, 0, 0};
;                     au = __builtin_amdgcn_mfma_scale_f32_16x16x128_f8f6f4(Av, Bv[st], au, 4, 0, 0, 0x7f7f7f7f, 0, 0x7f7f7f7f);
;                 }
;                 if (owner) *(f32x4*)(sact + 16 * T + 8 * hh) = au;
;             }
	v_lshl_add_u32 v230, v230, 9, v144
	v_lshl_add_u32 v231, v231, 9, v144
	v_lshl_add_u32 v232, v232, 9, v144
	v_lshl_add_u32 v233, v233, 9, v144
	global_load_dwordx4 v[32:35], v230, s[10:11]
	global_load_dwordx4 v[36:39], v230, s[10:11] offset:256
	global_load_dwordx4 v[40:43], v231, s[10:11]
	global_load_dwordx4 v[44:47], v231, s[10:11] offset:256
	global_load_dwordx4 v[48:51], v232, s[10:11]
	global_load_dwordx4 v[52:55], v232, s[10:11] offset:256
	global_load_dwordx4 v[56:59], v233, s[10:11]
	global_load_dwordx4 v[60:63], v233, s[10:11] offset:256
	s_waitcnt vmcnt(8)
	v_mfma_scale_f32_16x16x128_f8f6f4 v[64:67], v[0:3], v[194:201], 0, v133, v133 op_sel_hi:[0,0,0] cbsz:4
	v_mfma_scale_f32_16x16x128_f8f6f4 v[64:67], v[4:7], v[202:209], v[64:67], v133, v133 op_sel_hi:[0,0,0] cbsz:4
	v_mfma_scale_f32_16x16x128_f8f6f4 v[68:71], v[8:11], v[194:201], 0, v133, v133 op_sel_hi:[0,0,0] cbsz:4
	v_mfma_scale_f32_16x16x128_f8f6f4 v[68:71], v[12:15], v[202:209], v[68:71], v133, v133 op_sel_hi:[0,0,0] cbsz:4
	v_mfma_scale_f32_16x16x128_f8f6f4 v[72:75], v[16:19], v[194:201], 0, v133, v133 op_sel_hi:[0,0,0] cbsz:4
	v_mfma_scale_f32_16x16x128_f8f6f4 v[72:75], v[20:23], v[202:209], v[72:75], v133, v133 op_sel_hi:[0,0,0] cbsz:4
	v_mfma_scale_f32_16x16x128_f8f6f4 v[76:79], v[24:27], v[194:201], 0, v133, v133 op_sel_hi:[0,0,0] cbsz:4
	v_mfma_scale_f32_16x16x128_f8f6f4 v[76:79], v[28:31], v[202:209], v[76:79], v133, v133 op_sel_hi:[0,0,0] cbsz:4
	s_nop 3
	v_mul_f32_e32 v234, v158, v80
	v_mul_f32_e32 v235, v158, v84
	v_mul_f32_e32 v236, v158, v88
	v_mul_f32_e32 v237, v158, v92
	v_fmac_f32_e32 v234, v159, v81
	v_fmac_f32_e32 v235, v159, v85
	v_fmac_f32_e32 v236, v159, v89
	v_fmac_f32_e32 v237, v159, v93
	v_fmac_f32_e32 v234, v160, v82
	v_fmac_f32_e32 v235, v160, v86
	v_fmac_f32_e32 v236, v160, v90
	v_fmac_f32_e32 v237, v160, v94
	v_fmac_f32_e32 v234, v161, v83
	v_fmac_f32_e32 v235, v161, v87
	v_fmac_f32_e32 v236, v161, v91
	v_fmac_f32_e32 v237, v161, v95
	v_add_f32_dpp v234, v234, v234 quad_perm:[1,0,3,2] row_mask:0xf bank_mask:0xf
	v_add_f32_dpp v235, v235, v235 quad_perm:[1,0,3,2] row_mask:0xf bank_mask:0xf
	v_add_f32_dpp v236, v236, v236 quad_perm:[1,0,3,2] row_mask:0xf bank_mask:0xf
	v_add_f32_dpp v237, v237, v237 quad_perm:[1,0,3,2] row_mask:0xf bank_mask:0xf
	v_add_f32_dpp v234, v234, v234 quad_perm:[2,3,0,1] row_mask:0xf bank_mask:0xf
	v_add_f32_dpp v235, v235, v235 quad_perm:[2,3,0,1] row_mask:0xf bank_mask:0xf
	v_add_f32_dpp v236, v236, v236 quad_perm:[2,3,0,1] row_mask:0xf bank_mask:0xf
	v_add_f32_dpp v237, v237, v237 quad_perm:[2,3,0,1] row_mask:0xf bank_mask:0xf
	v_add_f32_dpp v234, v234, v234 row_half_mirror row_mask:0xf bank_mask:0xf
	v_add_f32_dpp v235, v235, v235 row_half_mirror row_mask:0xf bank_mask:0xf
	v_add_f32_dpp v236, v236, v236 row_half_mirror row_mask:0xf bank_mask:0xf
	v_add_f32_dpp v237, v237, v237 row_half_mirror row_mask:0xf bank_mask:0xf
	s_mov_b32 exec_lo, 0x10001
	s_mov_b32 exec_hi, 0x10001
	ds_write_b32 v155, v234 offset:768
	ds_write_b32 v155, v235 offset:784
	ds_write_b32 v155, v236 offset:800
	ds_write_b32 v155, v237 offset:816
	s_mov_b64 exec, -1
	ds_read2_b32 v[96:97], v242 offset0:64 offset1:68
	ds_read2_b32 v[98:99], v242 offset0:72 offset1:76
	s_waitcnt lgkmcnt(0)
	v_lshl_add_u32 v96, v96, 9, v144
	v_lshl_add_u32 v97, v97, 9, v144
	v_lshl_add_u32 v98, v98, 9, v144
	v_lshl_add_u32 v99, v99, 9, v144
	global_load_dwordx4 v[0:3], v96, s[10:11]
	global_load_dwordx4 v[4:7], v96, s[10:11] offset:256
	global_load_dwordx4 v[8:11], v97, s[10:11]
	global_load_dwordx4 v[12:15], v97, s[10:11] offset:256
	global_load_dwordx4 v[16:19], v98, s[10:11]
	global_load_dwordx4 v[20:23], v98, s[10:11] offset:256
	global_load_dwordx4 v[24:27], v99, s[10:11]
	global_load_dwordx4 v[28:31], v99, s[10:11] offset:256
	s_waitcnt vmcnt(8)
	v_mfma_scale_f32_16x16x128_f8f6f4 v[80:83], v[32:35], v[210:217], 0, v133, v133 op_sel_hi:[0,0,0] cbsz:4
	v_mfma_scale_f32_16x16x128_f8f6f4 v[80:83], v[36:39], v[218:225], v[80:83], v133, v133 op_sel_hi:[0,0,0] cbsz:4
	v_mfma_scale_f32_16x16x128_f8f6f4 v[84:87], v[40:43], v[210:217], 0, v133, v133 op_sel_hi:[0,0,0] cbsz:4
	v_mfma_scale_f32_16x16x128_f8f6f4 v[84:87], v[44:47], v[218:225], v[84:87], v133, v133 op_sel_hi:[0,0,0] cbsz:4
	v_mfma_scale_f32_16x16x128_f8f6f4 v[88:91], v[48:51], v[210:217], 0, v133, v133 op_sel_hi:[0,0,0] cbsz:4
	v_mfma_scale_f32_16x16x128_f8f6f4 v[88:91], v[52:55], v[218:225], v[88:91], v133, v133 op_sel_hi:[0,0,0] cbsz:4
	v_mfma_scale_f32_16x16x128_f8f6f4 v[92:95], v[56:59], v[210:217], 0, v133, v133 op_sel_hi:[0,0,0] cbsz:4
	v_mfma_scale_f32_16x16x128_f8f6f4 v[92:95], v[60:63], v[218:225], v[92:95], v133, v133 op_sel_hi:[0,0,0] cbsz:4
	s_nop 3
	v_mul_f32_e32 v234, v158, v64
	v_mul_f32_e32 v235, v158, v68
	v_mul_f32_e32 v236, v158, v72
	v_mul_f32_e32 v237, v158, v76
	v_fmac_f32_e32 v234, v159, v65
	v_fmac_f32_e32 v235, v159, v69
	v_fmac_f32_e32 v236, v159, v73
	v_fmac_f32_e32 v237, v159, v77
	v_fmac_f32_e32 v234, v160, v66
	v_fmac_f32_e32 v235, v160, v70
	v_fmac_f32_e32 v236, v160, v74
	v_fmac_f32_e32 v237, v160, v78
	v_fmac_f32_e32 v234, v161, v67
	v_fmac_f32_e32 v235, v161, v71
	v_fmac_f32_e32 v236, v161, v75
	v_fmac_f32_e32 v237, v161, v79
	v_add_f32_dpp v234, v234, v234 quad_perm:[1,0,3,2] row_mask:0xf bank_mask:0xf
	v_add_f32_dpp v235, v235, v235 quad_perm:[1,0,3,2] row_mask:0xf bank_mask:0xf
	v_add_f32_dpp v236, v236, v236 quad_perm:[1,0,3,2] row_mask:0xf bank_mask:0xf
	v_add_f32_dpp v237, v237, v237 quad_perm:[1,0,3,2] row_mask:0xf bank_mask:0xf
	v_add_f32_dpp v234, v234, v234 quad_perm:[2,3,0,1] row_mask:0xf bank_mask:0xf
	v_add_f32_dpp v235, v235, v235 quad_perm:[2,3,0,1] row_mask:0xf bank_mask:0xf
	v_add_f32_dpp v236, v236, v236 quad_perm:[2,3,0,1] row_mask:0xf bank_mask:0xf
	v_add_f32_dpp v237, v237, v237 quad_perm:[2,3,0,1] row_mask:0xf bank_mask:0xf
	v_add_f32_dpp v234, v234, v234 row_half_mirror row_mask:0xf bank_mask:0xf
	v_add_f32_dpp v235, v235, v235 row_half_mirror row_mask:0xf bank_mask:0xf
	v_add_f32_dpp v236, v236, v236 row_half_mirror row_mask:0xf bank_mask:0xf
	v_add_f32_dpp v237, v237, v237 row_half_mirror row_mask:0xf bank_mask:0xf
	s_mov_b32 exec_lo, 0x10001
	s_mov_b32 exec_hi, 0x10001
	ds_write_b32 v155, v234 offset:1280
	ds_write_b32 v155, v235 offset:1296
	ds_write_b32 v155, v236 offset:1312
	ds_write_b32 v155, v237 offset:1328
	s_mov_b64 exec, -1
	ds_read2_b32 v[230:231], v243 offset0:64 offset1:68
	ds_read2_b32 v[232:233], v243 offset0:72 offset1:76
	s_waitcnt lgkmcnt(0)
; __device__ __forceinline__ void peer_token(const Params& P, int t, int lane, int* sidx, float* sval, const int* sid, const float* sgate, const unsigned* szero) {
;     ...
;         for (int hh = 0; hh < 2; ++hh) off2[hh] = (unsigned)sid[8 * hh + (lr & 7)] * 512u + lofs;
; #pragma unroll
;         for (int hh = 0; hh < 2; ++hh)
; #pragma unroll
;             for (int st = 0; st < 4; ++st) abuf[0][hh][st] = *(const uint4*)(Ub + (off2[hh] + 128 * st));
; #pragma unroll
;         for (int T = 0; T < 8; ++T) {
;             if (T + 1 < 8) {
; #pragma unroll
;                 for (int hh = 0; hh < 2; ++hh) off2[hh] = (unsigned)sid[16 * (T + 1) + 8 * hh + (lr & 7)] * 512u + lofs;
; #pragma unroll
;                 for (int hh = 0; hh < 2; ++hh)
; #pragma unroll
;                     for (int st = 0; st < 4; ++st) abuf[(T + 1) & 1][hh][st] = *(const uint4*)(Ub + (off2[hh] + 128 * st));
;             }
; #pragma unroll
;             for (int hh = 0; hh < 2; ++hh) {
;                 f32x4 au = (f32x4){0.f, 0.f, 0.f, 0.f};
; #pragma unroll
;                 for (int st = 0; st < 4; ++st) {
;                     const uint4 a4 = abuf[T & 1][hh][st];
;                     const v8i Av = {(int)a4.x, (int)a4.y, (int)a4.z, (int)a4.w, 0, 0, 0, 0};
;                     au = __builtin_amdgcn_mfma_scale_f32_16x16x128_f8f6f4(Av, Bv[st], au, 4, 0, 0, 0x7f7f7f7f, 0, 0x7f7f7f7f);
;                 }
;                 if (owner) *(f32x4*)(sact + 16 * T + 8 * hh) = au;
;             }
	v_lshl_add_u32 v230, v230, 9, v144
	v_lshl_add_u32 v231, v231, 9, v144
	v_lshl_add_u32 v232, v232, 9, v144
	v_lshl_add_u32 v233, v233, 9, v144
	global_load_dwordx4 v[32:35], v230, s[10:11]
	global_load_dwordx4 v[36:39], v230, s[10:11] offset:256
	global_load_dwordx4 v[40:43], v231, s[10:11]
	global_load_dwordx4 v[44:47], v231, s[10:11] offset:256
	global_load_dwordx4 v[48:51], v232, s[10:11]
	global_load_dwordx4 v[52:55], v232, s[10:11] offset:256
	global_load_dwordx4 v[56:59], v233, s[10:11]
	global_load_dwordx4 v[60:63], v233, s[10:11] offset:256
	s_waitcnt vmcnt(8)
	v_mfma_scale_f32_16x16x128_f8f6f4 v[64:67], v[0:3], v[162:169], 0, v133, v133 op_sel_hi:[0,0,0] cbsz:4
	v_mfma_scale_f32_16x16x128_f8f6f4 v[64:67], v[4:7], v[170:177], v[64:67], v133, v133 op_sel_hi:[0,0,0] cbsz:4
	v_mfma_scale_f32_16x16x128_f8f6f4 v[68:71], v[8:11], v[162:169], 0, v133, v133 op_sel_hi:[0,0,0] cbsz:4
	v_mfma_scale_f32_16x16x128_f8f6f4 v[68:71], v[12:15], v[170:177], v[68:71], v133, v133 op_sel_hi:[0,0,0] cbsz:4
	v_mfma_scale_f32_16x16x128_f8f6f4 v[72:75], v[16:19], v[162:169], 0, v133, v133 op_sel_hi:[0,0,0] cbsz:4
	v_mfma_scale_f32_16x16x128_f8f6f4 v[72:75], v[20:23], v[170:177], v[72:75], v133, v133 op_sel_hi:[0,0,0] cbsz:4
	v_mfma_scale_f32_16x16x128_f8f6f4 v[76:79], v[24:27], v[162:169], 0, v133, v133 op_sel_hi:[0,0,0] cbsz:4
	v_mfma_scale_f32_16x16x128_f8f6f4 v[76:79], v[28:31], v[170:177], v[76:79], v133, v133 op_sel_hi:[0,0,0] cbsz:4
	s_nop 3
	v_mul_f32_e32 v234, v158, v80
	v_mul_f32_e32 v235, v158, v84
	v_mul_f32_e32 v236, v158, v88
	v_mul_f32_e32 v237, v158, v92
	v_fmac_f32_e32 v234, v159, v81
	v_fmac_f32_e32 v235, v159, v85
	v_fmac_f32_e32 v236, v159, v89
	v_fmac_f32_e32 v237, v159, v93
	v_fmac_f32_e32 v234, v160, v82
	v_fmac_f32_e32 v235, v160, v86
	v_fmac_f32_e32 v236, v160, v90
	v_fmac_f32_e32 v237, v160, v94
	v_fmac_f32_e32 v234, v161, v83
	v_fmac_f32_e32 v235, v161, v87
	v_fmac_f32_e32 v236, v161, v91
	v_fmac_f32_e32 v237, v161, v95
	v_add_f32_dpp v234, v234, v234 quad_perm:[1,0,3,2] row_mask:0xf bank_mask:0xf
	v_add_f32_dpp v235, v235, v235 quad_perm:[1,0,3,2] row_mask:0xf bank_mask:0xf
	v_add_f32_dpp v236, v236, v236 quad_perm:[1,0,3,2] row_mask:0xf bank_mask:0xf
	v_add_f32_dpp v237, v237, v237 quad_perm:[1,0,3,2] row_mask:0xf bank_mask:0xf
	v_add_f32_dpp v234, v234, v234 quad_perm:[2,3,0,1] row_mask:0xf bank_mask:0xf
	v_add_f32_dpp v235, v235, v235 quad_perm:[2,3,0,1] row_mask:0xf bank_mask:0xf
	v_add_f32_dpp v236, v236, v236 quad_perm:[2,3,0,1] row_mask:0xf bank_mask:0xf
	v_add_f32_dpp v237, v237, v237 quad_perm:[2,3,0,1] row_mask:0xf bank_mask:0xf
	v_add_f32_dpp v234, v234, v234 row_half_mirror row_mask:0xf bank_mask:0xf
	v_add_f32_dpp v235, v235, v235 row_half_mirror row_mask:0xf bank_mask:0xf
	v_add_f32_dpp v236, v236, v236 row_half_mirror row_mask:0xf bank_mask:0xf
	v_add_f32_dpp v237, v237, v237 row_half_mirror row_mask:0xf bank_mask:0xf
	s_mov_b32 exec_lo, 0x10001
	s_mov_b32 exec_hi, 0x10001
	ds_write_b32 v155, v234 offset:1792
	ds_write_b32 v155, v235 offset:1808
	ds_write_b32 v155, v236 offset:1824
	ds_write_b32 v155, v237 offset:1840
	s_mov_b64 exec, -1
	ds_read2_b32 v[96:97], v244 offset0:64 offset1:68
	ds_read2_b32 v[98:99], v244 offset0:72 offset1:76
	s_waitcnt lgkmcnt(0)
	v_lshl_add_u32 v96, v96, 9, v144
	v_lshl_add_u32 v97, v97, 9, v144
	v_lshl_add_u32 v98, v98, 9, v144
	v_lshl_add_u32 v99, v99, 9, v144
	global_load_dwordx4 v[0:3], v96, s[10:11]
	global_load_dwordx4 v[4:7], v96, s[10:11] offset:256
	global_load_dwordx4 v[8:11], v97, s[10:11]
	global_load_dwordx4 v[12:15], v97, s[10:11] offset:256
	global_load_dwordx4 v[16:19], v98, s[10:11]
	global_load_dwordx4 v[20:23], v98, s[10:11] offset:256
	global_load_dwordx4 v[24:27], v99, s[10:11]
	global_load_dwordx4 v[28:31], v99, s[10:11] offset:256
	s_waitcnt vmcnt(8)
	v_mfma_scale_f32_16x16x128_f8f6f4 v[80:83], v[32:35], v[178:185], 0, v133, v133 op_sel_hi:[0,0,0] cbsz:4
	v_mfma_scale_f32_16x16x128_f8f6f4 v[80:83], v[36:39], v[186:193], v[80:83], v133, v133 op_sel_hi:[0,0,0] cbsz:4
	v_mfma_scale_f32_16x16x128_f8f6f4 v[84:87], v[40:43], v[178:185], 0, v133, v133 op_sel_hi:[0,0,0] cbsz:4
	v_mfma_scale_f32_16x16x128_f8f6f4 v[84:87], v[44:47], v[186:193], v[84:87], v133, v133 op_sel_hi:[0,0,0] cbsz:4
	v_mfma_scale_f32_16x16x128_f8f6f4 v[88:91], v[48:51], v[178:185], 0, v133, v133 op_sel_hi:[0,0,0] cbsz:4
	v_mfma_scale_f32_16x16x128_f8f6f4 v[88:91], v[52:55], v[186:193], v[88:91], v133, v133 op_sel_hi:[0,0,0] cbsz:4
	v_mfma_scale_f32_16x16x128_f8f6f4 v[92:95], v[56:59], v[178:185], 0, v133, v133 op_sel_hi:[0,0,0] cbsz:4
	v_mfma_scale_f32_16x16x128_f8f6f4 v[92:95], v[60:63], v[186:193], v[92:95], v133, v133 op_sel_hi:[0,0,0] cbsz:4
	s_nop 3
	v_mul_f32_e32 v234, v226, v64
	v_mul_f32_e32 v235, v226, v68
	v_mul_f32_e32 v236, v226, v72
	v_mul_f32_e32 v237, v226, v76
	v_fmac_f32_e32 v234, v227, v65
	v_fmac_f32_e32 v235, v227, v69
	v_fmac_f32_e32 v236, v227, v73
	v_fmac_f32_e32 v237, v227, v77
	v_fmac_f32_e32 v234, v228, v66
	v_fmac_f32_e32 v235, v228, v70
	v_fmac_f32_e32 v236, v228, v74
	v_fmac_f32_e32 v237, v228, v78
	v_fmac_f32_e32 v234, v229, v67
	v_fmac_f32_e32 v235, v229, v71
	v_fmac_f32_e32 v236, v229, v75
	v_fmac_f32_e32 v237, v229, v79
	v_add_f32_dpp v234, v234, v234 quad_perm:[1,0,3,2] row_mask:0xf bank_mask:0xf
	v_add_f32_dpp v235, v235, v235 quad_perm:[1,0,3,2] row_mask:0xf bank_mask:0xf
	v_add_f32_dpp v236, v236, v236 quad_perm:[1,0,3,2] row_mask:0xf bank_mask:0xf
	v_add_f32_dpp v237, v237, v237 quad_perm:[1,0,3,2] row_mask:0xf bank_mask:0xf
	v_add_f32_dpp v234, v234, v234 quad_perm:[2,3,0,1] row_mask:0xf bank_mask:0xf
	v_add_f32_dpp v235, v235, v235 quad_perm:[2,3,0,1] row_mask:0xf bank_mask:0xf
	v_add_f32_dpp v236, v236, v236 quad_perm:[2,3,0,1] row_mask:0xf bank_mask:0xf
	v_add_f32_dpp v237, v237, v237 quad_perm:[2,3,0,1] row_mask:0xf bank_mask:0xf
	v_add_f32_dpp v234, v234, v234 row_half_mirror row_mask:0xf bank_mask:0xf
	v_add_f32_dpp v235, v235, v235 row_half_mirror row_mask:0xf bank_mask:0xf
	v_add_f32_dpp v236, v236, v236 row_half_mirror row_mask:0xf bank_mask:0xf
	v_add_f32_dpp v237, v237, v237 row_half_mirror row_mask:0xf bank_mask:0xf
	s_mov_b32 exec_lo, 0x1000100
	s_mov_b32 exec_hi, 0x1000100
	ds_write_b32 v155, v234 offset:2304
	ds_write_b32 v155, v235 offset:2320
	ds_write_b32 v155, v236 offset:2336
	ds_write_b32 v155, v237 offset:2352
	s_mov_b64 exec, -1
	ds_read2_b32 v[230:231], v245 offset0:64 offset1:68
	ds_read2_b32 v[232:233], v245 offset0:72 offset1:76
	s_waitcnt lgkmcnt(0)
; __device__ __forceinline__ void peer_token(const Params& P, int t, int lane, int* sidx, float* sval, const int* sid, const float* sgate, const unsigned* szero) {
;     ...
;         for (int hh = 0; hh < 2; ++hh) off2[hh] = (unsigned)sid[8 * hh + (lr & 7)] * 512u + lofs;
; #pragma unroll
;         for (int hh = 0; hh < 2; ++hh)
; #pragma unroll
;             for (int st = 0; st < 4; ++st) abuf[0][hh][st] = *(const uint4*)(Ub + (off2[hh] + 128 * st));
; #pragma unroll
;         for (int T = 0; T < 8; ++T) {
;             if (T + 1 < 8) {
; #pragma unroll
;                 for (int hh = 0; hh < 2; ++hh) off2[hh] = (unsigned)sid[16 * (T + 1) + 8 * hh + (lr & 7)] * 512u + lofs;
; #pragma unroll
;                 for (int hh = 0; hh < 2; ++hh)
; #pragma unroll
;                     for (int st = 0; st < 4; ++st) abuf[(T + 1) & 1][hh][st] = *(const uint4*)(Ub + (off2[hh] + 128 * st));
;             }
; #pragma unroll
;             for (int hh = 0; hh < 2; ++hh) {
;                 f32x4 au = (f32x4){0.f, 0.f, 0.f, 0.f};
; #pragma unroll
;                 for (int st = 0; st < 4; ++st) {
;                     const uint4 a4 = abuf[T & 1][hh][st];
;                     const v8i Av = {(int)a4.x, (int)a4.y, (int)a4.z, (int)a4.w, 0, 0, 0, 0};
;                     au = __builtin_amdgcn_mfma_scale_f32_16x16x128_f8f6f4(Av, Bv[st], au, 4, 0, 0, 0x7f7f7f7f, 0, 0x7f7f7f7f);
;                 }
;                 if (owner) *(f32x4*)(sact + 16 * T + 8 * hh) = au;
;             }
	v_lshl_add_u32 v230, v230, 9, v144
	v_lshl_add_u32 v231, v231, 9, v144
	v_lshl_add_u32 v232, v232, 9, v144
	v_lshl_add_u32 v233, v233, 9, v144
	global_load_dwordx4 v[32:35], v230, s[10:11]
	global_load_dwordx4 v[36:39], v230, s[10:11] offset:256
	global_load_dwordx4 v[40:43], v231, s[10:11]
	global_load_dwordx4 v[44:47], v231, s[10:11] offset:256
	global_load_dwordx4 v[48:51], v232, s[10:11]
	global_load_dwordx4 v[52:55], v232, s[10:11] offset:256
	global_load_dwordx4 v[56:59], v233, s[10:11]
	global_load_dwordx4 v[60:63], v233, s[10:11] offset:256
	s_waitcnt vmcnt(8)
	v_mfma_scale_f32_16x16x128_f8f6f4 v[64:67], v[0:3], v[194:201], 0, v133, v133 op_sel_hi:[0,0,0] cbsz:4
	v_mfma_scale_f32_16x16x128_f8f6f4 v[64:67], v[4:7], v[202:209], v[64:67], v133, v133 op_sel_hi:[0,0,0] cbsz:4
	v_mfma_scale_f32_16x16x128_f8f6f4 v[68:71], v[8:11], v[194:201], 0, v133, v133 op_sel_hi:[0,0,0] cbsz:4
	v_mfma_scale_f32_16x16x128_f8f6f4 v[68:71], v[12:15], v[202:209], v[68:71], v133, v133 op_sel_hi:[0,0,0] cbsz:4
	v_mfma_scale_f32_16x16x128_f8f6f4 v[72:75], v[16:19], v[194:201], 0, v133, v133 op_sel_hi:[0,0,0] cbsz:4
	v_mfma_scale_f32_16x16x128_f8f6f4 v[72:75], v[20:23], v[202:209], v[72:75], v133, v133 op_sel_hi:[0,0,0] cbsz:4
	v_mfma_scale_f32_16x16x128_f8f6f4 v[76:79], v[24:27], v[194:201], 0, v133, v133 op_sel_hi:[0,0,0] cbsz:4
	v_mfma_scale_f32_16x16x128_f8f6f4 v[76:79], v[28:31], v[202:209], v[76:79], v133, v133 op_sel_hi:[0,0,0] cbsz:4
	s_nop 3
	v_mul_f32_e32 v234, v226, v80
	v_mul_f32_e32 v235, v226, v84
	v_mul_f32_e32 v236, v226, v88
	v_mul_f32_e32 v237, v226, v92
	v_fmac_f32_e32 v234, v227, v81
	v_fmac_f32_e32 v235, v227, v85
	v_fmac_f32_e32 v236, v227, v89
	v_fmac_f32_e32 v237, v227, v93
	v_fmac_f32_e32 v234, v228, v82
	v_fmac_f32_e32 v235, v228, v86
	v_fmac_f32_e32 v236, v228, v90
	v_fmac_f32_e32 v237, v228, v94
	v_fmac_f32_e32 v234, v229, v83
	v_fmac_f32_e32 v235, v229, v87
	v_fmac_f32_e32 v236, v229, v91
	v_fmac_f32_e32 v237, v229, v95
	v_add_f32_dpp v234, v234, v234 quad_perm:[1,0,3,2] row_mask:0xf bank_mask:0xf
	v_add_f32_dpp v235, v235, v235 quad_perm:[1,0,3,2] row_mask:0xf bank_mask:0xf
	v_add_f32_dpp v236, v236, v236 quad_perm:[1,0,3,2] row_mask:0xf bank_mask:0xf
	v_add_f32_dpp v237, v237, v237 quad_perm:[1,0,3,2] row_mask:0xf bank_mask:0xf
	v_add_f32_dpp v234, v234, v234 quad_perm:[2,3,0,1] row_mask:0xf bank_mask:0xf
	v_add_f32_dpp v235, v235, v235 quad_perm:[2,3,0,1] row_mask:0xf bank_mask:0xf
	v_add_f32_dpp v236, v236, v236 quad_perm:[2,3,0,1] row_mask:0xf bank_mask:0xf
	v_add_f32_dpp v237, v237, v237 quad_perm:[2,3,0,1] row_mask:0xf bank_mask:0xf
	v_add_f32_dpp v234, v234, v234 row_half_mirror row_mask:0xf bank_mask:0xf
	v_add_f32_dpp v235, v235, v235 row_half_mirror row_mask:0xf bank_mask:0xf
	v_add_f32_dpp v236, v236, v236 row_half_mirror row_mask:0xf bank_mask:0xf
	v_add_f32_dpp v237, v237, v237 row_half_mirror row_mask:0xf bank_mask:0xf
	s_mov_b32 exec_lo, 0x1000100
	s_mov_b32 exec_hi, 0x1000100
	ds_write_b32 v155, v234 offset:2816
	ds_write_b32 v155, v235 offset:2832
	ds_write_b32 v155, v236 offset:2848
	ds_write_b32 v155, v237 offset:2864
	s_mov_b64 exec, -1
	ds_read2_b32 v[96:97], v238 offset0:80 offset1:84
	ds_read2_b32 v[98:99], v238 offset0:88 offset1:92
	s_waitcnt lgkmcnt(0)
	v_lshl_add_u32 v96, v96, 9, v144
	v_lshl_add_u32 v97, v97, 9, v144
	v_lshl_add_u32 v98, v98, 9, v144
	v_lshl_add_u32 v99, v99, 9, v144
	global_load_dwordx4 v[0:3], v96, s[10:11]
	global_load_dwordx4 v[4:7], v96, s[10:11] offset:256
	global_load_dwordx4 v[8:11], v97, s[10:11]
	global_load_dwordx4 v[12:15], v97, s[10:11] offset:256
	global_load_dwordx4 v[16:19], v98, s[10:11]
	global_load_dwordx4 v[20:23], v98, s[10:11] offset:256
	global_load_dwordx4 v[24:27], v99, s[10:11]
	global_load_dwordx4 v[28:31], v99, s[10:11] offset:256
	s_waitcnt vmcnt(8)
	v_mfma_scale_f32_16x16x128_f8f6f4 v[80:83], v[32:35], v[210:217], 0, v133, v133 op_sel_hi:[0,0,0] cbsz:4
	v_mfma_scale_f32_16x16x128_f8f6f4 v[80:83], v[36:39], v[218:225], v[80:83], v133, v133 op_sel_hi:[0,0,0] cbsz:4
	v_mfma_scale_f32_16x16x128_f8f6f4 v[84:87], v[40:43], v[210:217], 0, v133, v133 op_sel_hi:[0,0,0] cbsz:4
	v_mfma_scale_f32_16x16x128_f8f6f4 v[84:87], v[44:47], v[218:225], v[84:87], v133, v133 op_sel_hi:[0,0,0] cbsz:4
	v_mfma_scale_f32_16x16x128_f8f6f4 v[88:91], v[48:51], v[210:217], 0, v133, v133 op_sel_hi:[0,0,0] cbsz:4
	v_mfma_scale_f32_16x16x128_f8f6f4 v[88:91], v[52:55], v[218:225], v[88:91], v133, v133 op_sel_hi:[0,0,0] cbsz:4
	v_mfma_scale_f32_16x16x128_f8f6f4 v[92:95], v[56:59], v[210:217], 0, v133, v133 op_sel_hi:[0,0,0] cbsz:4
	v_mfma_scale_f32_16x16x128_f8f6f4 v[92:95], v[60:63], v[218:225], v[92:95], v133, v133 op_sel_hi:[0,0,0] cbsz:4
	s_nop 3
	v_mul_f32_e32 v234, v226, v64
	v_mul_f32_e32 v235, v226, v68
	v_mul_f32_e32 v236, v226, v72
	v_mul_f32_e32 v237, v226, v76
	v_fmac_f32_e32 v234, v227, v65
	v_fmac_f32_e32 v235, v227, v69
	v_fmac_f32_e32 v236, v227, v73
	v_fmac_f32_e32 v237, v227, v77
	v_fmac_f32_e32 v234, v228, v66
	v_fmac_f32_e32 v235, v228, v70
	v_fmac_f32_e32 v236, v228, v74
	v_fmac_f32_e32 v237, v228, v78
	v_fmac_f32_e32 v234, v229, v67
	v_fmac_f32_e32 v235, v229, v71
	v_fmac_f32_e32 v236, v229, v75
	v_fmac_f32_e32 v237, v229, v79
	v_add_f32_dpp v234, v234, v234 quad_perm:[1,0,3,2] row_mask:0xf bank_mask:0xf
	v_add_f32_dpp v235, v235, v235 quad_perm:[1,0,3,2] row_mask:0xf bank_mask:0xf
	v_add_f32_dpp v236, v236, v236 quad_perm:[1,0,3,2] row_mask:0xf bank_mask:0xf
	v_add_f32_dpp v237, v237, v237 quad_perm:[1,0,3,2] row_mask:0xf bank_mask:0xf
	v_add_f32_dpp v234, v234, v234 quad_perm:[2,3,0,1] row_mask:0xf bank_mask:0xf
	v_add_f32_dpp v235, v235, v235 quad_perm:[2,3,0,1] row_mask:0xf bank_mask:0xf
	v_add_f32_dpp v236, v236, v236 quad_perm:[2,3,0,1] row_mask:0xf bank_mask:0xf
	v_add_f32_dpp v237, v237, v237 quad_perm:[2,3,0,1] row_mask:0xf bank_mask:0xf
	v_add_f32_dpp v234, v234, v234 row_half_mirror row_mask:0xf bank_mask:0xf
	v_add_f32_dpp v235, v235, v235 row_half_mirror row_mask:0xf bank_mask:0xf
	v_add_f32_dpp v236, v236, v236 row_half_mirror row_mask:0xf bank_mask:0xf
	v_add_f32_dpp v237, v237, v237 row_half_mirror row_mask:0xf bank_mask:0xf
	s_mov_b32 exec_lo, 0x1000100
	s_mov_b32 exec_hi, 0x1000100
	ds_write_b32 v155, v234 offset:3328
	ds_write_b32 v155, v235 offset:3344
	ds_write_b32 v155, v236 offset:3360
	ds_write_b32 v155, v237 offset:3376
	s_mov_b64 exec, -1
	ds_read2_b32 v[230:231], v239 offset0:80 offset1:84
	ds_read2_b32 v[232:233], v239 offset0:88 offset1:92
	s_waitcnt lgkmcnt(0)
; __device__ __forceinline__ void peer_token(const Params& P, int t, int lane, int* sidx, float* sval, const int* sid, const float* sgate, const unsigned* szero) {
;     ...
;         for (int hh = 0; hh < 2; ++hh) off2[hh] = (unsigned)sid[8 * hh + (lr & 7)] * 512u + lofs;
; #pragma unroll
;         for (int hh = 0; hh < 2; ++hh)
; #pragma unroll
;             for (int st = 0; st < 4; ++st) abuf[0][hh][st] = *(const uint4*)(Ub + (off2[hh] + 128 * st));
; #pragma unroll
;         for (int T = 0; T < 8; ++T) {
;             if (T + 1 < 8) {
; #pragma unroll
;                 for (int hh = 0; hh < 2; ++hh) off2[hh] = (unsigned)sid[16 * (T + 1) + 8 * hh + (lr & 7)] * 512u + lofs;
; #pragma unroll
;                 for (int hh = 0; hh < 2; ++hh)
; #pragma unroll
;                     for (int st = 0; st < 4; ++st) abuf[(T + 1) & 1][hh][st] = *(const uint4*)(Ub + (off2[hh] + 128 * st));
;             }
; #pragma unroll
;             for (int hh = 0; hh < 2; ++hh) {
;                 f32x4 au = (f32x4){0.f, 0.f, 0.f, 0.f};
; #pragma unroll
;                 for (int st = 0; st < 4; ++st) {
;                     const uint4 a4 = abuf[T & 1][hh][st];
;                     const v8i Av = {(int)a4.x, (int)a4.y, (int)a4.z, (int)a4.w, 0, 0, 0, 0};
;                     au = __builtin_amdgcn_mfma_scale_f32_16x16x128_f8f6f4(Av, Bv[st], au, 4, 0, 0, 0x7f7f7f7f, 0, 0x7f7f7f7f);
;                 }
;                 if (owner) *(f32x4*)(sact + 16 * T + 8 * hh) = au;
;             }
	v_lshl_add_u32 v230, v230, 9, v144
	v_lshl_add_u32 v231, v231, 9, v144
	v_lshl_add_u32 v232, v232, 9, v144
	v_lshl_add_u32 v233, v233, 9, v144
	global_load_dwordx4 v[32:35], v230, s[10:11]
	global_load_dwordx4 v[36:39], v230, s[10:11] offset:256
	global_load_dwordx4 v[40:43], v231, s[10:11]
	global_load_dwordx4 v[44:47], v231, s[10:11] offset:256
	global_load_dwordx4 v[48:51], v232, s[10:11]
	global_load_dwordx4 v[52:55], v232, s[10:11] offset:256
	global_load_dwordx4 v[56:59], v233, s[10:11]
	global_load_dwordx4 v[60:63], v233, s[10:11] offset:256
	s_waitcnt vmcnt(8)
	v_mfma_scale_f32_16x16x128_f8f6f4 v[64:67], v[0:3], v[162:169], 0, v133, v133 op_sel_hi:[0,0,0] cbsz:4
	v_mfma_scale_f32_16x16x128_f8f6f4 v[64:67], v[4:7], v[170:177], v[64:67], v133, v133 op_sel_hi:[0,0,0] cbsz:4
	v_mfma_scale_f32_16x16x128_f8f6f4 v[68:71], v[8:11], v[162:169], 0, v133, v133 op_sel_hi:[0,0,0] cbsz:4
	v_mfma_scale_f32_16x16x128_f8f6f4 v[68:71], v[12:15], v[170:177], v[68:71], v133, v133 op_sel_hi:[0,0,0] cbsz:4
	v_mfma_scale_f32_16x16x128_f8f6f4 v[72:75], v[16:19], v[162:169], 0, v133, v133 op_sel_hi:[0,0,0] cbsz:4
	v_mfma_scale_f32_16x16x128_f8f6f4 v[72:75], v[20:23], v[170:177], v[72:75], v133, v133 op_sel_hi:[0,0,0] cbsz:4
	v_mfma_scale_f32_16x16x128_f8f6f4 v[76:79], v[24:27], v[162:169], 0, v133, v133 op_sel_hi:[0,0,0] cbsz:4
	v_mfma_scale_f32_16x16x128_f8f6f4 v[76:79], v[28:31], v[170:177], v[76:79], v133, v133 op_sel_hi:[0,0,0] cbsz:4
	s_nop 3
	v_mul_f32_e32 v234, v226, v80
	v_mul_f32_e32 v235, v226, v84
	v_mul_f32_e32 v236, v226, v88
	v_mul_f32_e32 v237, v226, v92
	v_fmac_f32_e32 v234, v227, v81
	v_fmac_f32_e32 v235, v227, v85
	v_fmac_f32_e32 v236, v227, v89
	v_fmac_f32_e32 v237, v227, v93
	v_fmac_f32_e32 v234, v228, v82
	v_fmac_f32_e32 v235, v228, v86
	v_fmac_f32_e32 v236, v228, v90
	v_fmac_f32_e32 v237, v228, v94
	v_fmac_f32_e32 v234, v229, v83
	v_fmac_f32_e32 v235, v229, v87
	v_fmac_f32_e32 v236, v229, v91
	v_fmac_f32_e32 v237, v229, v95
	v_add_f32_dpp v234, v234, v234 quad_perm:[1,0,3,2] row_mask:0xf bank_mask:0xf
	v_add_f32_dpp v235, v235, v235 quad_perm:[1,0,3,2] row_mask:0xf bank_mask:0xf
	v_add_f32_dpp v236, v236, v236 quad_perm:[1,0,3,2] row_mask:0xf bank_mask:0xf
	v_add_f32_dpp v237, v237, v237 quad_perm:[1,0,3,2] row_mask:0xf bank_mask:0xf
	v_add_f32_dpp v234, v234, v234 quad_perm:[2,3,0,1] row_mask:0xf bank_mask:0xf
	v_add_f32_dpp v235, v235, v235 quad_perm:[2,3,0,1] row_mask:0xf bank_mask:0xf
	v_add_f32_dpp v236, v236, v236 quad_perm:[2,3,0,1] row_mask:0xf bank_mask:0xf
	v_add_f32_dpp v237, v237, v237 quad_perm:[2,3,0,1] row_mask:0xf bank_mask:0xf
	v_add_f32_dpp v234, v234, v234 row_half_mirror row_mask:0xf bank_mask:0xf
	v_add_f32_dpp v235, v235, v235 row_half_mirror row_mask:0xf bank_mask:0xf
	v_add_f32_dpp v236, v236, v236 row_half_mirror row_mask:0xf bank_mask:0xf
	v_add_f32_dpp v237, v237, v237 row_half_mirror row_mask:0xf bank_mask:0xf
	s_mov_b32 exec_lo, 0x1000100
	s_mov_b32 exec_hi, 0x1000100
	ds_write_b32 v155, v234 offset:3840
	ds_write_b32 v155, v235 offset:3856
	ds_write_b32 v155, v236 offset:3872
	ds_write_b32 v155, v237 offset:3888
	s_mov_b64 exec, -1
	ds_read2_b32 v[96:97], v240 offset0:80 offset1:84
	ds_read2_b32 v[98:99], v240 offset0:88 offset1:92
	s_waitcnt lgkmcnt(0)
	v_lshl_add_u32 v96, v96, 9, v144
	v_lshl_add_u32 v97, v97, 9, v144
	v_lshl_add_u32 v98, v98, 9, v144
	v_lshl_add_u32 v99, v99, 9, v144
	global_load_dwordx4 v[0:3], v96, s[10:11]
	global_load_dwordx4 v[4:7], v96, s[10:11] offset:256
	global_load_dwordx4 v[8:11], v97, s[10:11]
	global_load_dwordx4 v[12:15], v97, s[10:11] offset:256
	global_load_dwordx4 v[16:19], v98, s[10:11]
	global_load_dwordx4 v[20:23], v98, s[10:11] offset:256
	global_load_dwordx4 v[24:27], v99, s[10:11]
	global_load_dwordx4 v[28:31], v99, s[10:11] offset:256
	s_waitcnt vmcnt(8)
	v_mfma_scale_f32_16x16x128_f8f6f4 v[80:83], v[32:35], v[178:185], 0, v133, v133 op_sel_hi:[0,0,0] cbsz:4
	v_mfma_scale_f32_16x16x128_f8f6f4 v[80:83], v[36:39], v[186:193], v[80:83], v133, v133 op_sel_hi:[0,0,0] cbsz:4
	v_mfma_scale_f32_16x16x128_f8f6f4 v[84:87], v[40:43], v[178:185], 0, v133, v133 op_sel_hi:[0,0,0] cbsz:4
	v_mfma_scale_f32_16x16x128_f8f6f4 v[84:87], v[44:47], v[186:193], v[84:87], v133, v133 op_sel_hi:[0,0,0] cbsz:4
	v_mfma_scale_f32_16x16x128_f8f6f4 v[88:91], v[48:51], v[178:185], 0, v133, v133 op_sel_hi:[0,0,0] cbsz:4
	v_mfma_scale_f32_16x16x128_f8f6f4 v[88:91], v[52:55], v[186:193], v[88:91], v133, v133 op_sel_hi:[0,0,0] cbsz:4
	v_mfma_scale_f32_16x16x128_f8f6f4 v[92:95], v[56:59], v[178:185], 0, v133, v133 op_sel_hi:[0,0,0] cbsz:4
	v_mfma_scale_f32_16x16x128_f8f6f4 v[92:95], v[60:63], v[186:193], v[92:95], v133, v133 op_sel_hi:[0,0,0] cbsz:4
	s_nop 3
	v_mul_f32_e32 v234, v158, v64
	v_mul_f32_e32 v235, v158, v68
	v_mul_f32_e32 v236, v158, v72
	v_mul_f32_e32 v237, v158, v76
	v_fmac_f32_e32 v234, v159, v65
	v_fmac_f32_e32 v235, v159, v69
	v_fmac_f32_e32 v236, v159, v73
	v_fmac_f32_e32 v237, v159, v77
	v_fmac_f32_e32 v234, v160, v66
	v_fmac_f32_e32 v235, v160, v70
	v_fmac_f32_e32 v236, v160, v74
	v_fmac_f32_e32 v237, v160, v78
	v_fmac_f32_e32 v234, v161, v67
	v_fmac_f32_e32 v235, v161, v71
	v_fmac_f32_e32 v236, v161, v75
	v_fmac_f32_e32 v237, v161, v79
	v_add_f32_dpp v234, v234, v234 quad_perm:[1,0,3,2] row_mask:0xf bank_mask:0xf
	v_add_f32_dpp v235, v235, v235 quad_perm:[1,0,3,2] row_mask:0xf bank_mask:0xf
	v_add_f32_dpp v236, v236, v236 quad_perm:[1,0,3,2] row_mask:0xf bank_mask:0xf
	v_add_f32_dpp v237, v237, v237 quad_perm:[1,0,3,2] row_mask:0xf bank_mask:0xf
	v_add_f32_dpp v234, v234, v234 quad_perm:[2,3,0,1] row_mask:0xf bank_mask:0xf
	v_add_f32_dpp v235, v235, v235 quad_perm:[2,3,0,1] row_mask:0xf bank_mask:0xf
	v_add_f32_dpp v236, v236, v236 quad_perm:[2,3,0,1] row_mask:0xf bank_mask:0xf
	v_add_f32_dpp v237, v237, v237 quad_perm:[2,3,0,1] row_mask:0xf bank_mask:0xf
	v_add_f32_dpp v234, v234, v234 row_half_mirror row_mask:0xf bank_mask:0xf
	v_add_f32_dpp v235, v235, v235 row_half_mirror row_mask:0xf bank_mask:0xf
	v_add_f32_dpp v236, v236, v236 row_half_mirror row_mask:0xf bank_mask:0xf
	v_add_f32_dpp v237, v237, v237 row_half_mirror row_mask:0xf bank_mask:0xf
	s_mov_b32 exec_lo, 0x10001
	s_mov_b32 exec_hi, 0x10001
	ds_write_b32 v155, v234 offset:320
	ds_write_b32 v155, v235 offset:336
	ds_write_b32 v155, v236 offset:352
	ds_write_b32 v155, v237 offset:368
	s_mov_b64 exec, -1
	ds_read2_b32 v[230:231], v241 offset0:80 offset1:84
	ds_read2_b32 v[232:233], v241 offset0:88 offset1:92
	s_waitcnt lgkmcnt(0)
; __device__ __forceinline__ void peer_token(const Params& P, int t, int lane, int* sidx, float* sval, const int* sid, const float* sgate, const unsigned* szero) {
;     ...
;         for (int hh = 0; hh < 2; ++hh) off2[hh] = (unsigned)sid[8 * hh + (lr & 7)] * 512u + lofs;
; #pragma unroll
;         for (int hh = 0; hh < 2; ++hh)
; #pragma unroll
;             for (int st = 0; st < 4; ++st) abuf[0][hh][st] = *(const uint4*)(Ub + (off2[hh] + 128 * st));
; #pragma unroll
;         for (int T = 0; T < 8; ++T) {
;             if (T + 1 < 8) {
; #pragma unroll
;                 for (int hh = 0; hh < 2; ++hh) off2[hh] = (unsigned)sid[16 * (T + 1) + 8 * hh + (lr & 7)] * 512u + lofs;
; #pragma unroll
;                 for (int hh = 0; hh < 2; ++hh)
; #pragma unroll
;                     for (int st = 0; st < 4; ++st) abuf[(T + 1) & 1][hh][st] = *(const uint4*)(Ub + (off2[hh] + 128 * st));
;             }
; #pragma unroll
;             for (int hh = 0; hh < 2; ++hh) {
;                 f32x4 au = (f32x4){0.f, 0.f, 0.f, 0.f};
; #pragma unroll
;                 for (int st = 0; st < 4; ++st) {
;                     const uint4 a4 = abuf[T & 1][hh][st];
;                     const v8i Av = {(int)a4.x, (int)a4.y, (int)a4.z, (int)a4.w, 0, 0, 0, 0};
;                     au = __builtin_amdgcn_mfma_scale_f32_16x16x128_f8f6f4(Av, Bv[st], au, 4, 0, 0, 0x7f7f7f7f, 0, 0x7f7f7f7f);
;                 }
;                 if (owner) *(f32x4*)(sact + 16 * T + 8 * hh) = au;
;             }
	v_lshl_add_u32 v230, v230, 9, v144
	v_lshl_add_u32 v231, v231, 9, v144
	v_lshl_add_u32 v232, v232, 9, v144
	v_lshl_add_u32 v233, v233, 9, v144
	global_load_dwordx4 v[32:35], v230, s[10:11]
	global_load_dwordx4 v[36:39], v230, s[10:11] offset:256
	global_load_dwordx4 v[40:43], v231, s[10:11]
	global_load_dwordx4 v[44:47], v231, s[10:11] offset:256
	global_load_dwordx4 v[48:51], v232, s[10:11]
	global_load_dwordx4 v[52:55], v232, s[10:11] offset:256
	global_load_dwordx4 v[56:59], v233, s[10:11]
	global_load_dwordx4 v[60:63], v233, s[10:11] offset:256
	s_waitcnt vmcnt(8)
	v_mfma_scale_f32_16x16x128_f8f6f4 v[64:67], v[0:3], v[194:201], 0, v133, v133 op_sel_hi:[0,0,0] cbsz:4
	v_mfma_scale_f32_16x16x128_f8f6f4 v[64:67], v[4:7], v[202:209], v[64:67], v133, v133 op_sel_hi:[0,0,0] cbsz:4
	v_mfma_scale_f32_16x16x128_f8f6f4 v[68:71], v[8:11], v[194:201], 0, v133, v133 op_sel_hi:[0,0,0] cbsz:4
	v_mfma_scale_f32_16x16x128_f8f6f4 v[68:71], v[12:15], v[202:209], v[68:71], v133, v133 op_sel_hi:[0,0,0] cbsz:4
	v_mfma_scale_f32_16x16x128_f8f6f4 v[72:75], v[16:19], v[194:201], 0, v133, v133 op_sel_hi:[0,0,0] cbsz:4
	v_mfma_scale_f32_16x16x128_f8f6f4 v[72:75], v[20:23], v[202:209], v[72:75], v133, v133 op_sel_hi:[0,0,0] cbsz:4
	v_mfma_scale_f32_16x16x128_f8f6f4 v[76:79], v[24:27], v[194:201], 0, v133, v133 op_sel_hi:[0,0,0] cbsz:4
	v_mfma_scale_f32_16x16x128_f8f6f4 v[76:79], v[28:31], v[202:209], v[76:79], v133, v133 op_sel_hi:[0,0,0] cbsz:4
	s_nop 3
	v_mul_f32_e32 v234, v158, v80
	v_mul_f32_e32 v235, v158, v84
	v_mul_f32_e32 v236, v158, v88
	v_mul_f32_e32 v237, v158, v92
	v_fmac_f32_e32 v234, v159, v81
	v_fmac_f32_e32 v235, v159, v85
	v_fmac_f32_e32 v236, v159, v89
	v_fmac_f32_e32 v237, v159, v93
	v_fmac_f32_e32 v234, v160, v82
	v_fmac_f32_e32 v235, v160, v86
	v_fmac_f32_e32 v236, v160, v90
	v_fmac_f32_e32 v237, v160, v94
	v_fmac_f32_e32 v234, v161, v83
	v_fmac_f32_e32 v235, v161, v87
	v_fmac_f32_e32 v236, v161, v91
	v_fmac_f32_e32 v237, v161, v95
	v_add_f32_dpp v234, v234, v234 quad_perm:[1,0,3,2] row_mask:0xf bank_mask:0xf
	v_add_f32_dpp v235, v235, v235 quad_perm:[1,0,3,2] row_mask:0xf bank_mask:0xf
	v_add_f32_dpp v236, v236, v236 quad_perm:[1,0,3,2] row_mask:0xf bank_mask:0xf
	v_add_f32_dpp v237, v237, v237 quad_perm:[1,0,3,2] row_mask:0xf bank_mask:0xf
	v_add_f32_dpp v234, v234, v234 quad_perm:[2,3,0,1] row_mask:0xf bank_mask:0xf
	v_add_f32_dpp v235, v235, v235 quad_perm:[2,3,0,1] row_mask:0xf bank_mask:0xf
	v_add_f32_dpp v236, v236, v236 quad_perm:[2,3,0,1] row_mask:0xf bank_mask:0xf
	v_add_f32_dpp v237, v237, v237 quad_perm:[2,3,0,1] row_mask:0xf bank_mask:0xf
	v_add_f32_dpp v234, v234, v234 row_half_mirror row_mask:0xf bank_mask:0xf
	v_add_f32_dpp v235, v235, v235 row_half_mirror row_mask:0xf bank_mask:0xf
	v_add_f32_dpp v236, v236, v236 row_half_mirror row_mask:0xf bank_mask:0xf
	v_add_f32_dpp v237, v237, v237 row_half_mirror row_mask:0xf bank_mask:0xf
	s_mov_b32 exec_lo, 0x10001
	s_mov_b32 exec_hi, 0x10001
	ds_write_b32 v155, v234 offset:832
	ds_write_b32 v155, v235 offset:848
	ds_write_b32 v155, v236 offset:864
	ds_write_b32 v155, v237 offset:880
	s_mov_b64 exec, -1
	ds_read2_b32 v[96:97], v242 offset0:80 offset1:84
	ds_read2_b32 v[98:99], v242 offset0:88 offset1:92
	s_waitcnt lgkmcnt(0)
	v_lshl_add_u32 v96, v96, 9, v144
	v_lshl_add_u32 v97, v97, 9, v144
	v_lshl_add_u32 v98, v98, 9, v144
	v_lshl_add_u32 v99, v99, 9, v144
	global_load_dwordx4 v[0:3], v96, s[10:11]
	global_load_dwordx4 v[4:7], v96, s[10:11] offset:256
	global_load_dwordx4 v[8:11], v97, s[10:11]
	global_load_dwordx4 v[12:15], v97, s[10:11] offset:256
	global_load_dwordx4 v[16:19], v98, s[10:11]
	global_load_dwordx4 v[20:23], v98, s[10:11] offset:256
	global_load_dwordx4 v[24:27], v99, s[10:11]
	global_load_dwordx4 v[28:31], v99, s[10:11] offset:256
	s_waitcnt vmcnt(8)
	v_mfma_scale_f32_16x16x128_f8f6f4 v[80:83], v[32:35], v[210:217], 0, v133, v133 op_sel_hi:[0,0,0] cbsz:4
	v_mfma_scale_f32_16x16x128_f8f6f4 v[80:83], v[36:39], v[218:225], v[80:83], v133, v133 op_sel_hi:[0,0,0] cbsz:4
	v_mfma_scale_f32_16x16x128_f8f6f4 v[84:87], v[40:43], v[210:217], 0, v133, v133 op_sel_hi:[0,0,0] cbsz:4
	v_mfma_scale_f32_16x16x128_f8f6f4 v[84:87], v[44:47], v[218:225], v[84:87], v133, v133 op_sel_hi:[0,0,0] cbsz:4
	v_mfma_scale_f32_16x16x128_f8f6f4 v[88:91], v[48:51], v[210:217], 0, v133, v133 op_sel_hi:[0,0,0] cbsz:4
	v_mfma_scale_f32_16x16x128_f8f6f4 v[88:91], v[52:55], v[218:225], v[88:91], v133, v133 op_sel_hi:[0,0,0] cbsz:4
	v_mfma_scale_f32_16x16x128_f8f6f4 v[92:95], v[56:59], v[210:217], 0, v133, v133 op_sel_hi:[0,0,0] cbsz:4
	v_mfma_scale_f32_16x16x128_f8f6f4 v[92:95], v[60:63], v[218:225], v[92:95], v133, v133 op_sel_hi:[0,0,0] cbsz:4
	s_nop 3
	v_mul_f32_e32 v234, v158, v64
	v_mul_f32_e32 v235, v158, v68
	v_mul_f32_e32 v236, v158, v72
	v_mul_f32_e32 v237, v158, v76
	v_fmac_f32_e32 v234, v159, v65
	v_fmac_f32_e32 v235, v159, v69
	v_fmac_f32_e32 v236, v159, v73
	v_fmac_f32_e32 v237, v159, v77
	v_fmac_f32_e32 v234, v160, v66
	v_fmac_f32_e32 v235, v160, v70
	v_fmac_f32_e32 v236, v160, v74
	v_fmac_f32_e32 v237, v160, v78
	v_fmac_f32_e32 v234, v161, v67
	v_fmac_f32_e32 v235, v161, v71
	v_fmac_f32_e32 v236, v161, v75
	v_fmac_f32_e32 v237, v161, v79
	v_add_f32_dpp v234, v234, v234 quad_perm:[1,0,3,2] row_mask:0xf bank_mask:0xf
	v_add_f32_dpp v235, v235, v235 quad_perm:[1,0,3,2] row_mask:0xf bank_mask:0xf
	v_add_f32_dpp v236, v236, v236 quad_perm:[1,0,3,2] row_mask:0xf bank_mask:0xf
	v_add_f32_dpp v237, v237, v237 quad_perm:[1,0,3,2] row_mask:0xf bank_mask:0xf
	v_add_f32_dpp v234, v234, v234 quad_perm:[2,3,0,1] row_mask:0xf bank_mask:0xf
	v_add_f32_dpp v235, v235, v235 quad_perm:[2,3,0,1] row_mask:0xf bank_mask:0xf
	v_add_f32_dpp v236, v236, v236 quad_perm:[2,3,0,1] row_mask:0xf bank_mask:0xf
	v_add_f32_dpp v237, v237, v237 quad_perm:[2,3,0,1] row_mask:0xf bank_mask:0xf
	v_add_f32_dpp v234, v234, v234 row_half_mirror row_mask:0xf bank_mask:0xf
	v_add_f32_dpp v235, v235, v235 row_half_mirror row_mask:0xf bank_mask:0xf
	v_add_f32_dpp v236, v236, v236 row_half_mirror row_mask:0xf bank_mask:0xf
	v_add_f32_dpp v237, v237, v237 row_half_mirror row_mask:0xf bank_mask:0xf
	s_mov_b32 exec_lo, 0x10001
	s_mov_b32 exec_hi, 0x10001
	ds_write_b32 v155, v234 offset:1344
	ds_write_b32 v155, v235 offset:1360
	ds_write_b32 v155, v236 offset:1376
	ds_write_b32 v155, v237 offset:1392
	s_mov_b64 exec, -1
	ds_read2_b32 v[230:231], v243 offset0:80 offset1:84
	ds_read2_b32 v[232:233], v243 offset0:88 offset1:92
	s_waitcnt lgkmcnt(0)
; __device__ __forceinline__ void peer_token(const Params& P, int t, int lane, int* sidx, float* sval, const int* sid, const float* sgate, const unsigned* szero) {
;     ...
;         uint4 abuf[2][2][4];
;         unsigned off2[2];
; #pragma unroll
;         for (int hh = 0; hh < 2; ++hh) off2[hh] = (unsigned)sid[8 * hh + (lr & 7)] * 512u + lofs;
; #pragma unroll
;         for (int hh = 0; hh < 2; ++hh)
; #pragma unroll
;             for (int st = 0; st < 4; ++st) abuf[0][hh][st] = *(const uint4*)(Ub + (off2[hh] + 128 * st));
; #pragma unroll
;         for (int T = 0; T < 8; ++T) {
;             if (T + 1 < 8) {
; #pragma unroll
;                 for (int hh = 0; hh < 2; ++hh) off2[hh] = (unsigned)sid[16 * (T + 1) + 8 * hh + (lr & 7)] * 512u + lofs;
; #pragma unroll
;                 for (int hh = 0; hh < 2; ++hh)
; #pragma unroll
;                     for (int st = 0; st < 4; ++st) abuf[(T + 1) & 1][hh][st] = *(const uint4*)(Ub + (off2[hh] + 128 * st));
;             }
; #pragma unroll
;             for (int hh = 0; hh < 2; ++hh) {
;                 f32x4 au = (f32x4){0.f, 0.f, 0.f, 0.f};
; #pragma unroll
;                 for (int st = 0; st < 4; ++st) {
;                     const uint4 a4 = abuf[T & 1][hh][st];
;                     const v8i Av = {(int)a4.x, (int)a4.y, (int)a4.z, (int)a4.w, 0, 0, 0, 0};
;                     au = __builtin_amdgcn_mfma_scale_f32_16x16x128_f8f6f4(Av, Bv[st], au, 4, 0, 0, 0x7f7f7f7f, 0, 0x7f7f7f7f);
;                 }
;                 if (owner) *(f32x4*)(sact + 16 * T + 8 * hh) = au;
;             }
;         }
	v_lshl_add_u32 v230, v230, 9, v144
	v_lshl_add_u32 v231, v231, 9, v144
	v_lshl_add_u32 v232, v232, 9, v144
	v_lshl_add_u32 v233, v233, 9, v144
	global_load_dwordx4 v[32:35], v230, s[10:11]
	global_load_dwordx4 v[36:39], v230, s[10:11] offset:256
	global_load_dwordx4 v[40:43], v231, s[10:11]
	global_load_dwordx4 v[44:47], v231, s[10:11] offset:256
	global_load_dwordx4 v[48:51], v232, s[10:11]
	global_load_dwordx4 v[52:55], v232, s[10:11] offset:256
	global_load_dwordx4 v[56:59], v233, s[10:11]
	global_load_dwordx4 v[60:63], v233, s[10:11] offset:256
	s_waitcnt vmcnt(8)
	v_mfma_scale_f32_16x16x128_f8f6f4 v[64:67], v[0:3], v[162:169], 0, v133, v133 op_sel_hi:[0,0,0] cbsz:4
	v_mfma_scale_f32_16x16x128_f8f6f4 v[64:67], v[4:7], v[170:177], v[64:67], v133, v133 op_sel_hi:[0,0,0] cbsz:4
	v_mfma_scale_f32_16x16x128_f8f6f4 v[68:71], v[8:11], v[162:169], 0, v133, v133 op_sel_hi:[0,0,0] cbsz:4
	v_mfma_scale_f32_16x16x128_f8f6f4 v[68:71], v[12:15], v[170:177], v[68:71], v133, v133 op_sel_hi:[0,0,0] cbsz:4
	v_mfma_scale_f32_16x16x128_f8f6f4 v[72:75], v[16:19], v[162:169], 0, v133, v133 op_sel_hi:[0,0,0] cbsz:4
	v_mfma_scale_f32_16x16x128_f8f6f4 v[72:75], v[20:23], v[170:177], v[72:75], v133, v133 op_sel_hi:[0,0,0] cbsz:4
	v_mfma_scale_f32_16x16x128_f8f6f4 v[76:79], v[24:27], v[162:169], 0, v133, v133 op_sel_hi:[0,0,0] cbsz:4
	v_mfma_scale_f32_16x16x128_f8f6f4 v[76:79], v[28:31], v[170:177], v[76:79], v133, v133 op_sel_hi:[0,0,0] cbsz:4
	s_nop 3
	v_mul_f32_e32 v234, v158, v80
	v_mul_f32_e32 v235, v158, v84
	v_mul_f32_e32 v236, v158, v88
	v_mul_f32_e32 v237, v158, v92
	v_fmac_f32_e32 v234, v159, v81
	v_fmac_f32_e32 v235, v159, v85
	v_fmac_f32_e32 v236, v159, v89
	v_fmac_f32_e32 v237, v159, v93
	v_fmac_f32_e32 v234, v160, v82
	v_fmac_f32_e32 v235, v160, v86
	v_fmac_f32_e32 v236, v160, v90
	v_fmac_f32_e32 v237, v160, v94
	v_fmac_f32_e32 v234, v161, v83
	v_fmac_f32_e32 v235, v161, v87
	v_fmac_f32_e32 v236, v161, v91
	v_fmac_f32_e32 v237, v161, v95
	v_add_f32_dpp v234, v234, v234 quad_perm:[1,0,3,2] row_mask:0xf bank_mask:0xf
	v_add_f32_dpp v235, v235, v235 quad_perm:[1,0,3,2] row_mask:0xf bank_mask:0xf
	v_add_f32_dpp v236, v236, v236 quad_perm:[1,0,3,2] row_mask:0xf bank_mask:0xf
	v_add_f32_dpp v237, v237, v237 quad_perm:[1,0,3,2] row_mask:0xf bank_mask:0xf
	v_add_f32_dpp v234, v234, v234 quad_perm:[2,3,0,1] row_mask:0xf bank_mask:0xf
	v_add_f32_dpp v235, v235, v235 quad_perm:[2,3,0,1] row_mask:0xf bank_mask:0xf
	v_add_f32_dpp v236, v236, v236 quad_perm:[2,3,0,1] row_mask:0xf bank_mask:0xf
	v_add_f32_dpp v237, v237, v237 quad_perm:[2,3,0,1] row_mask:0xf bank_mask:0xf
	v_add_f32_dpp v234, v234, v234 row_half_mirror row_mask:0xf bank_mask:0xf
	v_add_f32_dpp v235, v235, v235 row_half_mirror row_mask:0xf bank_mask:0xf
	v_add_f32_dpp v236, v236, v236 row_half_mirror row_mask:0xf bank_mask:0xf
	v_add_f32_dpp v237, v237, v237 row_half_mirror row_mask:0xf bank_mask:0xf
	s_mov_b32 exec_lo, 0x10001
	s_mov_b32 exec_hi, 0x10001
	ds_write_b32 v155, v234 offset:1856
	ds_write_b32 v155, v235 offset:1872
	ds_write_b32 v155, v236 offset:1888
	ds_write_b32 v155, v237 offset:1904
	s_mov_b64 exec, -1
	ds_read2_b32 v[96:97], v244 offset0:80 offset1:84
	ds_read2_b32 v[98:99], v244 offset0:88 offset1:92
	s_waitcnt lgkmcnt(0)
	v_lshl_add_u32 v96, v96, 9, v144
	v_lshl_add_u32 v97, v97, 9, v144
	v_lshl_add_u32 v98, v98, 9, v144
	v_lshl_add_u32 v99, v99, 9, v144
	global_load_dwordx4 v[0:3], v96, s[10:11]
	global_load_dwordx4 v[4:7], v96, s[10:11] offset:256
	global_load_dwordx4 v[8:11], v97, s[10:11]
	global_load_dwordx4 v[12:15], v97, s[10:11] offset:256
	global_load_dwordx4 v[16:19], v98, s[10:11]
	global_load_dwordx4 v[20:23], v98, s[10:11] offset:256
	global_load_dwordx4 v[24:27], v99, s[10:11]
	global_load_dwordx4 v[28:31], v99, s[10:11] offset:256
	s_waitcnt vmcnt(8)
	v_mfma_scale_f32_16x16x128_f8f6f4 v[80:83], v[32:35], v[178:185], 0, v133, v133 op_sel_hi:[0,0,0] cbsz:4
	v_mfma_scale_f32_16x16x128_f8f6f4 v[80:83], v[36:39], v[186:193], v[80:83], v133, v133 op_sel_hi:[0,0,0] cbsz:4
	v_mfma_scale_f32_16x16x128_f8f6f4 v[84:87], v[40:43], v[178:185], 0, v133, v133 op_sel_hi:[0,0,0] cbsz:4
	v_mfma_scale_f32_16x16x128_f8f6f4 v[84:87], v[44:47], v[186:193], v[84:87], v133, v133 op_sel_hi:[0,0,0] cbsz:4
	v_mfma_scale_f32_16x16x128_f8f6f4 v[88:91], v[48:51], v[178:185], 0, v133, v133 op_sel_hi:[0,0,0] cbsz:4
	v_mfma_scale_f32_16x16x128_f8f6f4 v[88:91], v[52:55], v[186:193], v[88:91], v133, v133 op_sel_hi:[0,0,0] cbsz:4
	v_mfma_scale_f32_16x16x128_f8f6f4 v[92:95], v[56:59], v[178:185], 0, v133, v133 op_sel_hi:[0,0,0] cbsz:4
	v_mfma_scale_f32_16x16x128_f8f6f4 v[92:95], v[60:63], v[186:193], v[92:95], v133, v133 op_sel_hi:[0,0,0] cbsz:4
	s_nop 3
	v_mul_f32_e32 v234, v226, v64
	v_mul_f32_e32 v235, v226, v68
	v_mul_f32_e32 v236, v226, v72
	v_mul_f32_e32 v237, v226, v76
	v_fmac_f32_e32 v234, v227, v65
	v_fmac_f32_e32 v235, v227, v69
	v_fmac_f32_e32 v236, v227, v73
	v_fmac_f32_e32 v237, v227, v77
	v_fmac_f32_e32 v234, v228, v66
	v_fmac_f32_e32 v235, v228, v70
	v_fmac_f32_e32 v236, v228, v74
	v_fmac_f32_e32 v237, v228, v78
	v_fmac_f32_e32 v234, v229, v67
	v_fmac_f32_e32 v235, v229, v71
	v_fmac_f32_e32 v236, v229, v75
	v_fmac_f32_e32 v237, v229, v79
	v_add_f32_dpp v234, v234, v234 quad_perm:[1,0,3,2] row_mask:0xf bank_mask:0xf
	v_add_f32_dpp v235, v235, v235 quad_perm:[1,0,3,2] row_mask:0xf bank_mask:0xf
	v_add_f32_dpp v236, v236, v236 quad_perm:[1,0,3,2] row_mask:0xf bank_mask:0xf
	v_add_f32_dpp v237, v237, v237 quad_perm:[1,0,3,2] row_mask:0xf bank_mask:0xf
	v_add_f32_dpp v234, v234, v234 quad_perm:[2,3,0,1] row_mask:0xf bank_mask:0xf
	v_add_f32_dpp v235, v235, v235 quad_perm:[2,3,0,1] row_mask:0xf bank_mask:0xf
	v_add_f32_dpp v236, v236, v236 quad_perm:[2,3,0,1] row_mask:0xf bank_mask:0xf
	v_add_f32_dpp v237, v237, v237 quad_perm:[2,3,0,1] row_mask:0xf bank_mask:0xf
	v_add_f32_dpp v234, v234, v234 row_half_mirror row_mask:0xf bank_mask:0xf
	v_add_f32_dpp v235, v235, v235 row_half_mirror row_mask:0xf bank_mask:0xf
	v_add_f32_dpp v236, v236, v236 row_half_mirror row_mask:0xf bank_mask:0xf
	v_add_f32_dpp v237, v237, v237 row_half_mirror row_mask:0xf bank_mask:0xf
	s_mov_b32 exec_lo, 0x1000100
	s_mov_b32 exec_hi, 0x1000100
	ds_write_b32 v155, v234 offset:2368
	ds_write_b32 v155, v235 offset:2384
	ds_write_b32 v155, v236 offset:2400
	ds_write_b32 v155, v237 offset:2416
	s_mov_b64 exec, -1
	ds_read2_b32 v[230:231], v245 offset0:80 offset1:84
	ds_read2_b32 v[232:233], v245 offset0:88 offset1:92
	s_waitcnt lgkmcnt(0)
; __device__ __forceinline__ void peer_token(const Params& P, int t, int lane, int* sidx, float* sval, const int* sid, const float* sgate, const unsigned* szero) {
;     ...
;         uint4 abuf[2][2][4];
;         unsigned off2[2];
; #pragma unroll
;         for (int hh = 0; hh < 2; ++hh) off2[hh] = (unsigned)sid[8 * hh + (lr & 7)] * 512u + lofs;
; #pragma unroll
;         for (int hh = 0; hh < 2; ++hh)
; #pragma unroll
;             for (int st = 0; st < 4; ++st) abuf[0][hh][st] = *(const uint4*)(Ub + (off2[hh] + 128 * st));
; #pragma unroll
;         for (int T = 0; T < 8; ++T) {
;             if (T + 1 < 8) {
; #pragma unroll
;                 for (int hh = 0; hh < 2; ++hh) off2[hh] = (unsigned)sid[16 * (T + 1) + 8 * hh + (lr & 7)] * 512u + lofs;
; #pragma unroll
;                 for (int hh = 0; hh < 2; ++hh)
; #pragma unroll
;                     for (int st = 0; st < 4; ++st) abuf[(T + 1) & 1][hh][st] = *(const uint4*)(Ub + (off2[hh] + 128 * st));
;             }
; #pragma unroll
;             for (int hh = 0; hh < 2; ++hh) {
;                 f32x4 au = (f32x4){0.f, 0.f, 0.f, 0.f};
; #pragma unroll
;                 for (int st = 0; st < 4; ++st) {
;                     const uint4 a4 = abuf[T & 1][hh][st];
;                     const v8i Av = {(int)a4.x, (int)a4.y, (int)a4.z, (int)a4.w, 0, 0, 0, 0};
;                     au = __builtin_amdgcn_mfma_scale_f32_16x16x128_f8f6f4(Av, Bv[st], au, 4, 0, 0, 0x7f7f7f7f, 0, 0x7f7f7f7f);
;                 }
;                 if (owner) *(f32x4*)(sact + 16 * T + 8 * hh) = au;
;             }
;         }
	v_lshl_add_u32 v230, v230, 9, v144
	v_lshl_add_u32 v231, v231, 9, v144
	v_lshl_add_u32 v232, v232, 9, v144
	v_lshl_add_u32 v233, v233, 9, v144
	global_load_dwordx4 v[32:35], v230, s[10:11]
	global_load_dwordx4 v[36:39], v230, s[10:11] offset:256
	global_load_dwordx4 v[40:43], v231, s[10:11]
	global_load_dwordx4 v[44:47], v231, s[10:11] offset:256
	global_load_dwordx4 v[48:51], v232, s[10:11]
	global_load_dwordx4 v[52:55], v232, s[10:11] offset:256
	global_load_dwordx4 v[56:59], v233, s[10:11]
	global_load_dwordx4 v[60:63], v233, s[10:11] offset:256
	s_waitcnt vmcnt(8)
	v_mfma_scale_f32_16x16x128_f8f6f4 v[64:67], v[0:3], v[194:201], 0, v133, v133 op_sel_hi:[0,0,0] cbsz:4
	v_mfma_scale_f32_16x16x128_f8f6f4 v[64:67], v[4:7], v[202:209], v[64:67], v133, v133 op_sel_hi:[0,0,0] cbsz:4
	v_mfma_scale_f32_16x16x128_f8f6f4 v[68:71], v[8:11], v[194:201], 0, v133, v133 op_sel_hi:[0,0,0] cbsz:4
	v_mfma_scale_f32_16x16x128_f8f6f4 v[68:71], v[12:15], v[202:209], v[68:71], v133, v133 op_sel_hi:[0,0,0] cbsz:4
	v_mfma_scale_f32_16x16x128_f8f6f4 v[72:75], v[16:19], v[194:201], 0, v133, v133 op_sel_hi:[0,0,0] cbsz:4
	v_mfma_scale_f32_16x16x128_f8f6f4 v[72:75], v[20:23], v[202:209], v[72:75], v133, v133 op_sel_hi:[0,0,0] cbsz:4
	v_mfma_scale_f32_16x16x128_f8f6f4 v[76:79], v[24:27], v[194:201], 0, v133, v133 op_sel_hi:[0,0,0] cbsz:4
	v_mfma_scale_f32_16x16x128_f8f6f4 v[76:79], v[28:31], v[202:209], v[76:79], v133, v133 op_sel_hi:[0,0,0] cbsz:4
	s_nop 3
	v_mul_f32_e32 v234, v226, v80
	v_mul_f32_e32 v235, v226, v84
	v_mul_f32_e32 v236, v226, v88
	v_mul_f32_e32 v237, v226, v92
	v_fmac_f32_e32 v234, v227, v81
	v_fmac_f32_e32 v235, v227, v85
	v_fmac_f32_e32 v236, v227, v89
	v_fmac_f32_e32 v237, v227, v93
	v_fmac_f32_e32 v234, v228, v82
	v_fmac_f32_e32 v235, v228, v86
	v_fmac_f32_e32 v236, v228, v90
	v_fmac_f32_e32 v237, v228, v94
	v_fmac_f32_e32 v234, v229, v83
	v_fmac_f32_e32 v235, v229, v87
	v_fmac_f32_e32 v236, v229, v91
	v_fmac_f32_e32 v237, v229, v95
	v_add_f32_dpp v234, v234, v234 quad_perm:[1,0,3,2] row_mask:0xf bank_mask:0xf
	v_add_f32_dpp v235, v235, v235 quad_perm:[1,0,3,2] row_mask:0xf bank_mask:0xf
	v_add_f32_dpp v236, v236, v236 quad_perm:[1,0,3,2] row_mask:0xf bank_mask:0xf
	v_add_f32_dpp v237, v237, v237 quad_perm:[1,0,3,2] row_mask:0xf bank_mask:0xf
	v_add_f32_dpp v234, v234, v234 quad_perm:[2,3,0,1] row_mask:0xf bank_mask:0xf
	v_add_f32_dpp v235, v235, v235 quad_perm:[2,3,0,1] row_mask:0xf bank_mask:0xf
	v_add_f32_dpp v236, v236, v236 quad_perm:[2,3,0,1] row_mask:0xf bank_mask:0xf
	v_add_f32_dpp v237, v237, v237 quad_perm:[2,3,0,1] row_mask:0xf bank_mask:0xf
	v_add_f32_dpp v234, v234, v234 row_half_mirror row_mask:0xf bank_mask:0xf
	v_add_f32_dpp v235, v235, v235 row_half_mirror row_mask:0xf bank_mask:0xf
	v_add_f32_dpp v236, v236, v236 row_half_mirror row_mask:0xf bank_mask:0xf
	v_add_f32_dpp v237, v237, v237 row_half_mirror row_mask:0xf bank_mask:0xf
	s_mov_b32 exec_lo, 0x1000100
	s_mov_b32 exec_hi, 0x1000100
	ds_write_b32 v155, v234 offset:2880
	ds_write_b32 v155, v235 offset:2896
	ds_write_b32 v155, v236 offset:2912
	ds_write_b32 v155, v237 offset:2928
	s_mov_b64 exec, -1
	ds_read2_b32 v[96:97], v238 offset0:96 offset1:100
	ds_read2_b32 v[98:99], v238 offset0:104 offset1:108
	s_waitcnt lgkmcnt(0)
	v_lshl_add_u32 v96, v96, 9, v144
	v_lshl_add_u32 v97, v97, 9, v144
	v_lshl_add_u32 v98, v98, 9, v144
	v_lshl_add_u32 v99, v99, 9, v144
	global_load_dwordx4 v[0:3], v96, s[10:11]
	global_load_dwordx4 v[4:7], v96, s[10:11] offset:256
	global_load_dwordx4 v[8:11], v97, s[10:11]
	global_load_dwordx4 v[12:15], v97, s[10:11] offset:256
	global_load_dwordx4 v[16:19], v98, s[10:11]
	global_load_dwordx4 v[20:23], v98, s[10:11] offset:256
	global_load_dwordx4 v[24:27], v99, s[10:11]
	global_load_dwordx4 v[28:31], v99, s[10:11] offset:256
	s_waitcnt vmcnt(8)
	v_mfma_scale_f32_16x16x128_f8f6f4 v[80:83], v[32:35], v[210:217], 0, v133, v133 op_sel_hi:[0,0,0] cbsz:4
	v_mfma_scale_f32_16x16x128_f8f6f4 v[80:83], v[36:39], v[218:225], v[80:83], v133, v133 op_sel_hi:[0,0,0] cbsz:4
	v_mfma_scale_f32_16x16x128_f8f6f4 v[84:87], v[40:43], v[210:217], 0, v133, v133 op_sel_hi:[0,0,0] cbsz:4
	v_mfma_scale_f32_16x16x128_f8f6f4 v[84:87], v[44:47], v[218:225], v[84:87], v133, v133 op_sel_hi:[0,0,0] cbsz:4
	v_mfma_scale_f32_16x16x128_f8f6f4 v[88:91], v[48:51], v[210:217], 0, v133, v133 op_sel_hi:[0,0,0] cbsz:4
	v_mfma_scale_f32_16x16x128_f8f6f4 v[88:91], v[52:55], v[218:225], v[88:91], v133, v133 op_sel_hi:[0,0,0] cbsz:4
	v_mfma_scale_f32_16x16x128_f8f6f4 v[92:95], v[56:59], v[210:217], 0, v133, v133 op_sel_hi:[0,0,0] cbsz:4
	v_mfma_scale_f32_16x16x128_f8f6f4 v[92:95], v[60:63], v[218:225], v[92:95], v133, v133 op_sel_hi:[0,0,0] cbsz:4
	s_nop 3
	v_mul_f32_e32 v234, v226, v64
	v_mul_f32_e32 v235, v226, v68
	v_mul_f32_e32 v236, v226, v72
	v_mul_f32_e32 v237, v226, v76
	v_fmac_f32_e32 v234, v227, v65
	v_fmac_f32_e32 v235, v227, v69
	v_fmac_f32_e32 v236, v227, v73
	v_fmac_f32_e32 v237, v227, v77
	v_fmac_f32_e32 v234, v228, v66
	v_fmac_f32_e32 v235, v228, v70
	v_fmac_f32_e32 v236, v228, v74
	v_fmac_f32_e32 v237, v228, v78
	v_fmac_f32_e32 v234, v229, v67
	v_fmac_f32_e32 v235, v229, v71
	v_fmac_f32_e32 v236, v229, v75
	v_fmac_f32_e32 v237, v229, v79
	v_add_f32_dpp v234, v234, v234 quad_perm:[1,0,3,2] row_mask:0xf bank_mask:0xf
	v_add_f32_dpp v235, v235, v235 quad_perm:[1,0,3,2] row_mask:0xf bank_mask:0xf
	v_add_f32_dpp v236, v236, v236 quad_perm:[1,0,3,2] row_mask:0xf bank_mask:0xf
	v_add_f32_dpp v237, v237, v237 quad_perm:[1,0,3,2] row_mask:0xf bank_mask:0xf
	v_add_f32_dpp v234, v234, v234 quad_perm:[2,3,0,1] row_mask:0xf bank_mask:0xf
	v_add_f32_dpp v235, v235, v235 quad_perm:[2,3,0,1] row_mask:0xf bank_mask:0xf
	v_add_f32_dpp v236, v236, v236 quad_perm:[2,3,0,1] row_mask:0xf bank_mask:0xf
	v_add_f32_dpp v237, v237, v237 quad_perm:[2,3,0,1] row_mask:0xf bank_mask:0xf
	v_add_f32_dpp v234, v234, v234 row_half_mirror row_mask:0xf bank_mask:0xf
	v_add_f32_dpp v235, v235, v235 row_half_mirror row_mask:0xf bank_mask:0xf
	v_add_f32_dpp v236, v236, v236 row_half_mirror row_mask:0xf bank_mask:0xf
	v_add_f32_dpp v237, v237, v237 row_half_mirror row_mask:0xf bank_mask:0xf
	s_mov_b32 exec_lo, 0x1000100
	s_mov_b32 exec_hi, 0x1000100
	ds_write_b32 v155, v234 offset:3392
	ds_write_b32 v155, v235 offset:3408
	ds_write_b32 v155, v236 offset:3424
	ds_write_b32 v155, v237 offset:3440
	s_mov_b64 exec, -1
	ds_read2_b32 v[230:231], v239 offset0:96 offset1:100
	ds_read2_b32 v[232:233], v239 offset0:104 offset1:108
	s_waitcnt lgkmcnt(0)
; __device__ __forceinline__ void peer_token(const Params& P, int t, int lane, int* sidx, float* sval, const int* sid, const float* sgate, const unsigned* szero) {
;     ...
;         uint4 abuf[2][2][4];
;         unsigned off2[2];
; #pragma unroll
;         for (int hh = 0; hh < 2; ++hh) off2[hh] = (unsigned)sid[8 * hh + (lr & 7)] * 512u + lofs;
; #pragma unroll
;         for (int hh = 0; hh < 2; ++hh)
; #pragma unroll
;             for (int st = 0; st < 4; ++st) abuf[0][hh][st] = *(const uint4*)(Ub + (off2[hh] + 128 * st));
; #pragma unroll
;         for (int T = 0; T < 8; ++T) {
;             if (T + 1 < 8) {
; #pragma unroll
;                 for (int hh = 0; hh < 2; ++hh) off2[hh] = (unsigned)sid[16 * (T + 1) + 8 * hh + (lr & 7)] * 512u + lofs;
; #pragma unroll
;                 for (int hh = 0; hh < 2; ++hh)
; #pragma unroll
;                     for (int st = 0; st < 4; ++st) abuf[(T + 1) & 1][hh][st] = *(const uint4*)(Ub + (off2[hh] + 128 * st));
;             }
; #pragma unroll
;             for (int hh = 0; hh < 2; ++hh) {
;                 f32x4 au = (f32x4){0.f, 0.f, 0.f, 0.f};
; #pragma unroll
;                 for (int st = 0; st < 4; ++st) {
;                     const uint4 a4 = abuf[T & 1][hh][st];
;                     const v8i Av = {(int)a4.x, (int)a4.y, (int)a4.z, (int)a4.w, 0, 0, 0, 0};
;                     au = __builtin_amdgcn_mfma_scale_f32_16x16x128_f8f6f4(Av, Bv[st], au, 4, 0, 0, 0x7f7f7f7f, 0, 0x7f7f7f7f);
;                 }
;                 if (owner) *(f32x4*)(sact + 16 * T + 8 * hh) = au;
;             }
;         }
	v_lshl_add_u32 v230, v230, 9, v144
	v_lshl_add_u32 v231, v231, 9, v144
	v_lshl_add_u32 v232, v232, 9, v144
	v_lshl_add_u32 v233, v233, 9, v144
	global_load_dwordx4 v[32:35], v230, s[10:11]
	global_load_dwordx4 v[36:39], v230, s[10:11] offset:256
	global_load_dwordx4 v[40:43], v231, s[10:11]
	global_load_dwordx4 v[44:47], v231, s[10:11] offset:256
	global_load_dwordx4 v[48:51], v232, s[10:11]
	global_load_dwordx4 v[52:55], v232, s[10:11] offset:256
	global_load_dwordx4 v[56:59], v233, s[10:11]
	global_load_dwordx4 v[60:63], v233, s[10:11] offset:256
	s_waitcnt vmcnt(8)
	v_mfma_scale_f32_16x16x128_f8f6f4 v[64:67], v[0:3], v[162:169], 0, v133, v133 op_sel_hi:[0,0,0] cbsz:4
	v_mfma_scale_f32_16x16x128_f8f6f4 v[64:67], v[4:7], v[170:177], v[64:67], v133, v133 op_sel_hi:[0,0,0] cbsz:4
	v_mfma_scale_f32_16x16x128_f8f6f4 v[68:71], v[8:11], v[162:169], 0, v133, v133 op_sel_hi:[0,0,0] cbsz:4
	v_mfma_scale_f32_16x16x128_f8f6f4 v[68:71], v[12:15], v[170:177], v[68:71], v133, v133 op_sel_hi:[0,0,0] cbsz:4
	v_mfma_scale_f32_16x16x128_f8f6f4 v[72:75], v[16:19], v[162:169], 0, v133, v133 op_sel_hi:[0,0,0] cbsz:4
	v_mfma_scale_f32_16x16x128_f8f6f4 v[72:75], v[20:23], v[170:177], v[72:75], v133, v133 op_sel_hi:[0,0,0] cbsz:4
	v_mfma_scale_f32_16x16x128_f8f6f4 v[76:79], v[24:27], v[162:169], 0, v133, v133 op_sel_hi:[0,0,0] cbsz:4
	v_mfma_scale_f32_16x16x128_f8f6f4 v[76:79], v[28:31], v[170:177], v[76:79], v133, v133 op_sel_hi:[0,0,0] cbsz:4
	s_nop 3
	v_mul_f32_e32 v234, v226, v80
	v_mul_f32_e32 v235, v226, v84
	v_mul_f32_e32 v236, v226, v88
	v_mul_f32_e32 v237, v226, v92
	v_fmac_f32_e32 v234, v227, v81
	v_fmac_f32_e32 v235, v227, v85
	v_fmac_f32_e32 v236, v227, v89
	v_fmac_f32_e32 v237, v227, v93
	v_fmac_f32_e32 v234, v228, v82
	v_fmac_f32_e32 v235, v228, v86
	v_fmac_f32_e32 v236, v228, v90
	v_fmac_f32_e32 v237, v228, v94
	v_fmac_f32_e32 v234, v229, v83
	v_fmac_f32_e32 v235, v229, v87
	v_fmac_f32_e32 v236, v229, v91
	v_fmac_f32_e32 v237, v229, v95
	v_add_f32_dpp v234, v234, v234 quad_perm:[1,0,3,2] row_mask:0xf bank_mask:0xf
	v_add_f32_dpp v235, v235, v235 quad_perm:[1,0,3,2] row_mask:0xf bank_mask:0xf
	v_add_f32_dpp v236, v236, v236 quad_perm:[1,0,3,2] row_mask:0xf bank_mask:0xf
	v_add_f32_dpp v237, v237, v237 quad_perm:[1,0,3,2] row_mask:0xf bank_mask:0xf
	v_add_f32_dpp v234, v234, v234 quad_perm:[2,3,0,1] row_mask:0xf bank_mask:0xf
	v_add_f32_dpp v235, v235, v235 quad_perm:[2,3,0,1] row_mask:0xf bank_mask:0xf
	v_add_f32_dpp v236, v236, v236 quad_perm:[2,3,0,1] row_mask:0xf bank_mask:0xf
	v_add_f32_dpp v237, v237, v237 quad_perm:[2,3,0,1] row_mask:0xf bank_mask:0xf
	v_add_f32_dpp v234, v234, v234 row_half_mirror row_mask:0xf bank_mask:0xf
	v_add_f32_dpp v235, v235, v235 row_half_mirror row_mask:0xf bank_mask:0xf
	v_add_f32_dpp v236, v236, v236 row_half_mirror row_mask:0xf bank_mask:0xf
	v_add_f32_dpp v237, v237, v237 row_half_mirror row_mask:0xf bank_mask:0xf
	s_mov_b32 exec_lo, 0x1000100
	s_mov_b32 exec_hi, 0x1000100
	ds_write_b32 v155, v234 offset:3904
	ds_write_b32 v155, v235 offset:3920
	ds_write_b32 v155, v236 offset:3936
	ds_write_b32 v155, v237 offset:3952
	s_mov_b64 exec, -1
	ds_read2_b32 v[96:97], v240 offset0:96 offset1:100
	ds_read2_b32 v[98:99], v240 offset0:104 offset1:108
	s_waitcnt lgkmcnt(0)
	v_lshl_add_u32 v96, v96, 9, v144
	v_lshl_add_u32 v97, v97, 9, v144
	v_lshl_add_u32 v98, v98, 9, v144
	v_lshl_add_u32 v99, v99, 9, v144
	global_load_dwordx4 v[0:3], v96, s[10:11]
	global_load_dwordx4 v[4:7], v96, s[10:11] offset:256
	global_load_dwordx4 v[8:11], v97, s[10:11]
	global_load_dwordx4 v[12:15], v97, s[10:11] offset:256
	global_load_dwordx4 v[16:19], v98, s[10:11]
	global_load_dwordx4 v[20:23], v98, s[10:11] offset:256
	global_load_dwordx4 v[24:27], v99, s[10:11]
	global_load_dwordx4 v[28:31], v99, s[10:11] offset:256
	s_waitcnt vmcnt(8)
	v_mfma_scale_f32_16x16x128_f8f6f4 v[80:83], v[32:35], v[178:185], 0, v133, v133 op_sel_hi:[0,0,0] cbsz:4
	v_mfma_scale_f32_16x16x128_f8f6f4 v[80:83], v[36:39], v[186:193], v[80:83], v133, v133 op_sel_hi:[0,0,0] cbsz:4
	v_mfma_scale_f32_16x16x128_f8f6f4 v[84:87], v[40:43], v[178:185], 0, v133, v133 op_sel_hi:[0,0,0] cbsz:4
	v_mfma_scale_f32_16x16x128_f8f6f4 v[84:87], v[44:47], v[186:193], v[84:87], v133, v133 op_sel_hi:[0,0,0] cbsz:4
	v_mfma_scale_f32_16x16x128_f8f6f4 v[88:91], v[48:51], v[178:185], 0, v133, v133 op_sel_hi:[0,0,0] cbsz:4
	v_mfma_scale_f32_16x16x128_f8f6f4 v[88:91], v[52:55], v[186:193], v[88:91], v133, v133 op_sel_hi:[0,0,0] cbsz:4
	v_mfma_scale_f32_16x16x128_f8f6f4 v[92:95], v[56:59], v[178:185], 0, v133, v133 op_sel_hi:[0,0,0] cbsz:4
	v_mfma_scale_f32_16x16x128_f8f6f4 v[92:95], v[60:63], v[186:193], v[92:95], v133, v133 op_sel_hi:[0,0,0] cbsz:4
	s_nop 3
	v_mul_f32_e32 v234, v158, v64
	v_mul_f32_e32 v235, v158, v68
	v_mul_f32_e32 v236, v158, v72
	v_mul_f32_e32 v237, v158, v76
	v_fmac_f32_e32 v234, v159, v65
	v_fmac_f32_e32 v235, v159, v69
	v_fmac_f32_e32 v236, v159, v73
	v_fmac_f32_e32 v237, v159, v77
	v_fmac_f32_e32 v234, v160, v66
	v_fmac_f32_e32 v235, v160, v70
	v_fmac_f32_e32 v236, v160, v74
	v_fmac_f32_e32 v237, v160, v78
	v_fmac_f32_e32 v234, v161, v67
	v_fmac_f32_e32 v235, v161, v71
	v_fmac_f32_e32 v236, v161, v75
	v_fmac_f32_e32 v237, v161, v79
	v_add_f32_dpp v234, v234, v234 quad_perm:[1,0,3,2] row_mask:0xf bank_mask:0xf
	v_add_f32_dpp v235, v235, v235 quad_perm:[1,0,3,2] row_mask:0xf bank_mask:0xf
	v_add_f32_dpp v236, v236, v236 quad_perm:[1,0,3,2] row_mask:0xf bank_mask:0xf
	v_add_f32_dpp v237, v237, v237 quad_perm:[1,0,3,2] row_mask:0xf bank_mask:0xf
	v_add_f32_dpp v234, v234, v234 quad_perm:[2,3,0,1] row_mask:0xf bank_mask:0xf
	v_add_f32_dpp v235, v235, v235 quad_perm:[2,3,0,1] row_mask:0xf bank_mask:0xf
	v_add_f32_dpp v236, v236, v236 quad_perm:[2,3,0,1] row_mask:0xf bank_mask:0xf
	v_add_f32_dpp v237, v237, v237 quad_perm:[2,3,0,1] row_mask:0xf bank_mask:0xf
	v_add_f32_dpp v234, v234, v234 row_half_mirror row_mask:0xf bank_mask:0xf
	v_add_f32_dpp v235, v235, v235 row_half_mirror row_mask:0xf bank_mask:0xf
	v_add_f32_dpp v236, v236, v236 row_half_mirror row_mask:0xf bank_mask:0xf
	v_add_f32_dpp v237, v237, v237 row_half_mirror row_mask:0xf bank_mask:0xf
	s_mov_b32 exec_lo, 0x10001
	s_mov_b32 exec_hi, 0x10001
	ds_write_b32 v155, v234 offset:384
	ds_write_b32 v155, v235 offset:400
	ds_write_b32 v155, v236 offset:416
	ds_write_b32 v155, v237 offset:432
	s_mov_b64 exec, -1
	ds_read2_b32 v[230:231], v241 offset0:96 offset1:100
	ds_read2_b32 v[232:233], v241 offset0:104 offset1:108
	s_waitcnt lgkmcnt(0)
; __device__ __forceinline__ void peer_token(const Params& P, int t, int lane, int* sidx, float* sval, const int* sid, const float* sgate, const unsigned* szero) {
;     ...
;         uint4 abuf[2][2][4];
;         unsigned off2[2];
; #pragma unroll
;         for (int hh = 0; hh < 2; ++hh) off2[hh] = (unsigned)sid[8 * hh + (lr & 7)] * 512u + lofs;
; #pragma unroll
;         for (int hh = 0; hh < 2; ++hh)
; #pragma unroll
;             for (int st = 0; st < 4; ++st) abuf[0][hh][st] = *(const uint4*)(Ub + (off2[hh] + 128 * st));
; #pragma unroll
;         for (int T = 0; T < 8; ++T) {
;             if (T + 1 < 8) {
; #pragma unroll
;                 for (int hh = 0; hh < 2; ++hh) off2[hh] = (unsigned)sid[16 * (T + 1) + 8 * hh + (lr & 7)] * 512u + lofs;
; #pragma unroll
;                 for (int hh = 0; hh < 2; ++hh)
; #pragma unroll
;                     for (int st = 0; st < 4; ++st) abuf[(T + 1) & 1][hh][st] = *(const uint4*)(Ub + (off2[hh] + 128 * st));
;             }
; #pragma unroll
;             for (int hh = 0; hh < 2; ++hh) {
;                 f32x4 au = (f32x4){0.f, 0.f, 0.f, 0.f};
; #pragma unroll
;                 for (int st = 0; st < 4; ++st) {
;                     const uint4 a4 = abuf[T & 1][hh][st];
;                     const v8i Av = {(int)a4.x, (int)a4.y, (int)a4.z, (int)a4.w, 0, 0, 0, 0};
;                     au = __builtin_amdgcn_mfma_scale_f32_16x16x128_f8f6f4(Av, Bv[st], au, 4, 0, 0, 0x7f7f7f7f, 0, 0x7f7f7f7f);
;                 }
;                 if (owner) *(f32x4*)(sact + 16 * T + 8 * hh) = au;
;             }
;         }
	v_lshl_add_u32 v230, v230, 9, v144
	v_lshl_add_u32 v231, v231, 9, v144
	v_lshl_add_u32 v232, v232, 9, v144
	v_lshl_add_u32 v233, v233, 9, v144
	global_load_dwordx4 v[32:35], v230, s[10:11]
	global_load_dwordx4 v[36:39], v230, s[10:11] offset:256
	global_load_dwordx4 v[40:43], v231, s[10:11]
	global_load_dwordx4 v[44:47], v231, s[10:11] offset:256
	global_load_dwordx4 v[48:51], v232, s[10:11]
	global_load_dwordx4 v[52:55], v232, s[10:11] offset:256
	global_load_dwordx4 v[56:59], v233, s[10:11]
	global_load_dwordx4 v[60:63], v233, s[10:11] offset:256
	s_waitcnt vmcnt(8)
	v_mfma_scale_f32_16x16x128_f8f6f4 v[64:67], v[0:3], v[194:201], 0, v133, v133 op_sel_hi:[0,0,0] cbsz:4
	v_mfma_scale_f32_16x16x128_f8f6f4 v[64:67], v[4:7], v[202:209], v[64:67], v133, v133 op_sel_hi:[0,0,0] cbsz:4
	v_mfma_scale_f32_16x16x128_f8f6f4 v[68:71], v[8:11], v[194:201], 0, v133, v133 op_sel_hi:[0,0,0] cbsz:4
	v_mfma_scale_f32_16x16x128_f8f6f4 v[68:71], v[12:15], v[202:209], v[68:71], v133, v133 op_sel_hi:[0,0,0] cbsz:4
	v_mfma_scale_f32_16x16x128_f8f6f4 v[72:75], v[16:19], v[194:201], 0, v133, v133 op_sel_hi:[0,0,0] cbsz:4
	v_mfma_scale_f32_16x16x128_f8f6f4 v[72:75], v[20:23], v[202:209], v[72:75], v133, v133 op_sel_hi:[0,0,0] cbsz:4
	v_mfma_scale_f32_16x16x128_f8f6f4 v[76:79], v[24:27], v[194:201], 0, v133, v133 op_sel_hi:[0,0,0] cbsz:4
	v_mfma_scale_f32_16x16x128_f8f6f4 v[76:79], v[28:31], v[202:209], v[76:79], v133, v133 op_sel_hi:[0,0,0] cbsz:4
	s_nop 3
	v_mul_f32_e32 v234, v158, v80
	v_mul_f32_e32 v235, v158, v84
	v_mul_f32_e32 v236, v158, v88
	v_mul_f32_e32 v237, v158, v92
	v_fmac_f32_e32 v234, v159, v81
	v_fmac_f32_e32 v235, v159, v85
	v_fmac_f32_e32 v236, v159, v89
	v_fmac_f32_e32 v237, v159, v93
	v_fmac_f32_e32 v234, v160, v82
	v_fmac_f32_e32 v235, v160, v86
	v_fmac_f32_e32 v236, v160, v90
	v_fmac_f32_e32 v237, v160, v94
	v_fmac_f32_e32 v234, v161, v83
	v_fmac_f32_e32 v235, v161, v87
	v_fmac_f32_e32 v236, v161, v91
	v_fmac_f32_e32 v237, v161, v95
	v_add_f32_dpp v234, v234, v234 quad_perm:[1,0,3,2] row_mask:0xf bank_mask:0xf
	v_add_f32_dpp v235, v235, v235 quad_perm:[1,0,3,2] row_mask:0xf bank_mask:0xf
	v_add_f32_dpp v236, v236, v236 quad_perm:[1,0,3,2] row_mask:0xf bank_mask:0xf
	v_add_f32_dpp v237, v237, v237 quad_perm:[1,0,3,2] row_mask:0xf bank_mask:0xf
	v_add_f32_dpp v234, v234, v234 quad_perm:[2,3,0,1] row_mask:0xf bank_mask:0xf
	v_add_f32_dpp v235, v235, v235 quad_perm:[2,3,0,1] row_mask:0xf bank_mask:0xf
	v_add_f32_dpp v236, v236, v236 quad_perm:[2,3,0,1] row_mask:0xf bank_mask:0xf
	v_add_f32_dpp v237, v237, v237 quad_perm:[2,3,0,1] row_mask:0xf bank_mask:0xf
	v_add_f32_dpp v234, v234, v234 row_half_mirror row_mask:0xf bank_mask:0xf
	v_add_f32_dpp v235, v235, v235 row_half_mirror row_mask:0xf bank_mask:0xf
	v_add_f32_dpp v236, v236, v236 row_half_mirror row_mask:0xf bank_mask:0xf
	v_add_f32_dpp v237, v237, v237 row_half_mirror row_mask:0xf bank_mask:0xf
	s_mov_b32 exec_lo, 0x10001
	s_mov_b32 exec_hi, 0x10001
	ds_write_b32 v155, v234 offset:896
	ds_write_b32 v155, v235 offset:912
	ds_write_b32 v155, v236 offset:928
	ds_write_b32 v155, v237 offset:944
	s_mov_b64 exec, -1
	ds_read2_b32 v[96:97], v242 offset0:96 offset1:100
	ds_read2_b32 v[98:99], v242 offset0:104 offset1:108
	s_waitcnt lgkmcnt(0)
	v_lshl_add_u32 v96, v96, 9, v144
	v_lshl_add_u32 v97, v97, 9, v144
	v_lshl_add_u32 v98, v98, 9, v144
	v_lshl_add_u32 v99, v99, 9, v144
	global_load_dwordx4 v[0:3], v96, s[10:11]
	global_load_dwordx4 v[4:7], v96, s[10:11] offset:256
	global_load_dwordx4 v[8:11], v97, s[10:11]
	global_load_dwordx4 v[12:15], v97, s[10:11] offset:256
	global_load_dwordx4 v[16:19], v98, s[10:11]
	global_load_dwordx4 v[20:23], v98, s[10:11] offset:256
	global_load_dwordx4 v[24:27], v99, s[10:11]
	global_load_dwordx4 v[28:31], v99, s[10:11] offset:256
	s_waitcnt vmcnt(8)
	v_mfma_scale_f32_16x16x128_f8f6f4 v[80:83], v[32:35], v[210:217], 0, v133, v133 op_sel_hi:[0,0,0] cbsz:4
	v_mfma_scale_f32_16x16x128_f8f6f4 v[80:83], v[36:39], v[218:225], v[80:83], v133, v133 op_sel_hi:[0,0,0] cbsz:4
	v_mfma_scale_f32_16x16x128_f8f6f4 v[84:87], v[40:43], v[210:217], 0, v133, v133 op_sel_hi:[0,0,0] cbsz:4
	v_mfma_scale_f32_16x16x128_f8f6f4 v[84:87], v[44:47], v[218:225], v[84:87], v133, v133 op_sel_hi:[0,0,0] cbsz:4
	v_mfma_scale_f32_16x16x128_f8f6f4 v[88:91], v[48:51], v[210:217], 0, v133, v133 op_sel_hi:[0,0,0] cbsz:4
	v_mfma_scale_f32_16x16x128_f8f6f4 v[88:91], v[52:55], v[218:225], v[88:91], v133, v133 op_sel_hi:[0,0,0] cbsz:4
	v_mfma_scale_f32_16x16x128_f8f6f4 v[92:95], v[56:59], v[210:217], 0, v133, v133 op_sel_hi:[0,0,0] cbsz:4
	v_mfma_scale_f32_16x16x128_f8f6f4 v[92:95], v[60:63], v[218:225], v[92:95], v133, v133 op_sel_hi:[0,0,0] cbsz:4
	s_nop 3
	v_mul_f32_e32 v234, v158, v64
	v_mul_f32_e32 v235, v158, v68
	v_mul_f32_e32 v236, v158, v72
	v_mul_f32_e32 v237, v158, v76
	v_fmac_f32_e32 v234, v159, v65
	v_fmac_f32_e32 v235, v159, v69
	v_fmac_f32_e32 v236, v159, v73
	v_fmac_f32_e32 v237, v159, v77
	v_fmac_f32_e32 v234, v160, v66
	v_fmac_f32_e32 v235, v160, v70
	v_fmac_f32_e32 v236, v160, v74
	v_fmac_f32_e32 v237, v160, v78
	v_fmac_f32_e32 v234, v161, v67
	v_fmac_f32_e32 v235, v161, v71
	v_fmac_f32_e32 v236, v161, v75
	v_fmac_f32_e32 v237, v161, v79
	v_add_f32_dpp v234, v234, v234 quad_perm:[1,0,3,2] row_mask:0xf bank_mask:0xf
	v_add_f32_dpp v235, v235, v235 quad_perm:[1,0,3,2] row_mask:0xf bank_mask:0xf
	v_add_f32_dpp v236, v236, v236 quad_perm:[1,0,3,2] row_mask:0xf bank_mask:0xf
	v_add_f32_dpp v237, v237, v237 quad_perm:[1,0,3,2] row_mask:0xf bank_mask:0xf
	v_add_f32_dpp v234, v234, v234 quad_perm:[2,3,0,1] row_mask:0xf bank_mask:0xf
	v_add_f32_dpp v235, v235, v235 quad_perm:[2,3,0,1] row_mask:0xf bank_mask:0xf
	v_add_f32_dpp v236, v236, v236 quad_perm:[2,3,0,1] row_mask:0xf bank_mask:0xf
	v_add_f32_dpp v237, v237, v237 quad_perm:[2,3,0,1] row_mask:0xf bank_mask:0xf
	v_add_f32_dpp v234, v234, v234 row_half_mirror row_mask:0xf bank_mask:0xf
	v_add_f32_dpp v235, v235, v235 row_half_mirror row_mask:0xf bank_mask:0xf
	v_add_f32_dpp v236, v236, v236 row_half_mirror row_mask:0xf bank_mask:0xf
	v_add_f32_dpp v237, v237, v237 row_half_mirror row_mask:0xf bank_mask:0xf
	s_mov_b32 exec_lo, 0x10001
	s_mov_b32 exec_hi, 0x10001
	ds_write_b32 v155, v234 offset:1408
	ds_write_b32 v155, v235 offset:1424
	ds_write_b32 v155, v236 offset:1440
	ds_write_b32 v155, v237 offset:1456
	s_mov_b64 exec, -1
	ds_read2_b32 v[230:231], v243 offset0:96 offset1:100
	ds_read2_b32 v[232:233], v243 offset0:104 offset1:108
	s_waitcnt lgkmcnt(0)
; __device__ __forceinline__ void peer_token(const Params& P, int t, int lane, int* sidx, float* sval, const int* sid, const float* sgate, const unsigned* szero) {
;     ...
;         uint4 abuf[2][2][4];
;         unsigned off2[2];
; #pragma unroll
;         for (int hh = 0; hh < 2; ++hh) off2[hh] = (unsigned)sid[8 * hh + (lr & 7)] * 512u + lofs;
; #pragma unroll
;         for (int hh = 0; hh < 2; ++hh)
; #pragma unroll
;             for (int st = 0; st < 4; ++st) abuf[0][hh][st] = *(const uint4*)(Ub + (off2[hh] + 128 * st));
; #pragma unroll
;         for (int T = 0; T < 8; ++T) {
;             if (T + 1 < 8) {
; #pragma unroll
;                 for (int hh = 0; hh < 2; ++hh) off2[hh] = (unsigned)sid[16 * (T + 1) + 8 * hh + (lr & 7)] * 512u + lofs;
; #pragma unroll
;                 for (int hh = 0; hh < 2; ++hh)
; #pragma unroll
;                     for (int st = 0; st < 4; ++st) abuf[(T + 1) & 1][hh][st] = *(const uint4*)(Ub + (off2[hh] + 128 * st));
;             }
; #pragma unroll
;             for (int hh = 0; hh < 2; ++hh) {
;                 f32x4 au = (f32x4){0.f, 0.f, 0.f, 0.f};
; #pragma unroll
;                 for (int st = 0; st < 4; ++st) {
;                     const uint4 a4 = abuf[T & 1][hh][st];
;                     const v8i Av = {(int)a4.x, (int)a4.y, (int)a4.z, (int)a4.w, 0, 0, 0, 0};
;                     au = __builtin_amdgcn_mfma_scale_f32_16x16x128_f8f6f4(Av, Bv[st], au, 4, 0, 0, 0x7f7f7f7f, 0, 0x7f7f7f7f);
;                 }
;                 if (owner) *(f32x4*)(sact + 16 * T + 8 * hh) = au;
;             }
;         }
	v_lshl_add_u32 v230, v230, 9, v144
	v_lshl_add_u32 v231, v231, 9, v144
	v_lshl_add_u32 v232, v232, 9, v144
	v_lshl_add_u32 v233, v233, 9, v144
	global_load_dwordx4 v[32:35], v230, s[10:11]
	global_load_dwordx4 v[36:39], v230, s[10:11] offset:256
	global_load_dwordx4 v[40:43], v231, s[10:11]
	global_load_dwordx4 v[44:47], v231, s[10:11] offset:256
	global_load_dwordx4 v[48:51], v232, s[10:11]
	global_load_dwordx4 v[52:55], v232, s[10:11] offset:256
	global_load_dwordx4 v[56:59], v233, s[10:11]
	global_load_dwordx4 v[60:63], v233, s[10:11] offset:256
	s_waitcnt vmcnt(8)
	v_mfma_scale_f32_16x16x128_f8f6f4 v[64:67], v[0:3], v[162:169], 0, v133, v133 op_sel_hi:[0,0,0] cbsz:4
	v_mfma_scale_f32_16x16x128_f8f6f4 v[64:67], v[4:7], v[170:177], v[64:67], v133, v133 op_sel_hi:[0,0,0] cbsz:4
	v_mfma_scale_f32_16x16x128_f8f6f4 v[68:71], v[8:11], v[162:169], 0, v133, v133 op_sel_hi:[0,0,0] cbsz:4
	v_mfma_scale_f32_16x16x128_f8f6f4 v[68:71], v[12:15], v[170:177], v[68:71], v133, v133 op_sel_hi:[0,0,0] cbsz:4
	v_mfma_scale_f32_16x16x128_f8f6f4 v[72:75], v[16:19], v[162:169], 0, v133, v133 op_sel_hi:[0,0,0] cbsz:4
	v_mfma_scale_f32_16x16x128_f8f6f4 v[72:75], v[20:23], v[170:177], v[72:75], v133, v133 op_sel_hi:[0,0,0] cbsz:4
	v_mfma_scale_f32_16x16x128_f8f6f4 v[76:79], v[24:27], v[162:169], 0, v133, v133 op_sel_hi:[0,0,0] cbsz:4
	v_mfma_scale_f32_16x16x128_f8f6f4 v[76:79], v[28:31], v[170:177], v[76:79], v133, v133 op_sel_hi:[0,0,0] cbsz:4
	s_nop 3
	v_mul_f32_e32 v234, v158, v80
	v_mul_f32_e32 v235, v158, v84
	v_mul_f32_e32 v236, v158, v88
	v_mul_f32_e32 v237, v158, v92
	v_fmac_f32_e32 v234, v159, v81
	v_fmac_f32_e32 v235, v159, v85
	v_fmac_f32_e32 v236, v159, v89
	v_fmac_f32_e32 v237, v159, v93
	v_fmac_f32_e32 v234, v160, v82
	v_fmac_f32_e32 v235, v160, v86
	v_fmac_f32_e32 v236, v160, v90
	v_fmac_f32_e32 v237, v160, v94
	v_fmac_f32_e32 v234, v161, v83
	v_fmac_f32_e32 v235, v161, v87
	v_fmac_f32_e32 v236, v161, v91
	v_fmac_f32_e32 v237, v161, v95
	v_add_f32_dpp v234, v234, v234 quad_perm:[1,0,3,2] row_mask:0xf bank_mask:0xf
	v_add_f32_dpp v235, v235, v235 quad_perm:[1,0,3,2] row_mask:0xf bank_mask:0xf
	v_add_f32_dpp v236, v236, v236 quad_perm:[1,0,3,2] row_mask:0xf bank_mask:0xf
	v_add_f32_dpp v237, v237, v237 quad_perm:[1,0,3,2] row_mask:0xf bank_mask:0xf
	v_add_f32_dpp v234, v234, v234 quad_perm:[2,3,0,1] row_mask:0xf bank_mask:0xf
	v_add_f32_dpp v235, v235, v235 quad_perm:[2,3,0,1] row_mask:0xf bank_mask:0xf
	v_add_f32_dpp v236, v236, v236 quad_perm:[2,3,0,1] row_mask:0xf bank_mask:0xf
	v_add_f32_dpp v237, v237, v237 quad_perm:[2,3,0,1] row_mask:0xf bank_mask:0xf
	v_add_f32_dpp v234, v234, v234 row_half_mirror row_mask:0xf bank_mask:0xf
	v_add_f32_dpp v235, v235, v235 row_half_mirror row_mask:0xf bank_mask:0xf
	v_add_f32_dpp v236, v236, v236 row_half_mirror row_mask:0xf bank_mask:0xf
	v_add_f32_dpp v237, v237, v237 row_half_mirror row_mask:0xf bank_mask:0xf
	s_mov_b32 exec_lo, 0x10001
	s_mov_b32 exec_hi, 0x10001
	ds_write_b32 v155, v234 offset:1920
	ds_write_b32 v155, v235 offset:1936
	ds_write_b32 v155, v236 offset:1952
	ds_write_b32 v155, v237 offset:1968
	s_mov_b64 exec, -1
	ds_read2_b32 v[96:97], v244 offset0:96 offset1:100
	ds_read2_b32 v[98:99], v244 offset0:104 offset1:108
	s_waitcnt lgkmcnt(0)
	v_lshl_add_u32 v96, v96, 9, v144
	v_lshl_add_u32 v97, v97, 9, v144
	v_lshl_add_u32 v98, v98, 9, v144
	v_lshl_add_u32 v99, v99, 9, v144
	global_load_dwordx4 v[0:3], v96, s[10:11]
	global_load_dwordx4 v[4:7], v96, s[10:11] offset:256
	global_load_dwordx4 v[8:11], v97, s[10:11]
	global_load_dwordx4 v[12:15], v97, s[10:11] offset:256
	global_load_dwordx4 v[16:19], v98, s[10:11]
	global_load_dwordx4 v[20:23], v98, s[10:11] offset:256
	global_load_dwordx4 v[24:27], v99, s[10:11]
	global_load_dwordx4 v[28:31], v99, s[10:11] offset:256
	s_waitcnt vmcnt(8)
	v_mfma_scale_f32_16x16x128_f8f6f4 v[80:83], v[32:35], v[178:185], 0, v133, v133 op_sel_hi:[0,0,0] cbsz:4
	v_mfma_scale_f32_16x16x128_f8f6f4 v[80:83], v[36:39], v[186:193], v[80:83], v133, v133 op_sel_hi:[0,0,0] cbsz:4
	v_mfma_scale_f32_16x16x128_f8f6f4 v[84:87], v[40:43], v[178:185], 0, v133, v133 op_sel_hi:[0,0,0] cbsz:4
	v_mfma_scale_f32_16x16x128_f8f6f4 v[84:87], v[44:47], v[186:193], v[84:87], v133, v133 op_sel_hi:[0,0,0] cbsz:4
	v_mfma_scale_f32_16x16x128_f8f6f4 v[88:91], v[48:51], v[178:185], 0, v133, v133 op_sel_hi:[0,0,0] cbsz:4
	v_mfma_scale_f32_16x16x128_f8f6f4 v[88:91], v[52:55], v[186:193], v[88:91], v133, v133 op_sel_hi:[0,0,0] cbsz:4
	v_mfma_scale_f32_16x16x128_f8f6f4 v[92:95], v[56:59], v[178:185], 0, v133, v133 op_sel_hi:[0,0,0] cbsz:4
	v_mfma_scale_f32_16x16x128_f8f6f4 v[92:95], v[60:63], v[186:193], v[92:95], v133, v133 op_sel_hi:[0,0,0] cbsz:4
	s_nop 3
	v_mul_f32_e32 v234, v226, v64
	v_mul_f32_e32 v235, v226, v68
	v_mul_f32_e32 v236, v226, v72
	v_mul_f32_e32 v237, v226, v76
	v_fmac_f32_e32 v234, v227, v65
	v_fmac_f32_e32 v235, v227, v69
	v_fmac_f32_e32 v236, v227, v73
	v_fmac_f32_e32 v237, v227, v77
	v_fmac_f32_e32 v234, v228, v66
	v_fmac_f32_e32 v235, v228, v70
	v_fmac_f32_e32 v236, v228, v74
	v_fmac_f32_e32 v237, v228, v78
	v_fmac_f32_e32 v234, v229, v67
	v_fmac_f32_e32 v235, v229, v71
	v_fmac_f32_e32 v236, v229, v75
	v_fmac_f32_e32 v237, v229, v79
	v_add_f32_dpp v234, v234, v234 quad_perm:[1,0,3,2] row_mask:0xf bank_mask:0xf
	v_add_f32_dpp v235, v235, v235 quad_perm:[1,0,3,2] row_mask:0xf bank_mask:0xf
	v_add_f32_dpp v236, v236, v236 quad_perm:[1,0,3,2] row_mask:0xf bank_mask:0xf
	v_add_f32_dpp v237, v237, v237 quad_perm:[1,0,3,2] row_mask:0xf bank_mask:0xf
	v_add_f32_dpp v234, v234, v234 quad_perm:[2,3,0,1] row_mask:0xf bank_mask:0xf
	v_add_f32_dpp v235, v235, v235 quad_perm:[2,3,0,1] row_mask:0xf bank_mask:0xf
	v_add_f32_dpp v236, v236, v236 quad_perm:[2,3,0,1] row_mask:0xf bank_mask:0xf
	v_add_f32_dpp v237, v237, v237 quad_perm:[2,3,0,1] row_mask:0xf bank_mask:0xf
	v_add_f32_dpp v234, v234, v234 row_half_mirror row_mask:0xf bank_mask:0xf
	v_add_f32_dpp v235, v235, v235 row_half_mirror row_mask:0xf bank_mask:0xf
	v_add_f32_dpp v236, v236, v236 row_half_mirror row_mask:0xf bank_mask:0xf
	v_add_f32_dpp v237, v237, v237 row_half_mirror row_mask:0xf bank_mask:0xf
	s_mov_b32 exec_lo, 0x1000100
	s_mov_b32 exec_hi, 0x1000100
	ds_write_b32 v155, v234 offset:2432
	ds_write_b32 v155, v235 offset:2448
	ds_write_b32 v155, v236 offset:2464
	ds_write_b32 v155, v237 offset:2480
	s_mov_b64 exec, -1
	ds_read2_b32 v[230:231], v245 offset0:96 offset1:100
	ds_read2_b32 v[232:233], v245 offset0:104 offset1:108
	s_waitcnt lgkmcnt(0)
; __device__ __forceinline__ void peer_token(const Params& P, int t, int lane, int* sidx, float* sval, const int* sid, const float* sgate, const unsigned* szero) {
;     ...
;         uint4 abuf[2][2][4];
;         unsigned off2[2];
; #pragma unroll
;         for (int hh = 0; hh < 2; ++hh) off2[hh] = (unsigned)sid[8 * hh + (lr & 7)] * 512u + lofs;
; #pragma unroll
;         for (int hh = 0; hh < 2; ++hh)
; #pragma unroll
;             for (int st = 0; st < 4; ++st) abuf[0][hh][st] = *(const uint4*)(Ub + (off2[hh] + 128 * st));
; #pragma unroll
;         for (int T = 0; T < 8; ++T) {
;             if (T + 1 < 8) {
; #pragma unroll
;                 for (int hh = 0; hh < 2; ++hh) off2[hh] = (unsigned)sid[16 * (T + 1) + 8 * hh + (lr & 7)] * 512u + lofs;
; #pragma unroll
;                 for (int hh = 0; hh < 2; ++hh)
; #pragma unroll
;                     for (int st = 0; st < 4; ++st) abuf[(T + 1) & 1][hh][st] = *(const uint4*)(Ub + (off2[hh] + 128 * st));
;             }
; #pragma unroll
;             for (int hh = 0; hh < 2; ++hh) {
;                 f32x4 au = (f32x4){0.f, 0.f, 0.f, 0.f};
; #pragma unroll
;                 for (int st = 0; st < 4; ++st) {
;                     const uint4 a4 = abuf[T & 1][hh][st];
;                     const v8i Av = {(int)a4.x, (int)a4.y, (int)a4.z, (int)a4.w, 0, 0, 0, 0};
;                     au = __builtin_amdgcn_mfma_scale_f32_16x16x128_f8f6f4(Av, Bv[st], au, 4, 0, 0, 0x7f7f7f7f, 0, 0x7f7f7f7f);
;                 }
;                 if (owner) *(f32x4*)(sact + 16 * T + 8 * hh) = au;
;             }
;         }
	v_lshl_add_u32 v230, v230, 9, v144
	v_lshl_add_u32 v231, v231, 9, v144
	v_lshl_add_u32 v232, v232, 9, v144
	v_lshl_add_u32 v233, v233, 9, v144
	global_load_dwordx4 v[32:35], v230, s[10:11]
	global_load_dwordx4 v[36:39], v230, s[10:11] offset:256
	global_load_dwordx4 v[40:43], v231, s[10:11]
	global_load_dwordx4 v[44:47], v231, s[10:11] offset:256
	global_load_dwordx4 v[48:51], v232, s[10:11]
	global_load_dwordx4 v[52:55], v232, s[10:11] offset:256
	global_load_dwordx4 v[56:59], v233, s[10:11]
	global_load_dwordx4 v[60:63], v233, s[10:11] offset:256
	s_waitcnt vmcnt(8)
	v_mfma_scale_f32_16x16x128_f8f6f4 v[64:67], v[0:3], v[194:201], 0, v133, v133 op_sel_hi:[0,0,0] cbsz:4
	v_mfma_scale_f32_16x16x128_f8f6f4 v[64:67], v[4:7], v[202:209], v[64:67], v133, v133 op_sel_hi:[0,0,0] cbsz:4
	v_mfma_scale_f32_16x16x128_f8f6f4 v[68:71], v[8:11], v[194:201], 0, v133, v133 op_sel_hi:[0,0,0] cbsz:4
	v_mfma_scale_f32_16x16x128_f8f6f4 v[68:71], v[12:15], v[202:209], v[68:71], v133, v133 op_sel_hi:[0,0,0] cbsz:4
	v_mfma_scale_f32_16x16x128_f8f6f4 v[72:75], v[16:19], v[194:201], 0, v133, v133 op_sel_hi:[0,0,0] cbsz:4
	v_mfma_scale_f32_16x16x128_f8f6f4 v[72:75], v[20:23], v[202:209], v[72:75], v133, v133 op_sel_hi:[0,0,0] cbsz:4
	v_mfma_scale_f32_16x16x128_f8f6f4 v[76:79], v[24:27], v[194:201], 0, v133, v133 op_sel_hi:[0,0,0] cbsz:4
	v_mfma_scale_f32_16x16x128_f8f6f4 v[76:79], v[28:31], v[202:209], v[76:79], v133, v133 op_sel_hi:[0,0,0] cbsz:4
	s_nop 3
	v_mul_f32_e32 v234, v226, v80
	v_mul_f32_e32 v235, v226, v84
	v_mul_f32_e32 v236, v226, v88
	v_mul_f32_e32 v237, v226, v92
	v_fmac_f32_e32 v234, v227, v81
	v_fmac_f32_e32 v235, v227, v85
	v_fmac_f32_e32 v236, v227, v89
	v_fmac_f32_e32 v237, v227, v93
	v_fmac_f32_e32 v234, v228, v82
	v_fmac_f32_e32 v235, v228, v86
	v_fmac_f32_e32 v236, v228, v90
	v_fmac_f32_e32 v237, v228, v94
	v_fmac_f32_e32 v234, v229, v83
	v_fmac_f32_e32 v235, v229, v87
	v_fmac_f32_e32 v236, v229, v91
	v_fmac_f32_e32 v237, v229, v95
	v_add_f32_dpp v234, v234, v234 quad_perm:[1,0,3,2] row_mask:0xf bank_mask:0xf
	v_add_f32_dpp v235, v235, v235 quad_perm:[1,0,3,2] row_mask:0xf bank_mask:0xf
	v_add_f32_dpp v236, v236, v236 quad_perm:[1,0,3,2] row_mask:0xf bank_mask:0xf
	v_add_f32_dpp v237, v237, v237 quad_perm:[1,0,3,2] row_mask:0xf bank_mask:0xf
	v_add_f32_dpp v234, v234, v234 quad_perm:[2,3,0,1] row_mask:0xf bank_mask:0xf
	v_add_f32_dpp v235, v235, v235 quad_perm:[2,3,0,1] row_mask:0xf bank_mask:0xf
	v_add_f32_dpp v236, v236, v236 quad_perm:[2,3,0,1] row_mask:0xf bank_mask:0xf
	v_add_f32_dpp v237, v237, v237 quad_perm:[2,3,0,1] row_mask:0xf bank_mask:0xf
	v_add_f32_dpp v234, v234, v234 row_half_mirror row_mask:0xf bank_mask:0xf
	v_add_f32_dpp v235, v235, v235 row_half_mirror row_mask:0xf bank_mask:0xf
	v_add_f32_dpp v236, v236, v236 row_half_mirror row_mask:0xf bank_mask:0xf
	v_add_f32_dpp v237, v237, v237 row_half_mirror row_mask:0xf bank_mask:0xf
	s_mov_b32 exec_lo, 0x1000100
	s_mov_b32 exec_hi, 0x1000100
	ds_write_b32 v155, v234 offset:2944
	ds_write_b32 v155, v235 offset:2960
	ds_write_b32 v155, v236 offset:2976
	ds_write_b32 v155, v237 offset:2992
	s_mov_b64 exec, -1
	ds_read2_b32 v[96:97], v238 offset0:112 offset1:116
	ds_read2_b32 v[98:99], v238 offset0:120 offset1:124
	s_waitcnt lgkmcnt(0)
	v_lshl_add_u32 v96, v96, 9, v144
	v_lshl_add_u32 v97, v97, 9, v144
	v_lshl_add_u32 v98, v98, 9, v144
	v_lshl_add_u32 v99, v99, 9, v144
	global_load_dwordx4 v[0:3], v96, s[10:11]
	global_load_dwordx4 v[4:7], v96, s[10:11] offset:256
	global_load_dwordx4 v[8:11], v97, s[10:11]
	global_load_dwordx4 v[12:15], v97, s[10:11] offset:256
	global_load_dwordx4 v[16:19], v98, s[10:11]
	global_load_dwordx4 v[20:23], v98, s[10:11] offset:256
	global_load_dwordx4 v[24:27], v99, s[10:11]
	global_load_dwordx4 v[28:31], v99, s[10:11] offset:256
	s_waitcnt vmcnt(8)
	v_mfma_scale_f32_16x16x128_f8f6f4 v[80:83], v[32:35], v[210:217], 0, v133, v133 op_sel_hi:[0,0,0] cbsz:4
	v_mfma_scale_f32_16x16x128_f8f6f4 v[80:83], v[36:39], v[218:225], v[80:83], v133, v133 op_sel_hi:[0,0,0] cbsz:4
	v_mfma_scale_f32_16x16x128_f8f6f4 v[84:87], v[40:43], v[210:217], 0, v133, v133 op_sel_hi:[0,0,0] cbsz:4
	v_mfma_scale_f32_16x16x128_f8f6f4 v[84:87], v[44:47], v[218:225], v[84:87], v133, v133 op_sel_hi:[0,0,0] cbsz:4
	v_mfma_scale_f32_16x16x128_f8f6f4 v[88:91], v[48:51], v[210:217], 0, v133, v133 op_sel_hi:[0,0,0] cbsz:4
	v_mfma_scale_f32_16x16x128_f8f6f4 v[88:91], v[52:55], v[218:225], v[88:91], v133, v133 op_sel_hi:[0,0,0] cbsz:4
	v_mfma_scale_f32_16x16x128_f8f6f4 v[92:95], v[56:59], v[210:217], 0, v133, v133 op_sel_hi:[0,0,0] cbsz:4
	v_mfma_scale_f32_16x16x128_f8f6f4 v[92:95], v[60:63], v[218:225], v[92:95], v133, v133 op_sel_hi:[0,0,0] cbsz:4
	s_nop 3
	v_mul_f32_e32 v234, v226, v64
	v_mul_f32_e32 v235, v226, v68
	v_mul_f32_e32 v236, v226, v72
	v_mul_f32_e32 v237, v226, v76
	v_fmac_f32_e32 v234, v227, v65
	v_fmac_f32_e32 v235, v227, v69
	v_fmac_f32_e32 v236, v227, v73
	v_fmac_f32_e32 v237, v227, v77
	v_fmac_f32_e32 v234, v228, v66
	v_fmac_f32_e32 v235, v228, v70
	v_fmac_f32_e32 v236, v228, v74
	v_fmac_f32_e32 v237, v228, v78
	v_fmac_f32_e32 v234, v229, v67
	v_fmac_f32_e32 v235, v229, v71
	v_fmac_f32_e32 v236, v229, v75
	v_fmac_f32_e32 v237, v229, v79
	v_add_f32_dpp v234, v234, v234 quad_perm:[1,0,3,2] row_mask:0xf bank_mask:0xf
	v_add_f32_dpp v235, v235, v235 quad_perm:[1,0,3,2] row_mask:0xf bank_mask:0xf
	v_add_f32_dpp v236, v236, v236 quad_perm:[1,0,3,2] row_mask:0xf bank_mask:0xf
	v_add_f32_dpp v237, v237, v237 quad_perm:[1,0,3,2] row_mask:0xf bank_mask:0xf
	v_add_f32_dpp v234, v234, v234 quad_perm:[2,3,0,1] row_mask:0xf bank_mask:0xf
	v_add_f32_dpp v235, v235, v235 quad_perm:[2,3,0,1] row_mask:0xf bank_mask:0xf
	v_add_f32_dpp v236, v236, v236 quad_perm:[2,3,0,1] row_mask:0xf bank_mask:0xf
	v_add_f32_dpp v237, v237, v237 quad_perm:[2,3,0,1] row_mask:0xf bank_mask:0xf
	v_add_f32_dpp v234, v234, v234 row_half_mirror row_mask:0xf bank_mask:0xf
	v_add_f32_dpp v235, v235, v235 row_half_mirror row_mask:0xf bank_mask:0xf
	v_add_f32_dpp v236, v236, v236 row_half_mirror row_mask:0xf bank_mask:0xf
	v_add_f32_dpp v237, v237, v237 row_half_mirror row_mask:0xf bank_mask:0xf
	s_mov_b32 exec_lo, 0x1000100
	s_mov_b32 exec_hi, 0x1000100
	ds_write_b32 v155, v234 offset:3456
	ds_write_b32 v155, v235 offset:3472
	ds_write_b32 v155, v236 offset:3488
	ds_write_b32 v155, v237 offset:3504
	s_mov_b64 exec, -1
	ds_read2_b32 v[230:231], v239 offset0:112 offset1:116
	ds_read2_b32 v[232:233], v239 offset0:120 offset1:124
	s_waitcnt lgkmcnt(0)
; __device__ __forceinline__ void peer_token(const Params& P, int t, int lane, int* sidx, float* sval, const int* sid, const float* sgate, const unsigned* szero) {
;     ...
;         uint4 abuf[2][2][4];
;         unsigned off2[2];
; #pragma unroll
;         for (int hh = 0; hh < 2; ++hh) off2[hh] = (unsigned)sid[8 * hh + (lr & 7)] * 512u + lofs;
; #pragma unroll
;         for (int hh = 0; hh < 2; ++hh)
; #pragma unroll
;             for (int st = 0; st < 4; ++st) abuf[0][hh][st] = *(const uint4*)(Ub + (off2[hh] + 128 * st));
; #pragma unroll
;         for (int T = 0; T < 8; ++T) {
;             if (T + 1 < 8) {
; #pragma unroll
;                 for (int hh = 0; hh < 2; ++hh) off2[hh] = (unsigned)sid[16 * (T + 1) + 8 * hh + (lr & 7)] * 512u + lofs;
; #pragma unroll
;                 for (int hh = 0; hh < 2; ++hh)
; #pragma unroll
;                     for (int st = 0; st < 4; ++st) abuf[(T + 1) & 1][hh][st] = *(const uint4*)(Ub + (off2[hh] + 128 * st));
;             }
; #pragma unroll
;             for (int hh = 0; hh < 2; ++hh) {
;                 f32x4 au = (f32x4){0.f, 0.f, 0.f, 0.f};
; #pragma unroll
;                 for (int st = 0; st < 4; ++st) {
;                     const uint4 a4 = abuf[T & 1][hh][st];
;                     const v8i Av = {(int)a4.x, (int)a4.y, (int)a4.z, (int)a4.w, 0, 0, 0, 0};
;                     au = __builtin_amdgcn_mfma_scale_f32_16x16x128_f8f6f4(Av, Bv[st], au, 4, 0, 0, 0x7f7f7f7f, 0, 0x7f7f7f7f);
;                 }
;                 if (owner) *(f32x4*)(sact + 16 * T + 8 * hh) = au;
;             }
;         }
	v_lshl_add_u32 v230, v230, 9, v144
	v_lshl_add_u32 v231, v231, 9, v144
	v_lshl_add_u32 v232, v232, 9, v144
	v_lshl_add_u32 v233, v233, 9, v144
	global_load_dwordx4 v[32:35], v230, s[10:11]
	global_load_dwordx4 v[36:39], v230, s[10:11] offset:256
	global_load_dwordx4 v[40:43], v231, s[10:11]
	global_load_dwordx4 v[44:47], v231, s[10:11] offset:256
	global_load_dwordx4 v[48:51], v232, s[10:11]
	global_load_dwordx4 v[52:55], v232, s[10:11] offset:256
	global_load_dwordx4 v[56:59], v233, s[10:11]
	global_load_dwordx4 v[60:63], v233, s[10:11] offset:256
	s_waitcnt vmcnt(8)
	v_mfma_scale_f32_16x16x128_f8f6f4 v[64:67], v[0:3], v[162:169], 0, v133, v133 op_sel_hi:[0,0,0] cbsz:4
	v_mfma_scale_f32_16x16x128_f8f6f4 v[64:67], v[4:7], v[170:177], v[64:67], v133, v133 op_sel_hi:[0,0,0] cbsz:4
	v_mfma_scale_f32_16x16x128_f8f6f4 v[68:71], v[8:11], v[162:169], 0, v133, v133 op_sel_hi:[0,0,0] cbsz:4
	v_mfma_scale_f32_16x16x128_f8f6f4 v[68:71], v[12:15], v[170:177], v[68:71], v133, v133 op_sel_hi:[0,0,0] cbsz:4
	v_mfma_scale_f32_16x16x128_f8f6f4 v[72:75], v[16:19], v[162:169], 0, v133, v133 op_sel_hi:[0,0,0] cbsz:4
	v_mfma_scale_f32_16x16x128_f8f6f4 v[72:75], v[20:23], v[170:177], v[72:75], v133, v133 op_sel_hi:[0,0,0] cbsz:4
	v_mfma_scale_f32_16x16x128_f8f6f4 v[76:79], v[24:27], v[162:169], 0, v133, v133 op_sel_hi:[0,0,0] cbsz:4
	v_mfma_scale_f32_16x16x128_f8f6f4 v[76:79], v[28:31], v[170:177], v[76:79], v133, v133 op_sel_hi:[0,0,0] cbsz:4
	s_nop 3
	v_mul_f32_e32 v234, v226, v80
	v_mul_f32_e32 v235, v226, v84
	v_mul_f32_e32 v236, v226, v88
	v_mul_f32_e32 v237, v226, v92
	v_fmac_f32_e32 v234, v227, v81
	v_fmac_f32_e32 v235, v227, v85
	v_fmac_f32_e32 v236, v227, v89
	v_fmac_f32_e32 v237, v227, v93
	v_fmac_f32_e32 v234, v228, v82
	v_fmac_f32_e32 v235, v228, v86
	v_fmac_f32_e32 v236, v228, v90
	v_fmac_f32_e32 v237, v228, v94
	v_fmac_f32_e32 v234, v229, v83
	v_fmac_f32_e32 v235, v229, v87
	v_fmac_f32_e32 v236, v229, v91
	v_fmac_f32_e32 v237, v229, v95
	v_add_f32_dpp v234, v234, v234 quad_perm:[1,0,3,2] row_mask:0xf bank_mask:0xf
	v_add_f32_dpp v235, v235, v235 quad_perm:[1,0,3,2] row_mask:0xf bank_mask:0xf
	v_add_f32_dpp v236, v236, v236 quad_perm:[1,0,3,2] row_mask:0xf bank_mask:0xf
	v_add_f32_dpp v237, v237, v237 quad_perm:[1,0,3,2] row_mask:0xf bank_mask:0xf
	v_add_f32_dpp v234, v234, v234 quad_perm:[2,3,0,1] row_mask:0xf bank_mask:0xf
	v_add_f32_dpp v235, v235, v235 quad_perm:[2,3,0,1] row_mask:0xf bank_mask:0xf
	v_add_f32_dpp v236, v236, v236 quad_perm:[2,3,0,1] row_mask:0xf bank_mask:0xf
	v_add_f32_dpp v237, v237, v237 quad_perm:[2,3,0,1] row_mask:0xf bank_mask:0xf
	v_add_f32_dpp v234, v234, v234 row_half_mirror row_mask:0xf bank_mask:0xf
	v_add_f32_dpp v235, v235, v235 row_half_mirror row_mask:0xf bank_mask:0xf
	v_add_f32_dpp v236, v236, v236 row_half_mirror row_mask:0xf bank_mask:0xf
	v_add_f32_dpp v237, v237, v237 row_half_mirror row_mask:0xf bank_mask:0xf
	s_mov_b32 exec_lo, 0x1000100
	s_mov_b32 exec_hi, 0x1000100
	ds_write_b32 v155, v234 offset:3968
	ds_write_b32 v155, v235 offset:3984
	ds_write_b32 v155, v236 offset:4000
	ds_write_b32 v155, v237 offset:4016
	s_mov_b64 exec, -1
	ds_read2_b32 v[96:97], v240 offset0:112 offset1:116
	ds_read2_b32 v[98:99], v240 offset0:120 offset1:124
	s_waitcnt lgkmcnt(0)
	v_lshl_add_u32 v96, v96, 9, v144
	v_lshl_add_u32 v97, v97, 9, v144
	v_lshl_add_u32 v98, v98, 9, v144
	v_lshl_add_u32 v99, v99, 9, v144
	global_load_dwordx4 v[0:3], v96, s[10:11]
	global_load_dwordx4 v[4:7], v96, s[10:11] offset:256
	global_load_dwordx4 v[8:11], v97, s[10:11]
	global_load_dwordx4 v[12:15], v97, s[10:11] offset:256
	global_load_dwordx4 v[16:19], v98, s[10:11]
	global_load_dwordx4 v[20:23], v98, s[10:11] offset:256
	global_load_dwordx4 v[24:27], v99, s[10:11]
	global_load_dwordx4 v[28:31], v99, s[10:11] offset:256
	s_waitcnt vmcnt(8)
	v_mfma_scale_f32_16x16x128_f8f6f4 v[80:83], v[32:35], v[178:185], 0, v133, v133 op_sel_hi:[0,0,0] cbsz:4
	v_mfma_scale_f32_16x16x128_f8f6f4 v[80:83], v[36:39], v[186:193], v[80:83], v133, v133 op_sel_hi:[0,0,0] cbsz:4
	v_mfma_scale_f32_16x16x128_f8f6f4 v[84:87], v[40:43], v[178:185], 0, v133, v133 op_sel_hi:[0,0,0] cbsz:4
	v_mfma_scale_f32_16x16x128_f8f6f4 v[84:87], v[44:47], v[186:193], v[84:87], v133, v133 op_sel_hi:[0,0,0] cbsz:4
	v_mfma_scale_f32_16x16x128_f8f6f4 v[88:91], v[48:51], v[178:185], 0, v133, v133 op_sel_hi:[0,0,0] cbsz:4
	v_mfma_scale_f32_16x16x128_f8f6f4 v[88:91], v[52:55], v[186:193], v[88:91], v133, v133 op_sel_hi:[0,0,0] cbsz:4
	v_mfma_scale_f32_16x16x128_f8f6f4 v[92:95], v[56:59], v[178:185], 0, v133, v133 op_sel_hi:[0,0,0] cbsz:4
	v_mfma_scale_f32_16x16x128_f8f6f4 v[92:95], v[60:63], v[186:193], v[92:95], v133, v133 op_sel_hi:[0,0,0] cbsz:4
	s_nop 3
	v_mul_f32_e32 v234, v158, v64
	v_mul_f32_e32 v235, v158, v68
	v_mul_f32_e32 v236, v158, v72
	v_mul_f32_e32 v237, v158, v76
	v_fmac_f32_e32 v234, v159, v65
	v_fmac_f32_e32 v235, v159, v69
	v_fmac_f32_e32 v236, v159, v73
	v_fmac_f32_e32 v237, v159, v77
	v_fmac_f32_e32 v234, v160, v66
	v_fmac_f32_e32 v235, v160, v70
	v_fmac_f32_e32 v236, v160, v74
	v_fmac_f32_e32 v237, v160, v78
	v_fmac_f32_e32 v234, v161, v67
	v_fmac_f32_e32 v235, v161, v71
	v_fmac_f32_e32 v236, v161, v75
	v_fmac_f32_e32 v237, v161, v79
	v_add_f32_dpp v234, v234, v234 quad_perm:[1,0,3,2] row_mask:0xf bank_mask:0xf
	v_add_f32_dpp v235, v235, v235 quad_perm:[1,0,3,2] row_mask:0xf bank_mask:0xf
	v_add_f32_dpp v236, v236, v236 quad_perm:[1,0,3,2] row_mask:0xf bank_mask:0xf
	v_add_f32_dpp v237, v237, v237 quad_perm:[1,0,3,2] row_mask:0xf bank_mask:0xf
	v_add_f32_dpp v234, v234, v234 quad_perm:[2,3,0,1] row_mask:0xf bank_mask:0xf
	v_add_f32_dpp v235, v235, v235 quad_perm:[2,3,0,1] row_mask:0xf bank_mask:0xf
	v_add_f32_dpp v236, v236, v236 quad_perm:[2,3,0,1] row_mask:0xf bank_mask:0xf
	v_add_f32_dpp v237, v237, v237 quad_perm:[2,3,0,1] row_mask:0xf bank_mask:0xf
	v_add_f32_dpp v234, v234, v234 row_half_mirror row_mask:0xf bank_mask:0xf
	v_add_f32_dpp v235, v235, v235 row_half_mirror row_mask:0xf bank_mask:0xf
	v_add_f32_dpp v236, v236, v236 row_half_mirror row_mask:0xf bank_mask:0xf
	v_add_f32_dpp v237, v237, v237 row_half_mirror row_mask:0xf bank_mask:0xf
	s_mov_b32 exec_lo, 0x10001
	s_mov_b32 exec_hi, 0x10001
	ds_write_b32 v155, v234 offset:448
	ds_write_b32 v155, v235 offset:464
	ds_write_b32 v155, v236 offset:480
	ds_write_b32 v155, v237 offset:496
	s_mov_b64 exec, -1
	ds_read2_b32 v[230:231], v241 offset0:112 offset1:116
	ds_read2_b32 v[232:233], v241 offset0:120 offset1:124
	s_waitcnt lgkmcnt(0)
; __device__ __forceinline__ void peer_token(const Params& P, int t, int lane, int* sidx, float* sval, const int* sid, const float* sgate, const unsigned* szero) {
;     ...
;         uint4 abuf[2][2][4];
;         unsigned off2[2];
; #pragma unroll
;         for (int hh = 0; hh < 2; ++hh) off2[hh] = (unsigned)sid[8 * hh + (lr & 7)] * 512u + lofs;
; #pragma unroll
;         for (int hh = 0; hh < 2; ++hh)
; #pragma unroll
;             for (int st = 0; st < 4; ++st) abuf[0][hh][st] = *(const uint4*)(Ub + (off2[hh] + 128 * st));
; #pragma unroll
;         for (int T = 0; T < 8; ++T) {
;             if (T + 1 < 8) {
; #pragma unroll
;                 for (int hh = 0; hh < 2; ++hh) off2[hh] = (unsigned)sid[16 * (T + 1) + 8 * hh + (lr & 7)] * 512u + lofs;
; #pragma unroll
;                 for (int hh = 0; hh < 2; ++hh)
; #pragma unroll
;                     for (int st = 0; st < 4; ++st) abuf[(T + 1) & 1][hh][st] = *(const uint4*)(Ub + (off2[hh] + 128 * st));
;             }
; #pragma unroll
;             for (int hh = 0; hh < 2; ++hh) {
;                 f32x4 au = (f32x4){0.f, 0.f, 0.f, 0.f};
; #pragma unroll
;                 for (int st = 0; st < 4; ++st) {
;                     const uint4 a4 = abuf[T & 1][hh][st];
;                     const v8i Av = {(int)a4.x, (int)a4.y, (int)a4.z, (int)a4.w, 0, 0, 0, 0};
;                     au = __builtin_amdgcn_mfma_scale_f32_16x16x128_f8f6f4(Av, Bv[st], au, 4, 0, 0, 0x7f7f7f7f, 0, 0x7f7f7f7f);
;                 }
;                 if (owner) *(f32x4*)(sact + 16 * T + 8 * hh) = au;
;             }
;         }
	v_lshl_add_u32 v230, v230, 9, v144
	v_lshl_add_u32 v231, v231, 9, v144
	v_lshl_add_u32 v232, v232, 9, v144
	v_lshl_add_u32 v233, v233, 9, v144
	global_load_dwordx4 v[32:35], v230, s[10:11]
	global_load_dwordx4 v[36:39], v230, s[10:11] offset:256
	global_load_dwordx4 v[40:43], v231, s[10:11]
	global_load_dwordx4 v[44:47], v231, s[10:11] offset:256
	global_load_dwordx4 v[48:51], v232, s[10:11]
	global_load_dwordx4 v[52:55], v232, s[10:11] offset:256
	global_load_dwordx4 v[56:59], v233, s[10:11]
	global_load_dwordx4 v[60:63], v233, s[10:11] offset:256
	s_waitcnt vmcnt(8)
	v_mfma_scale_f32_16x16x128_f8f6f4 v[64:67], v[0:3], v[194:201], 0, v133, v133 op_sel_hi:[0,0,0] cbsz:4
	v_mfma_scale_f32_16x16x128_f8f6f4 v[64:67], v[4:7], v[202:209], v[64:67], v133, v133 op_sel_hi:[0,0,0] cbsz:4
	v_mfma_scale_f32_16x16x128_f8f6f4 v[68:71], v[8:11], v[194:201], 0, v133, v133 op_sel_hi:[0,0,0] cbsz:4
	v_mfma_scale_f32_16x16x128_f8f6f4 v[68:71], v[12:15], v[202:209], v[68:71], v133, v133 op_sel_hi:[0,0,0] cbsz:4
	v_mfma_scale_f32_16x16x128_f8f6f4 v[72:75], v[16:19], v[194:201], 0, v133, v133 op_sel_hi:[0,0,0] cbsz:4
	v_mfma_scale_f32_16x16x128_f8f6f4 v[72:75], v[20:23], v[202:209], v[72:75], v133, v133 op_sel_hi:[0,0,0] cbsz:4
	v_mfma_scale_f32_16x16x128_f8f6f4 v[76:79], v[24:27], v[194:201], 0, v133, v133 op_sel_hi:[0,0,0] cbsz:4
	v_mfma_scale_f32_16x16x128_f8f6f4 v[76:79], v[28:31], v[202:209], v[76:79], v133, v133 op_sel_hi:[0,0,0] cbsz:4
	s_nop 3
	v_mul_f32_e32 v234, v158, v80
	v_mul_f32_e32 v235, v158, v84
	v_mul_f32_e32 v236, v158, v88
	v_mul_f32_e32 v237, v158, v92
	v_fmac_f32_e32 v234, v159, v81
	v_fmac_f32_e32 v235, v159, v85
	v_fmac_f32_e32 v236, v159, v89
	v_fmac_f32_e32 v237, v159, v93
	v_fmac_f32_e32 v234, v160, v82
	v_fmac_f32_e32 v235, v160, v86
	v_fmac_f32_e32 v236, v160, v90
	v_fmac_f32_e32 v237, v160, v94
	v_fmac_f32_e32 v234, v161, v83
	v_fmac_f32_e32 v235, v161, v87
	v_fmac_f32_e32 v236, v161, v91
	v_fmac_f32_e32 v237, v161, v95
	v_add_f32_dpp v234, v234, v234 quad_perm:[1,0,3,2] row_mask:0xf bank_mask:0xf
	v_add_f32_dpp v235, v235, v235 quad_perm:[1,0,3,2] row_mask:0xf bank_mask:0xf
	v_add_f32_dpp v236, v236, v236 quad_perm:[1,0,3,2] row_mask:0xf bank_mask:0xf
	v_add_f32_dpp v237, v237, v237 quad_perm:[1,0,3,2] row_mask:0xf bank_mask:0xf
	v_add_f32_dpp v234, v234, v234 quad_perm:[2,3,0,1] row_mask:0xf bank_mask:0xf
	v_add_f32_dpp v235, v235, v235 quad_perm:[2,3,0,1] row_mask:0xf bank_mask:0xf
	v_add_f32_dpp v236, v236, v236 quad_perm:[2,3,0,1] row_mask:0xf bank_mask:0xf
	v_add_f32_dpp v237, v237, v237 quad_perm:[2,3,0,1] row_mask:0xf bank_mask:0xf
	v_add_f32_dpp v234, v234, v234 row_half_mirror row_mask:0xf bank_mask:0xf
	v_add_f32_dpp v235, v235, v235 row_half_mirror row_mask:0xf bank_mask:0xf
	v_add_f32_dpp v236, v236, v236 row_half_mirror row_mask:0xf bank_mask:0xf
	v_add_f32_dpp v237, v237, v237 row_half_mirror row_mask:0xf bank_mask:0xf
	s_mov_b32 exec_lo, 0x10001
	s_mov_b32 exec_hi, 0x10001
	ds_write_b32 v155, v234 offset:960
	ds_write_b32 v155, v235 offset:976
	ds_write_b32 v155, v236 offset:992
	ds_write_b32 v155, v237 offset:1008
	s_mov_b64 exec, -1
	ds_read2_b32 v[96:97], v242 offset0:112 offset1:116
	ds_read2_b32 v[98:99], v242 offset0:120 offset1:124
	s_waitcnt lgkmcnt(0)
	v_lshl_add_u32 v96, v96, 9, v144
	v_lshl_add_u32 v97, v97, 9, v144
	v_lshl_add_u32 v98, v98, 9, v144
	v_lshl_add_u32 v99, v99, 9, v144
	global_load_dwordx4 v[0:3], v96, s[10:11]
	global_load_dwordx4 v[4:7], v96, s[10:11] offset:256
	global_load_dwordx4 v[8:11], v97, s[10:11]
	global_load_dwordx4 v[12:15], v97, s[10:11] offset:256
	global_load_dwordx4 v[16:19], v98, s[10:11]
	global_load_dwordx4 v[20:23], v98, s[10:11] offset:256
	global_load_dwordx4 v[24:27], v99, s[10:11]
	global_load_dwordx4 v[28:31], v99, s[10:11] offset:256
	s_waitcnt vmcnt(8)
	v_mfma_scale_f32_16x16x128_f8f6f4 v[80:83], v[32:35], v[210:217], 0, v133, v133 op_sel_hi:[0,0,0] cbsz:4
	v_mfma_scale_f32_16x16x128_f8f6f4 v[80:83], v[36:39], v[218:225], v[80:83], v133, v133 op_sel_hi:[0,0,0] cbsz:4
	v_mfma_scale_f32_16x16x128_f8f6f4 v[84:87], v[40:43], v[210:217], 0, v133, v133 op_sel_hi:[0,0,0] cbsz:4
	v_mfma_scale_f32_16x16x128_f8f6f4 v[84:87], v[44:47], v[218:225], v[84:87], v133, v133 op_sel_hi:[0,0,0] cbsz:4
	v_mfma_scale_f32_16x16x128_f8f6f4 v[88:91], v[48:51], v[210:217], 0, v133, v133 op_sel_hi:[0,0,0] cbsz:4
	v_mfma_scale_f32_16x16x128_f8f6f4 v[88:91], v[52:55], v[218:225], v[88:91], v133, v133 op_sel_hi:[0,0,0] cbsz:4
	v_mfma_scale_f32_16x16x128_f8f6f4 v[92:95], v[56:59], v[210:217], 0, v133, v133 op_sel_hi:[0,0,0] cbsz:4
	v_mfma_scale_f32_16x16x128_f8f6f4 v[92:95], v[60:63], v[218:225], v[92:95], v133, v133 op_sel_hi:[0,0,0] cbsz:4
	s_nop 3
	v_mul_f32_e32 v234, v158, v64
	v_mul_f32_e32 v235, v158, v68
	v_mul_f32_e32 v236, v158, v72
	v_mul_f32_e32 v237, v158, v76
	v_fmac_f32_e32 v234, v159, v65
	v_fmac_f32_e32 v235, v159, v69
	v_fmac_f32_e32 v236, v159, v73
	v_fmac_f32_e32 v237, v159, v77
	v_fmac_f32_e32 v234, v160, v66
	v_fmac_f32_e32 v235, v160, v70
	v_fmac_f32_e32 v236, v160, v74
	v_fmac_f32_e32 v237, v160, v78
	v_fmac_f32_e32 v234, v161, v67
	v_fmac_f32_e32 v235, v161, v71
	v_fmac_f32_e32 v236, v161, v75
	v_fmac_f32_e32 v237, v161, v79
	v_add_f32_dpp v234, v234, v234 quad_perm:[1,0,3,2] row_mask:0xf bank_mask:0xf
	v_add_f32_dpp v235, v235, v235 quad_perm:[1,0,3,2] row_mask:0xf bank_mask:0xf
	v_add_f32_dpp v236, v236, v236 quad_perm:[1,0,3,2] row_mask:0xf bank_mask:0xf
	v_add_f32_dpp v237, v237, v237 quad_perm:[1,0,3,2] row_mask:0xf bank_mask:0xf
	v_add_f32_dpp v234, v234, v234 quad_perm:[2,3,0,1] row_mask:0xf bank_mask:0xf
	v_add_f32_dpp v235, v235, v235 quad_perm:[2,3,0,1] row_mask:0xf bank_mask:0xf
	v_add_f32_dpp v236, v236, v236 quad_perm:[2,3,0,1] row_mask:0xf bank_mask:0xf
	v_add_f32_dpp v237, v237, v237 quad_perm:[2,3,0,1] row_mask:0xf bank_mask:0xf
	v_add_f32_dpp v234, v234, v234 row_half_mirror row_mask:0xf bank_mask:0xf
	v_add_f32_dpp v235, v235, v235 row_half_mirror row_mask:0xf bank_mask:0xf
	v_add_f32_dpp v236, v236, v236 row_half_mirror row_mask:0xf bank_mask:0xf
	v_add_f32_dpp v237, v237, v237 row_half_mirror row_mask:0xf bank_mask:0xf
	s_mov_b32 exec_lo, 0x10001
	s_mov_b32 exec_hi, 0x10001
	ds_write_b32 v155, v234 offset:1472
	ds_write_b32 v155, v235 offset:1488
	ds_write_b32 v155, v236 offset:1504
	ds_write_b32 v155, v237 offset:1520
	s_mov_b64 exec, -1
	ds_read2_b32 v[230:231], v243 offset0:112 offset1:116
	ds_read2_b32 v[232:233], v243 offset0:120 offset1:124
	s_waitcnt lgkmcnt(0)
; __device__ __forceinline__ void peer_token(const Params& P, int t, int lane, int* sidx, float* sval, const int* sid, const float* sgate, const unsigned* szero) {
;     ...
;         uint4 abuf[2][2][4];
;         unsigned off2[2];
; #pragma unroll
;         for (int hh = 0; hh < 2; ++hh) off2[hh] = (unsigned)sid[8 * hh + (lr & 7)] * 512u + lofs;
; #pragma unroll
;         for (int hh = 0; hh < 2; ++hh)
; #pragma unroll
;             for (int st = 0; st < 4; ++st) abuf[0][hh][st] = *(const uint4*)(Ub + (off2[hh] + 128 * st));
; #pragma unroll
;         for (int T = 0; T < 8; ++T) {
;             if (T + 1 < 8) {
; #pragma unroll
;                 for (int hh = 0; hh < 2; ++hh) off2[hh] = (unsigned)sid[16 * (T + 1) + 8 * hh + (lr & 7)] * 512u + lofs;
; #pragma unroll
;                 for (int hh = 0; hh < 2; ++hh)
; #pragma unroll
;                     for (int st = 0; st < 4; ++st) abuf[(T + 1) & 1][hh][st] = *(const uint4*)(Ub + (off2[hh] + 128 * st));
;             }
; #pragma unroll
;             for (int hh = 0; hh < 2; ++hh) {
;                 f32x4 au = (f32x4){0.f, 0.f, 0.f, 0.f};
; #pragma unroll
;                 for (int st = 0; st < 4; ++st) {
;                     const uint4 a4 = abuf[T & 1][hh][st];
;                     const v8i Av = {(int)a4.x, (int)a4.y, (int)a4.z, (int)a4.w, 0, 0, 0, 0};
;                     au = __builtin_amdgcn_mfma_scale_f32_16x16x128_f8f6f4(Av, Bv[st], au, 4, 0, 0, 0x7f7f7f7f, 0, 0x7f7f7f7f);
;                 }
;                 if (owner) *(f32x4*)(sact + 16 * T + 8 * hh) = au;
;             }
;         }
	v_lshl_add_u32 v230, v230, 9, v144
	v_lshl_add_u32 v231, v231, 9, v144
	v_lshl_add_u32 v232, v232, 9, v144
	v_lshl_add_u32 v233, v233, 9, v144
	global_load_dwordx4 v[32:35], v230, s[10:11]
	global_load_dwordx4 v[36:39], v230, s[10:11] offset:256
	global_load_dwordx4 v[40:43], v231, s[10:11]
	global_load_dwordx4 v[44:47], v231, s[10:11] offset:256
	global_load_dwordx4 v[48:51], v232, s[10:11]
	global_load_dwordx4 v[52:55], v232, s[10:11] offset:256
	global_load_dwordx4 v[56:59], v233, s[10:11]
	global_load_dwordx4 v[60:63], v233, s[10:11] offset:256
	s_waitcnt vmcnt(8)
	v_mfma_scale_f32_16x16x128_f8f6f4 v[64:67], v[0:3], v[162:169], 0, v133, v133 op_sel_hi:[0,0,0] cbsz:4
	v_mfma_scale_f32_16x16x128_f8f6f4 v[64:67], v[4:7], v[170:177], v[64:67], v133, v133 op_sel_hi:[0,0,0] cbsz:4
	v_mfma_scale_f32_16x16x128_f8f6f4 v[68:71], v[8:11], v[162:169], 0, v133, v133 op_sel_hi:[0,0,0] cbsz:4
	v_mfma_scale_f32_16x16x128_f8f6f4 v[68:71], v[12:15], v[170:177], v[68:71], v133, v133 op_sel_hi:[0,0,0] cbsz:4
	v_mfma_scale_f32_16x16x128_f8f6f4 v[72:75], v[16:19], v[162:169], 0, v133, v133 op_sel_hi:[0,0,0] cbsz:4
	v_mfma_scale_f32_16x16x128_f8f6f4 v[72:75], v[20:23], v[170:177], v[72:75], v133, v133 op_sel_hi:[0,0,0] cbsz:4
	v_mfma_scale_f32_16x16x128_f8f6f4 v[76:79], v[24:27], v[162:169], 0, v133, v133 op_sel_hi:[0,0,0] cbsz:4
	v_mfma_scale_f32_16x16x128_f8f6f4 v[76:79], v[28:31], v[170:177], v[76:79], v133, v133 op_sel_hi:[0,0,0] cbsz:4
	s_nop 3
	v_mul_f32_e32 v234, v158, v80
	v_mul_f32_e32 v235, v158, v84
	v_mul_f32_e32 v236, v158, v88
	v_mul_f32_e32 v237, v158, v92
	v_fmac_f32_e32 v234, v159, v81
	v_fmac_f32_e32 v235, v159, v85
	v_fmac_f32_e32 v236, v159, v89
	v_fmac_f32_e32 v237, v159, v93
	v_fmac_f32_e32 v234, v160, v82
	v_fmac_f32_e32 v235, v160, v86
	v_fmac_f32_e32 v236, v160, v90
	v_fmac_f32_e32 v237, v160, v94
	v_fmac_f32_e32 v234, v161, v83
	v_fmac_f32_e32 v235, v161, v87
	v_fmac_f32_e32 v236, v161, v91
	v_fmac_f32_e32 v237, v161, v95
	v_add_f32_dpp v234, v234, v234 quad_perm:[1,0,3,2] row_mask:0xf bank_mask:0xf
	v_add_f32_dpp v235, v235, v235 quad_perm:[1,0,3,2] row_mask:0xf bank_mask:0xf
	v_add_f32_dpp v236, v236, v236 quad_perm:[1,0,3,2] row_mask:0xf bank_mask:0xf
	v_add_f32_dpp v237, v237, v237 quad_perm:[1,0,3,2] row_mask:0xf bank_mask:0xf
	v_add_f32_dpp v234, v234, v234 quad_perm:[2,3,0,1] row_mask:0xf bank_mask:0xf
	v_add_f32_dpp v235, v235, v235 quad_perm:[2,3,0,1] row_mask:0xf bank_mask:0xf
	v_add_f32_dpp v236, v236, v236 quad_perm:[2,3,0,1] row_mask:0xf bank_mask:0xf
	v_add_f32_dpp v237, v237, v237 quad_perm:[2,3,0,1] row_mask:0xf bank_mask:0xf
	v_add_f32_dpp v234, v234, v234 row_half_mirror row_mask:0xf bank_mask:0xf
	v_add_f32_dpp v235, v235, v235 row_half_mirror row_mask:0xf bank_mask:0xf
	v_add_f32_dpp v236, v236, v236 row_half_mirror row_mask:0xf bank_mask:0xf
	v_add_f32_dpp v237, v237, v237 row_half_mirror row_mask:0xf bank_mask:0xf
	s_mov_b32 exec_lo, 0x10001
	s_mov_b32 exec_hi, 0x10001
	ds_write_b32 v155, v234 offset:1984
	ds_write_b32 v155, v235 offset:2000
	ds_write_b32 v155, v236 offset:2016
	ds_write_b32 v155, v237 offset:2032
	s_mov_b64 exec, -1
	ds_read2_b32 v[96:97], v244 offset0:112 offset1:116
	ds_read2_b32 v[98:99], v244 offset0:120 offset1:124
	s_waitcnt lgkmcnt(0)
	v_lshl_add_u32 v96, v96, 9, v144
	v_lshl_add_u32 v97, v97, 9, v144
	v_lshl_add_u32 v98, v98, 9, v144
	v_lshl_add_u32 v99, v99, 9, v144
	global_load_dwordx4 v[0:3], v96, s[10:11]
	global_load_dwordx4 v[4:7], v96, s[10:11] offset:256
	global_load_dwordx4 v[8:11], v97, s[10:11]
	global_load_dwordx4 v[12:15], v97, s[10:11] offset:256
	global_load_dwordx4 v[16:19], v98, s[10:11]
	global_load_dwordx4 v[20:23], v98, s[10:11] offset:256
	global_load_dwordx4 v[24:27], v99, s[10:11]
	global_load_dwordx4 v[28:31], v99, s[10:11] offset:256
	s_waitcnt vmcnt(8)
	v_mfma_scale_f32_16x16x128_f8f6f4 v[80:83], v[32:35], v[178:185], 0, v133, v133 op_sel_hi:[0,0,0] cbsz:4
	v_mfma_scale_f32_16x16x128_f8f6f4 v[80:83], v[36:39], v[186:193], v[80:83], v133, v133 op_sel_hi:[0,0,0] cbsz:4
	v_mfma_scale_f32_16x16x128_f8f6f4 v[84:87], v[40:43], v[178:185], 0, v133, v133 op_sel_hi:[0,0,0] cbsz:4
	v_mfma_scale_f32_16x16x128_f8f6f4 v[84:87], v[44:47], v[186:193], v[84:87], v133, v133 op_sel_hi:[0,0,0] cbsz:4
	v_mfma_scale_f32_16x16x128_f8f6f4 v[88:91], v[48:51], v[178:185], 0, v133, v133 op_sel_hi:[0,0,0] cbsz:4
	v_mfma_scale_f32_16x16x128_f8f6f4 v[88:91], v[52:55], v[186:193], v[88:91], v133, v133 op_sel_hi:[0,0,0] cbsz:4
	v_mfma_scale_f32_16x16x128_f8f6f4 v[92:95], v[56:59], v[178:185], 0, v133, v133 op_sel_hi:[0,0,0] cbsz:4
	v_mfma_scale_f32_16x16x128_f8f6f4 v[92:95], v[60:63], v[186:193], v[92:95], v133, v133 op_sel_hi:[0,0,0] cbsz:4
	s_nop 3
	v_mul_f32_e32 v234, v226, v64
	v_mul_f32_e32 v235, v226, v68
	v_mul_f32_e32 v236, v226, v72
	v_mul_f32_e32 v237, v226, v76
	v_fmac_f32_e32 v234, v227, v65
	v_fmac_f32_e32 v235, v227, v69
	v_fmac_f32_e32 v236, v227, v73
	v_fmac_f32_e32 v237, v227, v77
	v_fmac_f32_e32 v234, v228, v66
	v_fmac_f32_e32 v235, v228, v70
	v_fmac_f32_e32 v236, v228, v74
	v_fmac_f32_e32 v237, v228, v78
	v_fmac_f32_e32 v234, v229, v67
	v_fmac_f32_e32 v235, v229, v71
	v_fmac_f32_e32 v236, v229, v75
	v_fmac_f32_e32 v237, v229, v79
	v_add_f32_dpp v234, v234, v234 quad_perm:[1,0,3,2] row_mask:0xf bank_mask:0xf
	v_add_f32_dpp v235, v235, v235 quad_perm:[1,0,3,2] row_mask:0xf bank_mask:0xf
	v_add_f32_dpp v236, v236, v236 quad_perm:[1,0,3,2] row_mask:0xf bank_mask:0xf
	v_add_f32_dpp v237, v237, v237 quad_perm:[1,0,3,2] row_mask:0xf bank_mask:0xf
	v_add_f32_dpp v234, v234, v234 quad_perm:[2,3,0,1] row_mask:0xf bank_mask:0xf
	v_add_f32_dpp v235, v235, v235 quad_perm:[2,3,0,1] row_mask:0xf bank_mask:0xf
	v_add_f32_dpp v236, v236, v236 quad_perm:[2,3,0,1] row_mask:0xf bank_mask:0xf
	v_add_f32_dpp v237, v237, v237 quad_perm:[2,3,0,1] row_mask:0xf bank_mask:0xf
	v_add_f32_dpp v234, v234, v234 row_half_mirror row_mask:0xf bank_mask:0xf
	v_add_f32_dpp v235, v235, v235 row_half_mirror row_mask:0xf bank_mask:0xf
	v_add_f32_dpp v236, v236, v236 row_half_mirror row_mask:0xf bank_mask:0xf
	v_add_f32_dpp v237, v237, v237 row_half_mirror row_mask:0xf bank_mask:0xf
	s_mov_b32 exec_lo, 0x1000100
	s_mov_b32 exec_hi, 0x1000100
	ds_write_b32 v155, v234 offset:2496
	ds_write_b32 v155, v235 offset:2512
	ds_write_b32 v155, v236 offset:2528
	ds_write_b32 v155, v237 offset:2544
	s_mov_b64 exec, -1
	ds_read2_b32 v[230:231], v245 offset0:112 offset1:116
	ds_read2_b32 v[232:233], v245 offset0:120 offset1:124
	s_waitcnt lgkmcnt(0)
; __device__ __forceinline__ void peer_token(const Params& P, int t, int lane, int* sidx, float* sval, const int* sid, const float* sgate, const unsigned* szero) {
;     ...
;         uint4 abuf[2][2][4];
;         unsigned off2[2];
; #pragma unroll
;         for (int hh = 0; hh < 2; ++hh) off2[hh] = (unsigned)sid[8 * hh + (lr & 7)] * 512u + lofs;
; #pragma unroll
;         for (int hh = 0; hh < 2; ++hh)
; #pragma unroll
;             for (int st = 0; st < 4; ++st) abuf[0][hh][st] = *(const uint4*)(Ub + (off2[hh] + 128 * st));
; #pragma unroll
;         for (int T = 0; T < 8; ++T) {
;             if (T + 1 < 8) {
; #pragma unroll
;                 for (int hh = 0; hh < 2; ++hh) off2[hh] = (unsigned)sid[16 * (T + 1) + 8 * hh + (lr & 7)] * 512u + lofs;
; #pragma unroll
;                 for (int hh = 0; hh < 2; ++hh)
; #pragma unroll
;                     for (int st = 0; st < 4; ++st) abuf[(T + 1) & 1][hh][st] = *(const uint4*)(Ub + (off2[hh] + 128 * st));
;             }
; #pragma unroll
;             for (int hh = 0; hh < 2; ++hh) {
;                 f32x4 au = (f32x4){0.f, 0.f, 0.f, 0.f};
; #pragma unroll
;                 for (int st = 0; st < 4; ++st) {
;                     const uint4 a4 = abuf[T & 1][hh][st];
;                     const v8i Av = {(int)a4.x, (int)a4.y, (int)a4.z, (int)a4.w, 0, 0, 0, 0};
;                     au = __builtin_amdgcn_mfma_scale_f32_16x16x128_f8f6f4(Av, Bv[st], au, 4, 0, 0, 0x7f7f7f7f, 0, 0x7f7f7f7f);
;                 }
;                 if (owner) *(f32x4*)(sact + 16 * T + 8 * hh) = au;
;             }
;         }
	v_lshl_add_u32 v230, v230, 9, v144
	v_lshl_add_u32 v231, v231, 9, v144
	v_lshl_add_u32 v232, v232, 9, v144
	v_lshl_add_u32 v233, v233, 9, v144
	global_load_dwordx4 v[32:35], v230, s[10:11]
	global_load_dwordx4 v[36:39], v230, s[10:11] offset:256
	global_load_dwordx4 v[40:43], v231, s[10:11]
	global_load_dwordx4 v[44:47], v231, s[10:11] offset:256
	global_load_dwordx4 v[48:51], v232, s[10:11]
	global_load_dwordx4 v[52:55], v232, s[10:11] offset:256
	global_load_dwordx4 v[56:59], v233, s[10:11]
	global_load_dwordx4 v[60:63], v233, s[10:11] offset:256
	s_waitcnt vmcnt(8)
	v_mfma_scale_f32_16x16x128_f8f6f4 v[64:67], v[0:3], v[194:201], 0, v133, v133 op_sel_hi:[0,0,0] cbsz:4
	v_mfma_scale_f32_16x16x128_f8f6f4 v[64:67], v[4:7], v[202:209], v[64:67], v133, v133 op_sel_hi:[0,0,0] cbsz:4
	v_mfma_scale_f32_16x16x128_f8f6f4 v[68:71], v[8:11], v[194:201], 0, v133, v133 op_sel_hi:[0,0,0] cbsz:4
	v_mfma_scale_f32_16x16x128_f8f6f4 v[68:71], v[12:15], v[202:209], v[68:71], v133, v133 op_sel_hi:[0,0,0] cbsz:4
	v_mfma_scale_f32_16x16x128_f8f6f4 v[72:75], v[16:19], v[194:201], 0, v133, v133 op_sel_hi:[0,0,0] cbsz:4
	v_mfma_scale_f32_16x16x128_f8f6f4 v[72:75], v[20:23], v[202:209], v[72:75], v133, v133 op_sel_hi:[0,0,0] cbsz:4
	v_mfma_scale_f32_16x16x128_f8f6f4 v[76:79], v[24:27], v[194:201], 0, v133, v133 op_sel_hi:[0,0,0] cbsz:4
	v_mfma_scale_f32_16x16x128_f8f6f4 v[76:79], v[28:31], v[202:209], v[76:79], v133, v133 op_sel_hi:[0,0,0] cbsz:4
	s_nop 3
	v_mul_f32_e32 v234, v226, v80
	v_mul_f32_e32 v235, v226, v84
	v_mul_f32_e32 v236, v226, v88
	v_mul_f32_e32 v237, v226, v92
	v_fmac_f32_e32 v234, v227, v81
	v_fmac_f32_e32 v235, v227, v85
	v_fmac_f32_e32 v236, v227, v89
	v_fmac_f32_e32 v237, v227, v93
	v_fmac_f32_e32 v234, v228, v82
	v_fmac_f32_e32 v235, v228, v86
	v_fmac_f32_e32 v236, v228, v90
	v_fmac_f32_e32 v237, v228, v94
	v_fmac_f32_e32 v234, v229, v83
	v_fmac_f32_e32 v235, v229, v87
	v_fmac_f32_e32 v236, v229, v91
	v_fmac_f32_e32 v237, v229, v95
	v_add_f32_dpp v234, v234, v234 quad_perm:[1,0,3,2] row_mask:0xf bank_mask:0xf
	v_add_f32_dpp v235, v235, v235 quad_perm:[1,0,3,2] row_mask:0xf bank_mask:0xf
	v_add_f32_dpp v236, v236, v236 quad_perm:[1,0,3,2] row_mask:0xf bank_mask:0xf
	v_add_f32_dpp v237, v237, v237 quad_perm:[1,0,3,2] row_mask:0xf bank_mask:0xf
	v_add_f32_dpp v234, v234, v234 quad_perm:[2,3,0,1] row_mask:0xf bank_mask:0xf
	v_add_f32_dpp v235, v235, v235 quad_perm:[2,3,0,1] row_mask:0xf bank_mask:0xf
	v_add_f32_dpp v236, v236, v236 quad_perm:[2,3,0,1] row_mask:0xf bank_mask:0xf
	v_add_f32_dpp v237, v237, v237 quad_perm:[2,3,0,1] row_mask:0xf bank_mask:0xf
	v_add_f32_dpp v234, v234, v234 row_half_mirror row_mask:0xf bank_mask:0xf
	v_add_f32_dpp v235, v235, v235 row_half_mirror row_mask:0xf bank_mask:0xf
	v_add_f32_dpp v236, v236, v236 row_half_mirror row_mask:0xf bank_mask:0xf
	v_add_f32_dpp v237, v237, v237 row_half_mirror row_mask:0xf bank_mask:0xf
	s_mov_b32 exec_lo, 0x1000100
	s_mov_b32 exec_hi, 0x1000100
	ds_write_b32 v155, v234 offset:3008
	ds_write_b32 v155, v235 offset:3024
	ds_write_b32 v155, v236 offset:3040
	ds_write_b32 v155, v237 offset:3056
	s_mov_b64 exec, -1
	s_waitcnt vmcnt(0)
; __device__ __forceinline__ void peer_token(const Params& P, int t, int lane, int* sidx, float* sval, const int* sid, const float* sgate, const unsigned* szero) {
;     ...
;         for (int hh = 0; hh < 2; ++hh)
; #pragma unroll
;             for (int st = 0; st < 4; ++st) abuf[0][hh][st] = *(const uint4*)(Ub + (off2[hh] + 128 * st));
; #pragma unroll
;         for (int T = 0; T < 8; ++T) {
;             if (T + 1 < 8) {
; #pragma unroll
;                 for (int hh = 0; hh < 2; ++hh) off2[hh] = (unsigned)sid[16 * (T + 1) + 8 * hh + (lr & 7)] * 512u + lofs;
; #pragma unroll
;                 for (int hh = 0; hh < 2; ++hh)
; #pragma unroll
;                     for (int st = 0; st < 4; ++st) abuf[(T + 1) & 1][hh][st] = *(const uint4*)(Ub + (off2[hh] + 128 * st));
;             }
; #pragma unroll
;             for (int hh = 0; hh < 2; ++hh) {
;                 f32x4 au = (f32x4){0.f, 0.f, 0.f, 0.f};
; #pragma unroll
;                 for (int st = 0; st < 4; ++st) {
;                     const uint4 a4 = abuf[T & 1][hh][st];
;                     const v8i Av = {(int)a4.x, (int)a4.y, (int)a4.z, (int)a4.w, 0, 0, 0, 0};
;                     au = __builtin_amdgcn_mfma_scale_f32_16x16x128_f8f6f4(Av, Bv[st], au, 4, 0, 0, 0x7f7f7f7f, 0, 0x7f7f7f7f);
;                 }
;                 if (owner) *(f32x4*)(sact + 16 * T + 8 * hh) = au;
;             }
;         }
;     }
;     __builtin_amdgcn_s_waitcnt(0xc07f);
;     __builtin_amdgcn_wave_barrier();
	v_mfma_scale_f32_16x16x128_f8f6f4 v[80:83], v[32:35], v[210:217], 0, v133, v133 op_sel_hi:[0,0,0] cbsz:4
	v_mfma_scale_f32_16x16x128_f8f6f4 v[80:83], v[36:39], v[218:225], v[80:83], v133, v133 op_sel_hi:[0,0,0] cbsz:4
	v_mfma_scale_f32_16x16x128_f8f6f4 v[84:87], v[40:43], v[210:217], 0, v133, v133 op_sel_hi:[0,0,0] cbsz:4
	v_mfma_scale_f32_16x16x128_f8f6f4 v[84:87], v[44:47], v[218:225], v[84:87], v133, v133 op_sel_hi:[0,0,0] cbsz:4
	v_mfma_scale_f32_16x16x128_f8f6f4 v[88:91], v[48:51], v[210:217], 0, v133, v133 op_sel_hi:[0,0,0] cbsz:4
	v_mfma_scale_f32_16x16x128_f8f6f4 v[88:91], v[52:55], v[218:225], v[88:91], v133, v133 op_sel_hi:[0,0,0] cbsz:4
	v_mfma_scale_f32_16x16x128_f8f6f4 v[92:95], v[56:59], v[210:217], 0, v133, v133 op_sel_hi:[0,0,0] cbsz:4
	v_mfma_scale_f32_16x16x128_f8f6f4 v[92:95], v[60:63], v[218:225], v[92:95], v133, v133 op_sel_hi:[0,0,0] cbsz:4
	s_nop 3
	v_mul_f32_e32 v234, v226, v64
	v_mul_f32_e32 v235, v226, v68
	v_mul_f32_e32 v236, v226, v72
	v_mul_f32_e32 v237, v226, v76
	v_fmac_f32_e32 v234, v227, v65
	v_fmac_f32_e32 v235, v227, v69
	v_fmac_f32_e32 v236, v227, v73
	v_fmac_f32_e32 v237, v227, v77
	v_fmac_f32_e32 v234, v228, v66
	v_fmac_f32_e32 v235, v228, v70
	v_fmac_f32_e32 v236, v228, v74
	v_fmac_f32_e32 v237, v228, v78
	v_fmac_f32_e32 v234, v229, v67
	v_fmac_f32_e32 v235, v229, v71
	v_fmac_f32_e32 v236, v229, v75
	v_fmac_f32_e32 v237, v229, v79
	v_add_f32_dpp v234, v234, v234 quad_perm:[1,0,3,2] row_mask:0xf bank_mask:0xf
	v_add_f32_dpp v235, v235, v235 quad_perm:[1,0,3,2] row_mask:0xf bank_mask:0xf
	v_add_f32_dpp v236, v236, v236 quad_perm:[1,0,3,2] row_mask:0xf bank_mask:0xf
	v_add_f32_dpp v237, v237, v237 quad_perm:[1,0,3,2] row_mask:0xf bank_mask:0xf
	v_add_f32_dpp v234, v234, v234 quad_perm:[2,3,0,1] row_mask:0xf bank_mask:0xf
	v_add_f32_dpp v235, v235, v235 quad_perm:[2,3,0,1] row_mask:0xf bank_mask:0xf
	v_add_f32_dpp v236, v236, v236 quad_perm:[2,3,0,1] row_mask:0xf bank_mask:0xf
	v_add_f32_dpp v237, v237, v237 quad_perm:[2,3,0,1] row_mask:0xf bank_mask:0xf
	v_add_f32_dpp v234, v234, v234 row_half_mirror row_mask:0xf bank_mask:0xf
	v_add_f32_dpp v235, v235, v235 row_half_mirror row_mask:0xf bank_mask:0xf
	v_add_f32_dpp v236, v236, v236 row_half_mirror row_mask:0xf bank_mask:0xf
	v_add_f32_dpp v237, v237, v237 row_half_mirror row_mask:0xf bank_mask:0xf
	s_mov_b32 exec_lo, 0x1000100
	s_mov_b32 exec_hi, 0x1000100
	ds_write_b32 v155, v234 offset:3520
	ds_write_b32 v155, v235 offset:3536
	ds_write_b32 v155, v236 offset:3552
	ds_write_b32 v155, v237 offset:3568
	s_mov_b64 exec, -1
	s_nop 11
	v_mul_f32_e32 v234, v226, v80
	v_mul_f32_e32 v235, v226, v84
	v_mul_f32_e32 v236, v226, v88
	v_mul_f32_e32 v237, v226, v92
	v_fmac_f32_e32 v234, v227, v81
	v_fmac_f32_e32 v235, v227, v85
	v_fmac_f32_e32 v236, v227, v89
	v_fmac_f32_e32 v237, v227, v93
	v_fmac_f32_e32 v234, v228, v82
	v_fmac_f32_e32 v235, v228, v86
	v_fmac_f32_e32 v236, v228, v90
	v_fmac_f32_e32 v237, v228, v94
	v_fmac_f32_e32 v234, v229, v83
	v_fmac_f32_e32 v235, v229, v87
	v_fmac_f32_e32 v236, v229, v91
	v_fmac_f32_e32 v237, v229, v95
	v_add_f32_dpp v234, v234, v234 quad_perm:[1,0,3,2] row_mask:0xf bank_mask:0xf
	v_add_f32_dpp v235, v235, v235 quad_perm:[1,0,3,2] row_mask:0xf bank_mask:0xf
	v_add_f32_dpp v236, v236, v236 quad_perm:[1,0,3,2] row_mask:0xf bank_mask:0xf
	v_add_f32_dpp v237, v237, v237 quad_perm:[1,0,3,2] row_mask:0xf bank_mask:0xf
	v_add_f32_dpp v234, v234, v234 quad_perm:[2,3,0,1] row_mask:0xf bank_mask:0xf
	v_add_f32_dpp v235, v235, v235 quad_perm:[2,3,0,1] row_mask:0xf bank_mask:0xf
	v_add_f32_dpp v236, v236, v236 quad_perm:[2,3,0,1] row_mask:0xf bank_mask:0xf
	v_add_f32_dpp v237, v237, v237 quad_perm:[2,3,0,1] row_mask:0xf bank_mask:0xf
	v_add_f32_dpp v234, v234, v234 row_half_mirror row_mask:0xf bank_mask:0xf
	v_add_f32_dpp v235, v235, v235 row_half_mirror row_mask:0xf bank_mask:0xf
	v_add_f32_dpp v236, v236, v236 row_half_mirror row_mask:0xf bank_mask:0xf
	v_add_f32_dpp v237, v237, v237 row_half_mirror row_mask:0xf bank_mask:0xf
	s_mov_b32 exec_lo, 0x1000100
	s_mov_b32 exec_hi, 0x1000100
	ds_write_b32 v155, v234 offset:4032
	ds_write_b32 v155, v235 offset:4048
	ds_write_b32 v155, v236 offset:4064
	ds_write_b32 v155, v237 offset:4080
	s_mov_b64 exec, -1
	s_waitcnt lgkmcnt(0)
	s_mov_b32 s85, 0
